# epilogues: rstd via v_rsq_f32 everywhere (LN/RMS), phase-4 row stats and MLA q/kv ssq rows preloaded at epilogue start
# speedup vs baseline: 1.0143x; 1.0143x over previous
;     __device__ __forceinline__ void operator()(EPI_ARGS) const {
;         const int row0 = u.pm * BM + wr * 64 + fr, col0 = u.pn * BM + wc * 32 + 8 * fq;
;         f32x4 gg[2][2], bb[2][2];
;         if constexpr (RESLN) {
; #pragma unroll
;             for (int bj = 0; bj < 2; ++bj)
; #pragma unroll
;                 for (int n = 0; n < 2; ++n) { gg[bj][n] = *(const f32x4*)(lg + col0 + bj * HALF + 4 * n); bb[bj][n] = *(const f32x4*)(lb + col0 + bj * HALF + 4 * n); } }
; #pragma unroll
;         for (int ai = 0; ai < 2; ++ai)
; #pragma unroll
;             for (int m = 0; m < 4; ++m) { const int row = row0 + ai * HALF + m * 16; const size_t off = (size_t)row * DM + col0;
;                 float mu = 0.f, rs = 1.f; if constexpr (RESLN) ln_stats(stin, row, mu, rs);
;                 float ss = 0.f, qq = 0.f;
; #pragma unroll
;                 for (int bj = 0; bj < 2; ++bj) { f32x4 r0 = __builtin_nontemporal_load((const f32x4*)(res + off + bj * HALF)), r1 = __builtin_nontemporal_load((const f32x4*)(res + off + bj * HALF + 4));
;                     if constexpr (RESLN) { r0 = (r0 - mu) * rs * gg[bj][0] + bb[bj][0]; r1 = (r1 - mu) * rs * gg[bj][1] + bb[bj][1]; }
;                     const f32x4 y0 = r0 * DN_ALPHA + acc[ai][bj][m][0] * ascale, y1 = r1 * DN_ALPHA + acc[ai][bj][m][1] * ascale;
;                     if constexpr (COPY != 4) { __builtin_nontemporal_store(y0, (f32x4*)(Y + off + bj * HALF)); __builtin_nontemporal_store(y1, (f32x4*)(Y + off + bj * HALF + 4)); }
;                     if constexpr (STATS) { ss += ((y0[0] + y0[1]) + (y0[2] + y0[3])) + ((y1[0] + y1[1]) + (y1[2] + y1[3]));
;                         qq += ((y0[0] * y0[0] + y0[1] * y0[1]) + (y0[2] * y0[2] + y0[3] * y0[3])) + ((y1[0] * y1[0] + y1[1] * y1[1]) + (y1[2] * y1[2] + y1[3] * y1[3])); }
;                     if constexpr (COPY == 1) *(u32x2*)((unsigned char*)copy + off + bj * HALF) = pack8fp8(y0 * cscale, y1 * cscale);
;                     if constexpr (COPY == 3) *(u32x2*)((unsigned char*)copy + off + bj * HALF) = pack8i8(y0 * cscale, y1 * cscale);
;                     if constexpr (COPY == 2 || COPY == 4) *(u32x4*)((bf16_t*)copy + off + bj * HALF) = pack8bf(y0, y1); }
;                 if constexpr (STATS) { ss += __shfl_xor(ss, 16); ss += __shfl_xor(ss, 32); qq += __shfl_xor(qq, 16); qq += __shfl_xor(qq, 32);
.LBB0_3861:
	v_lshl_add_u32 v178, s69, 8, v186
	v_lshl_or_b32 v176, s70, 8, v188
	v_ashrrev_i32_e32 v179, 31, v178
	v_ashrrev_i32_e32 v177, 31, v176
	v_lshlrev_b64 v[0:1], 11, v[178:179]
	v_lshlrev_b64 v[180:181], 3, v[178:179]
	v_lshl_add_u64 v[184:185], v[0:1], 0, v[176:177]
	v_lshl_add_u64 v[0:1], s[14:15], 0, v[180:181]
	global_load_dwordx2 v[204:205], v[0:1], off
	v_lshl_add_u64 v[182:183], v[184:185], 2, s[18:19]
	global_load_dwordx4 v[196:199], v[182:183], off nt
	global_load_dwordx4 v[200:203], v[182:183], off offset:16 nt
	v_lshlrev_b64 v[0:1], 2, v[176:177]
	v_lshl_add_u64 v[4:5], s[8:9], 0, v[0:1]
	v_lshl_add_u64 v[12:13], s[10:11], 0, v[0:1]
	global_load_dwordx4 v[16:19], v[12:13], off
	global_load_dwordx4 v[28:31], v[4:5], off
	global_load_dwordx4 v[20:23], v[4:5], off offset:16
	global_load_dwordx4 v[24:27], v[12:13], off offset:16
	global_load_dwordx4 v[0:3], v[4:5], off offset:528
	global_load_dwordx4 v[8:11], v[4:5], off offset:512
	s_nop 0
	global_load_dwordx4 v[4:7], v[12:13], off offset:528
	s_nop 0
	global_load_dwordx4 v[12:15], v[12:13], off offset:512
	v_lshl_add_u64 v[184:185], s[20:21], 0, v[184:185]
	s_waitcnt vmcnt(0)
	v_pk_mul_f32 v[208:209], v[204:205], s[28:29] op_sel_hi:[1,0]
	s_nop 0
	v_fma_f32 v179, -v208, v208, v209
	v_add_f32_e32 v179, 0x3727c5ac, v179
	v_rsq_f32_e32 v254, v179
	v_sub_f32_e32 v199, v199, v208
	v_sub_f32_e32 v198, v198, v208
	v_sub_f32_e32 v197, v197, v208
	v_sub_f32_e32 v196, v196, v208
	v_sub_f32_e32 v203, v203, v208
	v_sub_f32_e32 v202, v202, v208
	v_sub_f32_e32 v201, v201, v208
	v_sub_f32_e32 v200, v200, v208
	s_nop 0
	s_nop 1
	v_mov_b32_e32 v210, v254
	v_pk_mul_f32 v[196:197], v[196:197], v[210:211] op_sel_hi:[1,0]
	v_pk_mul_f32 v[198:199], v[198:199], v[210:211] op_sel_hi:[1,0]
	v_pk_mul_f32 v[200:201], v[200:201], v[210:211] op_sel_hi:[1,0]
	v_pk_mul_f32 v[202:203], v[202:203], v[210:211] op_sel_hi:[1,0]
	v_pk_fma_f32 v[198:199], v[30:31], v[198:199], v[18:19]
	v_pk_fma_f32 v[196:197], v[28:29], v[196:197], v[16:17]
	v_pk_fma_f32 v[202:203], v[22:23], v[202:203], v[26:27]
	v_pk_fma_f32 v[200:201], v[20:21], v[200:201], v[24:25]
	v_pk_mul_f32 v[196:197], v[196:197], s[30:31] op_sel_hi:[1,0]
	v_pk_mul_f32 v[198:199], v[198:199], s[30:31] op_sel_hi:[1,0]
	v_pk_mul_f32 v[200:201], v[200:201], s[30:31] op_sel_hi:[1,0]
	v_pk_mul_f32 v[202:203], v[202:203], s[30:31] op_sel_hi:[1,0]
	v_pk_fma_f32 v[158:159], v[158:159], s[36:37], v[198:199] op_sel_hi:[1,0,1]
	v_pk_fma_f32 v[156:157], v[156:157], s[36:37], v[196:197] op_sel_hi:[1,0,1]
	v_pk_fma_f32 v[198:199], v[154:155], s[36:37], v[202:203] op_sel_hi:[1,0,1]
	v_pk_fma_f32 v[196:197], v[152:153], s[36:37], v[200:201] op_sel_hi:[1,0,1]
	v_pk_mul_f32 v[152:153], v[158:159], s[38:39] op_sel_hi:[1,0]
	v_pk_mul_f32 v[154:155], v[156:157], s[38:39] op_sel_hi:[1,0]
	v_pk_mul_f32 v[200:201], v[198:199], s[38:39] op_sel_hi:[1,0]
	v_pk_mul_f32 v[202:203], v[196:197], s[38:39] op_sel_hi:[1,0]
	v_med3_f32 v154, v154, s64, v195
	v_med3_f32 v155, v155, s64, v195
	v_med3_f32 v152, v152, s64, v195
	v_med3_f32 v153, v153, s64, v195
	v_med3_f32 v179, v202, s64, v195
	v_med3_f32 v202, v203, s64, v195
	v_med3_f32 v200, v200, s64, v195
	v_med3_f32 v201, v201, s64, v195
	v_add_f32_e32 v154, 0x4b400000, v154
	v_add_f32_e32 v155, 0x4b400000, v155
	v_add_f32_e32 v152, 0x4b400000, v152
	v_add_f32_e32 v153, 0x4b400000, v153
	v_add_f32_e32 v179, 0x4b400000, v179
	v_add_f32_e32 v202, 0x4b400000, v202
	v_add_f32_e32 v200, 0x4b400000, v200
	v_add_f32_e32 v201, 0x4b400000, v201
	v_perm_b32 v154, v155, v154, s65
	v_perm_b32 v152, v153, v152, s66
	v_perm_b32 v153, v202, v179, s65
	v_perm_b32 v155, v201, v200, s66
	v_or_b32_e32 v152, v154, v152
	v_or_b32_e32 v153, v153, v155
	global_store_dwordx4 v[182:183], v[156:159], off nt
	global_store_dwordx4 v[182:183], v[196:199], off offset:16 nt
	global_store_dwordx2 v[184:185], v[152:153], off
	global_load_dwordx4 v[200:203], v[182:183], off offset:512 nt
	global_load_dwordx4 v[204:207], v[182:183], off offset:528 nt
	v_and_b32_e32 v153, 64, v193
	v_xor_b32_e32 v152, 16, v193
	v_add_u32_e32 v153, 64, v153
	v_xor_b32_e32 v154, 32, v193
	v_cmp_lt_i32_e32 vcc, v152, v153
	v_add_f32_e32 v155, v158, v159
	v_add_f32_e32 v179, v196, v197
	v_cndmask_b32_e32 v152, v193, v152, vcc
	v_cmp_lt_i32_e32 vcc, v154, v153
	v_lshlrev_b32_e32 v153, 2, v152
	v_add_f32_e32 v209, v198, v199
	v_cndmask_b32_e32 v154, v193, v154, vcc
	v_lshlrev_b32_e32 v152, 2, v154
	v_add_f32_e32 v154, v156, v157
	v_mul_f32_e32 v157, v157, v157
	v_mul_f32_e32 v159, v159, v159
	v_mul_f32_e32 v197, v197, v197
	v_mul_f32_e32 v199, v199, v199
	v_add_f32_e32 v154, v154, v155
	v_add_f32_e32 v155, v179, v209
	v_fmac_f32_e32 v157, v156, v156
	v_fmac_f32_e32 v159, v158, v158
	v_fmac_f32_e32 v197, v196, v196
	v_fmac_f32_e32 v199, v198, v198
	v_add_f32_e32 v154, v154, v155
	v_add_f32_e32 v155, v157, v159
	v_add_f32_e32 v156, v197, v199
	v_add_f32_e32 v179, 0, v154
	v_add_f32_e32 v198, v155, v156
	s_waitcnt vmcnt(1)
	v_sub_f32_e32 v155, v203, v208
	v_sub_f32_e32 v154, v202, v208
	v_sub_f32_e32 v157, v201, v208
	v_sub_f32_e32 v156, v200, v208
	s_waitcnt vmcnt(0)
;     __device__ __forceinline__ void operator()(EPI_ARGS) const {
;         const int row0 = u.pm * BM + wr * 64 + fr, col0 = u.pn * BM + wc * 32 + 8 * fq;
;         f32x4 gg[2][2], bb[2][2];
;         if constexpr (RESLN) {
; #pragma unroll
;             for (int bj = 0; bj < 2; ++bj)
; #pragma unroll
;                 for (int n = 0; n < 2; ++n) { gg[bj][n] = *(const f32x4*)(lg + col0 + bj * HALF + 4 * n); bb[bj][n] = *(const f32x4*)(lb + col0 + bj * HALF + 4 * n); } }
; #pragma unroll
;         for (int ai = 0; ai < 2; ++ai)
; #pragma unroll
;             for (int m = 0; m < 4; ++m) { const int row = row0 + ai * HALF + m * 16; const size_t off = (size_t)row * DM + col0;
;                 float mu = 0.f, rs = 1.f; if constexpr (RESLN) ln_stats(stin, row, mu, rs);
;                 float ss = 0.f, qq = 0.f;
; #pragma unroll
;                 for (int bj = 0; bj < 2; ++bj) { f32x4 r0 = __builtin_nontemporal_load((const f32x4*)(res + off + bj * HALF)), r1 = __builtin_nontemporal_load((const f32x4*)(res + off + bj * HALF + 4));
;                     if constexpr (RESLN) { r0 = (r0 - mu) * rs * gg[bj][0] + bb[bj][0]; r1 = (r1 - mu) * rs * gg[bj][1] + bb[bj][1]; }
;                     const f32x4 y0 = r0 * DN_ALPHA + acc[ai][bj][m][0] * ascale, y1 = r1 * DN_ALPHA + acc[ai][bj][m][1] * ascale;
;                     if constexpr (COPY != 4) { __builtin_nontemporal_store(y0, (f32x4*)(Y + off + bj * HALF)); __builtin_nontemporal_store(y1, (f32x4*)(Y + off + bj * HALF + 4)); }
;                     if constexpr (STATS) { ss += ((y0[0] + y0[1]) + (y0[2] + y0[3])) + ((y1[0] + y1[1]) + (y1[2] + y1[3]));
;                         qq += ((y0[0] * y0[0] + y0[1] * y0[1]) + (y0[2] * y0[2] + y0[3] * y0[3])) + ((y1[0] * y1[0] + y1[1] * y1[1]) + (y1[2] * y1[2] + y1[3] * y1[3])); }
;                     if constexpr (COPY == 1) *(u32x2*)((unsigned char*)copy + off + bj * HALF) = pack8fp8(y0 * cscale, y1 * cscale);
;                     if constexpr (COPY == 3) *(u32x2*)((unsigned char*)copy + off + bj * HALF) = pack8i8(y0 * cscale, y1 * cscale);
;                     if constexpr (COPY == 2 || COPY == 4) *(u32x4*)((bf16_t*)copy + off + bj * HALF) = pack8bf(y0, y1); }
;                 if constexpr (STATS) { ss += __shfl_xor(ss, 16); ss += __shfl_xor(ss, 32); qq += __shfl_xor(qq, 16); qq += __shfl_xor(qq, 32);
	v_sub_f32_e32 v159, v207, v208
	v_sub_f32_e32 v158, v206, v208
	v_sub_f32_e32 v197, v205, v208
	v_sub_f32_e32 v196, v204, v208
	v_pk_mul_f32 v[156:157], v[156:157], v[210:211] op_sel_hi:[1,0]
	v_pk_mul_f32 v[154:155], v[154:155], v[210:211] op_sel_hi:[1,0]
	v_pk_mul_f32 v[196:197], v[196:197], v[210:211] op_sel_hi:[1,0]
	v_pk_mul_f32 v[158:159], v[158:159], v[210:211] op_sel_hi:[1,0]
	v_pk_fma_f32 v[154:155], v[10:11], v[154:155], v[14:15]
	v_pk_fma_f32 v[156:157], v[8:9], v[156:157], v[12:13]
	v_pk_fma_f32 v[158:159], v[2:3], v[158:159], v[6:7]
	v_pk_fma_f32 v[196:197], v[0:1], v[196:197], v[4:5]
	v_pk_mul_f32 v[156:157], v[156:157], s[30:31] op_sel_hi:[1,0]
	v_pk_mul_f32 v[154:155], v[154:155], s[30:31] op_sel_hi:[1,0]
	v_pk_mul_f32 v[196:197], v[196:197], s[30:31] op_sel_hi:[1,0]
	v_pk_mul_f32 v[158:159], v[158:159], s[30:31] op_sel_hi:[1,0]
	v_pk_fma_f32 v[150:151], v[150:151], s[36:37], v[154:155] op_sel_hi:[1,0,1]
	v_pk_fma_f32 v[148:149], v[148:149], s[36:37], v[156:157] op_sel_hi:[1,0,1]
	v_pk_fma_f32 v[146:147], v[146:147], s[36:37], v[158:159] op_sel_hi:[1,0,1]
	v_pk_fma_f32 v[144:145], v[144:145], s[36:37], v[196:197] op_sel_hi:[1,0,1]
	v_add_f32_e32 v196, v148, v149
	v_add_f32_e32 v197, v150, v151
	v_add_f32_e32 v199, v144, v145
	v_add_f32_e32 v200, v146, v147
	v_mul_f32_e32 v201, v149, v149
	v_mul_f32_e32 v202, v151, v151
	v_mul_f32_e32 v203, v145, v145
	v_mul_f32_e32 v204, v147, v147
	global_store_dwordx4 v[182:183], v[148:151], off offset:512 nt
	global_store_dwordx4 v[182:183], v[144:147], off offset:528 nt
	v_pk_mul_f32 v[156:157], v[148:149], s[38:39] op_sel_hi:[1,0]
	v_pk_mul_f32 v[158:159], v[146:147], s[38:39] op_sel_hi:[1,0]
	v_pk_mul_f32 v[182:183], v[144:145], s[38:39] op_sel_hi:[1,0]
	v_add_f32_e32 v145, v196, v197
	v_add_f32_e32 v147, v199, v200
	v_fmac_f32_e32 v201, v148, v148
	v_fmac_f32_e32 v202, v150, v150
	v_fmac_f32_e32 v203, v144, v144
	v_fmac_f32_e32 v204, v146, v146
	v_med3_f32 v144, v156, s64, v195
	v_add_f32_e32 v145, v145, v147
	v_add_f32_e32 v147, v201, v202
	v_add_f32_e32 v156, v203, v204
	v_med3_f32 v146, v157, s64, v195
	v_add_f32_e32 v147, v147, v156
	v_add_f32_e32 v144, 0x4b400000, v144
	v_add_f32_e32 v146, 0x4b400000, v146
	v_add_f32_e32 v145, v145, v179
	v_add_f32_e32 v147, v198, v147
	v_perm_b32 v144, v146, v144, s65
	ds_bpermute_b32 v146, v153, v145
	ds_bpermute_b32 v156, v153, v147
	v_pk_mul_f32 v[154:155], v[150:151], s[38:39] op_sel_hi:[1,0]
	v_med3_f32 v150, v182, s64, v195
	v_med3_f32 v148, v154, s64, v195
	v_med3_f32 v149, v155, s64, v195
	v_add_f32_e32 v148, 0x4b400000, v148
	v_add_f32_e32 v149, 0x4b400000, v149
	v_perm_b32 v148, v149, v148, s66
	v_or_b32_e32 v148, v144, v148
	s_waitcnt lgkmcnt(1)
	v_add_f32_e32 v144, v145, v146
	s_waitcnt lgkmcnt(0)
	v_add_f32_e32 v146, v147, v156
	ds_bpermute_b32 v145, v152, v144
	ds_bpermute_b32 v147, v152, v146
	v_med3_f32 v151, v183, s64, v195
	v_med3_f32 v154, v158, s64, v195
	v_med3_f32 v155, v159, s64, v195
	v_add_f32_e32 v150, 0x4b400000, v150
	v_add_f32_e32 v151, 0x4b400000, v151
	v_add_f32_e32 v154, 0x4b400000, v154
	v_add_f32_e32 v155, 0x4b400000, v155
	v_perm_b32 v149, v151, v150, s65
	v_perm_b32 v150, v155, v154, s66
	v_or_b32_e32 v149, v149, v150
	global_store_dwordx2 v[184:185], v[148:149], off offset:128
	s_and_saveexec_b64 s[6:7], s[2:3]
	s_cbranch_execz .LBB0_3863
	v_lshl_add_u64 v[148:149], s[12:13], 0, v[180:181]
	s_waitcnt lgkmcnt(1)
	v_add_f32_e32 v144, v144, v145
	s_waitcnt lgkmcnt(0)
	v_add_f32_e32 v145, v146, v147
	global_atomic_add_f32 v[148:149], v144, off
	global_atomic_add_f32 v[148:149], v145, off offset:4
.LBB0_3863:
	s_or_b64 exec, exec, s[6:7]
	v_or_b32_e32 v144, 16, v178
	s_waitcnt lgkmcnt(1)
	v_ashrrev_i32_e32 v145, 31, v144
	s_waitcnt lgkmcnt(0)
	v_lshlrev_b64 v[146:147], 11, v[144:145]
	v_lshlrev_b64 v[144:145], 3, v[144:145]
	v_lshl_add_u64 v[158:159], v[146:147], 0, v[176:177]
	v_lshl_add_u64 v[146:147], s[14:15], 0, v[144:145]
	global_load_dwordx2 v[180:181], v[146:147], off
	v_lshl_add_u64 v[146:147], v[158:159], 2, s[18:19]
	global_load_dwordx4 v[148:151], v[146:147], off nt
	global_load_dwordx4 v[154:157], v[146:147], off offset:16 nt
	v_lshl_add_u64 v[158:159], s[20:21], 0, v[158:159]
	s_waitcnt vmcnt(2)
	v_pk_mul_f32 v[180:181], v[180:181], s[28:29] op_sel_hi:[1,0]
	s_nop 0
	v_fma_f32 v179, -v180, v180, v181
	v_add_f32_e32 v179, 0x3727c5ac, v179
	v_rsq_f32_e32 v254, v179
	s_waitcnt vmcnt(1)
	v_sub_f32_e32 v151, v151, v180
	v_sub_f32_e32 v150, v150, v180
	v_sub_f32_e32 v149, v149, v180
	v_sub_f32_e32 v148, v148, v180
	s_waitcnt vmcnt(0)
;     __device__ __forceinline__ void operator()(EPI_ARGS) const {
;         const int row0 = u.pm * BM + wr * 64 + fr, col0 = u.pn * BM + wc * 32 + 8 * fq;
;         f32x4 gg[2][2], bb[2][2];
;         if constexpr (RESLN) {
; #pragma unroll
;             for (int bj = 0; bj < 2; ++bj)
; #pragma unroll
;                 for (int n = 0; n < 2; ++n) { gg[bj][n] = *(const f32x4*)(lg + col0 + bj * HALF + 4 * n); bb[bj][n] = *(const f32x4*)(lb + col0 + bj * HALF + 4 * n); } }
; #pragma unroll
;         for (int ai = 0; ai < 2; ++ai)
; #pragma unroll
;             for (int m = 0; m < 4; ++m) { const int row = row0 + ai * HALF + m * 16; const size_t off = (size_t)row * DM + col0;
;                 float mu = 0.f, rs = 1.f; if constexpr (RESLN) ln_stats(stin, row, mu, rs);
;                 float ss = 0.f, qq = 0.f;
; #pragma unroll
;                 for (int bj = 0; bj < 2; ++bj) { f32x4 r0 = __builtin_nontemporal_load((const f32x4*)(res + off + bj * HALF)), r1 = __builtin_nontemporal_load((const f32x4*)(res + off + bj * HALF + 4));
;                     if constexpr (RESLN) { r0 = (r0 - mu) * rs * gg[bj][0] + bb[bj][0]; r1 = (r1 - mu) * rs * gg[bj][1] + bb[bj][1]; }
;                     const f32x4 y0 = r0 * DN_ALPHA + acc[ai][bj][m][0] * ascale, y1 = r1 * DN_ALPHA + acc[ai][bj][m][1] * ascale;
;                     if constexpr (COPY != 4) { __builtin_nontemporal_store(y0, (f32x4*)(Y + off + bj * HALF)); __builtin_nontemporal_store(y1, (f32x4*)(Y + off + bj * HALF + 4)); }
;                     if constexpr (STATS) { ss += ((y0[0] + y0[1]) + (y0[2] + y0[3])) + ((y1[0] + y1[1]) + (y1[2] + y1[3]));
;                         qq += ((y0[0] * y0[0] + y0[1] * y0[1]) + (y0[2] * y0[2] + y0[3] * y0[3])) + ((y1[0] * y1[0] + y1[1] * y1[1]) + (y1[2] * y1[2] + y1[3] * y1[3])); }
;                     if constexpr (COPY == 1) *(u32x2*)((unsigned char*)copy + off + bj * HALF) = pack8fp8(y0 * cscale, y1 * cscale);
;                     if constexpr (COPY == 3) *(u32x2*)((unsigned char*)copy + off + bj * HALF) = pack8i8(y0 * cscale, y1 * cscale);
;                     if constexpr (COPY == 2 || COPY == 4) *(u32x4*)((bf16_t*)copy + off + bj * HALF) = pack8bf(y0, y1); }
;                 if constexpr (STATS) { ss += __shfl_xor(ss, 16); ss += __shfl_xor(ss, 32); qq += __shfl_xor(qq, 16); qq += __shfl_xor(qq, 32);
	v_sub_f32_e32 v157, v157, v180
	v_sub_f32_e32 v156, v156, v180
	v_sub_f32_e32 v155, v155, v180
	v_sub_f32_e32 v154, v154, v180
	s_nop 0
	s_nop 1
	v_mov_b32_e32 v182, v254
	v_pk_mul_f32 v[148:149], v[148:149], v[182:183] op_sel_hi:[1,0]
	v_pk_mul_f32 v[150:151], v[150:151], v[182:183] op_sel_hi:[1,0]
	v_pk_mul_f32 v[154:155], v[154:155], v[182:183] op_sel_hi:[1,0]
	v_pk_mul_f32 v[156:157], v[156:157], v[182:183] op_sel_hi:[1,0]
	v_pk_fma_f32 v[150:151], v[30:31], v[150:151], v[18:19]
	v_pk_fma_f32 v[148:149], v[28:29], v[148:149], v[16:17]
	v_pk_fma_f32 v[156:157], v[22:23], v[156:157], v[26:27]
	v_pk_fma_f32 v[154:155], v[20:21], v[154:155], v[24:25]
	v_pk_mul_f32 v[148:149], v[148:149], s[30:31] op_sel_hi:[1,0]
	v_pk_mul_f32 v[150:151], v[150:151], s[30:31] op_sel_hi:[1,0]
	v_pk_mul_f32 v[154:155], v[154:155], s[30:31] op_sel_hi:[1,0]
	v_pk_mul_f32 v[156:157], v[156:157], s[30:31] op_sel_hi:[1,0]
	v_pk_fma_f32 v[142:143], v[142:143], s[36:37], v[150:151] op_sel_hi:[1,0,1]
	v_pk_fma_f32 v[140:141], v[140:141], s[36:37], v[148:149] op_sel_hi:[1,0,1]
	v_pk_fma_f32 v[138:139], v[138:139], s[36:37], v[156:157] op_sel_hi:[1,0,1]
	v_pk_fma_f32 v[136:137], v[136:137], s[36:37], v[154:155] op_sel_hi:[1,0,1]
	v_pk_mul_f32 v[148:149], v[142:143], s[38:39] op_sel_hi:[1,0]
	v_pk_mul_f32 v[150:151], v[140:141], s[38:39] op_sel_hi:[1,0]
	v_pk_mul_f32 v[154:155], v[138:139], s[38:39] op_sel_hi:[1,0]
	v_pk_mul_f32 v[156:157], v[136:137], s[38:39] op_sel_hi:[1,0]
	v_med3_f32 v150, v150, s64, v195
	v_med3_f32 v151, v151, s64, v195
	v_med3_f32 v148, v148, s64, v195
	v_med3_f32 v149, v149, s64, v195
	v_med3_f32 v156, v156, s64, v195
	v_med3_f32 v157, v157, s64, v195
	v_med3_f32 v154, v154, s64, v195
	v_med3_f32 v155, v155, s64, v195
	v_add_f32_e32 v150, 0x4b400000, v150
	v_add_f32_e32 v151, 0x4b400000, v151
	v_add_f32_e32 v148, 0x4b400000, v148
	v_add_f32_e32 v149, 0x4b400000, v149
	v_add_f32_e32 v156, 0x4b400000, v156
	v_add_f32_e32 v157, 0x4b400000, v157
	v_add_f32_e32 v154, 0x4b400000, v154
	v_add_f32_e32 v155, 0x4b400000, v155
	v_perm_b32 v150, v151, v150, s65
	v_perm_b32 v148, v149, v148, s66
	v_perm_b32 v149, v157, v156, s65
	v_perm_b32 v151, v155, v154, s66
	v_or_b32_e32 v148, v150, v148
	v_or_b32_e32 v149, v149, v151
	global_store_dwordx4 v[146:147], v[140:143], off nt
	global_store_dwordx4 v[146:147], v[136:139], off offset:16 nt
	global_store_dwordx2 v[158:159], v[148:149], off
	global_load_dwordx4 v[148:151], v[146:147], off offset:512 nt
	s_nop 0
	global_load_dwordx4 v[154:157], v[146:147], off offset:528 nt
	v_add_f32_e32 v179, v140, v141
	v_add_f32_e32 v181, v142, v143
	v_add_f32_e32 v183, v136, v137
	v_add_f32_e32 v184, v138, v139
	v_mul_f32_e32 v141, v141, v141
	v_mul_f32_e32 v143, v143, v143
	v_mul_f32_e32 v137, v137, v137
	v_mul_f32_e32 v139, v139, v139
	v_add_f32_e32 v179, v179, v181
	v_add_f32_e32 v181, v183, v184
	v_fmac_f32_e32 v141, v140, v140
	v_fmac_f32_e32 v143, v142, v142
	v_fmac_f32_e32 v137, v136, v136
	v_fmac_f32_e32 v139, v138, v138
	v_add_f32_e32 v136, v179, v181
	v_add_f32_e32 v138, v141, v143
	v_add_f32_e32 v137, v137, v139
	v_add_f32_e32 v179, 0, v136
	v_add_f32_e32 v181, v138, v137
	s_waitcnt vmcnt(1)
	v_sub_f32_e32 v137, v151, v180
	v_sub_f32_e32 v136, v150, v180
	v_sub_f32_e32 v139, v149, v180
	v_sub_f32_e32 v138, v148, v180
	s_waitcnt vmcnt(0)
	v_sub_f32_e32 v141, v157, v180
	v_sub_f32_e32 v140, v156, v180
	v_sub_f32_e32 v143, v155, v180
	v_sub_f32_e32 v142, v154, v180
	v_pk_mul_f32 v[138:139], v[138:139], v[182:183] op_sel_hi:[1,0]
	v_pk_mul_f32 v[136:137], v[136:137], v[182:183] op_sel_hi:[1,0]
	v_pk_mul_f32 v[142:143], v[142:143], v[182:183] op_sel_hi:[1,0]
	v_pk_mul_f32 v[140:141], v[140:141], v[182:183] op_sel_hi:[1,0]
	v_pk_fma_f32 v[136:137], v[10:11], v[136:137], v[14:15]
	v_pk_fma_f32 v[138:139], v[8:9], v[138:139], v[12:13]
	v_pk_fma_f32 v[140:141], v[2:3], v[140:141], v[6:7]
	v_pk_fma_f32 v[142:143], v[0:1], v[142:143], v[4:5]
	v_pk_mul_f32 v[138:139], v[138:139], s[30:31] op_sel_hi:[1,0]
	v_pk_mul_f32 v[136:137], v[136:137], s[30:31] op_sel_hi:[1,0]
	v_pk_mul_f32 v[142:143], v[142:143], s[30:31] op_sel_hi:[1,0]
	v_pk_mul_f32 v[140:141], v[140:141], s[30:31] op_sel_hi:[1,0]
	v_pk_fma_f32 v[134:135], v[134:135], s[36:37], v[136:137] op_sel_hi:[1,0,1]
	v_pk_fma_f32 v[132:133], v[132:133], s[36:37], v[138:139] op_sel_hi:[1,0,1]
	v_pk_fma_f32 v[130:131], v[130:131], s[36:37], v[140:141] op_sel_hi:[1,0,1]
	v_pk_fma_f32 v[128:129], v[128:129], s[36:37], v[142:143] op_sel_hi:[1,0,1]
	global_store_dwordx4 v[146:147], v[132:135], off offset:512 nt
	global_store_dwordx4 v[146:147], v[128:131], off offset:528 nt
	v_add_f32_e32 v146, v132, v133
	v_add_f32_e32 v147, v134, v135
	v_add_f32_e32 v148, v128, v129
	v_add_f32_e32 v149, v130, v131
	v_mul_f32_e32 v150, v133, v133
	v_mul_f32_e32 v151, v135, v135
	v_mul_f32_e32 v154, v129, v129
	v_mul_f32_e32 v155, v131, v131
	v_pk_mul_f32 v[138:139], v[132:133], s[38:39] op_sel_hi:[1,0]
	v_pk_mul_f32 v[140:141], v[130:131], s[38:39] op_sel_hi:[1,0]
	v_pk_mul_f32 v[142:143], v[128:129], s[38:39] op_sel_hi:[1,0]
	v_add_f32_e32 v129, v146, v147
	v_add_f32_e32 v131, v148, v149
	v_fmac_f32_e32 v150, v132, v132
	v_fmac_f32_e32 v151, v134, v134
	v_fmac_f32_e32 v154, v128, v128
	v_fmac_f32_e32 v155, v130, v130
	v_med3_f32 v128, v138, s64, v195
	v_add_f32_e32 v129, v129, v131
	v_add_f32_e32 v131, v150, v151
	v_add_f32_e32 v138, v154, v155
	v_med3_f32 v130, v139, s64, v195
	v_add_f32_e32 v131, v131, v138
	v_add_f32_e32 v128, 0x4b400000, v128
	v_add_f32_e32 v130, 0x4b400000, v130
	v_add_f32_e32 v129, v129, v179
	v_add_f32_e32 v131, v181, v131
	v_perm_b32 v128, v130, v128, s65
	ds_bpermute_b32 v130, v153, v129
	ds_bpermute_b32 v138, v153, v131
	v_pk_mul_f32 v[136:137], v[134:135], s[38:39] op_sel_hi:[1,0]
	v_med3_f32 v134, v142, s64, v195
	v_med3_f32 v132, v136, s64, v195
	v_med3_f32 v133, v137, s64, v195
	v_add_f32_e32 v132, 0x4b400000, v132
	v_add_f32_e32 v133, 0x4b400000, v133
	v_perm_b32 v132, v133, v132, s66
	v_or_b32_e32 v132, v128, v132
	s_waitcnt lgkmcnt(1)
	v_add_f32_e32 v128, v129, v130
	s_waitcnt lgkmcnt(0)
	v_add_f32_e32 v130, v131, v138
	ds_bpermute_b32 v129, v152, v128
	ds_bpermute_b32 v131, v152, v130
	v_med3_f32 v135, v143, s64, v195
	v_med3_f32 v136, v140, s64, v195
	v_med3_f32 v137, v141, s64, v195
	v_add_f32_e32 v134, 0x4b400000, v134
	v_add_f32_e32 v135, 0x4b400000, v135
	v_add_f32_e32 v136, 0x4b400000, v136
	v_add_f32_e32 v137, 0x4b400000, v137
	v_perm_b32 v133, v135, v134, s65
	v_perm_b32 v134, v137, v136, s66
	v_or_b32_e32 v133, v133, v134
	global_store_dwordx2 v[158:159], v[132:133], off offset:128
	s_and_saveexec_b64 s[6:7], s[2:3]
	s_cbranch_execz .LBB0_3865
	v_lshl_add_u64 v[132:133], s[12:13], 0, v[144:145]
	s_waitcnt lgkmcnt(1)
	v_add_f32_e32 v128, v128, v129
	s_waitcnt lgkmcnt(0)
	v_add_f32_e32 v129, v130, v131
	global_atomic_add_f32 v[132:133], v128, off
	global_atomic_add_f32 v[132:133], v129, off offset:4
; __device__ __forceinline__ u32x2 pack8i8(const f32x4 a, const f32x4 b) { return (u32x2){pack4i8(a), pack4i8(b)}; }
; __device__ __forceinline__ u32x4 pack8bf(const f32x4 a, const f32x4 b) { u32x4 w; w.x = cvt_pk_bf16(a[0], a[1]); w.y = cvt_pk_bf16(a[2], a[3]); w.z = cvt_pk_bf16(b[0], b[1]); w.w = cvt_pk_bf16(b[2], b[3]); return w; }
;     __device__ __forceinline__ void operator()(EPI_ARGS) const {
;     ...
;             for (int m = 0; m < 4; ++m) { const int row = row0 + ai * HALF + m * 16; const size_t off = (size_t)row * DM + col0;
;                 float mu = 0.f, rs = 1.f; if constexpr (RESLN) ln_stats(stin, row, mu, rs);
;                 float ss = 0.f, qq = 0.f;
; #pragma unroll
;                 for (int bj = 0; bj < 2; ++bj) { f32x4 r0 = __builtin_nontemporal_load((const f32x4*)(res + off + bj * HALF)), r1 = __builtin_nontemporal_load((const f32x4*)(res + off + bj * HALF + 4));
;                     if constexpr (RESLN) { r0 = (r0 - mu) * rs * gg[bj][0] + bb[bj][0]; r1 = (r1 - mu) * rs * gg[bj][1] + bb[bj][1]; }
;                     const f32x4 y0 = r0 * DN_ALPHA + acc[ai][bj][m][0] * ascale, y1 = r1 * DN_ALPHA + acc[ai][bj][m][1] * ascale;
;                     if constexpr (COPY != 4) { __builtin_nontemporal_store(y0, (f32x4*)(Y + off + bj * HALF)); __builtin_nontemporal_store(y1, (f32x4*)(Y + off + bj * HALF + 4)); }
;                     if constexpr (STATS) { ss += ((y0[0] + y0[1]) + (y0[2] + y0[3])) + ((y1[0] + y1[1]) + (y1[2] + y1[3]));
;                         qq += ((y0[0] * y0[0] + y0[1] * y0[1]) + (y0[2] * y0[2] + y0[3] * y0[3])) + ((y1[0] * y1[0] + y1[1] * y1[1]) + (y1[2] * y1[2] + y1[3] * y1[3])); }
;                     if constexpr (COPY == 1) *(u32x2*)((unsigned char*)copy + off + bj * HALF) = pack8fp8(y0 * cscale, y1 * cscale);
;                     if constexpr (COPY == 3) *(u32x2*)((unsigned char*)copy + off + bj * HALF) = pack8i8(y0 * cscale, y1 * cscale);
;                     if constexpr (COPY == 2 || COPY == 4) *(u32x4*)((bf16_t*)copy + off + bj * HALF) = pack8bf(y0, y1); }
;                 if constexpr (STATS) { ss += __shfl_xor(ss, 16); ss += __shfl_xor(ss, 32); qq += __shfl_xor(qq, 16); qq += __shfl_xor(qq, 32);
;                     if (fq == 0) { unsafeAtomicAdd(stout + 2 * (size_t)row, ss); unsafeAtomicAdd(stout + 2 * (size_t)row + 1, qq); } }
.LBB0_3865:
	s_or_b64 exec, exec, s[6:7]
	v_or_b32_e32 v128, 32, v178
	s_waitcnt lgkmcnt(1)
	v_ashrrev_i32_e32 v129, 31, v128
	s_waitcnt lgkmcnt(0)
	v_lshlrev_b64 v[130:131], 11, v[128:129]
	v_lshlrev_b64 v[128:129], 3, v[128:129]
	v_lshl_add_u64 v[140:141], v[130:131], 0, v[176:177]
	v_lshl_add_u64 v[130:131], s[14:15], 0, v[128:129]
	global_load_dwordx2 v[142:143], v[130:131], off
	v_lshl_add_u64 v[130:131], v[140:141], 2, s[18:19]
	global_load_dwordx4 v[132:135], v[130:131], off nt
	global_load_dwordx4 v[136:139], v[130:131], off offset:16 nt
	v_lshl_add_u64 v[140:141], s[20:21], 0, v[140:141]
	s_waitcnt vmcnt(2)
	v_pk_mul_f32 v[142:143], v[142:143], s[28:29] op_sel_hi:[1,0]
	s_nop 0
	v_fma_f32 v143, -v142, v142, v143
	v_add_f32_e32 v143, 0x3727c5ac, v143
	v_rsq_f32_e32 v254, v143
	s_waitcnt vmcnt(1)
	v_sub_f32_e32 v135, v135, v142
	v_sub_f32_e32 v134, v134, v142
	v_sub_f32_e32 v133, v133, v142
	v_sub_f32_e32 v132, v132, v142
	s_waitcnt vmcnt(0)
	v_sub_f32_e32 v139, v139, v142
	v_sub_f32_e32 v138, v138, v142
	v_sub_f32_e32 v137, v137, v142
	v_sub_f32_e32 v136, v136, v142
	s_nop 0
	s_nop 1
	v_mov_b32_e32 v144, v254
	v_pk_mul_f32 v[132:133], v[132:133], v[144:145] op_sel_hi:[1,0]
	v_pk_mul_f32 v[134:135], v[134:135], v[144:145] op_sel_hi:[1,0]
	v_pk_mul_f32 v[136:137], v[136:137], v[144:145] op_sel_hi:[1,0]
	v_pk_mul_f32 v[138:139], v[138:139], v[144:145] op_sel_hi:[1,0]
	v_pk_fma_f32 v[134:135], v[30:31], v[134:135], v[18:19]
	v_pk_fma_f32 v[132:133], v[28:29], v[132:133], v[16:17]
	v_pk_fma_f32 v[138:139], v[22:23], v[138:139], v[26:27]
	v_pk_fma_f32 v[136:137], v[20:21], v[136:137], v[24:25]
	v_pk_mul_f32 v[132:133], v[132:133], s[30:31] op_sel_hi:[1,0]
	v_pk_mul_f32 v[134:135], v[134:135], s[30:31] op_sel_hi:[1,0]
	v_pk_mul_f32 v[136:137], v[136:137], s[30:31] op_sel_hi:[1,0]
	v_pk_mul_f32 v[138:139], v[138:139], s[30:31] op_sel_hi:[1,0]
	v_pk_fma_f32 v[126:127], v[126:127], s[36:37], v[134:135] op_sel_hi:[1,0,1]
	v_pk_fma_f32 v[124:125], v[124:125], s[36:37], v[132:133] op_sel_hi:[1,0,1]
	v_pk_fma_f32 v[122:123], v[122:123], s[36:37], v[138:139] op_sel_hi:[1,0,1]
	v_pk_fma_f32 v[120:121], v[120:121], s[36:37], v[136:137] op_sel_hi:[1,0,1]
	v_pk_mul_f32 v[132:133], v[126:127], s[38:39] op_sel_hi:[1,0]
	v_pk_mul_f32 v[134:135], v[124:125], s[38:39] op_sel_hi:[1,0]
	v_pk_mul_f32 v[136:137], v[122:123], s[38:39] op_sel_hi:[1,0]
	v_pk_mul_f32 v[138:139], v[120:121], s[38:39] op_sel_hi:[1,0]
	v_med3_f32 v134, v134, s64, v195
	v_med3_f32 v135, v135, s64, v195
	v_med3_f32 v132, v132, s64, v195
	v_med3_f32 v133, v133, s64, v195
	v_med3_f32 v138, v138, s64, v195
	v_med3_f32 v139, v139, s64, v195
	v_med3_f32 v136, v136, s64, v195
	v_med3_f32 v137, v137, s64, v195
	v_add_f32_e32 v134, 0x4b400000, v134
	v_add_f32_e32 v135, 0x4b400000, v135
	v_add_f32_e32 v132, 0x4b400000, v132
	v_add_f32_e32 v133, 0x4b400000, v133
	v_add_f32_e32 v138, 0x4b400000, v138
	v_add_f32_e32 v139, 0x4b400000, v139
	v_add_f32_e32 v136, 0x4b400000, v136
	v_add_f32_e32 v137, 0x4b400000, v137
	v_perm_b32 v134, v135, v134, s65
	v_perm_b32 v132, v133, v132, s66
	v_perm_b32 v133, v139, v138, s65
	v_perm_b32 v135, v137, v136, s66
	v_or_b32_e32 v132, v134, v132
	v_or_b32_e32 v133, v133, v135
	global_store_dwordx4 v[130:131], v[124:127], off nt
	global_store_dwordx4 v[130:131], v[120:123], off offset:16 nt
	global_store_dwordx2 v[140:141], v[132:133], off
	global_load_dwordx4 v[132:135], v[130:131], off offset:512 nt
	s_nop 0
	global_load_dwordx4 v[136:139], v[130:131], off offset:528 nt
	v_add_f32_e32 v143, v124, v125
	v_add_f32_e32 v145, v126, v127
	v_add_f32_e32 v146, v120, v121
	v_add_f32_e32 v147, v122, v123
	v_mul_f32_e32 v125, v125, v125
	v_mul_f32_e32 v127, v127, v127
	v_mul_f32_e32 v121, v121, v121
	v_mul_f32_e32 v123, v123, v123
	v_add_f32_e32 v143, v143, v145
	v_add_f32_e32 v145, v146, v147
	v_fmac_f32_e32 v125, v124, v124
	v_fmac_f32_e32 v127, v126, v126
	v_fmac_f32_e32 v121, v120, v120
	v_fmac_f32_e32 v123, v122, v122
	v_add_f32_e32 v120, v143, v145
	v_add_f32_e32 v122, v125, v127
	v_add_f32_e32 v121, v121, v123
	v_add_f32_e32 v143, 0, v120
	v_add_f32_e32 v145, v122, v121
	s_waitcnt vmcnt(1)
	v_sub_f32_e32 v121, v135, v142
	v_sub_f32_e32 v120, v134, v142
	v_sub_f32_e32 v123, v133, v142
	v_sub_f32_e32 v122, v132, v142
	s_waitcnt vmcnt(0)
	v_sub_f32_e32 v125, v139, v142
	v_sub_f32_e32 v124, v138, v142
	v_sub_f32_e32 v127, v137, v142
	v_sub_f32_e32 v126, v136, v142
	v_pk_mul_f32 v[122:123], v[122:123], v[144:145] op_sel_hi:[1,0]
	v_pk_mul_f32 v[120:121], v[120:121], v[144:145] op_sel_hi:[1,0]
	v_pk_mul_f32 v[126:127], v[126:127], v[144:145] op_sel_hi:[1,0]
	v_pk_mul_f32 v[124:125], v[124:125], v[144:145] op_sel_hi:[1,0]
	v_pk_fma_f32 v[120:121], v[10:11], v[120:121], v[14:15]
	v_pk_fma_f32 v[122:123], v[8:9], v[122:123], v[12:13]
	v_pk_fma_f32 v[124:125], v[2:3], v[124:125], v[6:7]
	v_pk_fma_f32 v[126:127], v[0:1], v[126:127], v[4:5]
	v_pk_mul_f32 v[122:123], v[122:123], s[30:31] op_sel_hi:[1,0]
	v_pk_mul_f32 v[120:121], v[120:121], s[30:31] op_sel_hi:[1,0]
	v_pk_mul_f32 v[126:127], v[126:127], s[30:31] op_sel_hi:[1,0]
	v_pk_mul_f32 v[124:125], v[124:125], s[30:31] op_sel_hi:[1,0]
	v_pk_fma_f32 v[118:119], v[118:119], s[36:37], v[120:121] op_sel_hi:[1,0,1]
	v_pk_fma_f32 v[116:117], v[116:117], s[36:37], v[122:123] op_sel_hi:[1,0,1]
	v_pk_fma_f32 v[114:115], v[114:115], s[36:37], v[124:125] op_sel_hi:[1,0,1]
	v_pk_fma_f32 v[112:113], v[112:113], s[36:37], v[126:127] op_sel_hi:[1,0,1]
	global_store_dwordx4 v[130:131], v[116:119], off offset:512 nt
	global_store_dwordx4 v[130:131], v[112:115], off offset:528 nt
	v_add_f32_e32 v130, v116, v117
	v_add_f32_e32 v131, v118, v119
	v_add_f32_e32 v132, v112, v113
	v_add_f32_e32 v133, v114, v115
	v_mul_f32_e32 v134, v117, v117
	v_mul_f32_e32 v135, v119, v119
	v_mul_f32_e32 v136, v113, v113
	v_mul_f32_e32 v137, v115, v115
	v_pk_mul_f32 v[122:123], v[116:117], s[38:39] op_sel_hi:[1,0]
	v_pk_mul_f32 v[124:125], v[114:115], s[38:39] op_sel_hi:[1,0]
	v_pk_mul_f32 v[126:127], v[112:113], s[38:39] op_sel_hi:[1,0]
	v_add_f32_e32 v113, v130, v131
	v_add_f32_e32 v115, v132, v133
	v_fmac_f32_e32 v134, v116, v116
	v_fmac_f32_e32 v135, v118, v118
	v_fmac_f32_e32 v136, v112, v112
	v_fmac_f32_e32 v137, v114, v114
	v_med3_f32 v112, v122, s64, v195
	v_add_f32_e32 v113, v113, v115
	v_add_f32_e32 v115, v134, v135
	v_add_f32_e32 v122, v136, v137
	v_med3_f32 v114, v123, s64, v195
	v_add_f32_e32 v115, v115, v122
	v_add_f32_e32 v112, 0x4b400000, v112
	v_add_f32_e32 v114, 0x4b400000, v114
	v_add_f32_e32 v113, v113, v143
	v_add_f32_e32 v115, v145, v115
	v_perm_b32 v112, v114, v112, s65
	ds_bpermute_b32 v114, v153, v113
	ds_bpermute_b32 v122, v153, v115
	v_pk_mul_f32 v[120:121], v[118:119], s[38:39] op_sel_hi:[1,0]
	v_med3_f32 v118, v126, s64, v195
	v_med3_f32 v116, v120, s64, v195
	v_med3_f32 v117, v121, s64, v195
	v_add_f32_e32 v116, 0x4b400000, v116
	v_add_f32_e32 v117, 0x4b400000, v117
	v_perm_b32 v116, v117, v116, s66
	v_or_b32_e32 v116, v112, v116
	s_waitcnt lgkmcnt(1)
; __device__ __forceinline__ u32x2 pack8i8(const f32x4 a, const f32x4 b) { return (u32x2){pack4i8(a), pack4i8(b)}; }
; __device__ __forceinline__ u32x4 pack8bf(const f32x4 a, const f32x4 b) { u32x4 w; w.x = cvt_pk_bf16(a[0], a[1]); w.y = cvt_pk_bf16(a[2], a[3]); w.z = cvt_pk_bf16(b[0], b[1]); w.w = cvt_pk_bf16(b[2], b[3]); return w; }
;     __device__ __forceinline__ void operator()(EPI_ARGS) const {
;     ...
;             for (int m = 0; m < 4; ++m) { const int row = row0 + ai * HALF + m * 16; const size_t off = (size_t)row * DM + col0;
;                 float mu = 0.f, rs = 1.f; if constexpr (RESLN) ln_stats(stin, row, mu, rs);
;                 float ss = 0.f, qq = 0.f;
; #pragma unroll
;                 for (int bj = 0; bj < 2; ++bj) { f32x4 r0 = __builtin_nontemporal_load((const f32x4*)(res + off + bj * HALF)), r1 = __builtin_nontemporal_load((const f32x4*)(res + off + bj * HALF + 4));
;                     if constexpr (RESLN) { r0 = (r0 - mu) * rs * gg[bj][0] + bb[bj][0]; r1 = (r1 - mu) * rs * gg[bj][1] + bb[bj][1]; }
;                     const f32x4 y0 = r0 * DN_ALPHA + acc[ai][bj][m][0] * ascale, y1 = r1 * DN_ALPHA + acc[ai][bj][m][1] * ascale;
;                     if constexpr (COPY != 4) { __builtin_nontemporal_store(y0, (f32x4*)(Y + off + bj * HALF)); __builtin_nontemporal_store(y1, (f32x4*)(Y + off + bj * HALF + 4)); }
;                     if constexpr (STATS) { ss += ((y0[0] + y0[1]) + (y0[2] + y0[3])) + ((y1[0] + y1[1]) + (y1[2] + y1[3]));
;                         qq += ((y0[0] * y0[0] + y0[1] * y0[1]) + (y0[2] * y0[2] + y0[3] * y0[3])) + ((y1[0] * y1[0] + y1[1] * y1[1]) + (y1[2] * y1[2] + y1[3] * y1[3])); }
;                     if constexpr (COPY == 1) *(u32x2*)((unsigned char*)copy + off + bj * HALF) = pack8fp8(y0 * cscale, y1 * cscale);
;                     if constexpr (COPY == 3) *(u32x2*)((unsigned char*)copy + off + bj * HALF) = pack8i8(y0 * cscale, y1 * cscale);
;                     if constexpr (COPY == 2 || COPY == 4) *(u32x4*)((bf16_t*)copy + off + bj * HALF) = pack8bf(y0, y1); }
;                 if constexpr (STATS) { ss += __shfl_xor(ss, 16); ss += __shfl_xor(ss, 32); qq += __shfl_xor(qq, 16); qq += __shfl_xor(qq, 32);
;                     if (fq == 0) { unsafeAtomicAdd(stout + 2 * (size_t)row, ss); unsafeAtomicAdd(stout + 2 * (size_t)row + 1, qq); } }
	v_add_f32_e32 v112, v113, v114
	s_waitcnt lgkmcnt(0)
	v_add_f32_e32 v114, v115, v122
	ds_bpermute_b32 v113, v152, v112
	ds_bpermute_b32 v115, v152, v114
	v_med3_f32 v119, v127, s64, v195
	v_med3_f32 v120, v124, s64, v195
	v_med3_f32 v121, v125, s64, v195
	v_add_f32_e32 v118, 0x4b400000, v118
	v_add_f32_e32 v119, 0x4b400000, v119
	v_add_f32_e32 v120, 0x4b400000, v120
	v_add_f32_e32 v121, 0x4b400000, v121
	v_perm_b32 v117, v119, v118, s65
	v_perm_b32 v118, v121, v120, s66
	v_or_b32_e32 v117, v117, v118
	global_store_dwordx2 v[140:141], v[116:117], off offset:128
	s_and_saveexec_b64 s[6:7], s[2:3]
	s_cbranch_execz .LBB0_3867
	v_lshl_add_u64 v[116:117], s[12:13], 0, v[128:129]
	s_waitcnt lgkmcnt(1)
	v_add_f32_e32 v112, v112, v113
	s_waitcnt lgkmcnt(0)
	v_add_f32_e32 v113, v114, v115
	global_atomic_add_f32 v[116:117], v112, off
	global_atomic_add_f32 v[116:117], v113, off offset:4
.LBB0_3867:
	s_or_b64 exec, exec, s[6:7]
	v_or_b32_e32 v112, 48, v178
	s_waitcnt lgkmcnt(1)
	v_ashrrev_i32_e32 v113, 31, v112
	s_waitcnt lgkmcnt(0)
	v_lshlrev_b64 v[114:115], 11, v[112:113]
	v_lshlrev_b64 v[112:113], 3, v[112:113]
	v_lshl_add_u64 v[124:125], v[114:115], 0, v[176:177]
	v_lshl_add_u64 v[114:115], s[14:15], 0, v[112:113]
	global_load_dwordx2 v[126:127], v[114:115], off
	v_lshl_add_u64 v[114:115], v[124:125], 2, s[18:19]
	global_load_dwordx4 v[116:119], v[114:115], off nt
	global_load_dwordx4 v[120:123], v[114:115], off offset:16 nt
	v_lshl_add_u64 v[124:125], s[20:21], 0, v[124:125]
	s_waitcnt vmcnt(2)
	v_pk_mul_f32 v[126:127], v[126:127], s[28:29] op_sel_hi:[1,0]
	s_nop 0
	v_fma_f32 v127, -v126, v126, v127
	v_add_f32_e32 v127, 0x3727c5ac, v127
	v_rsq_f32_e32 v254, v127
	s_waitcnt vmcnt(1)
	v_sub_f32_e32 v119, v119, v126
	v_sub_f32_e32 v118, v118, v126
	v_sub_f32_e32 v117, v117, v126
	v_sub_f32_e32 v116, v116, v126
	s_waitcnt vmcnt(0)
	v_sub_f32_e32 v123, v123, v126
	v_sub_f32_e32 v122, v122, v126
	v_sub_f32_e32 v121, v121, v126
	v_sub_f32_e32 v120, v120, v126
	s_nop 0
	s_nop 1
	v_mov_b32_e32 v128, v254
	v_pk_mul_f32 v[116:117], v[116:117], v[128:129] op_sel_hi:[1,0]
	v_pk_mul_f32 v[118:119], v[118:119], v[128:129] op_sel_hi:[1,0]
	v_pk_mul_f32 v[120:121], v[120:121], v[128:129] op_sel_hi:[1,0]
	v_pk_mul_f32 v[122:123], v[122:123], v[128:129] op_sel_hi:[1,0]
	v_pk_fma_f32 v[118:119], v[30:31], v[118:119], v[18:19]
	v_pk_fma_f32 v[116:117], v[28:29], v[116:117], v[16:17]
	v_pk_fma_f32 v[122:123], v[22:23], v[122:123], v[26:27]
	v_pk_fma_f32 v[120:121], v[20:21], v[120:121], v[24:25]
	v_pk_mul_f32 v[116:117], v[116:117], s[30:31] op_sel_hi:[1,0]
	v_pk_mul_f32 v[118:119], v[118:119], s[30:31] op_sel_hi:[1,0]
	v_pk_mul_f32 v[120:121], v[120:121], s[30:31] op_sel_hi:[1,0]
	v_pk_mul_f32 v[122:123], v[122:123], s[30:31] op_sel_hi:[1,0]
	v_pk_fma_f32 v[110:111], v[110:111], s[36:37], v[118:119] op_sel_hi:[1,0,1]
	v_pk_fma_f32 v[108:109], v[108:109], s[36:37], v[116:117] op_sel_hi:[1,0,1]
	v_pk_fma_f32 v[106:107], v[106:107], s[36:37], v[122:123] op_sel_hi:[1,0,1]
	v_pk_fma_f32 v[104:105], v[104:105], s[36:37], v[120:121] op_sel_hi:[1,0,1]
	v_pk_mul_f32 v[116:117], v[110:111], s[38:39] op_sel_hi:[1,0]
	v_pk_mul_f32 v[118:119], v[108:109], s[38:39] op_sel_hi:[1,0]
	v_pk_mul_f32 v[120:121], v[106:107], s[38:39] op_sel_hi:[1,0]
	v_pk_mul_f32 v[122:123], v[104:105], s[38:39] op_sel_hi:[1,0]
	v_med3_f32 v118, v118, s64, v195
	v_med3_f32 v119, v119, s64, v195
	v_med3_f32 v116, v116, s64, v195
	v_med3_f32 v117, v117, s64, v195
	v_med3_f32 v122, v122, s64, v195
	v_med3_f32 v123, v123, s64, v195
	v_med3_f32 v120, v120, s64, v195
	v_med3_f32 v121, v121, s64, v195
	v_add_f32_e32 v118, 0x4b400000, v118
	v_add_f32_e32 v119, 0x4b400000, v119
	v_add_f32_e32 v116, 0x4b400000, v116
	v_add_f32_e32 v117, 0x4b400000, v117
	v_add_f32_e32 v122, 0x4b400000, v122
	v_add_f32_e32 v123, 0x4b400000, v123
	v_add_f32_e32 v120, 0x4b400000, v120
	v_add_f32_e32 v121, 0x4b400000, v121
	v_perm_b32 v118, v119, v118, s65
	v_perm_b32 v116, v117, v116, s66
	v_perm_b32 v117, v123, v122, s65
	v_perm_b32 v119, v121, v120, s66
	v_or_b32_e32 v116, v118, v116
	v_or_b32_e32 v117, v117, v119
	global_store_dwordx4 v[114:115], v[108:111], off nt
	global_store_dwordx4 v[114:115], v[104:107], off offset:16 nt
	global_store_dwordx2 v[124:125], v[116:117], off
	global_load_dwordx4 v[116:119], v[114:115], off offset:512 nt
	s_nop 0
	global_load_dwordx4 v[120:123], v[114:115], off offset:528 nt
	v_add_f32_e32 v127, v108, v109
	v_add_f32_e32 v129, v110, v111
	v_add_f32_e32 v130, v104, v105
	v_add_f32_e32 v131, v106, v107
	v_mul_f32_e32 v109, v109, v109
	v_mul_f32_e32 v111, v111, v111
	v_mul_f32_e32 v105, v105, v105
	v_mul_f32_e32 v107, v107, v107
	v_add_f32_e32 v127, v127, v129
	v_add_f32_e32 v129, v130, v131
	v_fmac_f32_e32 v109, v108, v108
	v_fmac_f32_e32 v111, v110, v110
	v_fmac_f32_e32 v105, v104, v104
	v_fmac_f32_e32 v107, v106, v106
	v_add_f32_e32 v104, v127, v129
	v_add_f32_e32 v106, v109, v111
	v_add_f32_e32 v105, v105, v107
	v_add_f32_e32 v127, 0, v104
	v_add_f32_e32 v129, v106, v105
	s_waitcnt vmcnt(1)
	v_sub_f32_e32 v105, v119, v126
	v_sub_f32_e32 v104, v118, v126
	v_sub_f32_e32 v107, v117, v126
	v_sub_f32_e32 v106, v116, v126
	s_waitcnt vmcnt(0)
; __device__ __forceinline__ u32x2 pack8i8(const f32x4 a, const f32x4 b) { return (u32x2){pack4i8(a), pack4i8(b)}; }
; __device__ __forceinline__ u32x4 pack8bf(const f32x4 a, const f32x4 b) { u32x4 w; w.x = cvt_pk_bf16(a[0], a[1]); w.y = cvt_pk_bf16(a[2], a[3]); w.z = cvt_pk_bf16(b[0], b[1]); w.w = cvt_pk_bf16(b[2], b[3]); return w; }
;     __device__ __forceinline__ void operator()(EPI_ARGS) const {
;     ...
;             for (int m = 0; m < 4; ++m) { const int row = row0 + ai * HALF + m * 16; const size_t off = (size_t)row * DM + col0;
;                 float mu = 0.f, rs = 1.f; if constexpr (RESLN) ln_stats(stin, row, mu, rs);
;                 float ss = 0.f, qq = 0.f;
; #pragma unroll
;                 for (int bj = 0; bj < 2; ++bj) { f32x4 r0 = __builtin_nontemporal_load((const f32x4*)(res + off + bj * HALF)), r1 = __builtin_nontemporal_load((const f32x4*)(res + off + bj * HALF + 4));
;                     if constexpr (RESLN) { r0 = (r0 - mu) * rs * gg[bj][0] + bb[bj][0]; r1 = (r1 - mu) * rs * gg[bj][1] + bb[bj][1]; }
;                     const f32x4 y0 = r0 * DN_ALPHA + acc[ai][bj][m][0] * ascale, y1 = r1 * DN_ALPHA + acc[ai][bj][m][1] * ascale;
;                     if constexpr (COPY != 4) { __builtin_nontemporal_store(y0, (f32x4*)(Y + off + bj * HALF)); __builtin_nontemporal_store(y1, (f32x4*)(Y + off + bj * HALF + 4)); }
;                     if constexpr (STATS) { ss += ((y0[0] + y0[1]) + (y0[2] + y0[3])) + ((y1[0] + y1[1]) + (y1[2] + y1[3]));
;                         qq += ((y0[0] * y0[0] + y0[1] * y0[1]) + (y0[2] * y0[2] + y0[3] * y0[3])) + ((y1[0] * y1[0] + y1[1] * y1[1]) + (y1[2] * y1[2] + y1[3] * y1[3])); }
;                     if constexpr (COPY == 1) *(u32x2*)((unsigned char*)copy + off + bj * HALF) = pack8fp8(y0 * cscale, y1 * cscale);
;                     if constexpr (COPY == 3) *(u32x2*)((unsigned char*)copy + off + bj * HALF) = pack8i8(y0 * cscale, y1 * cscale);
;                     if constexpr (COPY == 2 || COPY == 4) *(u32x4*)((bf16_t*)copy + off + bj * HALF) = pack8bf(y0, y1); }
;                 if constexpr (STATS) { ss += __shfl_xor(ss, 16); ss += __shfl_xor(ss, 32); qq += __shfl_xor(qq, 16); qq += __shfl_xor(qq, 32);
;                     if (fq == 0) { unsafeAtomicAdd(stout + 2 * (size_t)row, ss); unsafeAtomicAdd(stout + 2 * (size_t)row + 1, qq); } }
	v_sub_f32_e32 v109, v123, v126
	v_sub_f32_e32 v108, v122, v126
	v_sub_f32_e32 v111, v121, v126
	v_sub_f32_e32 v110, v120, v126
	v_pk_mul_f32 v[106:107], v[106:107], v[128:129] op_sel_hi:[1,0]
	v_pk_mul_f32 v[104:105], v[104:105], v[128:129] op_sel_hi:[1,0]
	v_pk_mul_f32 v[110:111], v[110:111], v[128:129] op_sel_hi:[1,0]
	v_pk_mul_f32 v[108:109], v[108:109], v[128:129] op_sel_hi:[1,0]
	v_pk_fma_f32 v[104:105], v[10:11], v[104:105], v[14:15]
	v_pk_fma_f32 v[106:107], v[8:9], v[106:107], v[12:13]
	v_pk_fma_f32 v[108:109], v[2:3], v[108:109], v[6:7]
	v_pk_fma_f32 v[110:111], v[0:1], v[110:111], v[4:5]
	v_pk_mul_f32 v[106:107], v[106:107], s[30:31] op_sel_hi:[1,0]
	v_pk_mul_f32 v[104:105], v[104:105], s[30:31] op_sel_hi:[1,0]
	v_pk_mul_f32 v[110:111], v[110:111], s[30:31] op_sel_hi:[1,0]
	v_pk_mul_f32 v[108:109], v[108:109], s[30:31] op_sel_hi:[1,0]
	v_pk_fma_f32 v[102:103], v[102:103], s[36:37], v[104:105] op_sel_hi:[1,0,1]
	v_pk_fma_f32 v[100:101], v[100:101], s[36:37], v[106:107] op_sel_hi:[1,0,1]
	v_pk_fma_f32 v[98:99], v[98:99], s[36:37], v[108:109] op_sel_hi:[1,0,1]
	v_pk_fma_f32 v[96:97], v[96:97], s[36:37], v[110:111] op_sel_hi:[1,0,1]
	global_store_dwordx4 v[114:115], v[100:103], off offset:512 nt
	global_store_dwordx4 v[114:115], v[96:99], off offset:528 nt
	v_add_f32_e32 v114, v100, v101
	v_add_f32_e32 v115, v102, v103
	v_add_f32_e32 v116, v96, v97
	v_add_f32_e32 v117, v98, v99
	v_mul_f32_e32 v118, v101, v101
	v_mul_f32_e32 v119, v103, v103
	v_mul_f32_e32 v120, v97, v97
	v_mul_f32_e32 v121, v99, v99
	v_pk_mul_f32 v[106:107], v[100:101], s[38:39] op_sel_hi:[1,0]
	v_pk_mul_f32 v[108:109], v[98:99], s[38:39] op_sel_hi:[1,0]
	v_pk_mul_f32 v[110:111], v[96:97], s[38:39] op_sel_hi:[1,0]
	v_add_f32_e32 v97, v114, v115
	v_add_f32_e32 v99, v116, v117
	v_fmac_f32_e32 v118, v100, v100
	v_fmac_f32_e32 v119, v102, v102
	v_fmac_f32_e32 v120, v96, v96
	v_fmac_f32_e32 v121, v98, v98
	v_med3_f32 v96, v106, s64, v195
	v_add_f32_e32 v97, v97, v99
	v_add_f32_e32 v99, v118, v119
	v_add_f32_e32 v106, v120, v121
	v_med3_f32 v98, v107, s64, v195
	v_add_f32_e32 v99, v99, v106
	v_add_f32_e32 v96, 0x4b400000, v96
	v_add_f32_e32 v98, 0x4b400000, v98
	v_add_f32_e32 v97, v97, v127
	v_add_f32_e32 v99, v129, v99
	v_perm_b32 v96, v98, v96, s65
	ds_bpermute_b32 v98, v153, v97
	ds_bpermute_b32 v106, v153, v99
	v_pk_mul_f32 v[104:105], v[102:103], s[38:39] op_sel_hi:[1,0]
	v_med3_f32 v102, v110, s64, v195
	v_med3_f32 v100, v104, s64, v195
	v_med3_f32 v101, v105, s64, v195
	v_add_f32_e32 v100, 0x4b400000, v100
	v_add_f32_e32 v101, 0x4b400000, v101
	v_perm_b32 v100, v101, v100, s66
	v_or_b32_e32 v100, v96, v100
	s_waitcnt lgkmcnt(1)
	v_add_f32_e32 v96, v97, v98
	s_waitcnt lgkmcnt(0)
	v_add_f32_e32 v98, v99, v106
	ds_bpermute_b32 v97, v152, v96
	ds_bpermute_b32 v99, v152, v98
	v_med3_f32 v103, v111, s64, v195
	v_med3_f32 v104, v108, s64, v195
	v_med3_f32 v105, v109, s64, v195
	v_add_f32_e32 v102, 0x4b400000, v102
	v_add_f32_e32 v103, 0x4b400000, v103
	v_add_f32_e32 v104, 0x4b400000, v104
	v_add_f32_e32 v105, 0x4b400000, v105
	v_perm_b32 v101, v103, v102, s65
	v_perm_b32 v102, v105, v104, s66
	v_or_b32_e32 v101, v101, v102
	global_store_dwordx2 v[124:125], v[100:101], off offset:128
	s_and_saveexec_b64 s[6:7], s[2:3]
	s_cbranch_execz .LBB0_3869
	v_lshl_add_u64 v[100:101], s[12:13], 0, v[112:113]
	s_waitcnt lgkmcnt(1)
	v_add_f32_e32 v96, v96, v97
	s_waitcnt lgkmcnt(0)
	v_add_f32_e32 v97, v98, v99
	global_atomic_add_f32 v[100:101], v96, off
	global_atomic_add_f32 v[100:101], v97, off offset:4
.LBB0_3869:
	s_or_b64 exec, exec, s[6:7]
	v_add_u32_e32 v96, 0x80, v178
	s_waitcnt lgkmcnt(1)
	v_ashrrev_i32_e32 v97, 31, v96
	s_waitcnt lgkmcnt(0)
	v_lshlrev_b64 v[98:99], 11, v[96:97]
	v_lshlrev_b64 v[96:97], 3, v[96:97]
	v_lshl_add_u64 v[108:109], v[98:99], 0, v[176:177]
	v_lshl_add_u64 v[98:99], s[14:15], 0, v[96:97]
	global_load_dwordx2 v[110:111], v[98:99], off
	v_lshl_add_u64 v[98:99], v[108:109], 2, s[18:19]
	global_load_dwordx4 v[100:103], v[98:99], off nt
	global_load_dwordx4 v[104:107], v[98:99], off offset:16 nt
	v_lshl_add_u64 v[108:109], s[20:21], 0, v[108:109]
	s_waitcnt vmcnt(2)
	v_pk_mul_f32 v[110:111], v[110:111], s[28:29] op_sel_hi:[1,0]
	s_nop 0
	v_fma_f32 v111, -v110, v110, v111
	v_add_f32_e32 v111, 0x3727c5ac, v111
	v_rsq_f32_e32 v254, v111
	s_waitcnt vmcnt(1)
	v_sub_f32_e32 v103, v103, v110
	v_sub_f32_e32 v102, v102, v110
	v_sub_f32_e32 v101, v101, v110
	v_sub_f32_e32 v100, v100, v110
	s_waitcnt vmcnt(0)
; __device__ __forceinline__ u32x2 pack8i8(const f32x4 a, const f32x4 b) { return (u32x2){pack4i8(a), pack4i8(b)}; }
; __device__ __forceinline__ u32x4 pack8bf(const f32x4 a, const f32x4 b) { u32x4 w; w.x = cvt_pk_bf16(a[0], a[1]); w.y = cvt_pk_bf16(a[2], a[3]); w.z = cvt_pk_bf16(b[0], b[1]); w.w = cvt_pk_bf16(b[2], b[3]); return w; }
;     __device__ __forceinline__ void operator()(EPI_ARGS) const {
;     ...
;             for (int m = 0; m < 4; ++m) { const int row = row0 + ai * HALF + m * 16; const size_t off = (size_t)row * DM + col0;
;                 float mu = 0.f, rs = 1.f; if constexpr (RESLN) ln_stats(stin, row, mu, rs);
;                 float ss = 0.f, qq = 0.f;
; #pragma unroll
;                 for (int bj = 0; bj < 2; ++bj) { f32x4 r0 = __builtin_nontemporal_load((const f32x4*)(res + off + bj * HALF)), r1 = __builtin_nontemporal_load((const f32x4*)(res + off + bj * HALF + 4));
;                     if constexpr (RESLN) { r0 = (r0 - mu) * rs * gg[bj][0] + bb[bj][0]; r1 = (r1 - mu) * rs * gg[bj][1] + bb[bj][1]; }
;                     const f32x4 y0 = r0 * DN_ALPHA + acc[ai][bj][m][0] * ascale, y1 = r1 * DN_ALPHA + acc[ai][bj][m][1] * ascale;
;                     if constexpr (COPY != 4) { __builtin_nontemporal_store(y0, (f32x4*)(Y + off + bj * HALF)); __builtin_nontemporal_store(y1, (f32x4*)(Y + off + bj * HALF + 4)); }
;                     if constexpr (STATS) { ss += ((y0[0] + y0[1]) + (y0[2] + y0[3])) + ((y1[0] + y1[1]) + (y1[2] + y1[3]));
;                         qq += ((y0[0] * y0[0] + y0[1] * y0[1]) + (y0[2] * y0[2] + y0[3] * y0[3])) + ((y1[0] * y1[0] + y1[1] * y1[1]) + (y1[2] * y1[2] + y1[3] * y1[3])); }
;                     if constexpr (COPY == 1) *(u32x2*)((unsigned char*)copy + off + bj * HALF) = pack8fp8(y0 * cscale, y1 * cscale);
;                     if constexpr (COPY == 3) *(u32x2*)((unsigned char*)copy + off + bj * HALF) = pack8i8(y0 * cscale, y1 * cscale);
;                     if constexpr (COPY == 2 || COPY == 4) *(u32x4*)((bf16_t*)copy + off + bj * HALF) = pack8bf(y0, y1); }
;                 if constexpr (STATS) { ss += __shfl_xor(ss, 16); ss += __shfl_xor(ss, 32); qq += __shfl_xor(qq, 16); qq += __shfl_xor(qq, 32);
;                     if (fq == 0) { unsafeAtomicAdd(stout + 2 * (size_t)row, ss); unsafeAtomicAdd(stout + 2 * (size_t)row + 1, qq); } }
	v_sub_f32_e32 v107, v107, v110
	v_sub_f32_e32 v106, v106, v110
	v_sub_f32_e32 v105, v105, v110
	v_sub_f32_e32 v104, v104, v110
	s_nop 0
	s_nop 1
	v_mov_b32_e32 v112, v254
	v_pk_mul_f32 v[100:101], v[100:101], v[112:113] op_sel_hi:[1,0]
	v_pk_mul_f32 v[102:103], v[102:103], v[112:113] op_sel_hi:[1,0]
	v_pk_mul_f32 v[104:105], v[104:105], v[112:113] op_sel_hi:[1,0]
	v_pk_mul_f32 v[106:107], v[106:107], v[112:113] op_sel_hi:[1,0]
	v_pk_fma_f32 v[102:103], v[30:31], v[102:103], v[18:19]
	v_pk_fma_f32 v[100:101], v[28:29], v[100:101], v[16:17]
	v_pk_fma_f32 v[106:107], v[22:23], v[106:107], v[26:27]
	v_pk_fma_f32 v[104:105], v[20:21], v[104:105], v[24:25]
	v_pk_mul_f32 v[100:101], v[100:101], s[30:31] op_sel_hi:[1,0]
	v_pk_mul_f32 v[102:103], v[102:103], s[30:31] op_sel_hi:[1,0]
	v_pk_mul_f32 v[104:105], v[104:105], s[30:31] op_sel_hi:[1,0]
	v_pk_mul_f32 v[106:107], v[106:107], s[30:31] op_sel_hi:[1,0]
	v_pk_fma_f32 v[94:95], v[94:95], s[36:37], v[102:103] op_sel_hi:[1,0,1]
	v_pk_fma_f32 v[92:93], v[92:93], s[36:37], v[100:101] op_sel_hi:[1,0,1]
	v_pk_fma_f32 v[90:91], v[90:91], s[36:37], v[106:107] op_sel_hi:[1,0,1]
	v_pk_fma_f32 v[88:89], v[88:89], s[36:37], v[104:105] op_sel_hi:[1,0,1]
	v_pk_mul_f32 v[100:101], v[94:95], s[38:39] op_sel_hi:[1,0]
	v_pk_mul_f32 v[102:103], v[92:93], s[38:39] op_sel_hi:[1,0]
	v_pk_mul_f32 v[104:105], v[90:91], s[38:39] op_sel_hi:[1,0]
	v_pk_mul_f32 v[106:107], v[88:89], s[38:39] op_sel_hi:[1,0]
	v_med3_f32 v102, v102, s64, v195
	v_med3_f32 v103, v103, s64, v195
	v_med3_f32 v100, v100, s64, v195
	v_med3_f32 v101, v101, s64, v195
	v_med3_f32 v106, v106, s64, v195
	v_med3_f32 v107, v107, s64, v195
	v_med3_f32 v104, v104, s64, v195
	v_med3_f32 v105, v105, s64, v195
	v_add_f32_e32 v102, 0x4b400000, v102
	v_add_f32_e32 v103, 0x4b400000, v103
	v_add_f32_e32 v100, 0x4b400000, v100
	v_add_f32_e32 v101, 0x4b400000, v101
	v_add_f32_e32 v106, 0x4b400000, v106
	v_add_f32_e32 v107, 0x4b400000, v107
	v_add_f32_e32 v104, 0x4b400000, v104
	v_add_f32_e32 v105, 0x4b400000, v105
	v_perm_b32 v102, v103, v102, s65
	v_perm_b32 v100, v101, v100, s66
	v_perm_b32 v101, v107, v106, s65
	v_perm_b32 v103, v105, v104, s66
	v_or_b32_e32 v100, v102, v100
	v_or_b32_e32 v101, v101, v103
	global_store_dwordx4 v[98:99], v[92:95], off nt
	global_store_dwordx4 v[98:99], v[88:91], off offset:16 nt
	global_store_dwordx2 v[108:109], v[100:101], off
	global_load_dwordx4 v[100:103], v[98:99], off offset:512 nt
	s_nop 0
	global_load_dwordx4 v[104:107], v[98:99], off offset:528 nt
	v_add_f32_e32 v111, v92, v93
	v_add_f32_e32 v113, v94, v95
	v_add_f32_e32 v114, v88, v89
	v_add_f32_e32 v115, v90, v91
	v_mul_f32_e32 v93, v93, v93
	v_mul_f32_e32 v95, v95, v95
	v_mul_f32_e32 v89, v89, v89
	v_mul_f32_e32 v91, v91, v91
	v_add_f32_e32 v111, v111, v113
	v_add_f32_e32 v113, v114, v115
	v_fmac_f32_e32 v93, v92, v92
	v_fmac_f32_e32 v95, v94, v94
	v_fmac_f32_e32 v89, v88, v88
	v_fmac_f32_e32 v91, v90, v90
	v_add_f32_e32 v88, v111, v113
	v_add_f32_e32 v90, v93, v95
	v_add_f32_e32 v89, v89, v91
	v_add_f32_e32 v111, 0, v88
	v_add_f32_e32 v113, v90, v89
	s_waitcnt vmcnt(1)
	v_sub_f32_e32 v89, v103, v110
	v_sub_f32_e32 v88, v102, v110
	v_sub_f32_e32 v91, v101, v110
	v_sub_f32_e32 v90, v100, v110
	s_waitcnt vmcnt(0)
	v_sub_f32_e32 v93, v107, v110
	v_sub_f32_e32 v92, v106, v110
	v_sub_f32_e32 v95, v105, v110
	v_sub_f32_e32 v94, v104, v110
	v_pk_mul_f32 v[90:91], v[90:91], v[112:113] op_sel_hi:[1,0]
	v_pk_mul_f32 v[88:89], v[88:89], v[112:113] op_sel_hi:[1,0]
	v_pk_mul_f32 v[94:95], v[94:95], v[112:113] op_sel_hi:[1,0]
	v_pk_mul_f32 v[92:93], v[92:93], v[112:113] op_sel_hi:[1,0]
	v_pk_fma_f32 v[88:89], v[10:11], v[88:89], v[14:15]
	v_pk_fma_f32 v[90:91], v[8:9], v[90:91], v[12:13]
	v_pk_fma_f32 v[92:93], v[2:3], v[92:93], v[6:7]
	v_pk_fma_f32 v[94:95], v[0:1], v[94:95], v[4:5]
	v_pk_mul_f32 v[90:91], v[90:91], s[30:31] op_sel_hi:[1,0]
	v_pk_mul_f32 v[88:89], v[88:89], s[30:31] op_sel_hi:[1,0]
	v_pk_mul_f32 v[94:95], v[94:95], s[30:31] op_sel_hi:[1,0]
	v_pk_mul_f32 v[92:93], v[92:93], s[30:31] op_sel_hi:[1,0]
	v_pk_fma_f32 v[86:87], v[86:87], s[36:37], v[88:89] op_sel_hi:[1,0,1]
	v_pk_fma_f32 v[84:85], v[84:85], s[36:37], v[90:91] op_sel_hi:[1,0,1]
	v_pk_fma_f32 v[82:83], v[82:83], s[36:37], v[92:93] op_sel_hi:[1,0,1]
	v_pk_fma_f32 v[80:81], v[80:81], s[36:37], v[94:95] op_sel_hi:[1,0,1]
	global_store_dwordx4 v[98:99], v[84:87], off offset:512 nt
	global_store_dwordx4 v[98:99], v[80:83], off offset:528 nt
	v_add_f32_e32 v98, v84, v85
	v_add_f32_e32 v99, v86, v87
	v_add_f32_e32 v100, v80, v81
	v_add_f32_e32 v101, v82, v83
	v_mul_f32_e32 v102, v85, v85
	v_mul_f32_e32 v103, v87, v87
	v_mul_f32_e32 v104, v81, v81
	v_mul_f32_e32 v105, v83, v83
	v_pk_mul_f32 v[90:91], v[84:85], s[38:39] op_sel_hi:[1,0]
	v_pk_mul_f32 v[92:93], v[82:83], s[38:39] op_sel_hi:[1,0]
	v_pk_mul_f32 v[94:95], v[80:81], s[38:39] op_sel_hi:[1,0]
	v_add_f32_e32 v81, v98, v99
	v_add_f32_e32 v83, v100, v101
	v_fmac_f32_e32 v102, v84, v84
	v_fmac_f32_e32 v103, v86, v86
	v_fmac_f32_e32 v104, v80, v80
	v_fmac_f32_e32 v105, v82, v82
	v_med3_f32 v80, v90, s64, v195
	v_add_f32_e32 v81, v81, v83
	v_add_f32_e32 v83, v102, v103
	v_add_f32_e32 v90, v104, v105
	v_med3_f32 v82, v91, s64, v195
	v_add_f32_e32 v83, v83, v90
	v_add_f32_e32 v80, 0x4b400000, v80
	v_add_f32_e32 v82, 0x4b400000, v82
	v_add_f32_e32 v81, v81, v111
	v_add_f32_e32 v83, v113, v83
	v_perm_b32 v80, v82, v80, s65
	ds_bpermute_b32 v82, v153, v81
	ds_bpermute_b32 v90, v153, v83
	v_pk_mul_f32 v[88:89], v[86:87], s[38:39] op_sel_hi:[1,0]
	v_med3_f32 v86, v94, s64, v195
	v_med3_f32 v84, v88, s64, v195
	v_med3_f32 v85, v89, s64, v195
	v_add_f32_e32 v84, 0x4b400000, v84
	v_add_f32_e32 v85, 0x4b400000, v85
	v_perm_b32 v84, v85, v84, s66
	v_or_b32_e32 v84, v80, v84
	s_waitcnt lgkmcnt(1)
	v_add_f32_e32 v80, v81, v82
	s_waitcnt lgkmcnt(0)
	v_add_f32_e32 v82, v83, v90
	ds_bpermute_b32 v81, v152, v80
	ds_bpermute_b32 v83, v152, v82
	v_med3_f32 v87, v95, s64, v195
	v_med3_f32 v88, v92, s64, v195
	v_med3_f32 v89, v93, s64, v195
	v_add_f32_e32 v86, 0x4b400000, v86
	v_add_f32_e32 v87, 0x4b400000, v87
	v_add_f32_e32 v88, 0x4b400000, v88
	v_add_f32_e32 v89, 0x4b400000, v89
	v_perm_b32 v85, v87, v86, s65
	v_perm_b32 v86, v89, v88, s66
	v_or_b32_e32 v85, v85, v86
	global_store_dwordx2 v[108:109], v[84:85], off offset:128
	s_and_saveexec_b64 s[6:7], s[2:3]
	s_cbranch_execz .LBB0_3871
	v_lshl_add_u64 v[84:85], s[12:13], 0, v[96:97]
	s_waitcnt lgkmcnt(1)
	v_add_f32_e32 v80, v80, v81
	s_waitcnt lgkmcnt(0)
	v_add_f32_e32 v81, v82, v83
	global_atomic_add_f32 v[84:85], v80, off
	global_atomic_add_f32 v[84:85], v81, off offset:4
; __device__ __forceinline__ u32x2 pack8i8(const f32x4 a, const f32x4 b) { return (u32x2){pack4i8(a), pack4i8(b)}; }
; __device__ __forceinline__ u32x4 pack8bf(const f32x4 a, const f32x4 b) { u32x4 w; w.x = cvt_pk_bf16(a[0], a[1]); w.y = cvt_pk_bf16(a[2], a[3]); w.z = cvt_pk_bf16(b[0], b[1]); w.w = cvt_pk_bf16(b[2], b[3]); return w; }
;     __device__ __forceinline__ void operator()(EPI_ARGS) const {
;     ...
;             for (int m = 0; m < 4; ++m) { const int row = row0 + ai * HALF + m * 16; const size_t off = (size_t)row * DM + col0;
;                 float mu = 0.f, rs = 1.f; if constexpr (RESLN) ln_stats(stin, row, mu, rs);
;                 float ss = 0.f, qq = 0.f;
; #pragma unroll
;                 for (int bj = 0; bj < 2; ++bj) { f32x4 r0 = __builtin_nontemporal_load((const f32x4*)(res + off + bj * HALF)), r1 = __builtin_nontemporal_load((const f32x4*)(res + off + bj * HALF + 4));
;                     if constexpr (RESLN) { r0 = (r0 - mu) * rs * gg[bj][0] + bb[bj][0]; r1 = (r1 - mu) * rs * gg[bj][1] + bb[bj][1]; }
;                     const f32x4 y0 = r0 * DN_ALPHA + acc[ai][bj][m][0] * ascale, y1 = r1 * DN_ALPHA + acc[ai][bj][m][1] * ascale;
;                     if constexpr (COPY != 4) { __builtin_nontemporal_store(y0, (f32x4*)(Y + off + bj * HALF)); __builtin_nontemporal_store(y1, (f32x4*)(Y + off + bj * HALF + 4)); }
;                     if constexpr (STATS) { ss += ((y0[0] + y0[1]) + (y0[2] + y0[3])) + ((y1[0] + y1[1]) + (y1[2] + y1[3]));
;                         qq += ((y0[0] * y0[0] + y0[1] * y0[1]) + (y0[2] * y0[2] + y0[3] * y0[3])) + ((y1[0] * y1[0] + y1[1] * y1[1]) + (y1[2] * y1[2] + y1[3] * y1[3])); }
;                     if constexpr (COPY == 1) *(u32x2*)((unsigned char*)copy + off + bj * HALF) = pack8fp8(y0 * cscale, y1 * cscale);
;                     if constexpr (COPY == 3) *(u32x2*)((unsigned char*)copy + off + bj * HALF) = pack8i8(y0 * cscale, y1 * cscale);
;                     if constexpr (COPY == 2 || COPY == 4) *(u32x4*)((bf16_t*)copy + off + bj * HALF) = pack8bf(y0, y1); }
;                 if constexpr (STATS) { ss += __shfl_xor(ss, 16); ss += __shfl_xor(ss, 32); qq += __shfl_xor(qq, 16); qq += __shfl_xor(qq, 32);
;                     if (fq == 0) { unsafeAtomicAdd(stout + 2 * (size_t)row, ss); unsafeAtomicAdd(stout + 2 * (size_t)row + 1, qq); } }
.LBB0_3871:
	s_or_b64 exec, exec, s[6:7]
	v_add_u32_e32 v80, 0x90, v178
	s_waitcnt lgkmcnt(1)
	v_ashrrev_i32_e32 v81, 31, v80
	s_waitcnt lgkmcnt(0)
	v_lshlrev_b64 v[82:83], 11, v[80:81]
	v_lshlrev_b64 v[80:81], 3, v[80:81]
	v_lshl_add_u64 v[92:93], v[82:83], 0, v[176:177]
	v_lshl_add_u64 v[82:83], s[14:15], 0, v[80:81]
	global_load_dwordx2 v[94:95], v[82:83], off
	v_lshl_add_u64 v[82:83], v[92:93], 2, s[18:19]
	global_load_dwordx4 v[84:87], v[82:83], off nt
	global_load_dwordx4 v[88:91], v[82:83], off offset:16 nt
	v_lshl_add_u64 v[92:93], s[20:21], 0, v[92:93]
	s_waitcnt vmcnt(2)
	v_pk_mul_f32 v[94:95], v[94:95], s[28:29] op_sel_hi:[1,0]
	s_nop 0
	v_fma_f32 v95, -v94, v94, v95
	v_add_f32_e32 v95, 0x3727c5ac, v95
	v_rsq_f32_e32 v254, v95
	s_waitcnt vmcnt(1)
	v_sub_f32_e32 v87, v87, v94
	v_sub_f32_e32 v86, v86, v94
	v_sub_f32_e32 v85, v85, v94
	v_sub_f32_e32 v84, v84, v94
	s_waitcnt vmcnt(0)
	v_sub_f32_e32 v91, v91, v94
	v_sub_f32_e32 v90, v90, v94
	v_sub_f32_e32 v89, v89, v94
	v_sub_f32_e32 v88, v88, v94
	s_nop 0
	s_nop 1
	v_mov_b32_e32 v96, v254
	v_pk_mul_f32 v[84:85], v[84:85], v[96:97] op_sel_hi:[1,0]
	v_pk_mul_f32 v[86:87], v[86:87], v[96:97] op_sel_hi:[1,0]
	v_pk_mul_f32 v[88:89], v[88:89], v[96:97] op_sel_hi:[1,0]
	v_pk_mul_f32 v[90:91], v[90:91], v[96:97] op_sel_hi:[1,0]
	v_pk_fma_f32 v[86:87], v[30:31], v[86:87], v[18:19]
	v_pk_fma_f32 v[84:85], v[28:29], v[84:85], v[16:17]
	v_pk_fma_f32 v[90:91], v[22:23], v[90:91], v[26:27]
	v_pk_fma_f32 v[88:89], v[20:21], v[88:89], v[24:25]
	v_pk_mul_f32 v[84:85], v[84:85], s[30:31] op_sel_hi:[1,0]
	v_pk_mul_f32 v[86:87], v[86:87], s[30:31] op_sel_hi:[1,0]
	v_pk_mul_f32 v[88:89], v[88:89], s[30:31] op_sel_hi:[1,0]
	v_pk_mul_f32 v[90:91], v[90:91], s[30:31] op_sel_hi:[1,0]
	v_pk_fma_f32 v[78:79], v[78:79], s[36:37], v[86:87] op_sel_hi:[1,0,1]
	v_pk_fma_f32 v[76:77], v[76:77], s[36:37], v[84:85] op_sel_hi:[1,0,1]
	v_pk_fma_f32 v[74:75], v[74:75], s[36:37], v[90:91] op_sel_hi:[1,0,1]
	v_pk_fma_f32 v[72:73], v[72:73], s[36:37], v[88:89] op_sel_hi:[1,0,1]
	v_pk_mul_f32 v[84:85], v[78:79], s[38:39] op_sel_hi:[1,0]
	v_pk_mul_f32 v[86:87], v[76:77], s[38:39] op_sel_hi:[1,0]
	v_pk_mul_f32 v[88:89], v[74:75], s[38:39] op_sel_hi:[1,0]
	v_pk_mul_f32 v[90:91], v[72:73], s[38:39] op_sel_hi:[1,0]
	v_med3_f32 v86, v86, s64, v195
	v_med3_f32 v87, v87, s64, v195
	v_med3_f32 v84, v84, s64, v195
	v_med3_f32 v85, v85, s64, v195
	v_med3_f32 v90, v90, s64, v195
	v_med3_f32 v91, v91, s64, v195
	v_med3_f32 v88, v88, s64, v195
	v_med3_f32 v89, v89, s64, v195
	v_add_f32_e32 v86, 0x4b400000, v86
	v_add_f32_e32 v87, 0x4b400000, v87
	v_add_f32_e32 v84, 0x4b400000, v84
	v_add_f32_e32 v85, 0x4b400000, v85
	v_add_f32_e32 v90, 0x4b400000, v90
	v_add_f32_e32 v91, 0x4b400000, v91
	v_add_f32_e32 v88, 0x4b400000, v88
	v_add_f32_e32 v89, 0x4b400000, v89
	v_perm_b32 v86, v87, v86, s65
	v_perm_b32 v84, v85, v84, s66
	v_perm_b32 v85, v91, v90, s65
	v_perm_b32 v87, v89, v88, s66
	v_or_b32_e32 v84, v86, v84
	v_or_b32_e32 v85, v85, v87
	global_store_dwordx4 v[82:83], v[76:79], off nt
	global_store_dwordx4 v[82:83], v[72:75], off offset:16 nt
	global_store_dwordx2 v[92:93], v[84:85], off
	global_load_dwordx4 v[84:87], v[82:83], off offset:512 nt
	s_nop 0
	global_load_dwordx4 v[88:91], v[82:83], off offset:528 nt
	v_add_f32_e32 v95, v76, v77
	v_add_f32_e32 v97, v78, v79
	v_add_f32_e32 v98, v72, v73
	v_add_f32_e32 v99, v74, v75
	v_mul_f32_e32 v77, v77, v77
	v_mul_f32_e32 v79, v79, v79
	v_mul_f32_e32 v73, v73, v73
	v_mul_f32_e32 v75, v75, v75
	v_add_f32_e32 v95, v95, v97
	v_add_f32_e32 v97, v98, v99
	v_fmac_f32_e32 v77, v76, v76
	v_fmac_f32_e32 v79, v78, v78
	v_fmac_f32_e32 v73, v72, v72
	v_fmac_f32_e32 v75, v74, v74
	v_add_f32_e32 v72, v95, v97
	v_add_f32_e32 v74, v77, v79
	v_add_f32_e32 v73, v73, v75
	v_add_f32_e32 v95, 0, v72
	v_add_f32_e32 v97, v74, v73
	s_waitcnt vmcnt(1)
	v_sub_f32_e32 v73, v87, v94
	v_sub_f32_e32 v72, v86, v94
	v_sub_f32_e32 v75, v85, v94
	v_sub_f32_e32 v74, v84, v94
	s_waitcnt vmcnt(0)
	v_sub_f32_e32 v77, v91, v94
	v_sub_f32_e32 v76, v90, v94
	v_sub_f32_e32 v79, v89, v94
	v_sub_f32_e32 v78, v88, v94
	v_pk_mul_f32 v[74:75], v[74:75], v[96:97] op_sel_hi:[1,0]
	v_pk_mul_f32 v[72:73], v[72:73], v[96:97] op_sel_hi:[1,0]
	v_pk_mul_f32 v[78:79], v[78:79], v[96:97] op_sel_hi:[1,0]
	v_pk_mul_f32 v[76:77], v[76:77], v[96:97] op_sel_hi:[1,0]
	v_pk_fma_f32 v[72:73], v[10:11], v[72:73], v[14:15]
	v_pk_fma_f32 v[74:75], v[8:9], v[74:75], v[12:13]
	v_pk_fma_f32 v[76:77], v[2:3], v[76:77], v[6:7]
	v_pk_fma_f32 v[78:79], v[0:1], v[78:79], v[4:5]
	v_pk_mul_f32 v[74:75], v[74:75], s[30:31] op_sel_hi:[1,0]
	v_pk_mul_f32 v[72:73], v[72:73], s[30:31] op_sel_hi:[1,0]
	v_pk_mul_f32 v[78:79], v[78:79], s[30:31] op_sel_hi:[1,0]
	v_pk_mul_f32 v[76:77], v[76:77], s[30:31] op_sel_hi:[1,0]
	v_pk_fma_f32 v[70:71], v[70:71], s[36:37], v[72:73] op_sel_hi:[1,0,1]
	v_pk_fma_f32 v[68:69], v[68:69], s[36:37], v[74:75] op_sel_hi:[1,0,1]
	v_pk_fma_f32 v[66:67], v[66:67], s[36:37], v[76:77] op_sel_hi:[1,0,1]
	v_pk_fma_f32 v[64:65], v[64:65], s[36:37], v[78:79] op_sel_hi:[1,0,1]
	global_store_dwordx4 v[82:83], v[68:71], off offset:512 nt
	global_store_dwordx4 v[82:83], v[64:67], off offset:528 nt
	v_add_f32_e32 v82, v68, v69
	v_add_f32_e32 v83, v70, v71
	v_add_f32_e32 v84, v64, v65
	v_add_f32_e32 v85, v66, v67
	v_mul_f32_e32 v86, v69, v69
	v_mul_f32_e32 v87, v71, v71
	v_mul_f32_e32 v88, v65, v65
	v_mul_f32_e32 v89, v67, v67
	v_pk_mul_f32 v[74:75], v[68:69], s[38:39] op_sel_hi:[1,0]
	v_pk_mul_f32 v[76:77], v[66:67], s[38:39] op_sel_hi:[1,0]
	v_pk_mul_f32 v[78:79], v[64:65], s[38:39] op_sel_hi:[1,0]
	v_add_f32_e32 v65, v82, v83
	v_add_f32_e32 v67, v84, v85
	v_fmac_f32_e32 v86, v68, v68
	v_fmac_f32_e32 v87, v70, v70
	v_fmac_f32_e32 v88, v64, v64
	v_fmac_f32_e32 v89, v66, v66
	v_med3_f32 v64, v74, s64, v195
	v_add_f32_e32 v65, v65, v67
	v_add_f32_e32 v67, v86, v87
	v_add_f32_e32 v74, v88, v89
	v_med3_f32 v66, v75, s64, v195
	v_add_f32_e32 v67, v67, v74
	v_add_f32_e32 v64, 0x4b400000, v64
	v_add_f32_e32 v66, 0x4b400000, v66
	v_add_f32_e32 v65, v65, v95
	v_add_f32_e32 v67, v97, v67
	v_perm_b32 v64, v66, v64, s65
	ds_bpermute_b32 v66, v153, v65
	ds_bpermute_b32 v74, v153, v67
	v_pk_mul_f32 v[72:73], v[70:71], s[38:39] op_sel_hi:[1,0]
	v_med3_f32 v70, v78, s64, v195
	v_med3_f32 v68, v72, s64, v195
	v_med3_f32 v69, v73, s64, v195
	v_add_f32_e32 v68, 0x4b400000, v68
	v_add_f32_e32 v69, 0x4b400000, v69
	v_perm_b32 v68, v69, v68, s66
	v_or_b32_e32 v68, v64, v68
	s_waitcnt lgkmcnt(1)
; __device__ __forceinline__ u32x2 pack8i8(const f32x4 a, const f32x4 b) { return (u32x2){pack4i8(a), pack4i8(b)}; }
; __device__ __forceinline__ u32x4 pack8bf(const f32x4 a, const f32x4 b) { u32x4 w; w.x = cvt_pk_bf16(a[0], a[1]); w.y = cvt_pk_bf16(a[2], a[3]); w.z = cvt_pk_bf16(b[0], b[1]); w.w = cvt_pk_bf16(b[2], b[3]); return w; }
;     __device__ __forceinline__ void operator()(EPI_ARGS) const {
;     ...
;             for (int m = 0; m < 4; ++m) { const int row = row0 + ai * HALF + m * 16; const size_t off = (size_t)row * DM + col0;
;                 float mu = 0.f, rs = 1.f; if constexpr (RESLN) ln_stats(stin, row, mu, rs);
;                 float ss = 0.f, qq = 0.f;
; #pragma unroll
;                 for (int bj = 0; bj < 2; ++bj) { f32x4 r0 = __builtin_nontemporal_load((const f32x4*)(res + off + bj * HALF)), r1 = __builtin_nontemporal_load((const f32x4*)(res + off + bj * HALF + 4));
;                     if constexpr (RESLN) { r0 = (r0 - mu) * rs * gg[bj][0] + bb[bj][0]; r1 = (r1 - mu) * rs * gg[bj][1] + bb[bj][1]; }
;                     const f32x4 y0 = r0 * DN_ALPHA + acc[ai][bj][m][0] * ascale, y1 = r1 * DN_ALPHA + acc[ai][bj][m][1] * ascale;
;                     if constexpr (COPY != 4) { __builtin_nontemporal_store(y0, (f32x4*)(Y + off + bj * HALF)); __builtin_nontemporal_store(y1, (f32x4*)(Y + off + bj * HALF + 4)); }
;                     if constexpr (STATS) { ss += ((y0[0] + y0[1]) + (y0[2] + y0[3])) + ((y1[0] + y1[1]) + (y1[2] + y1[3]));
;                         qq += ((y0[0] * y0[0] + y0[1] * y0[1]) + (y0[2] * y0[2] + y0[3] * y0[3])) + ((y1[0] * y1[0] + y1[1] * y1[1]) + (y1[2] * y1[2] + y1[3] * y1[3])); }
;                     if constexpr (COPY == 1) *(u32x2*)((unsigned char*)copy + off + bj * HALF) = pack8fp8(y0 * cscale, y1 * cscale);
;                     if constexpr (COPY == 3) *(u32x2*)((unsigned char*)copy + off + bj * HALF) = pack8i8(y0 * cscale, y1 * cscale);
;                     if constexpr (COPY == 2 || COPY == 4) *(u32x4*)((bf16_t*)copy + off + bj * HALF) = pack8bf(y0, y1); }
;                 if constexpr (STATS) { ss += __shfl_xor(ss, 16); ss += __shfl_xor(ss, 32); qq += __shfl_xor(qq, 16); qq += __shfl_xor(qq, 32);
;                     if (fq == 0) { unsafeAtomicAdd(stout + 2 * (size_t)row, ss); unsafeAtomicAdd(stout + 2 * (size_t)row + 1, qq); } }
	v_add_f32_e32 v64, v65, v66
	s_waitcnt lgkmcnt(0)
	v_add_f32_e32 v66, v67, v74
	ds_bpermute_b32 v65, v152, v64
	ds_bpermute_b32 v67, v152, v66
	v_med3_f32 v71, v79, s64, v195
	v_med3_f32 v72, v76, s64, v195
	v_med3_f32 v73, v77, s64, v195
	v_add_f32_e32 v70, 0x4b400000, v70
	v_add_f32_e32 v71, 0x4b400000, v71
	v_add_f32_e32 v72, 0x4b400000, v72
	v_add_f32_e32 v73, 0x4b400000, v73
	v_perm_b32 v69, v71, v70, s65
	v_perm_b32 v70, v73, v72, s66
	v_or_b32_e32 v69, v69, v70
	global_store_dwordx2 v[92:93], v[68:69], off offset:128
	s_and_saveexec_b64 s[6:7], s[2:3]
	s_cbranch_execz .LBB0_3873
	v_lshl_add_u64 v[68:69], s[12:13], 0, v[80:81]
	s_waitcnt lgkmcnt(1)
	v_add_f32_e32 v64, v64, v65
	s_waitcnt lgkmcnt(0)
	v_add_f32_e32 v65, v66, v67
	global_atomic_add_f32 v[68:69], v64, off
	global_atomic_add_f32 v[68:69], v65, off offset:4
.LBB0_3873:
	s_or_b64 exec, exec, s[6:7]
	v_add_u32_e32 v64, 0xa0, v178
	s_waitcnt lgkmcnt(1)
	v_ashrrev_i32_e32 v65, 31, v64
	s_waitcnt lgkmcnt(0)
	v_lshlrev_b64 v[66:67], 11, v[64:65]
	v_lshlrev_b64 v[64:65], 3, v[64:65]
	v_lshl_add_u64 v[76:77], v[66:67], 0, v[176:177]
	v_lshl_add_u64 v[66:67], s[14:15], 0, v[64:65]
	global_load_dwordx2 v[78:79], v[66:67], off
	v_lshl_add_u64 v[66:67], v[76:77], 2, s[18:19]
	global_load_dwordx4 v[68:71], v[66:67], off nt
	global_load_dwordx4 v[72:75], v[66:67], off offset:16 nt
	v_lshl_add_u64 v[76:77], s[20:21], 0, v[76:77]
	s_waitcnt vmcnt(2)
	v_pk_mul_f32 v[78:79], v[78:79], s[28:29] op_sel_hi:[1,0]
	s_nop 0
	v_fma_f32 v79, -v78, v78, v79
	v_add_f32_e32 v79, 0x3727c5ac, v79
	v_rsq_f32_e32 v254, v79
	s_waitcnt vmcnt(1)
	v_sub_f32_e32 v71, v71, v78
	v_sub_f32_e32 v70, v70, v78
	v_sub_f32_e32 v69, v69, v78
	v_sub_f32_e32 v68, v68, v78
	s_waitcnt vmcnt(0)
	v_sub_f32_e32 v75, v75, v78
	v_sub_f32_e32 v74, v74, v78
	v_sub_f32_e32 v73, v73, v78
	v_sub_f32_e32 v72, v72, v78
	s_nop 0
	s_nop 1
	v_mov_b32_e32 v80, v254
	v_pk_mul_f32 v[68:69], v[68:69], v[80:81] op_sel_hi:[1,0]
	v_pk_mul_f32 v[70:71], v[70:71], v[80:81] op_sel_hi:[1,0]
	v_pk_mul_f32 v[72:73], v[72:73], v[80:81] op_sel_hi:[1,0]
	v_pk_mul_f32 v[74:75], v[74:75], v[80:81] op_sel_hi:[1,0]
	v_pk_fma_f32 v[70:71], v[30:31], v[70:71], v[18:19]
	v_pk_fma_f32 v[68:69], v[28:29], v[68:69], v[16:17]
	v_pk_fma_f32 v[74:75], v[22:23], v[74:75], v[26:27]
	v_pk_fma_f32 v[72:73], v[20:21], v[72:73], v[24:25]
	v_pk_mul_f32 v[68:69], v[68:69], s[30:31] op_sel_hi:[1,0]
	v_pk_mul_f32 v[70:71], v[70:71], s[30:31] op_sel_hi:[1,0]
	v_pk_mul_f32 v[72:73], v[72:73], s[30:31] op_sel_hi:[1,0]
	v_pk_mul_f32 v[74:75], v[74:75], s[30:31] op_sel_hi:[1,0]
	v_pk_fma_f32 v[62:63], v[62:63], s[36:37], v[70:71] op_sel_hi:[1,0,1]
	v_pk_fma_f32 v[60:61], v[60:61], s[36:37], v[68:69] op_sel_hi:[1,0,1]
	v_pk_fma_f32 v[58:59], v[58:59], s[36:37], v[74:75] op_sel_hi:[1,0,1]
	v_pk_fma_f32 v[56:57], v[56:57], s[36:37], v[72:73] op_sel_hi:[1,0,1]
	v_pk_mul_f32 v[68:69], v[62:63], s[38:39] op_sel_hi:[1,0]
	v_pk_mul_f32 v[70:71], v[60:61], s[38:39] op_sel_hi:[1,0]
	v_pk_mul_f32 v[72:73], v[58:59], s[38:39] op_sel_hi:[1,0]
	v_pk_mul_f32 v[74:75], v[56:57], s[38:39] op_sel_hi:[1,0]
	v_med3_f32 v70, v70, s64, v195
	v_med3_f32 v71, v71, s64, v195
	v_med3_f32 v68, v68, s64, v195
	v_med3_f32 v69, v69, s64, v195
	v_med3_f32 v74, v74, s64, v195
	v_med3_f32 v75, v75, s64, v195
	v_med3_f32 v72, v72, s64, v195
	v_med3_f32 v73, v73, s64, v195
	v_add_f32_e32 v70, 0x4b400000, v70
	v_add_f32_e32 v71, 0x4b400000, v71
	v_add_f32_e32 v68, 0x4b400000, v68
	v_add_f32_e32 v69, 0x4b400000, v69
	v_add_f32_e32 v74, 0x4b400000, v74
	v_add_f32_e32 v75, 0x4b400000, v75
	v_add_f32_e32 v72, 0x4b400000, v72
	v_add_f32_e32 v73, 0x4b400000, v73
	v_perm_b32 v70, v71, v70, s65
	v_perm_b32 v68, v69, v68, s66
	v_perm_b32 v69, v75, v74, s65
	v_perm_b32 v71, v73, v72, s66
	v_or_b32_e32 v68, v70, v68
	v_or_b32_e32 v69, v69, v71
	global_store_dwordx4 v[66:67], v[60:63], off nt
	global_store_dwordx4 v[66:67], v[56:59], off offset:16 nt
	global_store_dwordx2 v[76:77], v[68:69], off
	global_load_dwordx4 v[68:71], v[66:67], off offset:512 nt
	s_nop 0
	global_load_dwordx4 v[72:75], v[66:67], off offset:528 nt
	v_add_f32_e32 v79, v60, v61
	v_add_f32_e32 v81, v62, v63
	v_add_f32_e32 v82, v56, v57
	v_add_f32_e32 v83, v58, v59
	v_mul_f32_e32 v61, v61, v61
	v_mul_f32_e32 v63, v63, v63
	v_mul_f32_e32 v57, v57, v57
	v_mul_f32_e32 v59, v59, v59
	v_add_f32_e32 v79, v79, v81
	v_add_f32_e32 v81, v82, v83
	v_fmac_f32_e32 v61, v60, v60
	v_fmac_f32_e32 v63, v62, v62
	v_fmac_f32_e32 v57, v56, v56
	v_fmac_f32_e32 v59, v58, v58
	v_add_f32_e32 v56, v79, v81
	v_add_f32_e32 v58, v61, v63
	v_add_f32_e32 v57, v57, v59
	v_add_f32_e32 v79, 0, v56
	v_add_f32_e32 v81, v58, v57
	s_waitcnt vmcnt(1)
	v_sub_f32_e32 v57, v71, v78
	v_sub_f32_e32 v56, v70, v78
	v_sub_f32_e32 v59, v69, v78
	v_sub_f32_e32 v58, v68, v78
	s_waitcnt vmcnt(0)
; __device__ __forceinline__ u32x2 pack8i8(const f32x4 a, const f32x4 b) { return (u32x2){pack4i8(a), pack4i8(b)}; }
; __device__ __forceinline__ u32x4 pack8bf(const f32x4 a, const f32x4 b) { u32x4 w; w.x = cvt_pk_bf16(a[0], a[1]); w.y = cvt_pk_bf16(a[2], a[3]); w.z = cvt_pk_bf16(b[0], b[1]); w.w = cvt_pk_bf16(b[2], b[3]); return w; }
;     __device__ __forceinline__ void operator()(EPI_ARGS) const {
;     ...
;             for (int m = 0; m < 4; ++m) { const int row = row0 + ai * HALF + m * 16; const size_t off = (size_t)row * DM + col0;
;                 float mu = 0.f, rs = 1.f; if constexpr (RESLN) ln_stats(stin, row, mu, rs);
;                 float ss = 0.f, qq = 0.f;
; #pragma unroll
;                 for (int bj = 0; bj < 2; ++bj) { f32x4 r0 = __builtin_nontemporal_load((const f32x4*)(res + off + bj * HALF)), r1 = __builtin_nontemporal_load((const f32x4*)(res + off + bj * HALF + 4));
;                     if constexpr (RESLN) { r0 = (r0 - mu) * rs * gg[bj][0] + bb[bj][0]; r1 = (r1 - mu) * rs * gg[bj][1] + bb[bj][1]; }
;                     const f32x4 y0 = r0 * DN_ALPHA + acc[ai][bj][m][0] * ascale, y1 = r1 * DN_ALPHA + acc[ai][bj][m][1] * ascale;
;                     if constexpr (COPY != 4) { __builtin_nontemporal_store(y0, (f32x4*)(Y + off + bj * HALF)); __builtin_nontemporal_store(y1, (f32x4*)(Y + off + bj * HALF + 4)); }
;                     if constexpr (STATS) { ss += ((y0[0] + y0[1]) + (y0[2] + y0[3])) + ((y1[0] + y1[1]) + (y1[2] + y1[3]));
;                         qq += ((y0[0] * y0[0] + y0[1] * y0[1]) + (y0[2] * y0[2] + y0[3] * y0[3])) + ((y1[0] * y1[0] + y1[1] * y1[1]) + (y1[2] * y1[2] + y1[3] * y1[3])); }
;                     if constexpr (COPY == 1) *(u32x2*)((unsigned char*)copy + off + bj * HALF) = pack8fp8(y0 * cscale, y1 * cscale);
;                     if constexpr (COPY == 3) *(u32x2*)((unsigned char*)copy + off + bj * HALF) = pack8i8(y0 * cscale, y1 * cscale);
;                     if constexpr (COPY == 2 || COPY == 4) *(u32x4*)((bf16_t*)copy + off + bj * HALF) = pack8bf(y0, y1); }
;                 if constexpr (STATS) { ss += __shfl_xor(ss, 16); ss += __shfl_xor(ss, 32); qq += __shfl_xor(qq, 16); qq += __shfl_xor(qq, 32);
;                     if (fq == 0) { unsafeAtomicAdd(stout + 2 * (size_t)row, ss); unsafeAtomicAdd(stout + 2 * (size_t)row + 1, qq); } }
	v_sub_f32_e32 v61, v75, v78
	v_sub_f32_e32 v60, v74, v78
	v_sub_f32_e32 v63, v73, v78
	v_sub_f32_e32 v62, v72, v78
	v_pk_mul_f32 v[58:59], v[58:59], v[80:81] op_sel_hi:[1,0]
	v_pk_mul_f32 v[56:57], v[56:57], v[80:81] op_sel_hi:[1,0]
	v_pk_mul_f32 v[62:63], v[62:63], v[80:81] op_sel_hi:[1,0]
	v_pk_mul_f32 v[60:61], v[60:61], v[80:81] op_sel_hi:[1,0]
	v_pk_fma_f32 v[56:57], v[10:11], v[56:57], v[14:15]
	v_pk_fma_f32 v[58:59], v[8:9], v[58:59], v[12:13]
	v_pk_fma_f32 v[60:61], v[2:3], v[60:61], v[6:7]
	v_pk_fma_f32 v[62:63], v[0:1], v[62:63], v[4:5]
	v_pk_mul_f32 v[58:59], v[58:59], s[30:31] op_sel_hi:[1,0]
	v_pk_mul_f32 v[56:57], v[56:57], s[30:31] op_sel_hi:[1,0]
	v_pk_mul_f32 v[62:63], v[62:63], s[30:31] op_sel_hi:[1,0]
	v_pk_mul_f32 v[60:61], v[60:61], s[30:31] op_sel_hi:[1,0]
	v_pk_fma_f32 v[54:55], v[54:55], s[36:37], v[56:57] op_sel_hi:[1,0,1]
	v_pk_fma_f32 v[52:53], v[52:53], s[36:37], v[58:59] op_sel_hi:[1,0,1]
	v_pk_fma_f32 v[50:51], v[50:51], s[36:37], v[60:61] op_sel_hi:[1,0,1]
	v_pk_fma_f32 v[48:49], v[48:49], s[36:37], v[62:63] op_sel_hi:[1,0,1]
	global_store_dwordx4 v[66:67], v[52:55], off offset:512 nt
	global_store_dwordx4 v[66:67], v[48:51], off offset:528 nt
	v_add_f32_e32 v66, v52, v53
	v_add_f32_e32 v67, v54, v55
	v_add_f32_e32 v68, v48, v49
	v_add_f32_e32 v69, v50, v51
	v_mul_f32_e32 v70, v53, v53
	v_mul_f32_e32 v71, v55, v55
	v_mul_f32_e32 v72, v49, v49
	v_mul_f32_e32 v73, v51, v51
	v_pk_mul_f32 v[58:59], v[52:53], s[38:39] op_sel_hi:[1,0]
	v_pk_mul_f32 v[60:61], v[50:51], s[38:39] op_sel_hi:[1,0]
	v_pk_mul_f32 v[62:63], v[48:49], s[38:39] op_sel_hi:[1,0]
	v_add_f32_e32 v49, v66, v67
	v_add_f32_e32 v51, v68, v69
	v_fmac_f32_e32 v70, v52, v52
	v_fmac_f32_e32 v71, v54, v54
	v_fmac_f32_e32 v72, v48, v48
	v_fmac_f32_e32 v73, v50, v50
	v_med3_f32 v48, v58, s64, v195
	v_add_f32_e32 v49, v49, v51
	v_add_f32_e32 v51, v70, v71
	v_add_f32_e32 v58, v72, v73
	v_med3_f32 v50, v59, s64, v195
	v_add_f32_e32 v51, v51, v58
	v_add_f32_e32 v48, 0x4b400000, v48
	v_add_f32_e32 v50, 0x4b400000, v50
	v_add_f32_e32 v49, v49, v79
	v_add_f32_e32 v51, v81, v51
	v_perm_b32 v48, v50, v48, s65
	ds_bpermute_b32 v50, v153, v49
	ds_bpermute_b32 v58, v153, v51
	v_pk_mul_f32 v[56:57], v[54:55], s[38:39] op_sel_hi:[1,0]
	v_med3_f32 v54, v62, s64, v195
	v_med3_f32 v52, v56, s64, v195
	v_med3_f32 v53, v57, s64, v195
	v_add_f32_e32 v52, 0x4b400000, v52
	v_add_f32_e32 v53, 0x4b400000, v53
	v_perm_b32 v52, v53, v52, s66
	v_or_b32_e32 v52, v48, v52
	s_waitcnt lgkmcnt(1)
	v_add_f32_e32 v48, v49, v50
	s_waitcnt lgkmcnt(0)
	v_add_f32_e32 v50, v51, v58
	ds_bpermute_b32 v49, v152, v48
	ds_bpermute_b32 v51, v152, v50
	v_med3_f32 v55, v63, s64, v195
	v_med3_f32 v56, v60, s64, v195
	v_med3_f32 v57, v61, s64, v195
	v_add_f32_e32 v54, 0x4b400000, v54
	v_add_f32_e32 v55, 0x4b400000, v55
	v_add_f32_e32 v56, 0x4b400000, v56
	v_add_f32_e32 v57, 0x4b400000, v57
	v_perm_b32 v53, v55, v54, s65
	v_perm_b32 v54, v57, v56, s66
	v_or_b32_e32 v53, v53, v54
	global_store_dwordx2 v[76:77], v[52:53], off offset:128
	s_and_saveexec_b64 s[6:7], s[2:3]
	s_cbranch_execz .LBB0_3875
	v_lshl_add_u64 v[52:53], s[12:13], 0, v[64:65]
	s_waitcnt lgkmcnt(1)
	v_add_f32_e32 v48, v48, v49
	s_waitcnt lgkmcnt(0)
	v_add_f32_e32 v49, v50, v51
	global_atomic_add_f32 v[52:53], v48, off
	global_atomic_add_f32 v[52:53], v49, off offset:4
.LBB0_3875:
	s_or_b64 exec, exec, s[6:7]
	v_add_u32_e32 v48, 0xb0, v178
	s_waitcnt lgkmcnt(1)
	v_ashrrev_i32_e32 v49, 31, v48
	s_waitcnt lgkmcnt(0)
	v_lshlrev_b64 v[50:51], 11, v[48:49]
	v_lshlrev_b64 v[48:49], 3, v[48:49]
	v_lshl_add_u64 v[60:61], v[50:51], 0, v[176:177]
	v_lshl_add_u64 v[50:51], s[14:15], 0, v[48:49]
	global_load_dwordx2 v[62:63], v[50:51], off
	v_lshl_add_u64 v[50:51], v[60:61], 2, s[18:19]
	global_load_dwordx4 v[52:55], v[50:51], off nt
	global_load_dwordx4 v[56:59], v[50:51], off offset:16 nt
	v_lshl_add_u64 v[60:61], s[20:21], 0, v[60:61]
	s_waitcnt vmcnt(2)
	v_pk_mul_f32 v[62:63], v[62:63], s[28:29] op_sel_hi:[1,0]
	s_nop 0
	v_fma_f32 v63, -v62, v62, v63
	v_add_f32_e32 v63, 0x3727c5ac, v63
	v_rsq_f32_e32 v254, v63
	s_waitcnt vmcnt(1)
	v_sub_f32_e32 v55, v55, v62
	v_sub_f32_e32 v54, v54, v62
	v_sub_f32_e32 v53, v53, v62
	v_sub_f32_e32 v52, v52, v62
	s_waitcnt vmcnt(0)
; __device__ __forceinline__ u32x2 pack8i8(const f32x4 a, const f32x4 b) { return (u32x2){pack4i8(a), pack4i8(b)}; }
; __device__ __forceinline__ u32x4 pack8bf(const f32x4 a, const f32x4 b) { u32x4 w; w.x = cvt_pk_bf16(a[0], a[1]); w.y = cvt_pk_bf16(a[2], a[3]); w.z = cvt_pk_bf16(b[0], b[1]); w.w = cvt_pk_bf16(b[2], b[3]); return w; }
;     __device__ __forceinline__ void operator()(EPI_ARGS) const {
;     ...
;             for (int m = 0; m < 4; ++m) { const int row = row0 + ai * HALF + m * 16; const size_t off = (size_t)row * DM + col0;
;                 float mu = 0.f, rs = 1.f; if constexpr (RESLN) ln_stats(stin, row, mu, rs);
;                 float ss = 0.f, qq = 0.f;
; #pragma unroll
;                 for (int bj = 0; bj < 2; ++bj) { f32x4 r0 = __builtin_nontemporal_load((const f32x4*)(res + off + bj * HALF)), r1 = __builtin_nontemporal_load((const f32x4*)(res + off + bj * HALF + 4));
;                     if constexpr (RESLN) { r0 = (r0 - mu) * rs * gg[bj][0] + bb[bj][0]; r1 = (r1 - mu) * rs * gg[bj][1] + bb[bj][1]; }
;                     const f32x4 y0 = r0 * DN_ALPHA + acc[ai][bj][m][0] * ascale, y1 = r1 * DN_ALPHA + acc[ai][bj][m][1] * ascale;
;                     if constexpr (COPY != 4) { __builtin_nontemporal_store(y0, (f32x4*)(Y + off + bj * HALF)); __builtin_nontemporal_store(y1, (f32x4*)(Y + off + bj * HALF + 4)); }
;                     if constexpr (STATS) { ss += ((y0[0] + y0[1]) + (y0[2] + y0[3])) + ((y1[0] + y1[1]) + (y1[2] + y1[3]));
;                         qq += ((y0[0] * y0[0] + y0[1] * y0[1]) + (y0[2] * y0[2] + y0[3] * y0[3])) + ((y1[0] * y1[0] + y1[1] * y1[1]) + (y1[2] * y1[2] + y1[3] * y1[3])); }
;                     if constexpr (COPY == 1) *(u32x2*)((unsigned char*)copy + off + bj * HALF) = pack8fp8(y0 * cscale, y1 * cscale);
;                     if constexpr (COPY == 3) *(u32x2*)((unsigned char*)copy + off + bj * HALF) = pack8i8(y0 * cscale, y1 * cscale);
;                     if constexpr (COPY == 2 || COPY == 4) *(u32x4*)((bf16_t*)copy + off + bj * HALF) = pack8bf(y0, y1); }
;                 if constexpr (STATS) { ss += __shfl_xor(ss, 16); ss += __shfl_xor(ss, 32); qq += __shfl_xor(qq, 16); qq += __shfl_xor(qq, 32);
;                     if (fq == 0) { unsafeAtomicAdd(stout + 2 * (size_t)row, ss); unsafeAtomicAdd(stout + 2 * (size_t)row + 1, qq); } }
	v_sub_f32_e32 v59, v59, v62
	v_sub_f32_e32 v58, v58, v62
	v_sub_f32_e32 v57, v57, v62
	v_sub_f32_e32 v56, v56, v62
	s_nop 0
	s_nop 1
	v_mov_b32_e32 v64, v254
	v_pk_mul_f32 v[52:53], v[52:53], v[64:65] op_sel_hi:[1,0]
	v_pk_mul_f32 v[54:55], v[54:55], v[64:65] op_sel_hi:[1,0]
	v_pk_mul_f32 v[56:57], v[56:57], v[64:65] op_sel_hi:[1,0]
	v_pk_mul_f32 v[58:59], v[58:59], v[64:65] op_sel_hi:[1,0]
	v_pk_fma_f32 v[18:19], v[30:31], v[54:55], v[18:19]
	v_pk_fma_f32 v[16:17], v[28:29], v[52:53], v[16:17]
	v_pk_fma_f32 v[22:23], v[22:23], v[58:59], v[26:27]
	v_pk_fma_f32 v[20:21], v[20:21], v[56:57], v[24:25]
	v_pk_mul_f32 v[16:17], v[16:17], s[30:31] op_sel_hi:[1,0]
	v_pk_mul_f32 v[18:19], v[18:19], s[30:31] op_sel_hi:[1,0]
	v_pk_mul_f32 v[20:21], v[20:21], s[30:31] op_sel_hi:[1,0]
	v_pk_mul_f32 v[22:23], v[22:23], s[30:31] op_sel_hi:[1,0]
	v_pk_fma_f32 v[18:19], v[46:47], s[36:37], v[18:19] op_sel_hi:[1,0,1]
	v_pk_fma_f32 v[16:17], v[44:45], s[36:37], v[16:17] op_sel_hi:[1,0,1]
	v_pk_fma_f32 v[22:23], v[42:43], s[36:37], v[22:23] op_sel_hi:[1,0,1]
	v_pk_fma_f32 v[20:21], v[40:41], s[36:37], v[20:21] op_sel_hi:[1,0,1]
	v_pk_mul_f32 v[24:25], v[18:19], s[38:39] op_sel_hi:[1,0]
	v_pk_mul_f32 v[26:27], v[16:17], s[38:39] op_sel_hi:[1,0]
	v_pk_mul_f32 v[28:29], v[22:23], s[38:39] op_sel_hi:[1,0]
	v_pk_mul_f32 v[30:31], v[20:21], s[38:39] op_sel_hi:[1,0]
	v_med3_f32 v26, v26, s64, v195
	v_med3_f32 v27, v27, s64, v195
	v_med3_f32 v24, v24, s64, v195
	v_med3_f32 v25, v25, s64, v195
	v_med3_f32 v30, v30, s64, v195
	v_med3_f32 v31, v31, s64, v195
	v_med3_f32 v28, v28, s64, v195
	v_med3_f32 v29, v29, s64, v195
	v_add_f32_e32 v26, 0x4b400000, v26
	v_add_f32_e32 v27, 0x4b400000, v27
	v_add_f32_e32 v24, 0x4b400000, v24
	v_add_f32_e32 v25, 0x4b400000, v25
	v_add_f32_e32 v30, 0x4b400000, v30
	v_add_f32_e32 v31, 0x4b400000, v31
	v_add_f32_e32 v28, 0x4b400000, v28
	v_add_f32_e32 v29, 0x4b400000, v29
	v_perm_b32 v26, v27, v26, s65
	v_perm_b32 v24, v25, v24, s66
	v_perm_b32 v25, v31, v30, s65
	v_perm_b32 v27, v29, v28, s66
	v_or_b32_e32 v24, v26, v24
	v_or_b32_e32 v25, v25, v27
	global_store_dwordx4 v[50:51], v[16:19], off nt
	global_store_dwordx4 v[50:51], v[20:23], off offset:16 nt
	global_store_dwordx2 v[60:61], v[24:25], off
	global_load_dwordx4 v[24:27], v[50:51], off offset:512 nt
	s_nop 0
	global_load_dwordx4 v[28:31], v[50:51], off offset:528 nt
	v_add_f32_e32 v40, v16, v17
	v_add_f32_e32 v41, v18, v19
	v_add_f32_e32 v42, v20, v21
	v_add_f32_e32 v43, v22, v23
	v_mul_f32_e32 v17, v17, v17
	v_mul_f32_e32 v19, v19, v19
	v_mul_f32_e32 v21, v21, v21
	v_mul_f32_e32 v23, v23, v23
	v_add_f32_e32 v40, v40, v41
	v_add_f32_e32 v41, v42, v43
	v_fmac_f32_e32 v17, v16, v16
	v_fmac_f32_e32 v19, v18, v18
	v_fmac_f32_e32 v21, v20, v20
	v_fmac_f32_e32 v23, v22, v22
	v_add_f32_e32 v16, v40, v41
	v_add_f32_e32 v17, v17, v19
	v_add_f32_e32 v18, v21, v23
	v_add_f32_e32 v40, 0, v16
	v_add_f32_e32 v41, v17, v18
	s_waitcnt vmcnt(1)
	v_sub_f32_e32 v17, v27, v62
	v_sub_f32_e32 v16, v26, v62
	v_sub_f32_e32 v19, v25, v62
	v_sub_f32_e32 v18, v24, v62
	s_waitcnt vmcnt(0)
	v_sub_f32_e32 v21, v31, v62
	v_sub_f32_e32 v20, v30, v62
	v_sub_f32_e32 v23, v29, v62
	v_sub_f32_e32 v22, v28, v62
	v_pk_mul_f32 v[18:19], v[18:19], v[64:65] op_sel_hi:[1,0]
	v_pk_mul_f32 v[16:17], v[16:17], v[64:65] op_sel_hi:[1,0]
	v_pk_mul_f32 v[22:23], v[22:23], v[64:65] op_sel_hi:[1,0]
	v_pk_mul_f32 v[20:21], v[20:21], v[64:65] op_sel_hi:[1,0]
	v_pk_fma_f32 v[10:11], v[10:11], v[16:17], v[14:15]
	v_pk_fma_f32 v[8:9], v[8:9], v[18:19], v[12:13]
	v_pk_fma_f32 v[2:3], v[2:3], v[20:21], v[6:7]
	v_pk_fma_f32 v[0:1], v[0:1], v[22:23], v[4:5]
	v_pk_mul_f32 v[4:5], v[8:9], s[30:31] op_sel_hi:[1,0]
	v_pk_mul_f32 v[6:7], v[10:11], s[30:31] op_sel_hi:[1,0]
	v_pk_mul_f32 v[8:9], v[0:1], s[30:31] op_sel_hi:[1,0]
	v_pk_mul_f32 v[10:11], v[2:3], s[30:31] op_sel_hi:[1,0]
	v_pk_fma_f32 v[2:3], v[38:39], s[36:37], v[6:7] op_sel_hi:[1,0,1]
	v_pk_fma_f32 v[0:1], v[36:37], s[36:37], v[4:5] op_sel_hi:[1,0,1]
	v_pk_fma_f32 v[6:7], v[34:35], s[36:37], v[10:11] op_sel_hi:[1,0,1]
	v_pk_fma_f32 v[4:5], v[32:33], s[36:37], v[8:9] op_sel_hi:[1,0,1]
	v_add_f32_e32 v16, v0, v1
	v_add_f32_e32 v17, v2, v3
	v_add_f32_e32 v18, v4, v5
	v_add_f32_e32 v19, v6, v7
	v_mul_f32_e32 v20, v1, v1
	v_mul_f32_e32 v21, v3, v3
	v_mul_f32_e32 v22, v5, v5
	v_mul_f32_e32 v23, v7, v7
	global_store_dwordx4 v[50:51], v[0:3], off offset:512 nt
	global_store_dwordx4 v[50:51], v[4:7], off offset:528 nt
	v_pk_mul_f32 v[8:9], v[2:3], s[38:39] op_sel_hi:[1,0]
	v_pk_mul_f32 v[10:11], v[0:1], s[38:39] op_sel_hi:[1,0]
	v_add_f32_e32 v1, v16, v17
	v_add_f32_e32 v3, v18, v19
	v_fmac_f32_e32 v20, v0, v0
	v_fmac_f32_e32 v21, v2, v2
	v_fmac_f32_e32 v22, v4, v4
	v_fmac_f32_e32 v23, v6, v6
	v_med3_f32 v0, v10, s64, v195
	v_add_f32_e32 v1, v1, v3
	v_add_f32_e32 v3, v20, v21
	v_add_f32_e32 v10, v22, v23
	v_med3_f32 v2, v11, s64, v195
	v_add_f32_e32 v3, v3, v10
	v_add_f32_e32 v0, 0x4b400000, v0
	v_add_f32_e32 v2, 0x4b400000, v2
	v_add_f32_e32 v1, v1, v40
	v_add_f32_e32 v3, v41, v3
	v_perm_b32 v0, v2, v0, s65
	ds_bpermute_b32 v2, v153, v1
	ds_bpermute_b32 v10, v153, v3
	v_pk_mul_f32 v[14:15], v[4:5], s[38:39] op_sel_hi:[1,0]
	v_med3_f32 v4, v8, s64, v195
	v_med3_f32 v5, v9, s64, v195
	v_add_f32_e32 v4, 0x4b400000, v4
	v_add_f32_e32 v5, 0x4b400000, v5
	v_perm_b32 v4, v5, v4, s66
	v_or_b32_e32 v4, v0, v4
	s_waitcnt lgkmcnt(1)
	v_add_f32_e32 v0, v1, v2
	s_waitcnt lgkmcnt(0)
	v_add_f32_e32 v2, v3, v10
	v_pk_mul_f32 v[12:13], v[6:7], s[38:39] op_sel_hi:[1,0]
	ds_bpermute_b32 v1, v152, v0
	ds_bpermute_b32 v3, v152, v2
	v_med3_f32 v6, v14, s64, v195
	v_med3_f32 v7, v15, s64, v195
	v_med3_f32 v8, v12, s64, v195
	v_med3_f32 v9, v13, s64, v195
	v_add_f32_e32 v6, 0x4b400000, v6
	v_add_f32_e32 v7, 0x4b400000, v7
	v_add_f32_e32 v8, 0x4b400000, v8
	v_add_f32_e32 v9, 0x4b400000, v9
	v_perm_b32 v5, v7, v6, s65
	v_perm_b32 v6, v9, v8, s66
	v_or_b32_e32 v5, v5, v6
	global_store_dwordx2 v[60:61], v[4:5], off offset:128
	s_and_saveexec_b64 s[6:7], s[2:3]
	s_cbranch_execz .LBB0_3877
	v_lshl_add_u64 v[4:5], s[12:13], 0, v[48:49]
	s_waitcnt lgkmcnt(1)
	v_add_f32_e32 v0, v0, v1
	s_waitcnt lgkmcnt(0)
	v_add_f32_e32 v1, v2, v3
	global_atomic_add_f32 v[4:5], v0, off
	global_atomic_add_f32 v[4:5], v1, off offset:4

;     __device__ __forceinline__ float qscale(const Unit& u) const { return ((u.pn >= 8 && u.pn <= 11) || u.pn == 17) ? 0.5f : 1.0f; }
; __device__ __forceinline__ void ln_stats(const float* st, int row, float& mu, float& rs) { const f32x2 s = *(const f32x2*)(st + 2 * (size_t)row); mu = s[0] * (1.0f / DM); rs = 1.0f / sqrtf(s[1] * (1.0f / DM) - mu * mu + LN_EPS); }
;     ...
;         if constexpr (QM == 2) { const float qs0_ = g.qs * E.qscale(cur), qs1_ = qs0_ * g.qs_b1; _Pragma("unroll") for (int a = 0; a < 2; ++a) _Pragma("unroll") for (int b = 0; b < 2; ++b) _Pragma("unroll") for (int m = 0; m < 4; ++m) _Pragma("unroll") for (int n = 0; n < 2; ++n) { const v4i t_ = __builtin_bit_cast(v4i, acc[a][b][m][n]); acc[a][b][m][n] = (f32x4){(float)t_[0], (float)t_[1], (float)t_[2], (float)t_[3]} * (b == 0 ? qs0_ : qs1_); } }
;     __device__ __forceinline__ void operator()(EPI_ARGS) const {
;     ...
;         } else if (wc < 2) {
;             const int fi = 16 * wc + 4 * fq;
;             const f32x4 c0 = *(const f32x4*)(C + n0), c1 = *(const f32x4*)(C + n0 + 4), d0 = *(const f32x4*)(D + n0), d1 = *(const f32x4*)(D + n0 + 4);
; #pragma unroll
;             for (int ai = 0; ai < 2; ++ai)
; #pragma unroll
;                 for (int m = 0; m < 4; ++m) { const int row = row0 + ai * HALF + m * 16; float mu, rs; ln_stats(st, row, mu, rs);
;                     const f32x4 c4 = *(const f32x4*)(cs + (size_t)row * 32 + fi), s4 = *(const f32x4*)(sn + (size_t)row * 32 + fi);
.LBB0_3958:
	v_cvt_f32_i32_e32 v125, v125
	v_cvt_f32_i32_e32 v124, v124
	v_cvt_f32_i32_e32 v127, v127
	v_cvt_f32_i32_e32 v126, v126
	v_cvt_f32_i32_e32 v121, v121
	v_cvt_f32_i32_e32 v123, v123
	v_cvt_f32_i32_e32 v122, v122
	v_cvt_f32_i32_e32 v120, v120
	v_cvt_f32_i32_e32 v117, v117
	v_cvt_f32_i32_e32 v116, v116
	v_cvt_f32_i32_e32 v119, v119
	v_cvt_f32_i32_e32 v118, v118
	v_cvt_f32_i32_e32 v113, v113
	v_cvt_f32_i32_e32 v115, v115
	v_cvt_f32_i32_e32 v114, v114
	v_cvt_f32_i32_e32 v112, v112
	v_cvt_f32_i32_e32 v109, v109
	v_cvt_f32_i32_e32 v108, v108
	v_cvt_f32_i32_e32 v111, v111
	v_cvt_f32_i32_e32 v110, v110
	v_cvt_f32_i32_e32 v105, v105
	v_cvt_f32_i32_e32 v107, v107
	v_cvt_f32_i32_e32 v106, v106
	v_cvt_f32_i32_e32 v104, v104
	v_cvt_f32_i32_e32 v101, v101
	v_cvt_f32_i32_e32 v100, v100
	v_cvt_f32_i32_e32 v103, v103
	v_cvt_f32_i32_e32 v102, v102
	v_cvt_f32_i32_e32 v97, v97
	v_cvt_f32_i32_e32 v99, v99
	v_cvt_f32_i32_e32 v98, v98
	v_cvt_f32_i32_e32 v96, v96
	v_cvt_f32_i32_e32 v93, v93
	v_cvt_f32_i32_e32 v92, v92
	v_cvt_f32_i32_e32 v95, v95
	v_cvt_f32_i32_e32 v94, v94
	v_cvt_f32_i32_e32 v89, v89
	v_cvt_f32_i32_e32 v91, v91
	v_cvt_f32_i32_e32 v90, v90
	v_cvt_f32_i32_e32 v88, v88
	v_cvt_f32_i32_e32 v85, v85
	v_cvt_f32_i32_e32 v84, v84
	v_cvt_f32_i32_e32 v87, v87
	v_cvt_f32_i32_e32 v86, v86
	v_cvt_f32_i32_e32 v81, v81
	v_cvt_f32_i32_e32 v83, v83
	v_cvt_f32_i32_e32 v82, v82
	v_cvt_f32_i32_e32 v80, v80
	v_cvt_f32_i32_e32 v77, v77
	v_cvt_f32_i32_e32 v76, v76
	v_cvt_f32_i32_e32 v79, v79
	v_cvt_f32_i32_e32 v78, v78
	v_cvt_f32_i32_e32 v73, v73
	v_cvt_f32_i32_e32 v75, v75
	v_cvt_f32_i32_e32 v74, v74
	v_cvt_f32_i32_e32 v72, v72
	v_cvt_f32_i32_e32 v69, v69
	v_cvt_f32_i32_e32 v68, v68
	v_cvt_f32_i32_e32 v71, v71
	v_cvt_f32_i32_e32 v70, v70
	v_cvt_f32_i32_e32 v65, v65
	v_cvt_f32_i32_e32 v67, v67
	v_cvt_f32_i32_e32 v66, v66
	v_cvt_f32_i32_e32 v64, v64
	s_lshl_b32 s37, s44, 8
	v_pk_mul_f32 v[174:175], v[126:127], s[26:27] op_sel_hi:[1,0]
	v_pk_mul_f32 v[178:179], v[124:125], s[26:27] op_sel_hi:[1,0]
	v_pk_mul_f32 v[172:173], v[122:123], s[26:27] op_sel_hi:[1,0]
	v_pk_mul_f32 v[176:177], v[120:121], s[26:27] op_sel_hi:[1,0]
	v_pk_mul_f32 v[168:169], v[118:119], s[26:27] op_sel_hi:[1,0]
	v_pk_mul_f32 v[170:171], v[116:117], s[26:27] op_sel_hi:[1,0]
	v_pk_mul_f32 v[164:165], v[114:115], s[26:27] op_sel_hi:[1,0]
	v_pk_mul_f32 v[166:167], v[112:113], s[26:27] op_sel_hi:[1,0]
	v_pk_mul_f32 v[158:159], v[110:111], s[26:27] op_sel_hi:[1,0]
	v_pk_mul_f32 v[160:161], v[108:109], s[26:27] op_sel_hi:[1,0]
	v_pk_mul_f32 v[154:155], v[106:107], s[26:27] op_sel_hi:[1,0]
	v_pk_mul_f32 v[156:157], v[104:105], s[26:27] op_sel_hi:[1,0]
	v_pk_mul_f32 v[126:127], v[102:103], s[26:27] op_sel_hi:[1,0]
	v_pk_mul_f32 v[152:153], v[100:101], s[26:27] op_sel_hi:[1,0]
	v_pk_mul_f32 v[122:123], v[98:99], s[26:27] op_sel_hi:[1,0]
	v_pk_mul_f32 v[124:125], v[96:97], s[26:27] op_sel_hi:[1,0]
	v_pk_mul_f32 v[118:119], v[94:95], s[26:27] op_sel_hi:[1,0]
	v_pk_mul_f32 v[120:121], v[92:93], s[26:27] op_sel_hi:[1,0]
	v_pk_mul_f32 v[114:115], v[90:91], s[26:27] op_sel_hi:[1,0]
	v_pk_mul_f32 v[116:117], v[88:89], s[26:27] op_sel_hi:[1,0]
	v_pk_mul_f32 v[110:111], v[86:87], s[26:27] op_sel_hi:[1,0]
	v_pk_mul_f32 v[112:113], v[84:85], s[26:27] op_sel_hi:[1,0]
	v_pk_mul_f32 v[106:107], v[82:83], s[26:27] op_sel_hi:[1,0]
	v_pk_mul_f32 v[108:109], v[80:81], s[26:27] op_sel_hi:[1,0]
	v_pk_mul_f32 v[102:103], v[78:79], s[26:27] op_sel_hi:[1,0]
	v_pk_mul_f32 v[104:105], v[76:77], s[26:27] op_sel_hi:[1,0]
	v_pk_mul_f32 v[98:99], v[74:75], s[26:27] op_sel_hi:[1,0]
	v_pk_mul_f32 v[100:101], v[72:73], s[26:27] op_sel_hi:[1,0]
	v_pk_mul_f32 v[92:93], v[70:71], s[26:27] op_sel_hi:[1,0]
	v_pk_mul_f32 v[94:95], v[68:69], s[26:27] op_sel_hi:[1,0]
	v_pk_mul_f32 v[88:89], v[66:67], s[26:27] op_sel_hi:[1,0]
	v_pk_mul_f32 v[90:91], v[64:65], s[26:27] op_sel_hi:[1,0]
	v_lshl_add_u32 v96, s6, 8, v180
	v_or_b32_e32 v80, s37, v182
	s_cmp_gt_i32 s44, 3
	s_mov_b64 s[6:7], -1
	s_cbranch_scc0 .LBB0_3963
	s_andn2_b64 vcc, exec, s[24:25]
	s_cbranch_vccnz .LBB0_3961
	v_ashrrev_i32_e32 v97, 31, v96
	v_lshl_add_u64 v[66:67], v[96:97], 3, s[12:13]
	global_load_dwordx2 v[86:87], v[66:67], off
	v_mov_b32_e32 v81, v137
	v_lshlrev_b64 v[64:65], 2, v[80:81]
	v_lshl_add_u64 v[66:67], s[14:15], 0, v[64:65]
	global_load_dwordx4 v[76:79], v[66:67], off
	global_load_dwordx4 v[72:75], v[66:67], off offset:16
	v_lshl_add_u64 v[64:65], s[16:17], 0, v[64:65]
	v_lshlrev_b64 v[162:163], 7, v[96:97]
	global_load_dwordx4 v[68:71], v[64:65], off
	s_nop 0
	global_load_dwordx4 v[64:67], v[64:65], off offset:16
	v_lshl_add_u64 v[82:83], v[140:141], 0, v[162:163]
	global_load_dwordx4 v[82:85], v[82:83], off
	v_lshl_add_u64 v[162:163], v[138:139], 0, v[162:163]
	global_load_dwordx4 v[190:193], v[162:163], off
	v_lshlrev_b64 v[196:197], 6, v[96:97]
	v_mov_b32_e32 v162, v137
	v_mov_b32_e32 v163, v137
	v_or_b32_e32 v194, 16, v96
	s_waitcnt vmcnt(0)
; __device__ __forceinline__ void ln_stats(const float* st, int row, float& mu, float& rs) { const f32x2 s = *(const f32x2*)(st + 2 * (size_t)row); mu = s[0] * (1.0f / DM); rs = 1.0f / sqrtf(s[1] * (1.0f / DM) - mu * mu + LN_EPS); }
;     __device__ __forceinline__ void operator()(EPI_ARGS) const {
;     ...
;                 for (int m = 0; m < 4; ++m) { const int row = row0 + ai * HALF + m * 16; float mu, rs; ln_stats(st, row, mu, rs);
;                     const f32x4 c4 = *(const f32x4*)(cs + (size_t)row * 32 + fi), s4 = *(const f32x4*)(sn + (size_t)row * 32 + fi);
;                     const f32x4 v0 = (acc[ai][0][m][0] - c0 * mu) * rs + d0, v1 = (acc[ai][0][m][1] - c1 * mu) * rs + d1;
;                     *(u32x2*)((unsigned char*)KPE + (size_t)row * 64 + 32 * (fq & 1) + 8 * (2 * wc + (fq >> 1))) = pack8fp8(v0 * c4 - v1 * s4, v1 * c4 + v0 * s4); }
	v_pk_mul_f32 v[86:87], v[86:87], s[28:29] op_sel_hi:[1,0]
	s_nop 0
	v_fma_f32 v81, -v86, v86, v87
	v_add_f32_e32 v81, 0x3727c5ac, v81
	v_rsq_f32_e32 v254, v81
	v_xor_b32_e32 v79, 0x80000000, v79
	v_xor_b32_e32 v78, 0x80000000, v78
	v_pk_fma_f32 v[198:199], v[76:77], v[86:87], v[178:179] op_sel_hi:[1,0,1] neg_lo:[1,0,0] neg_hi:[1,0,0]
	v_xor_b32_e32 v75, 0x80000000, v75
	v_xor_b32_e32 v74, 0x80000000, v74
	v_pk_fma_f32 v[200:201], v[72:73], v[86:87], v[176:177] op_sel_hi:[1,0,1] neg_lo:[1,0,0] neg_hi:[1,0,0]
	v_pk_fma_f32 v[202:203], v[78:79], v[86:87], v[174:175] op_sel_hi:[1,0,1]
	v_pk_fma_f32 v[86:87], v[74:75], v[86:87], v[172:173] op_sel_hi:[1,0,1]
	s_nop 0
	s_nop 1
	v_mov_b32_e32 v136, v254
	v_pk_fma_f32 v[198:199], v[198:199], v[136:137], v[68:69] op_sel_hi:[1,0,1]
	v_pk_fma_f32 v[200:201], v[200:201], v[136:137], v[64:65] op_sel_hi:[1,0,1]
	v_pk_fma_f32 v[202:203], v[202:203], v[136:137], v[70:71] op_sel_hi:[1,0,1]
	v_pk_fma_f32 v[86:87], v[86:87], v[136:137], v[66:67] op_sel_hi:[1,0,1]
	v_pk_mul_f32 v[204:205], v[82:83], v[200:201]
	v_pk_mul_f32 v[82:83], v[82:83], v[198:199]
	v_pk_mul_f32 v[206:207], v[84:85], v[86:87]
	v_pk_mul_f32 v[84:85], v[84:85], v[202:203]
	v_pk_fma_f32 v[198:199], v[190:191], v[198:199], v[204:205] neg_lo:[0,0,1] neg_hi:[0,0,1]
	v_pk_fma_f32 v[82:83], v[190:191], v[200:201], v[82:83]
	v_pk_fma_f32 v[84:85], v[192:193], v[86:87], v[84:85]
	v_med3_f32 v81, v198, s68, v187
	v_med3_f32 v86, v199, s68, v187
	v_med3_f32 v82, v82, s68, v187
	v_med3_f32 v83, v83, s68, v187
	v_cvt_pk_fp8_f32 v162, v81, v86
	v_cvt_pk_fp8_f32 v163, v82, v83
	v_pk_fma_f32 v[202:203], v[192:193], v[202:203], v[206:207] neg_lo:[0,0,1] neg_hi:[0,0,1]
	v_med3_f32 v81, v84, s68, v187
	v_med3_f32 v87, v202, s68, v187
	v_med3_f32 v97, v203, s68, v187
	v_med3_f32 v82, v85, s68, v187
	v_cvt_pk_fp8_f32 v162, v87, v97 op_sel:[0,0,1]
	v_cvt_pk_fp8_f32 v163, v81, v82 op_sel:[0,0,1]
	v_ashrrev_i32_e32 v195, 31, v194
	v_lshl_add_u64 v[82:83], v[142:143], 0, v[196:197]
	v_lshl_add_u64 v[84:85], v[194:195], 3, s[12:13]
	global_store_dwordx2 v[82:83], v[162:163], off
	global_load_dwordx2 v[86:87], v[84:85], off
	v_lshlrev_b64 v[162:163], 7, v[194:195]
	v_lshl_add_u64 v[82:83], v[140:141], 0, v[162:163]
	global_load_dwordx4 v[82:85], v[82:83], off
	v_lshl_add_u64 v[162:163], v[138:139], 0, v[162:163]
	global_load_dwordx4 v[190:193], v[162:163], off
	v_mov_b32_e32 v162, v137
	v_mov_b32_e32 v163, v137
	v_or_b32_e32 v196, 32, v96
	v_ashrrev_i32_e32 v197, 31, v196
	s_waitcnt vmcnt(2)
	v_pk_mul_f32 v[86:87], v[86:87], s[28:29] op_sel_hi:[1,0]
	s_nop 0
	v_fma_f32 v81, -v86, v86, v87
	v_add_f32_e32 v81, 0x3727c5ac, v81
	v_rsq_f32_e32 v254, v81
	v_pk_fma_f32 v[198:199], v[78:79], v[86:87], v[168:169] op_sel_hi:[1,0,1]
	v_pk_fma_f32 v[200:201], v[76:77], v[86:87], v[170:171] op_sel_hi:[1,0,1] neg_lo:[1,0,0] neg_hi:[1,0,0]
	v_pk_fma_f32 v[202:203], v[74:75], v[86:87], v[164:165] op_sel_hi:[1,0,1]
	v_pk_fma_f32 v[86:87], v[72:73], v[86:87], v[166:167] op_sel_hi:[1,0,1] neg_lo:[1,0,0] neg_hi:[1,0,0]
	s_nop 1
	s_nop 1
	s_nop 1
	v_mov_b32_e32 v136, v254
	v_pk_fma_f32 v[200:201], v[200:201], v[136:137], v[68:69] op_sel_hi:[1,0,1]
	v_pk_fma_f32 v[86:87], v[86:87], v[136:137], v[64:65] op_sel_hi:[1,0,1]
	v_pk_fma_f32 v[198:199], v[198:199], v[136:137], v[70:71] op_sel_hi:[1,0,1]
	s_waitcnt vmcnt(1)
	v_pk_mul_f32 v[204:205], v[82:83], v[86:87]
	v_pk_mul_f32 v[82:83], v[82:83], v[200:201]
	s_waitcnt vmcnt(0)
	v_pk_fma_f32 v[200:201], v[190:191], v[200:201], v[204:205] neg_lo:[0,0,1] neg_hi:[0,0,1]
	v_pk_fma_f32 v[82:83], v[190:191], v[86:87], v[82:83]
	v_med3_f32 v81, v200, s68, v187
	v_med3_f32 v86, v201, s68, v187
	v_med3_f32 v82, v82, s68, v187
	v_med3_f32 v83, v83, s68, v187
	v_pk_fma_f32 v[202:203], v[202:203], v[136:137], v[66:67] op_sel_hi:[1,0,1]
	v_cvt_pk_fp8_f32 v162, v81, v86
	v_cvt_pk_fp8_f32 v163, v82, v83
	v_pk_mul_f32 v[206:207], v[84:85], v[202:203]
	v_pk_mul_f32 v[84:85], v[84:85], v[198:199]
	v_pk_fma_f32 v[198:199], v[192:193], v[198:199], v[206:207] neg_lo:[0,0,1] neg_hi:[0,0,1]
	v_pk_fma_f32 v[84:85], v[192:193], v[202:203], v[84:85]
	v_med3_f32 v87, v198, s68, v187
	v_med3_f32 v97, v199, s68, v187
	v_med3_f32 v81, v84, s68, v187
	v_med3_f32 v82, v85, s68, v187
	v_cvt_pk_fp8_f32 v162, v87, v97 op_sel:[0,0,1]
	v_cvt_pk_fp8_f32 v163, v81, v82 op_sel:[0,0,1]
	v_lshlrev_b64 v[82:83], 6, v[194:195]
	v_lshl_add_u64 v[82:83], v[142:143], 0, v[82:83]
	v_lshl_add_u64 v[84:85], v[196:197], 3, s[12:13]
	global_store_dwordx2 v[82:83], v[162:163], off
	global_load_dwordx2 v[86:87], v[84:85], off
	v_lshlrev_b64 v[162:163], 7, v[196:197]
	v_lshl_add_u64 v[82:83], v[140:141], 0, v[162:163]
	global_load_dwordx4 v[82:85], v[82:83], off
	v_lshl_add_u64 v[162:163], v[138:139], 0, v[162:163]
	global_load_dwordx4 v[190:193], v[162:163], off
	v_mov_b32_e32 v162, v137
	v_mov_b32_e32 v163, v137
	v_or_b32_e32 v194, 48, v96
	v_ashrrev_i32_e32 v195, 31, v194
	s_waitcnt vmcnt(2)
	v_pk_mul_f32 v[86:87], v[86:87], s[28:29] op_sel_hi:[1,0]
	s_nop 0
	v_fma_f32 v81, -v86, v86, v87
	v_add_f32_e32 v81, 0x3727c5ac, v81
	v_rsq_f32_e32 v254, v81
	v_pk_fma_f32 v[198:199], v[78:79], v[86:87], v[158:159] op_sel_hi:[1,0,1]
	v_pk_fma_f32 v[200:201], v[76:77], v[86:87], v[160:161] op_sel_hi:[1,0,1] neg_lo:[1,0,0] neg_hi:[1,0,0]
	v_pk_fma_f32 v[202:203], v[74:75], v[86:87], v[154:155] op_sel_hi:[1,0,1]
	v_pk_fma_f32 v[86:87], v[72:73], v[86:87], v[156:157] op_sel_hi:[1,0,1] neg_lo:[1,0,0] neg_hi:[1,0,0]
	s_nop 1
	s_nop 1
	s_nop 1
	v_mov_b32_e32 v136, v254
	v_pk_fma_f32 v[200:201], v[200:201], v[136:137], v[68:69] op_sel_hi:[1,0,1]
	v_pk_fma_f32 v[86:87], v[86:87], v[136:137], v[64:65] op_sel_hi:[1,0,1]
	v_pk_fma_f32 v[198:199], v[198:199], v[136:137], v[70:71] op_sel_hi:[1,0,1]
	s_waitcnt vmcnt(1)
; __device__ __forceinline__ void ln_stats(const float* st, int row, float& mu, float& rs) { const f32x2 s = *(const f32x2*)(st + 2 * (size_t)row); mu = s[0] * (1.0f / DM); rs = 1.0f / sqrtf(s[1] * (1.0f / DM) - mu * mu + LN_EPS); }
;     __device__ __forceinline__ void operator()(EPI_ARGS) const {
;     ...
;                 for (int m = 0; m < 4; ++m) { const int row = row0 + ai * HALF + m * 16; float mu, rs; ln_stats(st, row, mu, rs);
;                     const f32x4 c4 = *(const f32x4*)(cs + (size_t)row * 32 + fi), s4 = *(const f32x4*)(sn + (size_t)row * 32 + fi);
;                     const f32x4 v0 = (acc[ai][0][m][0] - c0 * mu) * rs + d0, v1 = (acc[ai][0][m][1] - c1 * mu) * rs + d1;
;                     *(u32x2*)((unsigned char*)KPE + (size_t)row * 64 + 32 * (fq & 1) + 8 * (2 * wc + (fq >> 1))) = pack8fp8(v0 * c4 - v1 * s4, v1 * c4 + v0 * s4); }
	v_pk_mul_f32 v[204:205], v[82:83], v[86:87]
	v_pk_mul_f32 v[82:83], v[82:83], v[200:201]
	s_waitcnt vmcnt(0)
	v_pk_fma_f32 v[200:201], v[190:191], v[200:201], v[204:205] neg_lo:[0,0,1] neg_hi:[0,0,1]
	v_pk_fma_f32 v[82:83], v[190:191], v[86:87], v[82:83]
	v_med3_f32 v81, v200, s68, v187
	v_med3_f32 v86, v201, s68, v187
	v_med3_f32 v82, v82, s68, v187
	v_med3_f32 v83, v83, s68, v187
	v_pk_fma_f32 v[202:203], v[202:203], v[136:137], v[66:67] op_sel_hi:[1,0,1]
	v_cvt_pk_fp8_f32 v162, v81, v86
	v_cvt_pk_fp8_f32 v163, v82, v83
	v_pk_mul_f32 v[206:207], v[84:85], v[202:203]
	v_pk_mul_f32 v[84:85], v[84:85], v[198:199]
	v_pk_fma_f32 v[198:199], v[192:193], v[198:199], v[206:207] neg_lo:[0,0,1] neg_hi:[0,0,1]
	v_pk_fma_f32 v[84:85], v[192:193], v[202:203], v[84:85]
	v_med3_f32 v87, v198, s68, v187
	v_med3_f32 v97, v199, s68, v187
	v_med3_f32 v81, v84, s68, v187
	v_med3_f32 v82, v85, s68, v187
	v_cvt_pk_fp8_f32 v162, v87, v97 op_sel:[0,0,1]
	v_cvt_pk_fp8_f32 v163, v81, v82 op_sel:[0,0,1]
	v_lshlrev_b64 v[82:83], 6, v[196:197]
	v_lshl_add_u64 v[82:83], v[142:143], 0, v[82:83]
	v_lshl_add_u64 v[84:85], v[194:195], 3, s[12:13]
	global_store_dwordx2 v[82:83], v[162:163], off
	global_load_dwordx2 v[86:87], v[84:85], off
	v_lshlrev_b64 v[162:163], 7, v[194:195]
	v_lshl_add_u64 v[82:83], v[140:141], 0, v[162:163]
	global_load_dwordx4 v[82:85], v[82:83], off
	v_lshl_add_u64 v[162:163], v[138:139], 0, v[162:163]
	global_load_dwordx4 v[190:193], v[162:163], off
	v_mov_b32_e32 v162, v137
	v_mov_b32_e32 v163, v137
	v_add_u32_e32 v196, 0x80, v96
	v_ashrrev_i32_e32 v197, 31, v196
	s_waitcnt vmcnt(2)
	v_pk_mul_f32 v[86:87], v[86:87], s[28:29] op_sel_hi:[1,0]
	s_nop 0
	v_fma_f32 v81, -v86, v86, v87
	v_add_f32_e32 v81, 0x3727c5ac, v81
	v_rsq_f32_e32 v254, v81
	v_pk_fma_f32 v[198:199], v[78:79], v[86:87], v[126:127] op_sel_hi:[1,0,1]
	v_pk_fma_f32 v[200:201], v[76:77], v[86:87], v[152:153] op_sel_hi:[1,0,1] neg_lo:[1,0,0] neg_hi:[1,0,0]
	v_pk_fma_f32 v[202:203], v[74:75], v[86:87], v[122:123] op_sel_hi:[1,0,1]
	v_pk_fma_f32 v[86:87], v[72:73], v[86:87], v[124:125] op_sel_hi:[1,0,1] neg_lo:[1,0,0] neg_hi:[1,0,0]
	s_nop 1
	s_nop 1
	s_nop 1
	v_mov_b32_e32 v136, v254
	v_pk_fma_f32 v[200:201], v[200:201], v[136:137], v[68:69] op_sel_hi:[1,0,1]
	v_pk_fma_f32 v[86:87], v[86:87], v[136:137], v[64:65] op_sel_hi:[1,0,1]
	v_pk_fma_f32 v[198:199], v[198:199], v[136:137], v[70:71] op_sel_hi:[1,0,1]
	s_waitcnt vmcnt(1)
	v_pk_mul_f32 v[204:205], v[82:83], v[86:87]
	v_pk_mul_f32 v[82:83], v[82:83], v[200:201]
	s_waitcnt vmcnt(0)
	v_pk_fma_f32 v[200:201], v[190:191], v[200:201], v[204:205] neg_lo:[0,0,1] neg_hi:[0,0,1]
	v_pk_fma_f32 v[82:83], v[190:191], v[86:87], v[82:83]
	v_med3_f32 v81, v200, s68, v187
	v_med3_f32 v86, v201, s68, v187
	v_med3_f32 v82, v82, s68, v187
	v_med3_f32 v83, v83, s68, v187
	v_pk_fma_f32 v[202:203], v[202:203], v[136:137], v[66:67] op_sel_hi:[1,0,1]
	v_cvt_pk_fp8_f32 v162, v81, v86
	v_cvt_pk_fp8_f32 v163, v82, v83
	v_pk_mul_f32 v[206:207], v[84:85], v[202:203]
	v_pk_mul_f32 v[84:85], v[84:85], v[198:199]
	v_pk_fma_f32 v[198:199], v[192:193], v[198:199], v[206:207] neg_lo:[0,0,1] neg_hi:[0,0,1]
	v_pk_fma_f32 v[84:85], v[192:193], v[202:203], v[84:85]
	v_med3_f32 v87, v198, s68, v187
	v_med3_f32 v97, v199, s68, v187
	v_med3_f32 v81, v84, s68, v187
	v_med3_f32 v82, v85, s68, v187
	v_cvt_pk_fp8_f32 v162, v87, v97 op_sel:[0,0,1]
	v_cvt_pk_fp8_f32 v163, v81, v82 op_sel:[0,0,1]
	v_lshlrev_b64 v[82:83], 6, v[194:195]
	v_lshl_add_u64 v[82:83], v[142:143], 0, v[82:83]
	v_lshl_add_u64 v[84:85], v[196:197], 3, s[12:13]
	global_store_dwordx2 v[82:83], v[162:163], off
	global_load_dwordx2 v[86:87], v[84:85], off
	v_lshlrev_b64 v[162:163], 7, v[196:197]
	v_lshl_add_u64 v[82:83], v[140:141], 0, v[162:163]
	global_load_dwordx4 v[82:85], v[82:83], off
	v_lshl_add_u64 v[162:163], v[138:139], 0, v[162:163]
	global_load_dwordx4 v[190:193], v[162:163], off
	v_mov_b32_e32 v162, v137
	v_mov_b32_e32 v163, v137
	v_add_u32_e32 v194, 0x90, v96
	v_ashrrev_i32_e32 v195, 31, v194
	s_waitcnt vmcnt(2)
	v_pk_mul_f32 v[86:87], v[86:87], s[28:29] op_sel_hi:[1,0]
	s_nop 0
	v_fma_f32 v81, -v86, v86, v87
	v_add_f32_e32 v81, 0x3727c5ac, v81
	v_rsq_f32_e32 v254, v81
	v_pk_fma_f32 v[198:199], v[78:79], v[86:87], v[118:119] op_sel_hi:[1,0,1]
	v_pk_fma_f32 v[200:201], v[76:77], v[86:87], v[120:121] op_sel_hi:[1,0,1] neg_lo:[1,0,0] neg_hi:[1,0,0]
	v_pk_fma_f32 v[202:203], v[74:75], v[86:87], v[114:115] op_sel_hi:[1,0,1]
	v_pk_fma_f32 v[86:87], v[72:73], v[86:87], v[116:117] op_sel_hi:[1,0,1] neg_lo:[1,0,0] neg_hi:[1,0,0]
	s_nop 1
	s_nop 1
	s_nop 1
	v_mov_b32_e32 v136, v254
	v_pk_fma_f32 v[200:201], v[200:201], v[136:137], v[68:69] op_sel_hi:[1,0,1]
	v_pk_fma_f32 v[86:87], v[86:87], v[136:137], v[64:65] op_sel_hi:[1,0,1]
	v_pk_fma_f32 v[198:199], v[198:199], v[136:137], v[70:71] op_sel_hi:[1,0,1]
	s_waitcnt vmcnt(1)
	v_pk_mul_f32 v[204:205], v[82:83], v[86:87]
	v_pk_mul_f32 v[82:83], v[82:83], v[200:201]
	s_waitcnt vmcnt(0)
; __device__ __forceinline__ void ln_stats(const float* st, int row, float& mu, float& rs) { const f32x2 s = *(const f32x2*)(st + 2 * (size_t)row); mu = s[0] * (1.0f / DM); rs = 1.0f / sqrtf(s[1] * (1.0f / DM) - mu * mu + LN_EPS); }
;     __device__ __forceinline__ void operator()(EPI_ARGS) const {
;     ...
;                 for (int m = 0; m < 4; ++m) { const int row = row0 + ai * HALF + m * 16; float mu, rs; ln_stats(st, row, mu, rs);
;                     const f32x4 c4 = *(const f32x4*)(cs + (size_t)row * 32 + fi), s4 = *(const f32x4*)(sn + (size_t)row * 32 + fi);
;                     const f32x4 v0 = (acc[ai][0][m][0] - c0 * mu) * rs + d0, v1 = (acc[ai][0][m][1] - c1 * mu) * rs + d1;
;                     *(u32x2*)((unsigned char*)KPE + (size_t)row * 64 + 32 * (fq & 1) + 8 * (2 * wc + (fq >> 1))) = pack8fp8(v0 * c4 - v1 * s4, v1 * c4 + v0 * s4); }
	v_pk_fma_f32 v[200:201], v[190:191], v[200:201], v[204:205] neg_lo:[0,0,1] neg_hi:[0,0,1]
	v_pk_fma_f32 v[82:83], v[190:191], v[86:87], v[82:83]
	v_med3_f32 v81, v200, s68, v187
	v_med3_f32 v86, v201, s68, v187
	v_med3_f32 v82, v82, s68, v187
	v_med3_f32 v83, v83, s68, v187
	v_pk_fma_f32 v[202:203], v[202:203], v[136:137], v[66:67] op_sel_hi:[1,0,1]
	v_cvt_pk_fp8_f32 v162, v81, v86
	v_cvt_pk_fp8_f32 v163, v82, v83
	v_pk_mul_f32 v[206:207], v[84:85], v[202:203]
	v_pk_mul_f32 v[84:85], v[84:85], v[198:199]
	v_pk_fma_f32 v[198:199], v[192:193], v[198:199], v[206:207] neg_lo:[0,0,1] neg_hi:[0,0,1]
	v_pk_fma_f32 v[84:85], v[192:193], v[202:203], v[84:85]
	v_med3_f32 v87, v198, s68, v187
	v_med3_f32 v97, v199, s68, v187
	v_med3_f32 v81, v84, s68, v187
	v_med3_f32 v82, v85, s68, v187
	v_cvt_pk_fp8_f32 v162, v87, v97 op_sel:[0,0,1]
	v_cvt_pk_fp8_f32 v163, v81, v82 op_sel:[0,0,1]
	v_lshlrev_b64 v[82:83], 6, v[196:197]
	v_lshl_add_u64 v[82:83], v[142:143], 0, v[82:83]
	v_lshl_add_u64 v[84:85], v[194:195], 3, s[12:13]
	global_store_dwordx2 v[82:83], v[162:163], off
	global_load_dwordx2 v[86:87], v[84:85], off
	v_lshlrev_b64 v[162:163], 7, v[194:195]
	v_lshl_add_u64 v[82:83], v[140:141], 0, v[162:163]
	global_load_dwordx4 v[82:85], v[82:83], off
	v_lshl_add_u64 v[162:163], v[138:139], 0, v[162:163]
	global_load_dwordx4 v[190:193], v[162:163], off
	v_mov_b32_e32 v162, v137
	v_mov_b32_e32 v163, v137
	v_add_u32_e32 v196, 0xa0, v96
	v_ashrrev_i32_e32 v197, 31, v196
	s_waitcnt vmcnt(2)
	v_pk_mul_f32 v[86:87], v[86:87], s[28:29] op_sel_hi:[1,0]
	s_nop 0
	v_fma_f32 v81, -v86, v86, v87
	v_add_f32_e32 v81, 0x3727c5ac, v81
	v_rsq_f32_e32 v254, v81
	v_pk_fma_f32 v[198:199], v[78:79], v[86:87], v[110:111] op_sel_hi:[1,0,1]
	v_pk_fma_f32 v[200:201], v[76:77], v[86:87], v[112:113] op_sel_hi:[1,0,1] neg_lo:[1,0,0] neg_hi:[1,0,0]
	v_pk_fma_f32 v[202:203], v[74:75], v[86:87], v[106:107] op_sel_hi:[1,0,1]
	v_pk_fma_f32 v[86:87], v[72:73], v[86:87], v[108:109] op_sel_hi:[1,0,1] neg_lo:[1,0,0] neg_hi:[1,0,0]
	s_nop 1
	s_nop 1
	s_nop 1
	v_mov_b32_e32 v136, v254
	v_pk_fma_f32 v[200:201], v[200:201], v[136:137], v[68:69] op_sel_hi:[1,0,1]
	v_pk_fma_f32 v[86:87], v[86:87], v[136:137], v[64:65] op_sel_hi:[1,0,1]
	v_pk_fma_f32 v[198:199], v[198:199], v[136:137], v[70:71] op_sel_hi:[1,0,1]
	s_waitcnt vmcnt(1)
	v_pk_mul_f32 v[204:205], v[82:83], v[86:87]
	v_pk_mul_f32 v[82:83], v[82:83], v[200:201]
	s_waitcnt vmcnt(0)
	v_pk_fma_f32 v[200:201], v[190:191], v[200:201], v[204:205] neg_lo:[0,0,1] neg_hi:[0,0,1]
	v_pk_fma_f32 v[82:83], v[190:191], v[86:87], v[82:83]
	v_med3_f32 v81, v200, s68, v187
	v_med3_f32 v86, v201, s68, v187
	v_med3_f32 v82, v82, s68, v187
	v_med3_f32 v83, v83, s68, v187
	v_pk_fma_f32 v[202:203], v[202:203], v[136:137], v[66:67] op_sel_hi:[1,0,1]
	v_cvt_pk_fp8_f32 v162, v81, v86
	v_cvt_pk_fp8_f32 v163, v82, v83
	v_pk_mul_f32 v[206:207], v[84:85], v[202:203]
	v_pk_mul_f32 v[84:85], v[84:85], v[198:199]
	v_pk_fma_f32 v[198:199], v[192:193], v[198:199], v[206:207] neg_lo:[0,0,1] neg_hi:[0,0,1]
	v_pk_fma_f32 v[84:85], v[192:193], v[202:203], v[84:85]
	v_med3_f32 v87, v198, s68, v187
	v_med3_f32 v97, v199, s68, v187
	v_med3_f32 v81, v84, s68, v187
	v_med3_f32 v82, v85, s68, v187
	v_cvt_pk_fp8_f32 v162, v87, v97 op_sel:[0,0,1]
	v_cvt_pk_fp8_f32 v163, v81, v82 op_sel:[0,0,1]
	v_lshlrev_b64 v[82:83], 6, v[194:195]
	v_lshl_add_u64 v[82:83], v[142:143], 0, v[82:83]
	v_lshl_add_u64 v[84:85], v[196:197], 3, s[12:13]
	global_store_dwordx2 v[82:83], v[162:163], off
	global_load_dwordx2 v[86:87], v[84:85], off
	v_lshlrev_b64 v[162:163], 7, v[196:197]
	v_lshl_add_u64 v[82:83], v[140:141], 0, v[162:163]
	global_load_dwordx4 v[82:85], v[82:83], off
	v_lshl_add_u64 v[162:163], v[138:139], 0, v[162:163]
	global_load_dwordx4 v[190:193], v[162:163], off
	v_mov_b32_e32 v162, v137
	v_mov_b32_e32 v163, v137
	v_add_u32_e32 v194, 0xb0, v96
	v_ashrrev_i32_e32 v195, 31, v194
	s_waitcnt vmcnt(2)
; __device__ __forceinline__ void ln_stats(const float* st, int row, float& mu, float& rs) { const f32x2 s = *(const f32x2*)(st + 2 * (size_t)row); mu = s[0] * (1.0f / DM); rs = 1.0f / sqrtf(s[1] * (1.0f / DM) - mu * mu + LN_EPS); }
;     __device__ __forceinline__ void operator()(EPI_ARGS) const {
;     ...
;                 for (int m = 0; m < 4; ++m) { const int row = row0 + ai * HALF + m * 16; float mu, rs; ln_stats(st, row, mu, rs);
;                     const f32x4 c4 = *(const f32x4*)(cs + (size_t)row * 32 + fi), s4 = *(const f32x4*)(sn + (size_t)row * 32 + fi);
;                     const f32x4 v0 = (acc[ai][0][m][0] - c0 * mu) * rs + d0, v1 = (acc[ai][0][m][1] - c1 * mu) * rs + d1;
;                     *(u32x2*)((unsigned char*)KPE + (size_t)row * 64 + 32 * (fq & 1) + 8 * (2 * wc + (fq >> 1))) = pack8fp8(v0 * c4 - v1 * s4, v1 * c4 + v0 * s4); }
	v_pk_mul_f32 v[86:87], v[86:87], s[28:29] op_sel_hi:[1,0]
	s_nop 0
	v_fma_f32 v81, -v86, v86, v87
	v_add_f32_e32 v81, 0x3727c5ac, v81
	v_rsq_f32_e32 v254, v81
	v_pk_fma_f32 v[198:199], v[78:79], v[86:87], v[102:103] op_sel_hi:[1,0,1]
	v_pk_fma_f32 v[200:201], v[76:77], v[86:87], v[104:105] op_sel_hi:[1,0,1] neg_lo:[1,0,0] neg_hi:[1,0,0]
	v_pk_fma_f32 v[202:203], v[74:75], v[86:87], v[98:99] op_sel_hi:[1,0,1]
	v_pk_fma_f32 v[86:87], v[72:73], v[86:87], v[100:101] op_sel_hi:[1,0,1] neg_lo:[1,0,0] neg_hi:[1,0,0]
	s_nop 1
	s_nop 1
	s_nop 1
	v_mov_b32_e32 v136, v254
	v_pk_fma_f32 v[200:201], v[200:201], v[136:137], v[68:69] op_sel_hi:[1,0,1]
	v_pk_fma_f32 v[86:87], v[86:87], v[136:137], v[64:65] op_sel_hi:[1,0,1]
	v_pk_fma_f32 v[198:199], v[198:199], v[136:137], v[70:71] op_sel_hi:[1,0,1]
	s_waitcnt vmcnt(1)
	v_pk_mul_f32 v[204:205], v[82:83], v[86:87]
	v_pk_mul_f32 v[82:83], v[82:83], v[200:201]
	s_waitcnt vmcnt(0)
	v_pk_fma_f32 v[200:201], v[190:191], v[200:201], v[204:205] neg_lo:[0,0,1] neg_hi:[0,0,1]
	v_pk_fma_f32 v[82:83], v[190:191], v[86:87], v[82:83]
	v_med3_f32 v81, v200, s68, v187
	v_med3_f32 v86, v201, s68, v187
	v_med3_f32 v82, v82, s68, v187
	v_med3_f32 v83, v83, s68, v187
	v_pk_fma_f32 v[202:203], v[202:203], v[136:137], v[66:67] op_sel_hi:[1,0,1]
	v_cvt_pk_fp8_f32 v162, v81, v86
	v_cvt_pk_fp8_f32 v163, v82, v83
	v_pk_mul_f32 v[206:207], v[84:85], v[202:203]
	v_pk_mul_f32 v[84:85], v[84:85], v[198:199]
	v_pk_fma_f32 v[198:199], v[192:193], v[198:199], v[206:207] neg_lo:[0,0,1] neg_hi:[0,0,1]
	v_pk_fma_f32 v[84:85], v[192:193], v[202:203], v[84:85]
	v_med3_f32 v87, v198, s68, v187
	v_med3_f32 v97, v199, s68, v187
	v_med3_f32 v81, v84, s68, v187
	v_med3_f32 v82, v85, s68, v187
	v_cvt_pk_fp8_f32 v162, v87, v97 op_sel:[0,0,1]
	v_cvt_pk_fp8_f32 v163, v81, v82 op_sel:[0,0,1]
	v_lshlrev_b64 v[82:83], 6, v[196:197]
	v_lshl_add_u64 v[82:83], v[142:143], 0, v[82:83]
	v_lshl_add_u64 v[84:85], v[194:195], 3, s[12:13]
	global_store_dwordx2 v[82:83], v[162:163], off
	global_load_dwordx2 v[86:87], v[84:85], off
	v_lshlrev_b64 v[162:163], 7, v[194:195]
	v_lshl_add_u64 v[82:83], v[140:141], 0, v[162:163]
	global_load_dwordx4 v[82:85], v[82:83], off
	v_lshl_add_u64 v[162:163], v[138:139], 0, v[162:163]
	global_load_dwordx4 v[190:193], v[162:163], off
	v_mov_b32_e32 v162, v137
	v_mov_b32_e32 v163, v137
	s_waitcnt vmcnt(2)
	v_pk_mul_f32 v[86:87], v[86:87], s[28:29] op_sel_hi:[1,0]
	s_nop 0
	v_fma_f32 v81, -v86, v86, v87
	v_add_f32_e32 v81, 0x3727c5ac, v81
	v_rsq_f32_e32 v254, v81
	v_pk_fma_f32 v[78:79], v[78:79], v[86:87], v[92:93] op_sel_hi:[1,0,1]
	v_pk_fma_f32 v[76:77], v[76:77], v[86:87], v[94:95] op_sel_hi:[1,0,1] neg_lo:[1,0,0] neg_hi:[1,0,0]
	v_pk_fma_f32 v[74:75], v[74:75], v[86:87], v[88:89] op_sel_hi:[1,0,1]
	v_pk_fma_f32 v[72:73], v[72:73], v[86:87], v[90:91] op_sel_hi:[1,0,1] neg_lo:[1,0,0] neg_hi:[1,0,0]
	s_nop 1
	s_nop 1
	s_nop 1
	v_mov_b32_e32 v86, v254
	v_pk_fma_f32 v[68:69], v[76:77], v[86:87], v[68:69] op_sel_hi:[1,0,1]
	v_pk_fma_f32 v[64:65], v[72:73], v[86:87], v[64:65] op_sel_hi:[1,0,1]
	s_waitcnt vmcnt(1)
	v_pk_mul_f32 v[76:77], v[82:83], v[68:69]
	v_pk_mul_f32 v[72:73], v[82:83], v[64:65]
	s_waitcnt vmcnt(0)
	v_pk_fma_f32 v[64:65], v[190:191], v[64:65], v[76:77]
	v_pk_fma_f32 v[68:69], v[190:191], v[68:69], v[72:73] neg_lo:[0,0,1] neg_hi:[0,0,1]
	v_med3_f32 v64, v64, s68, v187
	v_med3_f32 v68, v68, s68, v187
	v_med3_f32 v69, v69, s68, v187
	v_med3_f32 v65, v65, s68, v187
	v_pk_fma_f32 v[70:71], v[78:79], v[86:87], v[70:71] op_sel_hi:[1,0,1]
	v_pk_fma_f32 v[66:67], v[74:75], v[86:87], v[66:67] op_sel_hi:[1,0,1]
	v_cvt_pk_fp8_f32 v162, v68, v69
	v_cvt_pk_fp8_f32 v163, v64, v65
	v_pk_mul_f32 v[74:75], v[84:85], v[66:67]
	v_pk_mul_f32 v[78:79], v[84:85], v[70:71]
	v_pk_fma_f32 v[70:71], v[192:193], v[70:71], v[74:75] neg_lo:[0,0,1] neg_hi:[0,0,1]
	v_pk_fma_f32 v[66:67], v[192:193], v[66:67], v[78:79]
	v_med3_f32 v70, v70, s68, v187
	v_med3_f32 v71, v71, s68, v187
	v_med3_f32 v64, v66, s68, v187
	v_med3_f32 v65, v67, s68, v187
	v_cvt_pk_fp8_f32 v162, v70, v71 op_sel:[0,0,1]
	v_cvt_pk_fp8_f32 v163, v64, v65 op_sel:[0,0,1]
	v_lshlrev_b64 v[64:65], 6, v[194:195]
	v_lshl_add_u64 v[64:65], v[142:143], 0, v[64:65]
	global_store_dwordx2 v[64:65], v[162:163], off

; __device__ __forceinline__ u32x2 pack8i8(const f32x4 a, const f32x4 b) { return (u32x2){pack4i8(a), pack4i8(b)}; }
; __device__ __forceinline__ void ln_stats(const float* st, int row, float& mu, float& rs) { const f32x2 s = *(const f32x2*)(st + 2 * (size_t)row); mu = s[0] * (1.0f / DM); rs = 1.0f / sqrtf(s[1] * (1.0f / DM) - mu * mu + LN_EPS); }
;     __device__ __forceinline__ void operator()(EPI_ARGS) const {
;     ...
;                 for (int m = 0; m < 4; ++m) { const int row = row0 + ai * HALF + m * 16; float s = 0.f; float mu, rs; ln_stats(st, row, mu, rs);
; #pragma unroll
;                     for (int bj = 0; bj < 2; ++bj) { const f32x4 a = (acc[ai][bj][m][0] - cc[bj][0] * mu) * rs + dd[bj][0], b = (acc[ai][bj][m][1] - cc[bj][1] * mu) * rs + dd[bj][1];
;                         s += (a[0] * a[0] + a[1] * a[1]) + (a[2] * a[2] + a[3] * a[3]) + (b[0] * b[0] + b[1] * b[1]) + (b[2] * b[2] + b[3] * b[3]);
;                         *(u32x2*)((unsigned char*)dst + (size_t)row * 512 + col0 + bj * HALF) = pack8i8(a * lsc, b * lsc); }
;                     s += __shfl_xor(s, 16); s += __shfl_xor(s, 32);
;                     if (fq == 0) ssq[(size_t)row * 16 + slot] = s; }
.LBB0_3964:
	v_ashrrev_i32_e32 v97, 31, v96
	v_lshl_add_u64 v[66:67], v[96:97], 3, s[12:13]
	global_load_dwordx2 v[192:193], v[66:67], off
	v_ashrrev_i32_e32 v81, 31, v80
	v_lshlrev_b64 v[64:65], 2, v[80:81]
	v_lshl_add_u64 v[84:85], s[14:15], 0, v[64:65]
	global_load_dwordx4 v[80:83], v[84:85], off
	global_load_dwordx4 v[72:75], v[84:85], off offset:16
	v_lshl_add_u64 v[162:163], s[16:17], 0, v[64:65]
	global_load_dwordx4 v[68:71], v[162:163], off
	global_load_dwordx4 v[64:67], v[162:163], off offset:16
	v_cvt_f32_i32_e32 v199, v57
	v_and_b32_e32 v57, 64, v188
	v_cvt_f32_i32_e32 v198, v56
	v_xor_b32_e32 v56, 16, v188
	v_add_u32_e32 v57, 64, v57
	v_cvt_f32_i32_e32 v200, v58
	v_xor_b32_e32 v58, 32, v188
	v_cmp_lt_i32_e32 vcc, v56, v57
	v_cvt_f32_i32_e32 v195, v61
	v_cvt_f32_i32_e32 v194, v60
	v_cndmask_b32_e32 v136, v188, v56, vcc
	v_cmp_lt_i32_e32 vcc, v58, v57
	v_cvt_f32_i32_e32 v197, v63
	v_cvt_f32_i32_e32 v196, v62
	v_cvt_f32_i32_e32 v201, v59
	v_cndmask_b32_e32 v190, v188, v58, vcc
	global_load_dwordx4 v[76:79], v[84:85], off offset:528
	s_nop 0
	global_load_dwordx4 v[84:87], v[84:85], off offset:512
	s_nop 0
	global_load_dwordx4 v[56:59], v[162:163], off offset:528
	global_load_dwordx4 v[60:63], v[162:163], off offset:512
	s_cmp_lt_i32 s44, 2
	s_cselect_b32 s6, s69, 0x64000000
	s_add_u32 s6, s56, s6
	s_addc_u32 s7, s57, 0
	s_and_b32 s37, s37, 0x100
	v_lshlrev_b32_e32 v191, 2, v136
	v_or_b32_e32 v136, s37, v182
	v_lshl_add_u64 v[162:163], s[6:7], 0, v[136:137]
	v_lshlrev_b64 v[202:203], 9, v[96:97]
	v_lshl_add_u64 v[202:203], v[162:163], 0, v[202:203]
	v_lshlrev_b32_e32 v190, 2, v190
	s_lshl_b32 s39, s44, 2
	s_or_b32 s44, s39, s60
	s_ashr_i32 s45, s44, 31
	s_waitcnt vmcnt(0)
	v_pk_mul_f32 v[192:193], v[192:193], s[28:29] op_sel_hi:[1,0]
	s_nop 0
	v_fma_f32 v136, -v192, v192, v193
	v_add_f32_e32 v136, 0x3727c5ac, v136
	v_rsq_f32_e32 v254, v136
	v_xor_b32_e32 v83, 0x80000000, v83
	v_xor_b32_e32 v82, 0x80000000, v82
	v_xor_b32_e32 v75, 0x80000000, v75
	v_xor_b32_e32 v74, 0x80000000, v74
	v_pk_fma_f32 v[178:179], v[80:81], v[192:193], v[178:179] op_sel_hi:[1,0,1] neg_lo:[1,0,0] neg_hi:[1,0,0]
	v_pk_fma_f32 v[174:175], v[82:83], v[192:193], v[174:175] op_sel_hi:[1,0,1]
	v_pk_fma_f32 v[172:173], v[74:75], v[192:193], v[172:173] op_sel_hi:[1,0,1]
	v_pk_fma_f32 v[176:177], v[72:73], v[192:193], v[176:177] op_sel_hi:[1,0,1] neg_lo:[1,0,0] neg_hi:[1,0,0]
	s_nop 0
	s_nop 1
	v_mov_b32_e32 v136, v254
	v_pk_fma_f32 v[174:175], v[174:175], v[136:137], v[70:71] op_sel_hi:[1,0,1]
	v_pk_fma_f32 v[178:179], v[178:179], v[136:137], v[68:69] op_sel_hi:[1,0,1]
	v_pk_fma_f32 v[172:173], v[172:173], v[136:137], v[66:67] op_sel_hi:[1,0,1]
	v_mul_f32_e32 v213, v175, v175
	v_mul_f32_e32 v215, v173, v173
	v_pk_mul_f32 v[204:205], v[174:175], s[30:31] op_sel_hi:[1,0]
	v_pk_mul_f32 v[206:207], v[178:179], s[30:31] op_sel_hi:[1,0]
	v_pk_fma_f32 v[176:177], v[176:177], v[136:137], v[64:65] op_sel_hi:[1,0,1]
	v_pk_mul_f32 v[208:209], v[172:173], s[30:31] op_sel_hi:[1,0]
	v_fmac_f32_e32 v213, v174, v174
	v_fmac_f32_e32 v215, v172, v172
	v_med3_f32 v172, v206, s70, v189
	v_med3_f32 v173, v207, s70, v189
	v_med3_f32 v174, v204, s70, v189
	v_med3_f32 v175, v205, s70, v189
	v_mul_f32_e32 v214, v177, v177
	v_pk_mul_f32 v[210:211], v[176:177], s[30:31] op_sel_hi:[1,0]
	v_add_f32_e32 v172, 0x4b400000, v172
	v_add_f32_e32 v173, 0x4b400000, v173
	v_add_f32_e32 v174, 0x4b400000, v174
	v_add_f32_e32 v175, 0x4b400000, v175
	v_fmac_f32_e32 v214, v176, v176
	v_med3_f32 v176, v210, s70, v189
	v_perm_b32 v172, v173, v172, s71
	v_perm_b32 v173, v175, v174, s72
	v_or_b32_e32 v172, v172, v173
	v_add_f32_e32 v173, 0x4b400000, v176
	v_med3_f32 v174, v211, s70, v189
	v_med3_f32 v175, v208, s70, v189
	v_med3_f32 v176, v209, s70, v189
	v_mul_f32_e32 v212, v179, v179
	v_add_f32_e32 v174, 0x4b400000, v174
	v_add_f32_e32 v175, 0x4b400000, v175
	v_add_f32_e32 v176, 0x4b400000, v176
	v_fmac_f32_e32 v212, v178, v178
	v_perm_b32 v173, v174, v173, s71
	v_perm_b32 v174, v176, v175, s72
	v_add_f32_e32 v177, v212, v213
	v_or_b32_e32 v173, v173, v174
	v_add_f32_e32 v177, v214, v177
	global_store_dwordx2 v[202:203], v[172:173], off
	v_pk_mul_f32 v[172:173], v[86:87], v[192:193] op_sel_hi:[1,0]
	v_pk_mul_f32 v[174:175], v[84:85], v[192:193] op_sel_hi:[1,0]
	v_add_f32_e32 v204, v215, v177
	v_pk_fma_f32 v[172:173], v[196:197], s[26:27], v[172:173] op_sel_hi:[1,0,1] neg_lo:[0,0,1] neg_hi:[0,0,1]
	v_pk_fma_f32 v[174:175], v[194:195], s[26:27], v[174:175] op_sel_hi:[1,0,1] neg_lo:[0,0,1] neg_hi:[0,0,1]
	v_pk_mul_f32 v[176:177], v[78:79], v[192:193] op_sel_hi:[1,0]
	v_pk_mul_f32 v[178:179], v[76:77], v[192:193] op_sel_hi:[1,0]
	v_pk_fma_f32 v[172:173], v[172:173], v[136:137], v[62:63] op_sel_hi:[1,0,1]
	v_pk_fma_f32 v[174:175], v[174:175], v[136:137], v[60:61] op_sel_hi:[1,0,1]
	v_pk_fma_f32 v[176:177], v[200:201], s[26:27], v[176:177] op_sel_hi:[1,0,1] neg_lo:[0,0,1] neg_hi:[0,0,1]
	v_pk_fma_f32 v[178:179], v[198:199], s[26:27], v[178:179] op_sel_hi:[1,0,1] neg_lo:[0,0,1] neg_hi:[0,0,1]
	v_pk_fma_f32 v[176:177], v[176:177], v[136:137], v[58:59] op_sel_hi:[1,0,1]
	v_pk_fma_f32 v[178:179], v[178:179], v[136:137], v[56:57] op_sel_hi:[1,0,1]
	v_mul_f32_e32 v136, v175, v175
	v_mul_f32_e32 v192, v173, v173
	v_fmac_f32_e32 v136, v174, v174
	v_fmac_f32_e32 v192, v172, v172
	v_add_f32_e32 v136, v136, v192
	v_mul_f32_e32 v192, v179, v179
	v_pk_mul_f32 v[172:173], v[172:173], s[30:31] op_sel_hi:[1,0]
	v_pk_mul_f32 v[174:175], v[174:175], s[30:31] op_sel_hi:[1,0]
	v_fmac_f32_e32 v192, v178, v178
	v_med3_f32 v174, v174, s70, v189
	v_med3_f32 v175, v175, s70, v189
	v_med3_f32 v172, v172, s70, v189
	v_med3_f32 v173, v173, s70, v189
	v_add_f32_e32 v136, v192, v136
	v_mul_f32_e32 v192, v177, v177
	v_add_f32_e32 v174, 0x4b400000, v174
	v_add_f32_e32 v175, 0x4b400000, v175
	v_add_f32_e32 v172, 0x4b400000, v172
	v_add_f32_e32 v173, 0x4b400000, v173
	v_fmac_f32_e32 v192, v176, v176
	v_pk_mul_f32 v[178:179], v[178:179], s[30:31] op_sel_hi:[1,0]
	v_perm_b32 v174, v175, v174, s71
	v_perm_b32 v172, v173, v172, s72
	v_add_f32_e32 v136, v192, v136
	v_or_b32_e32 v174, v174, v172
	v_med3_f32 v172, v178, s70, v189
	v_add_f32_e32 v136, v204, v136
	v_add_f32_e32 v173, 0x4b400000, v172
	v_med3_f32 v172, v179, s70, v189
	v_add_f32_e32 v175, 0x4b400000, v172
	ds_bpermute_b32 v172, v191, v136
	v_pk_mul_f32 v[176:177], v[176:177], s[30:31] op_sel_hi:[1,0]
	v_perm_b32 v173, v175, v173, s71
	v_med3_f32 v176, v176, s70, v189
	v_med3_f32 v177, v177, s70, v189
	s_waitcnt lgkmcnt(0)
	v_add_f32_e32 v136, v136, v172
	ds_bpermute_b32 v172, v190, v136
	v_add_f32_e32 v176, 0x4b400000, v176
	v_add_f32_e32 v177, 0x4b400000, v177
	v_perm_b32 v175, v177, v176, s72
	v_or_b32_e32 v175, v173, v175
	global_store_dwordx2 v[202:203], v[174:175], off offset:128
	s_and_saveexec_b64 s[6:7], s[2:3]
	s_cbranch_execz .LBB0_3966
; __device__ __forceinline__ u32x2 pack8i8(const f32x4 a, const f32x4 b) { return (u32x2){pack4i8(a), pack4i8(b)}; }
; __device__ __forceinline__ void ln_stats(const float* st, int row, float& mu, float& rs) { const f32x2 s = *(const f32x2*)(st + 2 * (size_t)row); mu = s[0] * (1.0f / DM); rs = 1.0f / sqrtf(s[1] * (1.0f / DM) - mu * mu + LN_EPS); }
;     __device__ __forceinline__ void operator()(EPI_ARGS) const {
;     ...
;                 for (int m = 0; m < 4; ++m) { const int row = row0 + ai * HALF + m * 16; float s = 0.f; float mu, rs; ln_stats(st, row, mu, rs);
; #pragma unroll
;                     for (int bj = 0; bj < 2; ++bj) { const f32x4 a = (acc[ai][bj][m][0] - cc[bj][0] * mu) * rs + dd[bj][0], b = (acc[ai][bj][m][1] - cc[bj][1] * mu) * rs + dd[bj][1];
;                         s += (a[0] * a[0] + a[1] * a[1]) + (a[2] * a[2] + a[3] * a[3]) + (b[0] * b[0] + b[1] * b[1]) + (b[2] * b[2] + b[3] * b[3]);
;                         *(u32x2*)((unsigned char*)dst + (size_t)row * 512 + col0 + bj * HALF) = pack8i8(a * lsc, b * lsc); }
;                     s += __shfl_xor(s, 16); s += __shfl_xor(s, 32);
;                     if (fq == 0) ssq[(size_t)row * 16 + slot] = s; }
	v_lshlrev_b64 v[174:175], 6, v[96:97]
	v_lshl_add_u64 v[174:175], s[10:11], 0, v[174:175]
	v_lshl_add_u64 v[174:175], s[44:45], 2, v[174:175]
	s_waitcnt lgkmcnt(0)
	v_add_f32_e32 v97, v136, v172
	global_store_dword v[174:175], v97, off
.LBB0_3966:
	s_or_b64 exec, exec, s[6:7]
	s_waitcnt lgkmcnt(0)
	v_or_b32_e32 v172, 16, v96
	v_ashrrev_i32_e32 v173, 31, v172
	v_lshl_add_u64 v[174:175], v[172:173], 3, s[12:13]
	global_load_dwordx2 v[174:175], v[174:175], off
	v_cvt_f32_i32_e32 v49, v49
	v_cvt_f32_i32_e32 v48, v48
	v_cvt_f32_i32_e32 v55, v55
	v_cvt_f32_i32_e32 v54, v54
	v_cvt_f32_i32_e32 v53, v53
	v_cvt_f32_i32_e32 v52, v52
	v_cvt_f32_i32_e32 v51, v51
	v_cvt_f32_i32_e32 v50, v50
	v_lshlrev_b64 v[176:177], 9, v[172:173]
	v_lshl_add_u64 v[176:177], v[162:163], 0, v[176:177]
	s_waitcnt vmcnt(0)
	v_pk_mul_f32 v[174:175], v[174:175], s[28:29] op_sel_hi:[1,0]
	s_nop 0
	v_fma_f32 v97, -v174, v174, v175
	v_add_f32_e32 v97, 0x3727c5ac, v97
	v_rsq_f32_e32 v254, v97
	v_pk_fma_f32 v[168:169], v[82:83], v[174:175], v[168:169] op_sel_hi:[1,0,1]
	v_pk_fma_f32 v[170:171], v[80:81], v[174:175], v[170:171] op_sel_hi:[1,0,1] neg_lo:[1,0,0] neg_hi:[1,0,0]
	v_pk_fma_f32 v[164:165], v[74:75], v[174:175], v[164:165] op_sel_hi:[1,0,1]
	v_pk_fma_f32 v[166:167], v[72:73], v[174:175], v[166:167] op_sel_hi:[1,0,1] neg_lo:[1,0,0] neg_hi:[1,0,0]
	v_pk_mul_f32 v[178:179], v[86:87], v[174:175] op_sel_hi:[1,0]
	v_pk_mul_f32 v[192:193], v[84:85], v[174:175] op_sel_hi:[1,0]
	v_pk_mul_f32 v[194:195], v[78:79], v[174:175] op_sel_hi:[1,0]
	v_pk_mul_f32 v[174:175], v[76:77], v[174:175] op_sel_hi:[1,0]
	v_pk_fma_f32 v[54:55], v[54:55], s[26:27], v[178:179] op_sel_hi:[1,0,1] neg_lo:[0,0,1] neg_hi:[0,0,1]
	v_pk_fma_f32 v[48:49], v[48:49], s[26:27], v[174:175] op_sel_hi:[1,0,1] neg_lo:[0,0,1] neg_hi:[0,0,1]
	v_pk_fma_f32 v[52:53], v[52:53], s[26:27], v[192:193] op_sel_hi:[1,0,1] neg_lo:[0,0,1] neg_hi:[0,0,1]
	v_pk_fma_f32 v[50:51], v[50:51], s[26:27], v[194:195] op_sel_hi:[1,0,1] neg_lo:[0,0,1] neg_hi:[0,0,1]
	s_nop 1
	s_nop 1
	v_mov_b32_e32 v136, v254
	v_pk_fma_f32 v[168:169], v[168:169], v[136:137], v[70:71] op_sel_hi:[1,0,1]
	v_pk_fma_f32 v[170:171], v[170:171], v[136:137], v[68:69] op_sel_hi:[1,0,1]
	v_pk_fma_f32 v[164:165], v[164:165], v[136:137], v[66:67] op_sel_hi:[1,0,1]
	v_pk_fma_f32 v[166:167], v[166:167], v[136:137], v[64:65] op_sel_hi:[1,0,1]
	v_pk_fma_f32 v[54:55], v[54:55], v[136:137], v[62:63] op_sel_hi:[1,0,1]
	v_pk_fma_f32 v[52:53], v[52:53], v[136:137], v[60:61] op_sel_hi:[1,0,1]
	v_pk_fma_f32 v[50:51], v[50:51], v[136:137], v[58:59] op_sel_hi:[1,0,1]
	v_pk_fma_f32 v[48:49], v[48:49], v[136:137], v[56:57] op_sel_hi:[1,0,1]
	v_mul_f32_e32 v97, v171, v171
	v_mul_f32_e32 v136, v169, v169
	v_mul_f32_e32 v200, v167, v167
	v_mul_f32_e32 v201, v165, v165
	v_pk_mul_f32 v[174:175], v[168:169], s[30:31] op_sel_hi:[1,0]
	v_pk_mul_f32 v[178:179], v[170:171], s[30:31] op_sel_hi:[1,0]
	v_pk_mul_f32 v[192:193], v[164:165], s[30:31] op_sel_hi:[1,0]
	v_pk_mul_f32 v[194:195], v[166:167], s[30:31] op_sel_hi:[1,0]
	v_mul_f32_e32 v165, v53, v53
	v_mul_f32_e32 v167, v55, v55
	v_mul_f32_e32 v169, v49, v49
	v_pk_mul_f32 v[196:197], v[54:55], s[30:31] op_sel_hi:[1,0]
	v_pk_mul_f32 v[198:199], v[52:53], s[30:31] op_sel_hi:[1,0]
	v_fmac_f32_e32 v97, v170, v170
	v_fmac_f32_e32 v136, v168, v168
	v_fmac_f32_e32 v200, v166, v166
	v_fmac_f32_e32 v201, v164, v164
	v_med3_f32 v53, v178, s70, v189
	v_med3_f32 v55, v179, s70, v189
	v_med3_f32 v164, v174, s70, v189
	v_med3_f32 v166, v175, s70, v189
	v_med3_f32 v168, v194, s70, v189
	v_med3_f32 v170, v195, s70, v189
	v_med3_f32 v174, v192, s70, v189
	v_med3_f32 v175, v193, s70, v189
	v_fmac_f32_e32 v165, v52, v52
	v_fmac_f32_e32 v167, v54, v54
	v_mul_f32_e32 v171, v51, v51
	v_fmac_f32_e32 v169, v48, v48
	v_add_f32_e32 v52, v97, v136
	v_add_f32_e32 v53, 0x4b400000, v53
	v_add_f32_e32 v54, 0x4b400000, v55
	v_add_f32_e32 v55, 0x4b400000, v164
	v_add_f32_e32 v97, 0x4b400000, v166
	v_add_f32_e32 v136, 0x4b400000, v168
	v_add_f32_e32 v164, 0x4b400000, v170
	v_add_f32_e32 v166, 0x4b400000, v174
	v_add_f32_e32 v168, 0x4b400000, v175
	v_add_f32_e32 v165, v165, v167
	v_fmac_f32_e32 v171, v50, v50
	v_add_f32_e32 v52, v200, v52
	v_perm_b32 v53, v54, v53, s71
	v_perm_b32 v54, v97, v55, s72
	v_perm_b32 v55, v164, v136, s71
	v_perm_b32 v97, v168, v166, s72
	v_add_f32_e32 v136, v169, v165
	v_add_f32_e32 v164, v201, v52
	v_or_b32_e32 v52, v53, v54
	v_or_b32_e32 v53, v55, v97
	v_add_f32_e32 v54, v171, v136
	global_store_dwordx2 v[176:177], v[52:53], off
	v_add_f32_e32 v53, v164, v54
	v_med3_f32 v52, v198, s70, v189
	v_med3_f32 v54, v199, s70, v189
	v_med3_f32 v55, v196, s70, v189
	v_med3_f32 v97, v197, s70, v189
	v_pk_mul_f32 v[48:49], v[48:49], s[30:31] op_sel_hi:[1,0]
	v_add_f32_e32 v52, 0x4b400000, v52
	v_add_f32_e32 v54, 0x4b400000, v54
	v_add_f32_e32 v55, 0x4b400000, v55
	v_add_f32_e32 v97, 0x4b400000, v97
	v_perm_b32 v52, v54, v52, s71
	v_perm_b32 v54, v97, v55, s72
	v_med3_f32 v48, v48, s70, v189
	v_or_b32_e32 v52, v52, v54
	v_add_f32_e32 v54, 0x4b400000, v48
	v_med3_f32 v48, v49, s70, v189
	v_add_f32_e32 v55, 0x4b400000, v48
	ds_bpermute_b32 v48, v191, v53
	v_pk_mul_f32 v[50:51], v[50:51], s[30:31] op_sel_hi:[1,0]
	s_waitcnt lgkmcnt(0)
	v_add_f32_e32 v48, v53, v48
	v_med3_f32 v49, v50, s70, v189
	v_add_f32_e32 v50, 0x4b400000, v49
	v_med3_f32 v49, v51, s70, v189
	v_add_f32_e32 v51, 0x4b400000, v49
	ds_bpermute_b32 v49, v190, v48
	v_perm_b32 v53, v55, v54, s71
	v_perm_b32 v50, v51, v50, s72
	v_or_b32_e32 v53, v53, v50
	global_store_dwordx2 v[176:177], v[52:53], off offset:128
	s_and_saveexec_b64 s[6:7], s[2:3]
	s_cbranch_execz .LBB0_3968
	v_lshlrev_b64 v[50:51], 6, v[172:173]
	v_lshl_add_u64 v[50:51], s[10:11], 0, v[50:51]
	v_lshl_add_u64 v[50:51], s[44:45], 2, v[50:51]
	s_waitcnt lgkmcnt(0)
	v_add_f32_e32 v48, v48, v49
	global_store_dword v[50:51], v48, off
; __device__ __forceinline__ u32x2 pack8i8(const f32x4 a, const f32x4 b) { return (u32x2){pack4i8(a), pack4i8(b)}; }
; __device__ __forceinline__ void ln_stats(const float* st, int row, float& mu, float& rs) { const f32x2 s = *(const f32x2*)(st + 2 * (size_t)row); mu = s[0] * (1.0f / DM); rs = 1.0f / sqrtf(s[1] * (1.0f / DM) - mu * mu + LN_EPS); }
;     __device__ __forceinline__ void operator()(EPI_ARGS) const {
;     ...
;                 for (int m = 0; m < 4; ++m) { const int row = row0 + ai * HALF + m * 16; float s = 0.f; float mu, rs; ln_stats(st, row, mu, rs);
; #pragma unroll
;                     for (int bj = 0; bj < 2; ++bj) { const f32x4 a = (acc[ai][bj][m][0] - cc[bj][0] * mu) * rs + dd[bj][0], b = (acc[ai][bj][m][1] - cc[bj][1] * mu) * rs + dd[bj][1];
;                         s += (a[0] * a[0] + a[1] * a[1]) + (a[2] * a[2] + a[3] * a[3]) + (b[0] * b[0] + b[1] * b[1]) + (b[2] * b[2] + b[3] * b[3]);
;                         *(u32x2*)((unsigned char*)dst + (size_t)row * 512 + col0 + bj * HALF) = pack8i8(a * lsc, b * lsc); }
;                     s += __shfl_xor(s, 16); s += __shfl_xor(s, 32);
;                     if (fq == 0) ssq[(size_t)row * 16 + slot] = s; }
.LBB0_3968:
	s_or_b64 exec, exec, s[6:7]
	v_or_b32_e32 v48, 32, v96
	s_waitcnt lgkmcnt(0)
	v_ashrrev_i32_e32 v49, 31, v48
	v_lshl_add_u64 v[50:51], v[48:49], 3, s[12:13]
	global_load_dwordx2 v[50:51], v[50:51], off
	v_cvt_f32_i32_e32 v41, v41
	v_cvt_f32_i32_e32 v40, v40
	v_cvt_f32_i32_e32 v47, v47
	v_cvt_f32_i32_e32 v46, v46
	v_cvt_f32_i32_e32 v45, v45
	v_cvt_f32_i32_e32 v44, v44
	v_cvt_f32_i32_e32 v43, v43
	v_cvt_f32_i32_e32 v42, v42
	v_lshlrev_b64 v[52:53], 9, v[48:49]
	v_lshl_add_u64 v[52:53], v[162:163], 0, v[52:53]
	s_waitcnt vmcnt(0)
	v_pk_mul_f32 v[50:51], v[50:51], s[28:29] op_sel_hi:[1,0]
	s_nop 0
	v_fma_f32 v97, -v50, v50, v51
	v_add_f32_e32 v97, 0x3727c5ac, v97
	v_rsq_f32_e32 v254, v97
	v_pk_fma_f32 v[54:55], v[82:83], v[50:51], v[158:159] op_sel_hi:[1,0,1]
	v_pk_fma_f32 v[158:159], v[80:81], v[50:51], v[160:161] op_sel_hi:[1,0,1] neg_lo:[1,0,0] neg_hi:[1,0,0]
	v_pk_fma_f32 v[154:155], v[74:75], v[50:51], v[154:155] op_sel_hi:[1,0,1]
	v_pk_fma_f32 v[156:157], v[72:73], v[50:51], v[156:157] op_sel_hi:[1,0,1] neg_lo:[1,0,0] neg_hi:[1,0,0]
	v_pk_mul_f32 v[160:161], v[86:87], v[50:51] op_sel_hi:[1,0]
	v_pk_mul_f32 v[164:165], v[84:85], v[50:51] op_sel_hi:[1,0]
	v_pk_mul_f32 v[166:167], v[78:79], v[50:51] op_sel_hi:[1,0]
	v_pk_mul_f32 v[50:51], v[76:77], v[50:51] op_sel_hi:[1,0]
	v_pk_fma_f32 v[46:47], v[46:47], s[26:27], v[160:161] op_sel_hi:[1,0,1] neg_lo:[0,0,1] neg_hi:[0,0,1]
	v_pk_fma_f32 v[40:41], v[40:41], s[26:27], v[50:51] op_sel_hi:[1,0,1] neg_lo:[0,0,1] neg_hi:[0,0,1]
	v_pk_fma_f32 v[44:45], v[44:45], s[26:27], v[164:165] op_sel_hi:[1,0,1] neg_lo:[0,0,1] neg_hi:[0,0,1]
	v_pk_fma_f32 v[42:43], v[42:43], s[26:27], v[166:167] op_sel_hi:[1,0,1] neg_lo:[0,0,1] neg_hi:[0,0,1]
	s_nop 1
	s_nop 1
	v_mov_b32_e32 v50, v254
	v_pk_fma_f32 v[54:55], v[54:55], v[50:51], v[70:71] op_sel_hi:[1,0,1]
	v_pk_fma_f32 v[158:159], v[158:159], v[50:51], v[68:69] op_sel_hi:[1,0,1]
	v_pk_fma_f32 v[154:155], v[154:155], v[50:51], v[66:67] op_sel_hi:[1,0,1]
	v_pk_fma_f32 v[156:157], v[156:157], v[50:51], v[64:65] op_sel_hi:[1,0,1]
	v_pk_fma_f32 v[46:47], v[46:47], v[50:51], v[62:63] op_sel_hi:[1,0,1]
	v_pk_fma_f32 v[44:45], v[44:45], v[50:51], v[60:61] op_sel_hi:[1,0,1]
	v_pk_fma_f32 v[42:43], v[42:43], v[50:51], v[58:59] op_sel_hi:[1,0,1]
	v_pk_fma_f32 v[40:41], v[40:41], v[50:51], v[56:57] op_sel_hi:[1,0,1]
	v_mul_f32_e32 v97, v159, v159
	v_mul_f32_e32 v136, v55, v55
	v_mul_f32_e32 v172, v157, v157
	v_mul_f32_e32 v173, v155, v155
	v_pk_mul_f32 v[50:51], v[54:55], s[30:31] op_sel_hi:[1,0]
	v_pk_mul_f32 v[160:161], v[158:159], s[30:31] op_sel_hi:[1,0]
	v_pk_mul_f32 v[164:165], v[154:155], s[30:31] op_sel_hi:[1,0]
	v_pk_mul_f32 v[166:167], v[156:157], s[30:31] op_sel_hi:[1,0]
	v_mul_f32_e32 v55, v45, v45
	v_mul_f32_e32 v155, v47, v47
	v_mul_f32_e32 v157, v41, v41
	v_pk_mul_f32 v[168:169], v[46:47], s[30:31] op_sel_hi:[1,0]
	v_pk_mul_f32 v[170:171], v[44:45], s[30:31] op_sel_hi:[1,0]
	v_fmac_f32_e32 v97, v158, v158
	v_fmac_f32_e32 v136, v54, v54
	v_fmac_f32_e32 v172, v156, v156
	v_fmac_f32_e32 v173, v154, v154
	v_med3_f32 v45, v160, s70, v189
	v_med3_f32 v47, v161, s70, v189
	v_med3_f32 v50, v50, s70, v189
	v_med3_f32 v51, v51, s70, v189
	v_med3_f32 v54, v166, s70, v189
	v_med3_f32 v154, v167, s70, v189
	v_med3_f32 v156, v164, s70, v189
	v_med3_f32 v158, v165, s70, v189
	v_fmac_f32_e32 v55, v44, v44
	v_fmac_f32_e32 v155, v46, v46
	v_mul_f32_e32 v159, v43, v43
	v_fmac_f32_e32 v157, v40, v40
	v_add_f32_e32 v44, v97, v136
	v_add_f32_e32 v45, 0x4b400000, v45
	v_add_f32_e32 v46, 0x4b400000, v47
	v_add_f32_e32 v47, 0x4b400000, v50
	v_add_f32_e32 v50, 0x4b400000, v51
	v_add_f32_e32 v51, 0x4b400000, v54
	v_add_f32_e32 v54, 0x4b400000, v154
	v_add_f32_e32 v97, 0x4b400000, v156
	v_add_f32_e32 v136, 0x4b400000, v158
	v_add_f32_e32 v55, v55, v155
	v_fmac_f32_e32 v159, v42, v42
	v_add_f32_e32 v44, v172, v44
	v_perm_b32 v45, v46, v45, s71
	v_perm_b32 v46, v50, v47, s72
	v_perm_b32 v47, v54, v51, s71
	v_perm_b32 v50, v136, v97, s72
	v_add_f32_e32 v51, v157, v55
	v_add_f32_e32 v54, v173, v44
	v_or_b32_e32 v44, v45, v46
	v_or_b32_e32 v45, v47, v50
	v_add_f32_e32 v46, v159, v51
	global_store_dwordx2 v[52:53], v[44:45], off
	v_add_f32_e32 v45, v54, v46
	v_med3_f32 v44, v170, s70, v189
	v_med3_f32 v46, v171, s70, v189
	v_med3_f32 v47, v168, s70, v189
	v_med3_f32 v50, v169, s70, v189
	v_pk_mul_f32 v[40:41], v[40:41], s[30:31] op_sel_hi:[1,0]
	v_add_f32_e32 v44, 0x4b400000, v44
	v_add_f32_e32 v46, 0x4b400000, v46
	v_add_f32_e32 v47, 0x4b400000, v47
	v_add_f32_e32 v50, 0x4b400000, v50
	v_perm_b32 v44, v46, v44, s71
	v_perm_b32 v46, v50, v47, s72
	v_med3_f32 v40, v40, s70, v189
	v_or_b32_e32 v44, v44, v46
	v_add_f32_e32 v46, 0x4b400000, v40
	v_med3_f32 v40, v41, s70, v189
	v_add_f32_e32 v47, 0x4b400000, v40
	ds_bpermute_b32 v40, v191, v45
	v_pk_mul_f32 v[42:43], v[42:43], s[30:31] op_sel_hi:[1,0]
	s_waitcnt lgkmcnt(0)
	v_add_f32_e32 v40, v45, v40
	v_med3_f32 v41, v42, s70, v189
	v_add_f32_e32 v42, 0x4b400000, v41
	v_med3_f32 v41, v43, s70, v189
	v_add_f32_e32 v43, 0x4b400000, v41
	ds_bpermute_b32 v41, v190, v40
	v_perm_b32 v45, v47, v46, s71
	v_perm_b32 v42, v43, v42, s72
	v_or_b32_e32 v45, v45, v42
	global_store_dwordx2 v[52:53], v[44:45], off offset:128
	s_and_saveexec_b64 s[6:7], s[2:3]
	s_cbranch_execz .LBB0_3970
	v_lshlrev_b64 v[42:43], 6, v[48:49]
	v_lshl_add_u64 v[42:43], s[10:11], 0, v[42:43]
	v_lshl_add_u64 v[42:43], s[44:45], 2, v[42:43]
	s_waitcnt lgkmcnt(0)
	v_add_f32_e32 v40, v40, v41
	global_store_dword v[42:43], v40, off
; __device__ __forceinline__ u32x2 pack8i8(const f32x4 a, const f32x4 b) { return (u32x2){pack4i8(a), pack4i8(b)}; }
; __device__ __forceinline__ void ln_stats(const float* st, int row, float& mu, float& rs) { const f32x2 s = *(const f32x2*)(st + 2 * (size_t)row); mu = s[0] * (1.0f / DM); rs = 1.0f / sqrtf(s[1] * (1.0f / DM) - mu * mu + LN_EPS); }
;     __device__ __forceinline__ void operator()(EPI_ARGS) const {
;     ...
;                 for (int m = 0; m < 4; ++m) { const int row = row0 + ai * HALF + m * 16; float s = 0.f; float mu, rs; ln_stats(st, row, mu, rs);
; #pragma unroll
;                     for (int bj = 0; bj < 2; ++bj) { const f32x4 a = (acc[ai][bj][m][0] - cc[bj][0] * mu) * rs + dd[bj][0], b = (acc[ai][bj][m][1] - cc[bj][1] * mu) * rs + dd[bj][1];
;                         s += (a[0] * a[0] + a[1] * a[1]) + (a[2] * a[2] + a[3] * a[3]) + (b[0] * b[0] + b[1] * b[1]) + (b[2] * b[2] + b[3] * b[3]);
;                         *(u32x2*)((unsigned char*)dst + (size_t)row * 512 + col0 + bj * HALF) = pack8i8(a * lsc, b * lsc); }
;                     s += __shfl_xor(s, 16); s += __shfl_xor(s, 32);
;                     if (fq == 0) ssq[(size_t)row * 16 + slot] = s; }
.LBB0_3970:
	s_or_b64 exec, exec, s[6:7]
	v_or_b32_e32 v40, 48, v96
	s_waitcnt lgkmcnt(0)
	v_ashrrev_i32_e32 v41, 31, v40
	v_lshl_add_u64 v[42:43], v[40:41], 3, s[12:13]
	global_load_dwordx2 v[42:43], v[42:43], off
	v_cvt_f32_i32_e32 v33, v33
	v_cvt_f32_i32_e32 v32, v32
	v_cvt_f32_i32_e32 v39, v39
	v_cvt_f32_i32_e32 v38, v38
	v_cvt_f32_i32_e32 v37, v37
	v_cvt_f32_i32_e32 v36, v36
	v_cvt_f32_i32_e32 v35, v35
	v_cvt_f32_i32_e32 v34, v34
	v_lshlrev_b64 v[44:45], 9, v[40:41]
	v_lshl_add_u64 v[44:45], v[162:163], 0, v[44:45]
	s_waitcnt vmcnt(0)
	v_pk_mul_f32 v[42:43], v[42:43], s[28:29] op_sel_hi:[1,0]
	s_nop 0
	v_fma_f32 v97, -v42, v42, v43
	v_add_f32_e32 v97, 0x3727c5ac, v97
	v_rsq_f32_e32 v254, v97
	v_pk_fma_f32 v[46:47], v[82:83], v[42:43], v[126:127] op_sel_hi:[1,0,1]
	v_pk_fma_f32 v[48:49], v[80:81], v[42:43], v[152:153] op_sel_hi:[1,0,1] neg_lo:[1,0,0] neg_hi:[1,0,0]
	v_pk_fma_f32 v[50:51], v[74:75], v[42:43], v[122:123] op_sel_hi:[1,0,1]
	v_pk_fma_f32 v[52:53], v[72:73], v[42:43], v[124:125] op_sel_hi:[1,0,1] neg_lo:[1,0,0] neg_hi:[1,0,0]
	v_pk_mul_f32 v[54:55], v[86:87], v[42:43] op_sel_hi:[1,0]
	v_pk_mul_f32 v[122:123], v[84:85], v[42:43] op_sel_hi:[1,0]
	v_pk_mul_f32 v[124:125], v[78:79], v[42:43] op_sel_hi:[1,0]
	v_pk_mul_f32 v[42:43], v[76:77], v[42:43] op_sel_hi:[1,0]
	v_pk_fma_f32 v[38:39], v[38:39], s[26:27], v[54:55] op_sel_hi:[1,0,1] neg_lo:[0,0,1] neg_hi:[0,0,1]
	v_pk_fma_f32 v[32:33], v[32:33], s[26:27], v[42:43] op_sel_hi:[1,0,1] neg_lo:[0,0,1] neg_hi:[0,0,1]
	v_pk_fma_f32 v[36:37], v[36:37], s[26:27], v[122:123] op_sel_hi:[1,0,1] neg_lo:[0,0,1] neg_hi:[0,0,1]
	v_pk_fma_f32 v[34:35], v[34:35], s[26:27], v[124:125] op_sel_hi:[1,0,1] neg_lo:[0,0,1] neg_hi:[0,0,1]
	s_nop 1
	s_nop 1
	v_mov_b32_e32 v42, v254
	v_pk_fma_f32 v[46:47], v[46:47], v[42:43], v[70:71] op_sel_hi:[1,0,1]
	v_pk_fma_f32 v[48:49], v[48:49], v[42:43], v[68:69] op_sel_hi:[1,0,1]
	v_pk_fma_f32 v[50:51], v[50:51], v[42:43], v[66:67] op_sel_hi:[1,0,1]
	v_pk_fma_f32 v[52:53], v[52:53], v[42:43], v[64:65] op_sel_hi:[1,0,1]
	v_pk_fma_f32 v[38:39], v[38:39], v[42:43], v[62:63] op_sel_hi:[1,0,1]
	v_pk_fma_f32 v[36:37], v[36:37], v[42:43], v[60:61] op_sel_hi:[1,0,1]
	v_pk_fma_f32 v[34:35], v[34:35], v[42:43], v[58:59] op_sel_hi:[1,0,1]
	v_pk_fma_f32 v[32:33], v[32:33], v[42:43], v[56:57] op_sel_hi:[1,0,1]
	v_mul_f32_e32 v97, v49, v49
	v_mul_f32_e32 v136, v47, v47
	v_mul_f32_e32 v154, v53, v53
	v_mul_f32_e32 v155, v51, v51
	v_pk_mul_f32 v[42:43], v[46:47], s[30:31] op_sel_hi:[1,0]
	v_pk_mul_f32 v[54:55], v[48:49], s[30:31] op_sel_hi:[1,0]
	v_pk_mul_f32 v[122:123], v[50:51], s[30:31] op_sel_hi:[1,0]
	v_pk_mul_f32 v[124:125], v[52:53], s[30:31] op_sel_hi:[1,0]
	v_mul_f32_e32 v47, v37, v37
	v_mul_f32_e32 v49, v39, v39
	v_mul_f32_e32 v51, v33, v33
	v_pk_mul_f32 v[126:127], v[38:39], s[30:31] op_sel_hi:[1,0]
	v_pk_mul_f32 v[152:153], v[36:37], s[30:31] op_sel_hi:[1,0]
	v_fmac_f32_e32 v97, v48, v48
	v_fmac_f32_e32 v136, v46, v46
	v_fmac_f32_e32 v154, v52, v52
	v_fmac_f32_e32 v155, v50, v50
	v_med3_f32 v37, v54, s70, v189
	v_med3_f32 v39, v55, s70, v189
	v_med3_f32 v42, v42, s70, v189
	v_med3_f32 v43, v43, s70, v189
	v_med3_f32 v46, v124, s70, v189
	v_med3_f32 v48, v125, s70, v189
	v_med3_f32 v50, v122, s70, v189
	v_med3_f32 v52, v123, s70, v189
	v_fmac_f32_e32 v47, v36, v36
	v_fmac_f32_e32 v49, v38, v38
	v_mul_f32_e32 v53, v35, v35
	v_fmac_f32_e32 v51, v32, v32
	v_add_f32_e32 v36, v97, v136
	v_add_f32_e32 v37, 0x4b400000, v37
	v_add_f32_e32 v38, 0x4b400000, v39
	v_add_f32_e32 v39, 0x4b400000, v42
	v_add_f32_e32 v42, 0x4b400000, v43
	v_add_f32_e32 v43, 0x4b400000, v46
	v_add_f32_e32 v46, 0x4b400000, v48
	v_add_f32_e32 v48, 0x4b400000, v50
	v_add_f32_e32 v50, 0x4b400000, v52
	v_add_f32_e32 v47, v47, v49
	v_fmac_f32_e32 v53, v34, v34
	v_add_f32_e32 v36, v154, v36
	v_perm_b32 v37, v38, v37, s71
	v_perm_b32 v38, v42, v39, s72
	v_perm_b32 v39, v46, v43, s71
	v_perm_b32 v42, v50, v48, s72
	v_add_f32_e32 v43, v51, v47
	v_add_f32_e32 v46, v155, v36
	v_or_b32_e32 v36, v37, v38
	v_or_b32_e32 v37, v39, v42
	v_add_f32_e32 v38, v53, v43
	global_store_dwordx2 v[44:45], v[36:37], off
	v_add_f32_e32 v37, v46, v38
	v_med3_f32 v36, v152, s70, v189
	v_med3_f32 v38, v153, s70, v189
	v_med3_f32 v39, v126, s70, v189
	v_med3_f32 v42, v127, s70, v189
	v_pk_mul_f32 v[32:33], v[32:33], s[30:31] op_sel_hi:[1,0]
	v_add_f32_e32 v36, 0x4b400000, v36
	v_add_f32_e32 v38, 0x4b400000, v38
	v_add_f32_e32 v39, 0x4b400000, v39
	v_add_f32_e32 v42, 0x4b400000, v42
	v_perm_b32 v36, v38, v36, s71
	v_perm_b32 v38, v42, v39, s72
	v_med3_f32 v32, v32, s70, v189
	v_or_b32_e32 v36, v36, v38
	v_add_f32_e32 v38, 0x4b400000, v32
	v_med3_f32 v32, v33, s70, v189
	v_add_f32_e32 v39, 0x4b400000, v32
	ds_bpermute_b32 v32, v191, v37
	v_pk_mul_f32 v[34:35], v[34:35], s[30:31] op_sel_hi:[1,0]
	s_waitcnt lgkmcnt(0)
	v_add_f32_e32 v32, v37, v32
	v_med3_f32 v33, v34, s70, v189
	v_add_f32_e32 v34, 0x4b400000, v33
	v_med3_f32 v33, v35, s70, v189
	v_add_f32_e32 v35, 0x4b400000, v33
	ds_bpermute_b32 v33, v190, v32
	v_perm_b32 v37, v39, v38, s71
	v_perm_b32 v34, v35, v34, s72
	v_or_b32_e32 v37, v37, v34
	global_store_dwordx2 v[44:45], v[36:37], off offset:128
	s_and_saveexec_b64 s[6:7], s[2:3]
	s_cbranch_execz .LBB0_3972
	v_lshlrev_b64 v[34:35], 6, v[40:41]
	v_lshl_add_u64 v[34:35], s[10:11], 0, v[34:35]
	v_lshl_add_u64 v[34:35], s[44:45], 2, v[34:35]
	s_waitcnt lgkmcnt(0)
	v_add_f32_e32 v32, v32, v33
	global_store_dword v[34:35], v32, off
; __device__ __forceinline__ u32x2 pack8i8(const f32x4 a, const f32x4 b) { return (u32x2){pack4i8(a), pack4i8(b)}; }
; __device__ __forceinline__ void ln_stats(const float* st, int row, float& mu, float& rs) { const f32x2 s = *(const f32x2*)(st + 2 * (size_t)row); mu = s[0] * (1.0f / DM); rs = 1.0f / sqrtf(s[1] * (1.0f / DM) - mu * mu + LN_EPS); }
;     __device__ __forceinline__ void operator()(EPI_ARGS) const {
;     ...
;                 for (int m = 0; m < 4; ++m) { const int row = row0 + ai * HALF + m * 16; float s = 0.f; float mu, rs; ln_stats(st, row, mu, rs);
; #pragma unroll
;                     for (int bj = 0; bj < 2; ++bj) { const f32x4 a = (acc[ai][bj][m][0] - cc[bj][0] * mu) * rs + dd[bj][0], b = (acc[ai][bj][m][1] - cc[bj][1] * mu) * rs + dd[bj][1];
;                         s += (a[0] * a[0] + a[1] * a[1]) + (a[2] * a[2] + a[3] * a[3]) + (b[0] * b[0] + b[1] * b[1]) + (b[2] * b[2] + b[3] * b[3]);
;                         *(u32x2*)((unsigned char*)dst + (size_t)row * 512 + col0 + bj * HALF) = pack8i8(a * lsc, b * lsc); }
;                     s += __shfl_xor(s, 16); s += __shfl_xor(s, 32);
;                     if (fq == 0) ssq[(size_t)row * 16 + slot] = s; }
.LBB0_3972:
	s_or_b64 exec, exec, s[6:7]
	v_add_u32_e32 v32, 0x80, v96
	s_waitcnt lgkmcnt(0)
	v_ashrrev_i32_e32 v33, 31, v32
	v_lshl_add_u64 v[34:35], v[32:33], 3, s[12:13]
	global_load_dwordx2 v[34:35], v[34:35], off
	v_cvt_f32_i32_e32 v25, v25
	v_cvt_f32_i32_e32 v24, v24
	v_cvt_f32_i32_e32 v31, v31
	v_cvt_f32_i32_e32 v30, v30
	v_cvt_f32_i32_e32 v29, v29
	v_cvt_f32_i32_e32 v28, v28
	v_cvt_f32_i32_e32 v27, v27
	v_cvt_f32_i32_e32 v26, v26
	v_lshlrev_b64 v[36:37], 9, v[32:33]
	v_lshl_add_u64 v[36:37], v[162:163], 0, v[36:37]
	s_waitcnt vmcnt(0)
	v_pk_mul_f32 v[34:35], v[34:35], s[28:29] op_sel_hi:[1,0]
	s_nop 0
	v_fma_f32 v52, -v34, v34, v35
	v_add_f32_e32 v52, 0x3727c5ac, v52
	v_rsq_f32_e32 v254, v52
	v_pk_fma_f32 v[38:39], v[82:83], v[34:35], v[118:119] op_sel_hi:[1,0,1]
	v_pk_fma_f32 v[40:41], v[80:81], v[34:35], v[120:121] op_sel_hi:[1,0,1] neg_lo:[1,0,0] neg_hi:[1,0,0]
	v_pk_fma_f32 v[42:43], v[74:75], v[34:35], v[114:115] op_sel_hi:[1,0,1]
	v_pk_fma_f32 v[44:45], v[72:73], v[34:35], v[116:117] op_sel_hi:[1,0,1] neg_lo:[1,0,0] neg_hi:[1,0,0]
	v_pk_mul_f32 v[46:47], v[86:87], v[34:35] op_sel_hi:[1,0]
	v_pk_mul_f32 v[48:49], v[84:85], v[34:35] op_sel_hi:[1,0]
	v_pk_mul_f32 v[50:51], v[78:79], v[34:35] op_sel_hi:[1,0]
	v_pk_mul_f32 v[34:35], v[76:77], v[34:35] op_sel_hi:[1,0]
	v_pk_fma_f32 v[30:31], v[30:31], s[26:27], v[46:47] op_sel_hi:[1,0,1] neg_lo:[0,0,1] neg_hi:[0,0,1]
	v_pk_fma_f32 v[24:25], v[24:25], s[26:27], v[34:35] op_sel_hi:[1,0,1] neg_lo:[0,0,1] neg_hi:[0,0,1]
	v_pk_fma_f32 v[28:29], v[28:29], s[26:27], v[48:49] op_sel_hi:[1,0,1] neg_lo:[0,0,1] neg_hi:[0,0,1]
	v_pk_fma_f32 v[26:27], v[26:27], s[26:27], v[50:51] op_sel_hi:[1,0,1] neg_lo:[0,0,1] neg_hi:[0,0,1]
	s_nop 1
	s_nop 1
	v_mov_b32_e32 v34, v254
	v_pk_fma_f32 v[38:39], v[38:39], v[34:35], v[70:71] op_sel_hi:[1,0,1]
	v_pk_fma_f32 v[40:41], v[40:41], v[34:35], v[68:69] op_sel_hi:[1,0,1]
	v_pk_fma_f32 v[42:43], v[42:43], v[34:35], v[66:67] op_sel_hi:[1,0,1]
	v_pk_fma_f32 v[44:45], v[44:45], v[34:35], v[64:65] op_sel_hi:[1,0,1]
	v_pk_fma_f32 v[30:31], v[30:31], v[34:35], v[62:63] op_sel_hi:[1,0,1]
	v_pk_fma_f32 v[28:29], v[28:29], v[34:35], v[60:61] op_sel_hi:[1,0,1]
	v_pk_fma_f32 v[26:27], v[26:27], v[34:35], v[58:59] op_sel_hi:[1,0,1]
	v_pk_fma_f32 v[24:25], v[24:25], v[34:35], v[56:57] op_sel_hi:[1,0,1]
	v_mul_f32_e32 v97, v41, v41
	v_mul_f32_e32 v114, v39, v39
	v_mul_f32_e32 v115, v45, v45
	v_mul_f32_e32 v116, v43, v43
	v_pk_mul_f32 v[34:35], v[38:39], s[30:31] op_sel_hi:[1,0]
	v_pk_mul_f32 v[46:47], v[40:41], s[30:31] op_sel_hi:[1,0]
	v_pk_mul_f32 v[48:49], v[42:43], s[30:31] op_sel_hi:[1,0]
	v_pk_mul_f32 v[50:51], v[44:45], s[30:31] op_sel_hi:[1,0]
	v_mul_f32_e32 v39, v29, v29
	v_mul_f32_e32 v41, v31, v31
	v_mul_f32_e32 v43, v25, v25
	v_pk_mul_f32 v[52:53], v[30:31], s[30:31] op_sel_hi:[1,0]
	v_pk_mul_f32 v[54:55], v[28:29], s[30:31] op_sel_hi:[1,0]
	v_fmac_f32_e32 v97, v40, v40
	v_fmac_f32_e32 v114, v38, v38
	v_fmac_f32_e32 v115, v44, v44
	v_fmac_f32_e32 v116, v42, v42
	v_med3_f32 v29, v46, s70, v189
	v_med3_f32 v31, v47, s70, v189
	v_med3_f32 v34, v34, s70, v189
	v_med3_f32 v35, v35, s70, v189
	v_med3_f32 v38, v50, s70, v189
	v_med3_f32 v40, v51, s70, v189
	v_med3_f32 v42, v48, s70, v189
	v_med3_f32 v44, v49, s70, v189
	v_fmac_f32_e32 v39, v28, v28
	v_fmac_f32_e32 v41, v30, v30
	v_mul_f32_e32 v45, v27, v27
	v_fmac_f32_e32 v43, v24, v24
	v_add_f32_e32 v28, v97, v114
	v_add_f32_e32 v29, 0x4b400000, v29
	v_add_f32_e32 v30, 0x4b400000, v31
	v_add_f32_e32 v31, 0x4b400000, v34
	v_add_f32_e32 v34, 0x4b400000, v35
	v_add_f32_e32 v35, 0x4b400000, v38
	v_add_f32_e32 v38, 0x4b400000, v40
	v_add_f32_e32 v40, 0x4b400000, v42
	v_add_f32_e32 v42, 0x4b400000, v44
	v_add_f32_e32 v39, v39, v41
	v_fmac_f32_e32 v45, v26, v26
	v_add_f32_e32 v28, v115, v28
	v_perm_b32 v29, v30, v29, s71
	v_perm_b32 v30, v34, v31, s72
	v_perm_b32 v31, v38, v35, s71
	v_perm_b32 v34, v42, v40, s72
	v_add_f32_e32 v35, v43, v39
	v_add_f32_e32 v38, v116, v28
	v_or_b32_e32 v28, v29, v30
	v_or_b32_e32 v29, v31, v34
	v_add_f32_e32 v30, v45, v35
	global_store_dwordx2 v[36:37], v[28:29], off
	v_add_f32_e32 v29, v38, v30
	v_med3_f32 v28, v54, s70, v189
	v_med3_f32 v30, v55, s70, v189
	v_med3_f32 v31, v52, s70, v189
	v_med3_f32 v34, v53, s70, v189
	v_pk_mul_f32 v[24:25], v[24:25], s[30:31] op_sel_hi:[1,0]
	v_add_f32_e32 v28, 0x4b400000, v28
	v_add_f32_e32 v30, 0x4b400000, v30
	v_add_f32_e32 v31, 0x4b400000, v31
	v_add_f32_e32 v34, 0x4b400000, v34
	v_perm_b32 v28, v30, v28, s71
	v_perm_b32 v30, v34, v31, s72
	v_med3_f32 v24, v24, s70, v189
	v_or_b32_e32 v28, v28, v30
	v_add_f32_e32 v30, 0x4b400000, v24
	v_med3_f32 v24, v25, s70, v189
	v_add_f32_e32 v31, 0x4b400000, v24
	ds_bpermute_b32 v24, v191, v29
	v_pk_mul_f32 v[26:27], v[26:27], s[30:31] op_sel_hi:[1,0]
	s_waitcnt lgkmcnt(0)
	v_add_f32_e32 v24, v29, v24
	v_med3_f32 v25, v26, s70, v189
	v_add_f32_e32 v26, 0x4b400000, v25
	v_med3_f32 v25, v27, s70, v189
	v_add_f32_e32 v27, 0x4b400000, v25
	ds_bpermute_b32 v25, v190, v24
	v_perm_b32 v29, v31, v30, s71
	v_perm_b32 v26, v27, v26, s72
	v_or_b32_e32 v29, v29, v26
	global_store_dwordx2 v[36:37], v[28:29], off offset:128
	s_and_saveexec_b64 s[6:7], s[2:3]
	s_cbranch_execz .LBB0_3974
	v_lshlrev_b64 v[26:27], 6, v[32:33]
	v_lshl_add_u64 v[26:27], s[10:11], 0, v[26:27]
	v_lshl_add_u64 v[26:27], s[44:45], 2, v[26:27]
	s_waitcnt lgkmcnt(0)
	v_add_f32_e32 v24, v24, v25
	global_store_dword v[26:27], v24, off
; __device__ __forceinline__ u32x2 pack8i8(const f32x4 a, const f32x4 b) { return (u32x2){pack4i8(a), pack4i8(b)}; }
; __device__ __forceinline__ void ln_stats(const float* st, int row, float& mu, float& rs) { const f32x2 s = *(const f32x2*)(st + 2 * (size_t)row); mu = s[0] * (1.0f / DM); rs = 1.0f / sqrtf(s[1] * (1.0f / DM) - mu * mu + LN_EPS); }
;     __device__ __forceinline__ void operator()(EPI_ARGS) const {
;     ...
;                 for (int m = 0; m < 4; ++m) { const int row = row0 + ai * HALF + m * 16; float s = 0.f; float mu, rs; ln_stats(st, row, mu, rs);
; #pragma unroll
;                     for (int bj = 0; bj < 2; ++bj) { const f32x4 a = (acc[ai][bj][m][0] - cc[bj][0] * mu) * rs + dd[bj][0], b = (acc[ai][bj][m][1] - cc[bj][1] * mu) * rs + dd[bj][1];
;                         s += (a[0] * a[0] + a[1] * a[1]) + (a[2] * a[2] + a[3] * a[3]) + (b[0] * b[0] + b[1] * b[1]) + (b[2] * b[2] + b[3] * b[3]);
;                         *(u32x2*)((unsigned char*)dst + (size_t)row * 512 + col0 + bj * HALF) = pack8i8(a * lsc, b * lsc); }
;                     s += __shfl_xor(s, 16); s += __shfl_xor(s, 32);
;                     if (fq == 0) ssq[(size_t)row * 16 + slot] = s; }
.LBB0_3974:
	s_or_b64 exec, exec, s[6:7]
	v_add_u32_e32 v24, 0x90, v96
	s_waitcnt lgkmcnt(0)
	v_ashrrev_i32_e32 v25, 31, v24
	v_lshl_add_u64 v[26:27], v[24:25], 3, s[12:13]
	global_load_dwordx2 v[26:27], v[26:27], off
	v_cvt_f32_i32_e32 v17, v17
	v_cvt_f32_i32_e32 v16, v16
	v_cvt_f32_i32_e32 v23, v23
	v_cvt_f32_i32_e32 v22, v22
	v_cvt_f32_i32_e32 v21, v21
	v_cvt_f32_i32_e32 v20, v20
	v_cvt_f32_i32_e32 v19, v19
	v_cvt_f32_i32_e32 v18, v18
	v_lshlrev_b64 v[28:29], 9, v[24:25]
	v_lshl_add_u64 v[28:29], v[162:163], 0, v[28:29]
	s_waitcnt vmcnt(0)
	v_pk_mul_f32 v[26:27], v[26:27], s[28:29] op_sel_hi:[1,0]
	s_nop 0
	v_fma_f32 v44, -v26, v26, v27
	v_add_f32_e32 v44, 0x3727c5ac, v44
	v_rsq_f32_e32 v254, v44
	v_pk_fma_f32 v[30:31], v[82:83], v[26:27], v[110:111] op_sel_hi:[1,0,1]
	v_pk_fma_f32 v[32:33], v[80:81], v[26:27], v[112:113] op_sel_hi:[1,0,1] neg_lo:[1,0,0] neg_hi:[1,0,0]
	v_pk_fma_f32 v[34:35], v[74:75], v[26:27], v[106:107] op_sel_hi:[1,0,1]
	v_pk_fma_f32 v[36:37], v[72:73], v[26:27], v[108:109] op_sel_hi:[1,0,1] neg_lo:[1,0,0] neg_hi:[1,0,0]
	v_pk_mul_f32 v[38:39], v[86:87], v[26:27] op_sel_hi:[1,0]
	v_pk_mul_f32 v[40:41], v[84:85], v[26:27] op_sel_hi:[1,0]
	v_pk_mul_f32 v[42:43], v[78:79], v[26:27] op_sel_hi:[1,0]
	v_pk_mul_f32 v[26:27], v[76:77], v[26:27] op_sel_hi:[1,0]
	v_pk_fma_f32 v[22:23], v[22:23], s[26:27], v[38:39] op_sel_hi:[1,0,1] neg_lo:[0,0,1] neg_hi:[0,0,1]
	v_pk_fma_f32 v[16:17], v[16:17], s[26:27], v[26:27] op_sel_hi:[1,0,1] neg_lo:[0,0,1] neg_hi:[0,0,1]
	v_pk_fma_f32 v[20:21], v[20:21], s[26:27], v[40:41] op_sel_hi:[1,0,1] neg_lo:[0,0,1] neg_hi:[0,0,1]
	v_pk_fma_f32 v[18:19], v[18:19], s[26:27], v[42:43] op_sel_hi:[1,0,1] neg_lo:[0,0,1] neg_hi:[0,0,1]
	s_nop 1
	s_nop 1
	v_mov_b32_e32 v26, v254
	v_pk_fma_f32 v[30:31], v[30:31], v[26:27], v[70:71] op_sel_hi:[1,0,1]
	v_pk_fma_f32 v[32:33], v[32:33], v[26:27], v[68:69] op_sel_hi:[1,0,1]
	v_pk_fma_f32 v[34:35], v[34:35], v[26:27], v[66:67] op_sel_hi:[1,0,1]
	v_pk_fma_f32 v[36:37], v[36:37], v[26:27], v[64:65] op_sel_hi:[1,0,1]
	v_pk_fma_f32 v[22:23], v[22:23], v[26:27], v[62:63] op_sel_hi:[1,0,1]
	v_pk_fma_f32 v[20:21], v[20:21], v[26:27], v[60:61] op_sel_hi:[1,0,1]
	v_pk_fma_f32 v[18:19], v[18:19], v[26:27], v[58:59] op_sel_hi:[1,0,1]
	v_pk_fma_f32 v[16:17], v[16:17], v[26:27], v[56:57] op_sel_hi:[1,0,1]
	v_mul_f32_e32 v48, v33, v33
	v_mul_f32_e32 v49, v31, v31
	v_mul_f32_e32 v50, v37, v37
	v_mul_f32_e32 v51, v35, v35
	v_pk_mul_f32 v[26:27], v[30:31], s[30:31] op_sel_hi:[1,0]
	v_pk_mul_f32 v[38:39], v[32:33], s[30:31] op_sel_hi:[1,0]
	v_pk_mul_f32 v[40:41], v[34:35], s[30:31] op_sel_hi:[1,0]
	v_pk_mul_f32 v[42:43], v[36:37], s[30:31] op_sel_hi:[1,0]
	v_mul_f32_e32 v31, v21, v21
	v_mul_f32_e32 v33, v23, v23
	v_mul_f32_e32 v35, v17, v17
	v_pk_mul_f32 v[44:45], v[22:23], s[30:31] op_sel_hi:[1,0]
	v_pk_mul_f32 v[46:47], v[20:21], s[30:31] op_sel_hi:[1,0]
	v_fmac_f32_e32 v48, v32, v32
	v_fmac_f32_e32 v49, v30, v30
	v_fmac_f32_e32 v50, v36, v36
	v_fmac_f32_e32 v51, v34, v34
	v_med3_f32 v21, v38, s70, v189
	v_med3_f32 v23, v39, s70, v189
	v_med3_f32 v26, v26, s70, v189
	v_med3_f32 v27, v27, s70, v189
	v_med3_f32 v30, v42, s70, v189
	v_med3_f32 v32, v43, s70, v189
	v_med3_f32 v34, v40, s70, v189
	v_med3_f32 v36, v41, s70, v189
	v_fmac_f32_e32 v31, v20, v20
	v_fmac_f32_e32 v33, v22, v22
	v_mul_f32_e32 v37, v19, v19
	v_fmac_f32_e32 v35, v16, v16
	v_add_f32_e32 v20, v48, v49
	v_add_f32_e32 v21, 0x4b400000, v21
	v_add_f32_e32 v22, 0x4b400000, v23
	v_add_f32_e32 v23, 0x4b400000, v26
	v_add_f32_e32 v26, 0x4b400000, v27
	v_add_f32_e32 v27, 0x4b400000, v30
	v_add_f32_e32 v30, 0x4b400000, v32
	v_add_f32_e32 v32, 0x4b400000, v34
	v_add_f32_e32 v34, 0x4b400000, v36
	v_add_f32_e32 v31, v31, v33
	v_fmac_f32_e32 v37, v18, v18
	v_add_f32_e32 v20, v50, v20
	v_perm_b32 v21, v22, v21, s71
	v_perm_b32 v22, v26, v23, s72
	v_perm_b32 v23, v30, v27, s71
	v_perm_b32 v26, v34, v32, s72
	v_add_f32_e32 v27, v35, v31
	v_add_f32_e32 v30, v51, v20
	v_or_b32_e32 v20, v21, v22
	v_or_b32_e32 v21, v23, v26
	v_add_f32_e32 v22, v37, v27
	global_store_dwordx2 v[28:29], v[20:21], off
	v_add_f32_e32 v21, v30, v22
	v_med3_f32 v20, v46, s70, v189
	v_med3_f32 v22, v47, s70, v189
	v_med3_f32 v23, v44, s70, v189
	v_med3_f32 v26, v45, s70, v189
	v_pk_mul_f32 v[16:17], v[16:17], s[30:31] op_sel_hi:[1,0]
	v_add_f32_e32 v20, 0x4b400000, v20
	v_add_f32_e32 v22, 0x4b400000, v22
	v_add_f32_e32 v23, 0x4b400000, v23
	v_add_f32_e32 v26, 0x4b400000, v26
	v_perm_b32 v20, v22, v20, s71
	v_perm_b32 v22, v26, v23, s72
	v_med3_f32 v16, v16, s70, v189
	v_or_b32_e32 v20, v20, v22
	v_add_f32_e32 v22, 0x4b400000, v16
	v_med3_f32 v16, v17, s70, v189
	v_add_f32_e32 v23, 0x4b400000, v16
	ds_bpermute_b32 v16, v191, v21
	v_pk_mul_f32 v[18:19], v[18:19], s[30:31] op_sel_hi:[1,0]
	s_waitcnt lgkmcnt(0)
	v_add_f32_e32 v16, v21, v16
	v_med3_f32 v17, v18, s70, v189
	v_add_f32_e32 v18, 0x4b400000, v17
	v_med3_f32 v17, v19, s70, v189
	v_add_f32_e32 v19, 0x4b400000, v17
	ds_bpermute_b32 v17, v190, v16
	v_perm_b32 v21, v23, v22, s71
	v_perm_b32 v18, v19, v18, s72
	v_or_b32_e32 v21, v21, v18
	global_store_dwordx2 v[28:29], v[20:21], off offset:128
	s_and_saveexec_b64 s[6:7], s[2:3]
	s_cbranch_execz .LBB0_3976
	v_lshlrev_b64 v[18:19], 6, v[24:25]
	v_lshl_add_u64 v[18:19], s[10:11], 0, v[18:19]
	v_lshl_add_u64 v[18:19], s[44:45], 2, v[18:19]
	s_waitcnt lgkmcnt(0)
	v_add_f32_e32 v16, v16, v17
	global_store_dword v[18:19], v16, off
; __device__ __forceinline__ u32x2 pack8i8(const f32x4 a, const f32x4 b) { return (u32x2){pack4i8(a), pack4i8(b)}; }
; __device__ __forceinline__ void ln_stats(const float* st, int row, float& mu, float& rs) { const f32x2 s = *(const f32x2*)(st + 2 * (size_t)row); mu = s[0] * (1.0f / DM); rs = 1.0f / sqrtf(s[1] * (1.0f / DM) - mu * mu + LN_EPS); }
;     __device__ __forceinline__ void operator()(EPI_ARGS) const {
;     ...
;                 for (int m = 0; m < 4; ++m) { const int row = row0 + ai * HALF + m * 16; float s = 0.f; float mu, rs; ln_stats(st, row, mu, rs);
; #pragma unroll
;                     for (int bj = 0; bj < 2; ++bj) { const f32x4 a = (acc[ai][bj][m][0] - cc[bj][0] * mu) * rs + dd[bj][0], b = (acc[ai][bj][m][1] - cc[bj][1] * mu) * rs + dd[bj][1];
;                         s += (a[0] * a[0] + a[1] * a[1]) + (a[2] * a[2] + a[3] * a[3]) + (b[0] * b[0] + b[1] * b[1]) + (b[2] * b[2] + b[3] * b[3]);
;                         *(u32x2*)((unsigned char*)dst + (size_t)row * 512 + col0 + bj * HALF) = pack8i8(a * lsc, b * lsc); }
;                     s += __shfl_xor(s, 16); s += __shfl_xor(s, 32);
;                     if (fq == 0) ssq[(size_t)row * 16 + slot] = s; }
.LBB0_3976:
	s_or_b64 exec, exec, s[6:7]
	v_add_u32_e32 v16, 0xa0, v96
	s_waitcnt lgkmcnt(0)
	v_ashrrev_i32_e32 v17, 31, v16
	v_lshl_add_u64 v[18:19], v[16:17], 3, s[12:13]
	global_load_dwordx2 v[18:19], v[18:19], off
	v_cvt_f32_i32_e32 v9, v9
	v_cvt_f32_i32_e32 v8, v8
	v_cvt_f32_i32_e32 v15, v15
	v_cvt_f32_i32_e32 v14, v14
	v_cvt_f32_i32_e32 v13, v13
	v_cvt_f32_i32_e32 v12, v12
	v_cvt_f32_i32_e32 v11, v11
	v_cvt_f32_i32_e32 v10, v10
	v_lshlrev_b64 v[20:21], 9, v[16:17]
	v_lshl_add_u64 v[20:21], v[162:163], 0, v[20:21]
	s_waitcnt vmcnt(0)
	v_pk_mul_f32 v[18:19], v[18:19], s[28:29] op_sel_hi:[1,0]
	s_nop 0
	v_fma_f32 v36, -v18, v18, v19
	v_add_f32_e32 v36, 0x3727c5ac, v36
	v_rsq_f32_e32 v254, v36
	v_pk_fma_f32 v[22:23], v[82:83], v[18:19], v[102:103] op_sel_hi:[1,0,1]
	v_pk_fma_f32 v[24:25], v[80:81], v[18:19], v[104:105] op_sel_hi:[1,0,1] neg_lo:[1,0,0] neg_hi:[1,0,0]
	v_pk_fma_f32 v[26:27], v[74:75], v[18:19], v[98:99] op_sel_hi:[1,0,1]
	v_pk_fma_f32 v[28:29], v[72:73], v[18:19], v[100:101] op_sel_hi:[1,0,1] neg_lo:[1,0,0] neg_hi:[1,0,0]
	v_pk_mul_f32 v[30:31], v[86:87], v[18:19] op_sel_hi:[1,0]
	v_pk_mul_f32 v[32:33], v[84:85], v[18:19] op_sel_hi:[1,0]
	v_pk_mul_f32 v[34:35], v[78:79], v[18:19] op_sel_hi:[1,0]
	v_pk_mul_f32 v[18:19], v[76:77], v[18:19] op_sel_hi:[1,0]
	v_pk_fma_f32 v[14:15], v[14:15], s[26:27], v[30:31] op_sel_hi:[1,0,1] neg_lo:[0,0,1] neg_hi:[0,0,1]
	v_pk_fma_f32 v[8:9], v[8:9], s[26:27], v[18:19] op_sel_hi:[1,0,1] neg_lo:[0,0,1] neg_hi:[0,0,1]
	v_pk_fma_f32 v[12:13], v[12:13], s[26:27], v[32:33] op_sel_hi:[1,0,1] neg_lo:[0,0,1] neg_hi:[0,0,1]
	v_pk_fma_f32 v[10:11], v[10:11], s[26:27], v[34:35] op_sel_hi:[1,0,1] neg_lo:[0,0,1] neg_hi:[0,0,1]
	s_nop 1
	s_nop 1
	v_mov_b32_e32 v18, v254
	v_pk_fma_f32 v[22:23], v[22:23], v[18:19], v[70:71] op_sel_hi:[1,0,1]
	v_pk_fma_f32 v[24:25], v[24:25], v[18:19], v[68:69] op_sel_hi:[1,0,1]
	v_pk_fma_f32 v[26:27], v[26:27], v[18:19], v[66:67] op_sel_hi:[1,0,1]
	v_pk_fma_f32 v[28:29], v[28:29], v[18:19], v[64:65] op_sel_hi:[1,0,1]
	v_pk_fma_f32 v[14:15], v[14:15], v[18:19], v[62:63] op_sel_hi:[1,0,1]
	v_pk_fma_f32 v[12:13], v[12:13], v[18:19], v[60:61] op_sel_hi:[1,0,1]
	v_pk_fma_f32 v[10:11], v[10:11], v[18:19], v[58:59] op_sel_hi:[1,0,1]
	v_pk_fma_f32 v[8:9], v[8:9], v[18:19], v[56:57] op_sel_hi:[1,0,1]
	v_mul_f32_e32 v40, v25, v25
	v_mul_f32_e32 v41, v23, v23
	v_mul_f32_e32 v42, v29, v29
	v_mul_f32_e32 v43, v27, v27
	v_pk_mul_f32 v[18:19], v[22:23], s[30:31] op_sel_hi:[1,0]
	v_pk_mul_f32 v[30:31], v[24:25], s[30:31] op_sel_hi:[1,0]
	v_pk_mul_f32 v[32:33], v[26:27], s[30:31] op_sel_hi:[1,0]
	v_pk_mul_f32 v[34:35], v[28:29], s[30:31] op_sel_hi:[1,0]
	v_mul_f32_e32 v23, v13, v13
	v_mul_f32_e32 v25, v15, v15
	v_mul_f32_e32 v27, v9, v9
	v_pk_mul_f32 v[36:37], v[14:15], s[30:31] op_sel_hi:[1,0]
	v_pk_mul_f32 v[38:39], v[12:13], s[30:31] op_sel_hi:[1,0]
	v_fmac_f32_e32 v40, v24, v24
	v_fmac_f32_e32 v41, v22, v22
	v_fmac_f32_e32 v42, v28, v28
	v_fmac_f32_e32 v43, v26, v26
	v_med3_f32 v13, v30, s70, v189
	v_med3_f32 v15, v31, s70, v189
	v_med3_f32 v18, v18, s70, v189
	v_med3_f32 v19, v19, s70, v189
	v_med3_f32 v22, v34, s70, v189
	v_med3_f32 v24, v35, s70, v189
	v_med3_f32 v26, v32, s70, v189
	v_med3_f32 v28, v33, s70, v189
	v_fmac_f32_e32 v23, v12, v12
	v_fmac_f32_e32 v25, v14, v14
	v_mul_f32_e32 v29, v11, v11
	v_fmac_f32_e32 v27, v8, v8
	v_add_f32_e32 v12, v40, v41
	v_add_f32_e32 v13, 0x4b400000, v13
	v_add_f32_e32 v14, 0x4b400000, v15
	v_add_f32_e32 v15, 0x4b400000, v18
	v_add_f32_e32 v18, 0x4b400000, v19
	v_add_f32_e32 v19, 0x4b400000, v22
	v_add_f32_e32 v22, 0x4b400000, v24
	v_add_f32_e32 v24, 0x4b400000, v26
	v_add_f32_e32 v26, 0x4b400000, v28
	v_add_f32_e32 v23, v23, v25
	v_fmac_f32_e32 v29, v10, v10
	v_add_f32_e32 v12, v42, v12
	v_perm_b32 v13, v14, v13, s71
	v_perm_b32 v14, v18, v15, s72
	v_perm_b32 v15, v22, v19, s71
	v_perm_b32 v18, v26, v24, s72
	v_add_f32_e32 v19, v27, v23
	v_add_f32_e32 v22, v43, v12
	v_or_b32_e32 v12, v13, v14
	v_or_b32_e32 v13, v15, v18
	v_add_f32_e32 v14, v29, v19
	global_store_dwordx2 v[20:21], v[12:13], off
	v_add_f32_e32 v13, v22, v14
	v_med3_f32 v12, v38, s70, v189
	v_med3_f32 v14, v39, s70, v189
	v_med3_f32 v15, v36, s70, v189
	v_med3_f32 v18, v37, s70, v189
	v_pk_mul_f32 v[8:9], v[8:9], s[30:31] op_sel_hi:[1,0]
	v_add_f32_e32 v12, 0x4b400000, v12
	v_add_f32_e32 v14, 0x4b400000, v14
	v_add_f32_e32 v15, 0x4b400000, v15
	v_add_f32_e32 v18, 0x4b400000, v18
	v_perm_b32 v12, v14, v12, s71
	v_perm_b32 v14, v18, v15, s72
	v_med3_f32 v8, v8, s70, v189
	v_or_b32_e32 v12, v12, v14
	v_add_f32_e32 v14, 0x4b400000, v8
	v_med3_f32 v8, v9, s70, v189
	v_add_f32_e32 v15, 0x4b400000, v8
	ds_bpermute_b32 v8, v191, v13
	v_pk_mul_f32 v[10:11], v[10:11], s[30:31] op_sel_hi:[1,0]
	s_waitcnt lgkmcnt(0)
	v_add_f32_e32 v8, v13, v8
	v_med3_f32 v9, v10, s70, v189
	v_add_f32_e32 v10, 0x4b400000, v9
	v_med3_f32 v9, v11, s70, v189
	v_add_f32_e32 v11, 0x4b400000, v9
	ds_bpermute_b32 v9, v190, v8
	v_perm_b32 v13, v15, v14, s71
	v_perm_b32 v10, v11, v10, s72
	v_or_b32_e32 v13, v13, v10
	global_store_dwordx2 v[20:21], v[12:13], off offset:128
	s_and_saveexec_b64 s[6:7], s[2:3]
	s_cbranch_execz .LBB0_3978
	v_lshlrev_b64 v[10:11], 6, v[16:17]
	v_lshl_add_u64 v[10:11], s[10:11], 0, v[10:11]
	v_lshl_add_u64 v[10:11], s[44:45], 2, v[10:11]
	s_waitcnt lgkmcnt(0)
	v_add_f32_e32 v8, v8, v9
	global_store_dword v[10:11], v8, off
; __device__ __forceinline__ u32x2 pack8i8(const f32x4 a, const f32x4 b) { return (u32x2){pack4i8(a), pack4i8(b)}; }
; __device__ __forceinline__ void ln_stats(const float* st, int row, float& mu, float& rs) { const f32x2 s = *(const f32x2*)(st + 2 * (size_t)row); mu = s[0] * (1.0f / DM); rs = 1.0f / sqrtf(s[1] * (1.0f / DM) - mu * mu + LN_EPS); }
;     __device__ __forceinline__ void operator()(EPI_ARGS) const {
;     ...
;                 for (int m = 0; m < 4; ++m) { const int row = row0 + ai * HALF + m * 16; float s = 0.f; float mu, rs; ln_stats(st, row, mu, rs);
; #pragma unroll
;                     for (int bj = 0; bj < 2; ++bj) { const f32x4 a = (acc[ai][bj][m][0] - cc[bj][0] * mu) * rs + dd[bj][0], b = (acc[ai][bj][m][1] - cc[bj][1] * mu) * rs + dd[bj][1];
;                         s += (a[0] * a[0] + a[1] * a[1]) + (a[2] * a[2] + a[3] * a[3]) + (b[0] * b[0] + b[1] * b[1]) + (b[2] * b[2] + b[3] * b[3]);
;                         *(u32x2*)((unsigned char*)dst + (size_t)row * 512 + col0 + bj * HALF) = pack8i8(a * lsc, b * lsc); }
;                     s += __shfl_xor(s, 16); s += __shfl_xor(s, 32);
;                     if (fq == 0) ssq[(size_t)row * 16 + slot] = s; }
.LBB0_3978:
	s_or_b64 exec, exec, s[6:7]
	v_add_u32_e32 v8, 0xb0, v96
	s_waitcnt lgkmcnt(0)
	v_ashrrev_i32_e32 v9, 31, v8
	v_lshl_add_u64 v[10:11], v[8:9], 3, s[12:13]
	global_load_dwordx2 v[10:11], v[10:11], off
	v_cvt_f32_i32_e32 v1, v1
	v_cvt_f32_i32_e32 v0, v0
	v_cvt_f32_i32_e32 v7, v7
	v_cvt_f32_i32_e32 v6, v6
	v_cvt_f32_i32_e32 v5, v5
	v_cvt_f32_i32_e32 v4, v4
	v_cvt_f32_i32_e32 v3, v3
	v_cvt_f32_i32_e32 v2, v2
	v_lshlrev_b64 v[12:13], 9, v[8:9]
	v_lshl_add_u64 v[12:13], v[162:163], 0, v[12:13]
	s_waitcnt vmcnt(0)
	v_pk_mul_f32 v[10:11], v[10:11], s[28:29] op_sel_hi:[1,0]
	s_nop 0
	v_fma_f32 v28, -v10, v10, v11
	v_add_f32_e32 v28, 0x3727c5ac, v28
	v_rsq_f32_e32 v254, v28
	v_pk_fma_f32 v[14:15], v[82:83], v[10:11], v[92:93] op_sel_hi:[1,0,1]
	v_pk_fma_f32 v[16:17], v[80:81], v[10:11], v[94:95] op_sel_hi:[1,0,1] neg_lo:[1,0,0] neg_hi:[1,0,0]
	v_pk_fma_f32 v[18:19], v[74:75], v[10:11], v[88:89] op_sel_hi:[1,0,1]
	v_pk_fma_f32 v[20:21], v[72:73], v[10:11], v[90:91] op_sel_hi:[1,0,1] neg_lo:[1,0,0] neg_hi:[1,0,0]
	v_pk_mul_f32 v[22:23], v[86:87], v[10:11] op_sel_hi:[1,0]
	v_pk_mul_f32 v[24:25], v[84:85], v[10:11] op_sel_hi:[1,0]
	v_pk_mul_f32 v[26:27], v[78:79], v[10:11] op_sel_hi:[1,0]
	v_pk_mul_f32 v[10:11], v[76:77], v[10:11] op_sel_hi:[1,0]
	v_pk_fma_f32 v[6:7], v[6:7], s[26:27], v[22:23] op_sel_hi:[1,0,1] neg_lo:[0,0,1] neg_hi:[0,0,1]
	v_pk_fma_f32 v[0:1], v[0:1], s[26:27], v[10:11] op_sel_hi:[1,0,1] neg_lo:[0,0,1] neg_hi:[0,0,1]
	v_pk_fma_f32 v[4:5], v[4:5], s[26:27], v[24:25] op_sel_hi:[1,0,1] neg_lo:[0,0,1] neg_hi:[0,0,1]
	v_pk_fma_f32 v[2:3], v[2:3], s[26:27], v[26:27] op_sel_hi:[1,0,1] neg_lo:[0,0,1] neg_hi:[0,0,1]
	s_nop 1
	s_nop 1
	v_mov_b32_e32 v10, v254
	v_pk_fma_f32 v[14:15], v[14:15], v[10:11], v[70:71] op_sel_hi:[1,0,1]
	v_pk_fma_f32 v[16:17], v[16:17], v[10:11], v[68:69] op_sel_hi:[1,0,1]
	v_pk_fma_f32 v[18:19], v[18:19], v[10:11], v[66:67] op_sel_hi:[1,0,1]
	v_pk_fma_f32 v[20:21], v[20:21], v[10:11], v[64:65] op_sel_hi:[1,0,1]
	v_pk_fma_f32 v[6:7], v[6:7], v[10:11], v[62:63] op_sel_hi:[1,0,1]
	v_pk_fma_f32 v[4:5], v[4:5], v[10:11], v[60:61] op_sel_hi:[1,0,1]
	v_pk_fma_f32 v[2:3], v[2:3], v[10:11], v[58:59] op_sel_hi:[1,0,1]
	v_pk_fma_f32 v[0:1], v[0:1], v[10:11], v[56:57] op_sel_hi:[1,0,1]
	v_mul_f32_e32 v32, v17, v17
	v_mul_f32_e32 v33, v15, v15
	v_mul_f32_e32 v34, v21, v21
	v_mul_f32_e32 v35, v19, v19
	v_pk_mul_f32 v[10:11], v[14:15], s[30:31] op_sel_hi:[1,0]
	v_pk_mul_f32 v[22:23], v[16:17], s[30:31] op_sel_hi:[1,0]
	v_pk_mul_f32 v[24:25], v[18:19], s[30:31] op_sel_hi:[1,0]
	v_pk_mul_f32 v[26:27], v[20:21], s[30:31] op_sel_hi:[1,0]
	v_mul_f32_e32 v15, v5, v5
	v_mul_f32_e32 v17, v7, v7
	v_mul_f32_e32 v19, v1, v1
	v_pk_mul_f32 v[28:29], v[6:7], s[30:31] op_sel_hi:[1,0]
	v_pk_mul_f32 v[30:31], v[4:5], s[30:31] op_sel_hi:[1,0]
	v_fmac_f32_e32 v32, v16, v16
	v_fmac_f32_e32 v33, v14, v14
	v_fmac_f32_e32 v34, v20, v20
	v_fmac_f32_e32 v35, v18, v18
	v_med3_f32 v5, v22, s70, v189
	v_med3_f32 v7, v23, s70, v189
	v_med3_f32 v10, v10, s70, v189
	v_med3_f32 v11, v11, s70, v189
	v_med3_f32 v14, v26, s70, v189
	v_med3_f32 v16, v27, s70, v189
	v_med3_f32 v18, v24, s70, v189
	v_med3_f32 v20, v25, s70, v189
	v_fmac_f32_e32 v15, v4, v4
	v_fmac_f32_e32 v17, v6, v6
	v_mul_f32_e32 v21, v3, v3
	v_fmac_f32_e32 v19, v0, v0
	v_add_f32_e32 v4, v32, v33
	v_add_f32_e32 v5, 0x4b400000, v5
	v_add_f32_e32 v6, 0x4b400000, v7
	v_add_f32_e32 v7, 0x4b400000, v10
	v_add_f32_e32 v10, 0x4b400000, v11
	v_add_f32_e32 v11, 0x4b400000, v14
	v_add_f32_e32 v14, 0x4b400000, v16
	v_add_f32_e32 v16, 0x4b400000, v18
	v_add_f32_e32 v18, 0x4b400000, v20
	v_add_f32_e32 v15, v15, v17
	v_fmac_f32_e32 v21, v2, v2
	v_add_f32_e32 v4, v34, v4
	v_perm_b32 v5, v6, v5, s71
	v_perm_b32 v6, v10, v7, s72
	v_perm_b32 v7, v14, v11, s71
	v_perm_b32 v10, v18, v16, s72
	v_add_f32_e32 v11, v19, v15
	v_add_f32_e32 v14, v35, v4
	v_or_b32_e32 v4, v5, v6
	v_or_b32_e32 v5, v7, v10
	v_add_f32_e32 v6, v21, v11
	global_store_dwordx2 v[12:13], v[4:5], off
	v_add_f32_e32 v5, v14, v6
	v_med3_f32 v4, v30, s70, v189
	v_med3_f32 v6, v31, s70, v189
	v_med3_f32 v7, v28, s70, v189
	v_med3_f32 v10, v29, s70, v189
	v_pk_mul_f32 v[0:1], v[0:1], s[30:31] op_sel_hi:[1,0]
	v_add_f32_e32 v4, 0x4b400000, v4
	v_add_f32_e32 v6, 0x4b400000, v6
	v_add_f32_e32 v7, 0x4b400000, v7
	v_add_f32_e32 v10, 0x4b400000, v10
	v_perm_b32 v4, v6, v4, s71
	v_perm_b32 v6, v10, v7, s72
	v_med3_f32 v0, v0, s70, v189
	v_or_b32_e32 v4, v4, v6
	v_add_f32_e32 v6, 0x4b400000, v0
	v_med3_f32 v0, v1, s70, v189
	v_add_f32_e32 v7, 0x4b400000, v0
	ds_bpermute_b32 v0, v191, v5
	v_pk_mul_f32 v[2:3], v[2:3], s[30:31] op_sel_hi:[1,0]
	s_waitcnt lgkmcnt(0)
	v_add_f32_e32 v0, v5, v0
	v_med3_f32 v1, v2, s70, v189
	v_add_f32_e32 v2, 0x4b400000, v1
	v_med3_f32 v1, v3, s70, v189
	v_add_f32_e32 v3, 0x4b400000, v1
	ds_bpermute_b32 v1, v190, v0
	v_perm_b32 v5, v7, v6, s71
	v_perm_b32 v2, v3, v2, s72
	v_or_b32_e32 v5, v5, v2
	global_store_dwordx2 v[12:13], v[4:5], off offset:128
	s_and_saveexec_b64 s[6:7], s[2:3]
	s_cbranch_execz .LBB0_3980
	v_lshlrev_b64 v[2:3], 6, v[8:9]
	v_lshl_add_u64 v[2:3], s[10:11], 0, v[2:3]
	v_lshl_add_u64 v[2:3], s[44:45], 2, v[2:3]
	s_waitcnt lgkmcnt(0)
	v_add_f32_e32 v0, v0, v1
	global_store_dword v[2:3], v0, off

; __device__ __forceinline__ u32x4 pack8bf(const f32x4 a, const f32x4 b) { u32x4 w; w.x = cvt_pk_bf16(a[0], a[1]); w.y = cvt_pk_bf16(a[2], a[3]); w.z = cvt_pk_bf16(b[0], b[1]); w.w = cvt_pk_bf16(b[2], b[3]); return w; }
; __device__ __forceinline__ float rms_scale(const float* ssq, int row, int which) {
;     const f32x4 a = *(const f32x4*)(ssq + (size_t)row * 16 + which * 8), b = *(const f32x4*)(ssq + (size_t)row * 16 + which * 8 + 4);
;     const float s = ((a[0] + a[1]) + (a[2] + a[3])) + ((b[0] + b[1]) + (b[2] + b[3]));
;     return 1.0f / sqrtf(s * (1.0f / 512.0f) + RMS_EPS);
;     __device__ __forceinline__ void operator()(EPI_ARGS) const {
;     ...
;             for (int m = 0; m < 4; ++m) { const int row = row0 + ai * HALF + m * 16; const float rs = rms_scale(ssq, row, 0);
;                 if (u.pn < 8) {
; #pragma unroll
;                     for (int bj = 0; bj < 2; ++bj) { const int h = 2 * u.pn + bj;
;                         *(u32x4*)(Q + ((size_t)h * NTOK + row) * 192 + 32 * wc + 8 * fq) = pack8bf(acc[ai][bj][m][0] * rs, acc[ai][bj][m][1] * rs); }
;                 } else { const int fi = 16 * (wc & 1) + 4 * fq;
;                     const f32x4 c4 = *(const f32x4*)(cs + (size_t)row * 32 + fi), s4 = *(const f32x4*)(sn + (size_t)row * 32 + fi);
; #pragma unroll
;                     for (int bj = 0; bj < 2; ++bj) { const int h = 4 * (u.pn - 8) + 2 * bj + (wc >> 1); const f32x4 v0 = acc[ai][bj][m][0] * rs, v1 = acc[ai][bj][m][1] * rs;
;                         *(u32x4*)(Q + ((size_t)h * NTOK + row) * 192 + 128 + 32 * (wc & 1) + 8 * fq) = pack8bf(v0 * c4 - v1 * s4, v1 * c4 + v0 * s4); } }
;             }
.LBB0_4057:
	v_lshl_add_u32 v152, s4, 8, v139
	v_ashrrev_i32_e32 v153, 31, v152
	v_lshlrev_b64 v[154:155], 6, v[152:153]
	v_lshl_add_u64 v[154:155], s[10:11], 0, v[154:155]
	global_load_dwordx4 v[198:201], v[154:155], off offset:1024
	global_load_dwordx4 v[202:205], v[154:155], off offset:1040
	global_load_dwordx4 v[206:209], v[154:155], off offset:2048
	global_load_dwordx4 v[210:213], v[154:155], off offset:2064
	global_load_dwordx4 v[214:217], v[154:155], off offset:3072
	global_load_dwordx4 v[218:221], v[154:155], off offset:3088
	v_mov_b32_e32 v252, 0x2000
	v_mov_b32_e32 v253, 0
	v_lshl_add_u64 v[252:253], v[154:155], 0, v[252:253]
	global_load_dwordx4 v[222:225], v[252:253], off offset:0
	global_load_dwordx4 v[226:229], v[252:253], off offset:16
	global_load_dwordx4 v[230:233], v[252:253], off offset:1024
	global_load_dwordx4 v[234:237], v[252:253], off offset:1040
	global_load_dwordx4 v[238:241], v[252:253], off offset:2048
	global_load_dwordx4 v[242:245], v[252:253], off offset:2064
	global_load_dwordx4 v[246:249], v[252:253], off offset:3072
	global_load_dwordx4 v[250:253], v[252:253], off offset:3088
	global_load_dwordx4 v[164:167], v[154:155], off
	global_load_dwordx4 v[168:171], v[154:155], off offset:16
	v_cvt_f32_i32_e32 v125, v125
	v_cvt_f32_i32_e32 v124, v124
	v_cvt_f32_i32_e32 v127, v127
	v_cvt_f32_i32_e32 v126, v126
	v_cvt_f32_i32_e32 v121, v121
	v_cvt_f32_i32_e32 v120, v120
	v_cvt_f32_i32_e32 v123, v123
	v_cvt_f32_i32_e32 v122, v122
	v_pk_mul_f32 v[154:155], v[126:127], s[26:27] op_sel_hi:[1,0]
	v_pk_mul_f32 v[156:157], v[124:125], s[26:27] op_sel_hi:[1,0]
	v_pk_mul_f32 v[126:127], v[120:121], s[26:27] op_sel_hi:[1,0]
	v_pk_mul_f32 v[124:125], v[122:123], s[26:27] op_sel_hi:[1,0]
	v_cvt_f32_i32_e32 v117, v117
	v_cvt_f32_i32_e32 v116, v116
	v_cvt_f32_i32_e32 v119, v119
	v_cvt_f32_i32_e32 v118, v118
	v_cvt_f32_i32_e32 v173, v113
	v_cvt_f32_i32_e32 v172, v112
	v_cvt_f32_i32_e32 v175, v115
	v_cvt_f32_i32_e32 v174, v114
	s_cmp_gt_i32 s42, 7
	s_cselect_b64 s[44:45], -1, 0
	s_lshl_b32 s4, s42, 2
	s_add_i32 s40, s4, s74
	s_and_b64 s[4:5], exec, s[44:45]
	v_pk_mul_f32 v[118:119], v[118:119], s[26:27] op_sel_hi:[1,0]
	s_waitcnt vmcnt(0)
	v_add_f32_e32 v120, v164, v165
	v_add_f32_e32 v121, v166, v167
	v_add_f32_e32 v122, v168, v169
	v_add_f32_e32 v123, v170, v171
	v_add_f32_e32 v120, v120, v121
	v_add_f32_e32 v121, v122, v123
	v_add_f32_e32 v120, v120, v121
	v_fmamk_f32 v120, v120, 0x3b000000, v162
	v_rsq_f32_e32 v254, v120
	s_nop 1
	v_pk_mul_f32 v[120:121], v[116:117], s[26:27] op_sel_hi:[1,0]
	v_pk_mul_f32 v[116:117], v[174:175], s[26:27] op_sel_hi:[1,0]
	s_nop 1
	s_nop 1
	s_nop 1
	v_pk_mul_f32 v[122:123], v[172:173], s[26:27] op_sel_hi:[1,0]
	v_mov_b32_e32 v136, v254
	s_mov_b64 vcc, s[4:5]
	s_cbranch_vccz .LBB0_4059
	v_lshlrev_b64 v[158:159], 7, v[152:153]
	v_lshl_add_u64 v[112:113], v[142:143], 0, v[158:159]
	global_load_dwordx4 v[112:115], v[112:113], off
	v_lshl_add_u64 v[158:159], v[140:141], 0, v[158:159]
	global_load_dwordx4 v[164:167], v[158:159], off
	s_or_b32 s4, s40, 2
	s_ashr_i32 s41, s40, 31
	s_ashr_i32 s5, s4, 31
	s_lshl_b64 s[6:7], s[40:41], 14
	s_lshl_b64 s[4:5], s[4:5], 14
	v_mov_b64_e32 v[158:159], s[20:21]
	v_lshl_add_u64 v[184:185], s[6:7], 0, v[152:153]
	v_lshl_add_u64 v[188:189], s[4:5], 0, v[152:153]
	v_pk_mul_f32 v[168:169], v[154:155], v[136:137] op_sel_hi:[1,0]
	v_pk_mul_f32 v[170:171], v[156:157], v[136:137] op_sel_hi:[1,0]
	v_pk_mul_f32 v[172:173], v[124:125], v[136:137] op_sel_hi:[1,0]
	v_pk_mul_f32 v[174:175], v[126:127], v[136:137] op_sel_hi:[1,0]
	v_pk_mul_f32 v[176:177], v[118:119], v[136:137] op_sel_hi:[1,0]
	v_pk_mul_f32 v[178:179], v[120:121], v[136:137] op_sel_hi:[1,0]
	v_pk_mul_f32 v[180:181], v[116:117], v[136:137] op_sel_hi:[1,0]
	v_pk_mul_f32 v[182:183], v[122:123], v[136:137] op_sel_hi:[1,0]
	v_mad_u64_u32 v[186:187], s[6:7], v184, s81, v[146:147]
	v_mad_u64_u32 v[158:159], s[4:5], v188, s81, v[158:159]
	v_mad_i32_i24 v187, v185, s81, v187
	v_mad_i32_i24 v159, v189, s81, v159
	v_lshl_add_u64 v[158:159], v[158:159], 0, s[24:25]
	s_mov_b64 s[46:47], 0
	s_waitcnt vmcnt(1)
	v_pk_mul_f32 v[184:185], v[172:173], v[114:115]
	v_pk_mul_f32 v[188:189], v[174:175], v[112:113]
	v_pk_mul_f32 v[190:191], v[168:169], v[114:115]
	v_pk_mul_f32 v[192:193], v[170:171], v[112:113]
	v_pk_mul_f32 v[194:195], v[180:181], v[114:115]
	v_pk_mul_f32 v[196:197], v[182:183], v[112:113]
	v_pk_mul_f32 v[114:115], v[176:177], v[114:115]
	v_pk_mul_f32 v[112:113], v[178:179], v[112:113]
	s_waitcnt vmcnt(0)
	v_pk_fma_f32 v[168:169], v[168:169], v[166:167], v[184:185] neg_lo:[0,0,1] neg_hi:[0,0,1]
	v_pk_fma_f32 v[170:171], v[170:171], v[164:165], v[188:189] neg_lo:[0,0,1] neg_hi:[0,0,1]
	v_pk_fma_f32 v[172:173], v[172:173], v[166:167], v[190:191]
	v_pk_fma_f32 v[174:175], v[174:175], v[164:165], v[192:193]
	v_pk_fma_f32 v[176:177], v[176:177], v[166:167], v[194:195] neg_lo:[0,0,1] neg_hi:[0,0,1]
	v_pk_fma_f32 v[178:179], v[178:179], v[164:165], v[196:197] neg_lo:[0,0,1] neg_hi:[0,0,1]
	v_pk_fma_f32 v[166:167], v[180:181], v[166:167], v[114:115]
	v_pk_fma_f32 v[164:165], v[182:183], v[164:165], v[112:113]
	v_cvt_pk_bf16_f32 v112, v170, v171
	v_cvt_pk_bf16_f32 v113, v168, v169
	v_cvt_pk_bf16_f32 v114, v174, v175
	v_cvt_pk_bf16_f32 v115, v172, v173
	global_store_dwordx4 v[186:187], v[112:115], off offset:256
	s_nop 1
	v_cvt_pk_bf16_f32 v112, v178, v179
	v_cvt_pk_bf16_f32 v113, v176, v177
	v_cvt_pk_bf16_f32 v114, v164, v165
	v_cvt_pk_bf16_f32 v115, v166, v167

; __device__ __forceinline__ u32x4 pack8bf(const f32x4 a, const f32x4 b) { u32x4 w; w.x = cvt_pk_bf16(a[0], a[1]); w.y = cvt_pk_bf16(a[2], a[3]); w.z = cvt_pk_bf16(b[0], b[1]); w.w = cvt_pk_bf16(b[2], b[3]); return w; }
; __device__ __forceinline__ float rms_scale(const float* ssq, int row, int which) {
;     const f32x4 a = *(const f32x4*)(ssq + (size_t)row * 16 + which * 8), b = *(const f32x4*)(ssq + (size_t)row * 16 + which * 8 + 4);
;     const float s = ((a[0] + a[1]) + (a[2] + a[3])) + ((b[0] + b[1]) + (b[2] + b[3]));
;     return 1.0f / sqrtf(s * (1.0f / 512.0f) + RMS_EPS);
;     __device__ __forceinline__ void operator()(EPI_ARGS) const {
;     ...
;             for (int m = 0; m < 4; ++m) { const int row = row0 + ai * HALF + m * 16; const float rs = rms_scale(ssq, row, 0);
;                 if (u.pn < 8) {
; #pragma unroll
;                     for (int bj = 0; bj < 2; ++bj) { const int h = 2 * u.pn + bj;
;                         *(u32x4*)(Q + ((size_t)h * NTOK + row) * 192 + 32 * wc + 8 * fq) = pack8bf(acc[ai][bj][m][0] * rs, acc[ai][bj][m][1] * rs); }
;                 } else { const int fi = 16 * (wc & 1) + 4 * fq;
;                     const f32x4 c4 = *(const f32x4*)(cs + (size_t)row * 32 + fi), s4 = *(const f32x4*)(sn + (size_t)row * 32 + fi);
; #pragma unroll
;                     for (int bj = 0; bj < 2; ++bj) { const int h = 4 * (u.pn - 8) + 2 * bj + (wc >> 1); const f32x4 v0 = acc[ai][bj][m][0] * rs, v1 = acc[ai][bj][m][1] * rs;
;                         *(u32x4*)(Q + ((size_t)h * NTOK + row) * 192 + 128 + 32 * (wc & 1) + 8 * fq) = pack8bf(v0 * c4 - v1 * s4, v1 * c4 + v0 * s4); } }
;             }
.LBB0_4061:
	v_lshlrev_b32_e32 v136, 1, v138
	v_lshl_add_u64 v[116:117], v[158:159], 0, v[136:137]
	global_store_dwordx4 v[116:117], v[112:115], off
	v_cvt_f32_i32_e32 v109, v109
	v_cvt_f32_i32_e32 v108, v108
	v_or_b32_e32 v112, 16, v152
	v_ashrrev_i32_e32 v113, 31, v112
	v_lshlrev_b64 v[114:115], 6, v[112:113]
	v_lshl_add_u64 v[114:115], s[10:11], 0, v[114:115]
	v_mov_b32_e32 v118, v198
	v_mov_b32_e32 v119, v199
	v_mov_b32_e32 v120, v200
	v_mov_b32_e32 v121, v201
	v_mov_b32_e32 v122, v202
	v_mov_b32_e32 v123, v203
	v_mov_b32_e32 v124, v204
	v_mov_b32_e32 v125, v205
	v_cvt_f32_i32_e32 v111, v111
	v_cvt_f32_i32_e32 v110, v110
	v_cvt_f32_i32_e32 v105, v105
	v_cvt_f32_i32_e32 v104, v104
	v_cvt_f32_i32_e32 v107, v107
	v_cvt_f32_i32_e32 v106, v106
	v_cndmask_b32_e64 v114, 0, 1, s[44:45]
	v_cmp_ne_u32_e64 s[4:5], 1, v114
	v_pk_mul_f32 v[114:115], v[110:111], s[26:27] op_sel_hi:[1,0]
	v_pk_mul_f32 v[116:117], v[108:109], s[26:27] op_sel_hi:[1,0]
	v_pk_mul_f32 v[108:109], v[106:107], s[26:27] op_sel_hi:[1,0]
	v_pk_mul_f32 v[110:111], v[104:105], s[26:27] op_sel_hi:[1,0]
	v_cvt_f32_i32_e32 v101, v101
	v_cvt_f32_i32_e32 v100, v100
	v_cvt_f32_i32_e32 v99, v99
	v_cvt_f32_i32_e32 v98, v98
	v_cvt_f32_i32_e32 v97, v97
	v_cvt_f32_i32_e32 v96, v96
	v_cvt_f32_i32_e32 v103, v103
	v_cvt_f32_i32_e32 v102, v102
	v_pk_mul_f32 v[102:103], v[102:103], s[26:27] op_sel_hi:[1,0]
	v_add_f32_e32 v104, v118, v119
	v_add_f32_e32 v105, v120, v121
	v_add_f32_e32 v106, v122, v123
	v_add_f32_e32 v107, v124, v125
	v_add_f32_e32 v104, v104, v105
	v_add_f32_e32 v105, v106, v107
	v_add_f32_e32 v104, v104, v105
	v_fmamk_f32 v104, v104, 0x3b000000, v162
	v_rsq_f32_e32 v254, v104
	s_nop 1
	v_pk_mul_f32 v[104:105], v[100:101], s[26:27] op_sel_hi:[1,0]
	v_pk_mul_f32 v[100:101], v[98:99], s[26:27] op_sel_hi:[1,0]
	s_nop 1
	s_nop 1
	s_nop 1
	v_pk_mul_f32 v[106:107], v[96:97], s[26:27] op_sel_hi:[1,0]
	s_andn2_b64 vcc, exec, s[44:45]
	v_mov_b32_e32 v118, v254
	s_mov_b64 s[6:7], -1
	s_cbranch_vccnz .LBB0_4063
	v_lshlrev_b64 v[120:121], 7, v[112:113]
	v_lshl_add_u64 v[96:97], v[142:143], 0, v[120:121]
	global_load_dwordx4 v[96:99], v[96:97], off
	v_lshl_add_u64 v[120:121], v[140:141], 0, v[120:121]
	global_load_dwordx4 v[122:125], v[120:121], off
	s_or_b32 s6, s40, 2
	s_ashr_i32 s41, s40, 31
	s_ashr_i32 s7, s6, 31
	s_lshl_b64 s[44:45], s[40:41], 14
	s_lshl_b64 s[6:7], s[6:7], 14
	v_mov_b64_e32 v[120:121], s[20:21]
	v_lshl_add_u64 v[172:173], s[44:45], 0, v[112:113]
	v_lshl_add_u64 v[176:177], s[6:7], 0, v[112:113]
	v_pk_mul_f32 v[126:127], v[114:115], v[118:119] op_sel_hi:[1,0]
	v_pk_mul_f32 v[154:155], v[116:117], v[118:119] op_sel_hi:[1,0]
	v_pk_mul_f32 v[156:157], v[108:109], v[118:119] op_sel_hi:[1,0]
	v_pk_mul_f32 v[158:159], v[110:111], v[118:119] op_sel_hi:[1,0]
	v_pk_mul_f32 v[164:165], v[102:103], v[118:119] op_sel_hi:[1,0]
	v_pk_mul_f32 v[166:167], v[104:105], v[118:119] op_sel_hi:[1,0]
	v_pk_mul_f32 v[168:169], v[100:101], v[118:119] op_sel_hi:[1,0]
	v_pk_mul_f32 v[170:171], v[106:107], v[118:119] op_sel_hi:[1,0]
	v_mad_u64_u32 v[174:175], s[44:45], v172, s81, v[146:147]
	v_mad_u64_u32 v[120:121], s[6:7], v176, s81, v[120:121]
	v_mad_i32_i24 v175, v173, s81, v175
	v_mad_i32_i24 v121, v177, s81, v121
	v_lshl_add_u64 v[120:121], v[120:121], 0, s[24:25]
	s_mov_b64 s[6:7], 0
	s_waitcnt vmcnt(1)
	v_pk_mul_f32 v[172:173], v[156:157], v[98:99]
	v_pk_mul_f32 v[176:177], v[158:159], v[96:97]
	v_pk_mul_f32 v[178:179], v[126:127], v[98:99]
	v_pk_mul_f32 v[180:181], v[154:155], v[96:97]
	v_pk_mul_f32 v[182:183], v[168:169], v[98:99]
	v_pk_mul_f32 v[184:185], v[170:171], v[96:97]
	v_pk_mul_f32 v[98:99], v[164:165], v[98:99]
	v_pk_mul_f32 v[96:97], v[166:167], v[96:97]
	s_waitcnt vmcnt(0)
	v_pk_fma_f32 v[126:127], v[126:127], v[124:125], v[172:173] neg_lo:[0,0,1] neg_hi:[0,0,1]
	v_pk_fma_f32 v[154:155], v[154:155], v[122:123], v[176:177] neg_lo:[0,0,1] neg_hi:[0,0,1]
	v_pk_fma_f32 v[156:157], v[156:157], v[124:125], v[178:179]
	v_pk_fma_f32 v[158:159], v[158:159], v[122:123], v[180:181]
	v_pk_fma_f32 v[164:165], v[164:165], v[124:125], v[182:183] neg_lo:[0,0,1] neg_hi:[0,0,1]
	v_pk_fma_f32 v[166:167], v[166:167], v[122:123], v[184:185] neg_lo:[0,0,1] neg_hi:[0,0,1]
	v_pk_fma_f32 v[124:125], v[168:169], v[124:125], v[98:99]
	v_pk_fma_f32 v[122:123], v[170:171], v[122:123], v[96:97]
	v_cvt_pk_bf16_f32 v96, v154, v155
	v_cvt_pk_bf16_f32 v97, v126, v127
	v_cvt_pk_bf16_f32 v98, v158, v159
	v_cvt_pk_bf16_f32 v99, v156, v157
	global_store_dwordx4 v[174:175], v[96:99], off offset:256
	s_nop 1
	v_cvt_pk_bf16_f32 v96, v166, v167
	v_cvt_pk_bf16_f32 v97, v164, v165
	v_cvt_pk_bf16_f32 v98, v122, v123
	v_cvt_pk_bf16_f32 v99, v124, v125

; __device__ __forceinline__ u32x4 pack8bf(const f32x4 a, const f32x4 b) { u32x4 w; w.x = cvt_pk_bf16(a[0], a[1]); w.y = cvt_pk_bf16(a[2], a[3]); w.z = cvt_pk_bf16(b[0], b[1]); w.w = cvt_pk_bf16(b[2], b[3]); return w; }
; __device__ __forceinline__ float rms_scale(const float* ssq, int row, int which) {
;     const f32x4 a = *(const f32x4*)(ssq + (size_t)row * 16 + which * 8), b = *(const f32x4*)(ssq + (size_t)row * 16 + which * 8 + 4);
;     const float s = ((a[0] + a[1]) + (a[2] + a[3])) + ((b[0] + b[1]) + (b[2] + b[3]));
;     return 1.0f / sqrtf(s * (1.0f / 512.0f) + RMS_EPS);
;     __device__ __forceinline__ void operator()(EPI_ARGS) const {
;     ...
;             for (int m = 0; m < 4; ++m) { const int row = row0 + ai * HALF + m * 16; const float rs = rms_scale(ssq, row, 0);
;                 if (u.pn < 8) {
; #pragma unroll
;                     for (int bj = 0; bj < 2; ++bj) { const int h = 2 * u.pn + bj;
;                         *(u32x4*)(Q + ((size_t)h * NTOK + row) * 192 + 32 * wc + 8 * fq) = pack8bf(acc[ai][bj][m][0] * rs, acc[ai][bj][m][1] * rs); }
;                 } else { const int fi = 16 * (wc & 1) + 4 * fq;
;                     const f32x4 c4 = *(const f32x4*)(cs + (size_t)row * 32 + fi), s4 = *(const f32x4*)(sn + (size_t)row * 32 + fi);
; #pragma unroll
;                     for (int bj = 0; bj < 2; ++bj) { const int h = 4 * (u.pn - 8) + 2 * bj + (wc >> 1); const f32x4 v0 = acc[ai][bj][m][0] * rs, v1 = acc[ai][bj][m][1] * rs;
;                         *(u32x4*)(Q + ((size_t)h * NTOK + row) * 192 + 128 + 32 * (wc & 1) + 8 * fq) = pack8bf(v0 * c4 - v1 * s4, v1 * c4 + v0 * s4); } }
;             }
.LBB0_4065:
	v_lshl_add_u64 v[100:101], v[120:121], 0, v[136:137]
	global_store_dwordx4 v[100:101], v[96:99], off
	v_cvt_f32_i32_e32 v93, v93
	v_cvt_f32_i32_e32 v92, v92
	v_or_b32_e32 v96, 32, v152
	v_ashrrev_i32_e32 v97, 31, v96
	v_lshlrev_b64 v[98:99], 6, v[96:97]
	v_lshl_add_u64 v[98:99], s[10:11], 0, v[98:99]
	v_mov_b32_e32 v102, v206
	v_mov_b32_e32 v103, v207
	v_mov_b32_e32 v104, v208
	v_mov_b32_e32 v105, v209
	v_mov_b32_e32 v106, v210
	v_mov_b32_e32 v107, v211
	v_mov_b32_e32 v108, v212
	v_mov_b32_e32 v109, v213
	v_cvt_f32_i32_e32 v95, v95
	v_cvt_f32_i32_e32 v94, v94
	v_cvt_f32_i32_e32 v89, v89
	v_cvt_f32_i32_e32 v88, v88
	v_pk_mul_f32 v[100:101], v[92:93], s[26:27] op_sel_hi:[1,0]
	v_pk_mul_f32 v[98:99], v[94:95], s[26:27] op_sel_hi:[1,0]
	v_cvt_f32_i32_e32 v85, v85
	v_pk_mul_f32 v[94:95], v[88:89], s[26:27] op_sel_hi:[1,0]
	v_cvt_f32_i32_e32 v84, v84
	v_cvt_f32_i32_e32 v83, v83
	v_cvt_f32_i32_e32 v82, v82
	v_cvt_f32_i32_e32 v81, v81
	v_cvt_f32_i32_e32 v80, v80
	v_cvt_f32_i32_e32 v91, v91
	v_cvt_f32_i32_e32 v90, v90
	v_cvt_f32_i32_e32 v87, v87
	v_cvt_f32_i32_e32 v86, v86
	v_pk_mul_f32 v[90:91], v[90:91], s[26:27] op_sel_hi:[1,0]
	v_pk_mul_f32 v[86:87], v[86:87], s[26:27] op_sel_hi:[1,0]
	v_add_f32_e32 v88, v102, v103
	v_add_f32_e32 v89, v104, v105
	v_add_f32_e32 v92, v106, v107
	v_add_f32_e32 v93, v108, v109
	v_add_f32_e32 v88, v88, v89
	v_add_f32_e32 v89, v92, v93
	v_add_f32_e32 v88, v88, v89
	v_fmamk_f32 v88, v88, 0x3b000000, v162
	v_rsq_f32_e32 v254, v88
	s_nop 1
	v_pk_mul_f32 v[88:89], v[84:85], s[26:27] op_sel_hi:[1,0]
	v_pk_mul_f32 v[84:85], v[82:83], s[26:27] op_sel_hi:[1,0]
	s_nop 1
	s_nop 1
	s_nop 1
	v_pk_mul_f32 v[92:93], v[80:81], s[26:27] op_sel_hi:[1,0]
	s_and_b64 vcc, exec, s[4:5]
	v_mov_b32_e32 v102, v254
	s_mov_b64 s[6:7], -1
	s_cbranch_vccnz .LBB0_4067
	v_lshlrev_b64 v[104:105], 7, v[96:97]
	v_lshl_add_u64 v[80:81], v[142:143], 0, v[104:105]
	global_load_dwordx4 v[80:83], v[80:81], off
	v_lshl_add_u64 v[104:105], v[140:141], 0, v[104:105]
	global_load_dwordx4 v[106:109], v[104:105], off
	s_or_b32 s6, s40, 2
	s_ashr_i32 s41, s40, 31
	s_ashr_i32 s7, s6, 31
	s_lshl_b64 s[44:45], s[40:41], 14
	s_lshl_b64 s[6:7], s[6:7], 14
	v_mov_b64_e32 v[104:105], s[20:21]
	v_lshl_add_u64 v[126:127], s[44:45], 0, v[96:97]
	v_lshl_add_u64 v[156:157], s[6:7], 0, v[96:97]
	v_pk_mul_f32 v[110:111], v[98:99], v[102:103] op_sel_hi:[1,0]
	v_pk_mul_f32 v[112:113], v[100:101], v[102:103] op_sel_hi:[1,0]
	v_pk_mul_f32 v[114:115], v[90:91], v[102:103] op_sel_hi:[1,0]
	v_pk_mul_f32 v[116:117], v[94:95], v[102:103] op_sel_hi:[1,0]
	v_pk_mul_f32 v[118:119], v[86:87], v[102:103] op_sel_hi:[1,0]
	v_pk_mul_f32 v[120:121], v[88:89], v[102:103] op_sel_hi:[1,0]
	v_pk_mul_f32 v[122:123], v[84:85], v[102:103] op_sel_hi:[1,0]
	v_pk_mul_f32 v[124:125], v[92:93], v[102:103] op_sel_hi:[1,0]
	v_mad_u64_u32 v[154:155], s[44:45], v126, s81, v[146:147]
	v_mad_u64_u32 v[104:105], s[6:7], v156, s81, v[104:105]
	v_mad_i32_i24 v155, v127, s81, v155
	v_mad_i32_i24 v105, v157, s81, v105
	v_lshl_add_u64 v[104:105], v[104:105], 0, s[24:25]
	s_mov_b64 s[6:7], 0
	s_waitcnt vmcnt(1)
	v_pk_mul_f32 v[126:127], v[114:115], v[82:83]
	v_pk_mul_f32 v[156:157], v[116:117], v[80:81]
	v_pk_mul_f32 v[158:159], v[110:111], v[82:83]
	v_pk_mul_f32 v[164:165], v[112:113], v[80:81]
	v_pk_mul_f32 v[166:167], v[122:123], v[82:83]
	v_pk_mul_f32 v[168:169], v[124:125], v[80:81]
	v_pk_mul_f32 v[82:83], v[118:119], v[82:83]
	v_pk_mul_f32 v[80:81], v[120:121], v[80:81]
	s_waitcnt vmcnt(0)
	v_pk_fma_f32 v[110:111], v[110:111], v[108:109], v[126:127] neg_lo:[0,0,1] neg_hi:[0,0,1]
	v_pk_fma_f32 v[112:113], v[112:113], v[106:107], v[156:157] neg_lo:[0,0,1] neg_hi:[0,0,1]
	v_pk_fma_f32 v[114:115], v[114:115], v[108:109], v[158:159]
	v_pk_fma_f32 v[116:117], v[116:117], v[106:107], v[164:165]
	v_pk_fma_f32 v[118:119], v[118:119], v[108:109], v[166:167] neg_lo:[0,0,1] neg_hi:[0,0,1]
	v_pk_fma_f32 v[120:121], v[120:121], v[106:107], v[168:169] neg_lo:[0,0,1] neg_hi:[0,0,1]
	v_pk_fma_f32 v[108:109], v[122:123], v[108:109], v[82:83]
	v_pk_fma_f32 v[106:107], v[124:125], v[106:107], v[80:81]
	v_cvt_pk_bf16_f32 v80, v112, v113
	v_cvt_pk_bf16_f32 v81, v110, v111
	v_cvt_pk_bf16_f32 v82, v116, v117
	v_cvt_pk_bf16_f32 v83, v114, v115
	global_store_dwordx4 v[154:155], v[80:83], off offset:256
	s_nop 1
	v_cvt_pk_bf16_f32 v80, v120, v121
	v_cvt_pk_bf16_f32 v81, v118, v119
	v_cvt_pk_bf16_f32 v82, v106, v107
	v_cvt_pk_bf16_f32 v83, v108, v109

; __device__ __forceinline__ u32x4 pack8bf(const f32x4 a, const f32x4 b) { u32x4 w; w.x = cvt_pk_bf16(a[0], a[1]); w.y = cvt_pk_bf16(a[2], a[3]); w.z = cvt_pk_bf16(b[0], b[1]); w.w = cvt_pk_bf16(b[2], b[3]); return w; }
; __device__ __forceinline__ float rms_scale(const float* ssq, int row, int which) {
;     const f32x4 a = *(const f32x4*)(ssq + (size_t)row * 16 + which * 8), b = *(const f32x4*)(ssq + (size_t)row * 16 + which * 8 + 4);
;     const float s = ((a[0] + a[1]) + (a[2] + a[3])) + ((b[0] + b[1]) + (b[2] + b[3]));
;     return 1.0f / sqrtf(s * (1.0f / 512.0f) + RMS_EPS);
;     __device__ __forceinline__ void operator()(EPI_ARGS) const {
;     ...
;             for (int m = 0; m < 4; ++m) { const int row = row0 + ai * HALF + m * 16; const float rs = rms_scale(ssq, row, 0);
;                 if (u.pn < 8) {
; #pragma unroll
;                     for (int bj = 0; bj < 2; ++bj) { const int h = 2 * u.pn + bj;
;                         *(u32x4*)(Q + ((size_t)h * NTOK + row) * 192 + 32 * wc + 8 * fq) = pack8bf(acc[ai][bj][m][0] * rs, acc[ai][bj][m][1] * rs); }
;                 } else { const int fi = 16 * (wc & 1) + 4 * fq;
;                     const f32x4 c4 = *(const f32x4*)(cs + (size_t)row * 32 + fi), s4 = *(const f32x4*)(sn + (size_t)row * 32 + fi);
; #pragma unroll
;                     for (int bj = 0; bj < 2; ++bj) { const int h = 4 * (u.pn - 8) + 2 * bj + (wc >> 1); const f32x4 v0 = acc[ai][bj][m][0] * rs, v1 = acc[ai][bj][m][1] * rs;
;                         *(u32x4*)(Q + ((size_t)h * NTOK + row) * 192 + 128 + 32 * (wc & 1) + 8 * fq) = pack8bf(v0 * c4 - v1 * s4, v1 * c4 + v0 * s4); } }
;             }
.LBB0_4069:
	v_lshl_add_u64 v[84:85], v[104:105], 0, v[136:137]
	global_store_dwordx4 v[84:85], v[80:83], off
	v_cvt_f32_i32_e32 v77, v77
	v_cvt_f32_i32_e32 v76, v76
	v_or_b32_e32 v80, 48, v152
	v_ashrrev_i32_e32 v81, 31, v80
	v_lshlrev_b64 v[82:83], 6, v[80:81]
	v_lshl_add_u64 v[82:83], s[10:11], 0, v[82:83]
	v_mov_b32_e32 v86, v214
	v_mov_b32_e32 v87, v215
	v_mov_b32_e32 v88, v216
	v_mov_b32_e32 v89, v217
	v_mov_b32_e32 v90, v218
	v_mov_b32_e32 v91, v219
	v_mov_b32_e32 v92, v220
	v_mov_b32_e32 v93, v221
	v_cvt_f32_i32_e32 v79, v79
	v_cvt_f32_i32_e32 v78, v78
	v_cvt_f32_i32_e32 v73, v73
	v_cvt_f32_i32_e32 v72, v72
	v_pk_mul_f32 v[84:85], v[76:77], s[26:27] op_sel_hi:[1,0]
	v_pk_mul_f32 v[82:83], v[78:79], s[26:27] op_sel_hi:[1,0]
	v_cvt_f32_i32_e32 v69, v69
	v_pk_mul_f32 v[78:79], v[72:73], s[26:27] op_sel_hi:[1,0]
	v_cvt_f32_i32_e32 v68, v68
	v_cvt_f32_i32_e32 v67, v67
	v_cvt_f32_i32_e32 v66, v66
	v_cvt_f32_i32_e32 v65, v65
	v_cvt_f32_i32_e32 v64, v64
	v_cvt_f32_i32_e32 v75, v75
	v_cvt_f32_i32_e32 v74, v74
	v_cvt_f32_i32_e32 v71, v71
	v_cvt_f32_i32_e32 v70, v70
	v_pk_mul_f32 v[74:75], v[74:75], s[26:27] op_sel_hi:[1,0]
	v_pk_mul_f32 v[70:71], v[70:71], s[26:27] op_sel_hi:[1,0]
	v_add_f32_e32 v72, v86, v87
	v_add_f32_e32 v73, v88, v89
	v_add_f32_e32 v76, v90, v91
	v_add_f32_e32 v77, v92, v93
	v_add_f32_e32 v72, v72, v73
	v_add_f32_e32 v73, v76, v77
	v_add_f32_e32 v72, v72, v73
	v_fmamk_f32 v72, v72, 0x3b000000, v162
	v_rsq_f32_e32 v254, v72
	s_nop 1
	v_pk_mul_f32 v[72:73], v[68:69], s[26:27] op_sel_hi:[1,0]
	v_pk_mul_f32 v[68:69], v[66:67], s[26:27] op_sel_hi:[1,0]
	s_nop 1
	s_nop 1
	s_nop 1
	v_pk_mul_f32 v[76:77], v[64:65], s[26:27] op_sel_hi:[1,0]
	s_and_b64 vcc, exec, s[4:5]
	v_mov_b32_e32 v86, v254
	s_mov_b64 s[6:7], -1
	s_cbranch_vccnz .LBB0_4071
	v_lshlrev_b64 v[88:89], 7, v[80:81]
	v_lshl_add_u64 v[64:65], v[142:143], 0, v[88:89]
	global_load_dwordx4 v[64:67], v[64:65], off
	v_lshl_add_u64 v[88:89], v[140:141], 0, v[88:89]
	global_load_dwordx4 v[90:93], v[88:89], off
	s_or_b32 s6, s40, 2
	s_ashr_i32 s41, s40, 31
	s_ashr_i32 s7, s6, 31
	s_lshl_b64 s[44:45], s[40:41], 14
	s_lshl_b64 s[6:7], s[6:7], 14
	v_mov_b64_e32 v[88:89], s[20:21]
	v_lshl_add_u64 v[110:111], s[44:45], 0, v[80:81]
	v_lshl_add_u64 v[114:115], s[6:7], 0, v[80:81]
	v_pk_mul_f32 v[94:95], v[82:83], v[86:87] op_sel_hi:[1,0]
	v_pk_mul_f32 v[96:97], v[84:85], v[86:87] op_sel_hi:[1,0]
	v_pk_mul_f32 v[98:99], v[74:75], v[86:87] op_sel_hi:[1,0]
	v_pk_mul_f32 v[100:101], v[78:79], v[86:87] op_sel_hi:[1,0]
	v_pk_mul_f32 v[102:103], v[70:71], v[86:87] op_sel_hi:[1,0]
	v_pk_mul_f32 v[104:105], v[72:73], v[86:87] op_sel_hi:[1,0]
	v_pk_mul_f32 v[106:107], v[68:69], v[86:87] op_sel_hi:[1,0]
	v_pk_mul_f32 v[108:109], v[76:77], v[86:87] op_sel_hi:[1,0]
	v_mad_u64_u32 v[112:113], s[44:45], v110, s81, v[146:147]
	v_mad_u64_u32 v[88:89], s[6:7], v114, s81, v[88:89]
	v_mad_i32_i24 v113, v111, s81, v113
	v_mad_i32_i24 v89, v115, s81, v89
	v_lshl_add_u64 v[88:89], v[88:89], 0, s[24:25]
	s_mov_b64 s[6:7], 0
	s_waitcnt vmcnt(1)
	v_pk_mul_f32 v[110:111], v[98:99], v[66:67]
	v_pk_mul_f32 v[114:115], v[100:101], v[64:65]
	v_pk_mul_f32 v[116:117], v[94:95], v[66:67]
	v_pk_mul_f32 v[118:119], v[96:97], v[64:65]
	v_pk_mul_f32 v[120:121], v[106:107], v[66:67]
	v_pk_mul_f32 v[122:123], v[108:109], v[64:65]
	v_pk_mul_f32 v[66:67], v[102:103], v[66:67]
	v_pk_mul_f32 v[64:65], v[104:105], v[64:65]
	s_waitcnt vmcnt(0)
	v_pk_fma_f32 v[94:95], v[94:95], v[92:93], v[110:111] neg_lo:[0,0,1] neg_hi:[0,0,1]
	v_pk_fma_f32 v[96:97], v[96:97], v[90:91], v[114:115] neg_lo:[0,0,1] neg_hi:[0,0,1]
	v_pk_fma_f32 v[98:99], v[98:99], v[92:93], v[116:117]
	v_pk_fma_f32 v[100:101], v[100:101], v[90:91], v[118:119]
	v_pk_fma_f32 v[102:103], v[102:103], v[92:93], v[120:121] neg_lo:[0,0,1] neg_hi:[0,0,1]
	v_pk_fma_f32 v[104:105], v[104:105], v[90:91], v[122:123] neg_lo:[0,0,1] neg_hi:[0,0,1]
	v_pk_fma_f32 v[92:93], v[106:107], v[92:93], v[66:67]
	v_pk_fma_f32 v[90:91], v[108:109], v[90:91], v[64:65]
	v_cvt_pk_bf16_f32 v64, v96, v97
	v_cvt_pk_bf16_f32 v65, v94, v95
	v_cvt_pk_bf16_f32 v66, v100, v101
	v_cvt_pk_bf16_f32 v67, v98, v99
	global_store_dwordx4 v[112:113], v[64:67], off offset:256
	s_nop 1
	v_cvt_pk_bf16_f32 v64, v104, v105
	v_cvt_pk_bf16_f32 v65, v102, v103
	v_cvt_pk_bf16_f32 v66, v90, v91
	v_cvt_pk_bf16_f32 v67, v92, v93

; __device__ __forceinline__ u32x4 pack8bf(const f32x4 a, const f32x4 b) { u32x4 w; w.x = cvt_pk_bf16(a[0], a[1]); w.y = cvt_pk_bf16(a[2], a[3]); w.z = cvt_pk_bf16(b[0], b[1]); w.w = cvt_pk_bf16(b[2], b[3]); return w; }
; __device__ __forceinline__ float rms_scale(const float* ssq, int row, int which) {
;     const f32x4 a = *(const f32x4*)(ssq + (size_t)row * 16 + which * 8), b = *(const f32x4*)(ssq + (size_t)row * 16 + which * 8 + 4);
;     const float s = ((a[0] + a[1]) + (a[2] + a[3])) + ((b[0] + b[1]) + (b[2] + b[3]));
;     return 1.0f / sqrtf(s * (1.0f / 512.0f) + RMS_EPS);
;     __device__ __forceinline__ void operator()(EPI_ARGS) const {
;     ...
;             for (int m = 0; m < 4; ++m) { const int row = row0 + ai * HALF + m * 16; const float rs = rms_scale(ssq, row, 0);
;                 if (u.pn < 8) {
; #pragma unroll
;                     for (int bj = 0; bj < 2; ++bj) { const int h = 2 * u.pn + bj;
;                         *(u32x4*)(Q + ((size_t)h * NTOK + row) * 192 + 32 * wc + 8 * fq) = pack8bf(acc[ai][bj][m][0] * rs, acc[ai][bj][m][1] * rs); }
;                 } else { const int fi = 16 * (wc & 1) + 4 * fq;
;                     const f32x4 c4 = *(const f32x4*)(cs + (size_t)row * 32 + fi), s4 = *(const f32x4*)(sn + (size_t)row * 32 + fi);
; #pragma unroll
;                     for (int bj = 0; bj < 2; ++bj) { const int h = 4 * (u.pn - 8) + 2 * bj + (wc >> 1); const f32x4 v0 = acc[ai][bj][m][0] * rs, v1 = acc[ai][bj][m][1] * rs;
;                         *(u32x4*)(Q + ((size_t)h * NTOK + row) * 192 + 128 + 32 * (wc & 1) + 8 * fq) = pack8bf(v0 * c4 - v1 * s4, v1 * c4 + v0 * s4); } }
;             }
.LBB0_4073:
	v_lshl_add_u64 v[68:69], v[88:89], 0, v[136:137]
	global_store_dwordx4 v[68:69], v[64:67], off
	v_cvt_f32_i32_e32 v61, v61
	v_cvt_f32_i32_e32 v60, v60
	v_add_u32_e32 v64, 0x80, v152
	v_ashrrev_i32_e32 v65, 31, v64
	v_lshlrev_b64 v[66:67], 6, v[64:65]
	v_lshl_add_u64 v[66:67], s[10:11], 0, v[66:67]
	v_mov_b32_e32 v70, v222
	v_mov_b32_e32 v71, v223
	v_mov_b32_e32 v72, v224
	v_mov_b32_e32 v73, v225
	v_mov_b32_e32 v74, v226
	v_mov_b32_e32 v75, v227
	v_mov_b32_e32 v76, v228
	v_mov_b32_e32 v77, v229
	v_cvt_f32_i32_e32 v63, v63
	v_cvt_f32_i32_e32 v62, v62
	v_cvt_f32_i32_e32 v57, v57
	v_cvt_f32_i32_e32 v56, v56
	v_pk_mul_f32 v[68:69], v[60:61], s[26:27] op_sel_hi:[1,0]
	v_pk_mul_f32 v[66:67], v[62:63], s[26:27] op_sel_hi:[1,0]
	v_cvt_f32_i32_e32 v53, v53
	v_pk_mul_f32 v[62:63], v[56:57], s[26:27] op_sel_hi:[1,0]
	v_cvt_f32_i32_e32 v52, v52
	v_cvt_f32_i32_e32 v51, v51
	v_cvt_f32_i32_e32 v50, v50
	v_cvt_f32_i32_e32 v49, v49
	v_cvt_f32_i32_e32 v48, v48
	v_cvt_f32_i32_e32 v59, v59
	v_cvt_f32_i32_e32 v58, v58
	v_cvt_f32_i32_e32 v55, v55
	v_cvt_f32_i32_e32 v54, v54
	v_pk_mul_f32 v[58:59], v[58:59], s[26:27] op_sel_hi:[1,0]
	v_pk_mul_f32 v[54:55], v[54:55], s[26:27] op_sel_hi:[1,0]
	v_add_f32_e32 v56, v70, v71
	v_add_f32_e32 v57, v72, v73
	v_add_f32_e32 v60, v74, v75
	v_add_f32_e32 v61, v76, v77
	v_add_f32_e32 v56, v56, v57
	v_add_f32_e32 v57, v60, v61
	v_add_f32_e32 v56, v56, v57
	v_fmamk_f32 v56, v56, 0x3b000000, v162
	v_rsq_f32_e32 v254, v56
	s_nop 1
	v_pk_mul_f32 v[56:57], v[52:53], s[26:27] op_sel_hi:[1,0]
	v_pk_mul_f32 v[52:53], v[50:51], s[26:27] op_sel_hi:[1,0]
	s_nop 1
	s_nop 1
	s_nop 1
	v_pk_mul_f32 v[60:61], v[48:49], s[26:27] op_sel_hi:[1,0]
	s_and_b64 vcc, exec, s[4:5]
	v_mov_b32_e32 v70, v254
	s_mov_b64 s[6:7], -1
	s_cbranch_vccnz .LBB0_4075
	v_lshlrev_b64 v[72:73], 7, v[64:65]
	v_lshl_add_u64 v[48:49], v[142:143], 0, v[72:73]
	global_load_dwordx4 v[48:51], v[48:49], off
	v_lshl_add_u64 v[72:73], v[140:141], 0, v[72:73]
	global_load_dwordx4 v[74:77], v[72:73], off
	s_or_b32 s6, s40, 2
	s_ashr_i32 s41, s40, 31
	s_ashr_i32 s7, s6, 31
	s_lshl_b64 s[44:45], s[40:41], 14
	s_lshl_b64 s[6:7], s[6:7], 14
	v_mov_b64_e32 v[72:73], s[20:21]
	v_lshl_add_u64 v[94:95], s[44:45], 0, v[64:65]
	v_lshl_add_u64 v[98:99], s[6:7], 0, v[64:65]
	v_pk_mul_f32 v[78:79], v[66:67], v[70:71] op_sel_hi:[1,0]
	v_pk_mul_f32 v[80:81], v[68:69], v[70:71] op_sel_hi:[1,0]
	v_pk_mul_f32 v[82:83], v[58:59], v[70:71] op_sel_hi:[1,0]
	v_pk_mul_f32 v[84:85], v[62:63], v[70:71] op_sel_hi:[1,0]
	v_pk_mul_f32 v[86:87], v[54:55], v[70:71] op_sel_hi:[1,0]
	v_pk_mul_f32 v[88:89], v[56:57], v[70:71] op_sel_hi:[1,0]
	v_pk_mul_f32 v[90:91], v[52:53], v[70:71] op_sel_hi:[1,0]
	v_pk_mul_f32 v[92:93], v[60:61], v[70:71] op_sel_hi:[1,0]
	v_mad_u64_u32 v[96:97], s[44:45], v94, s81, v[146:147]
	v_mad_u64_u32 v[72:73], s[6:7], v98, s81, v[72:73]
	v_mad_i32_i24 v97, v95, s81, v97
	v_mad_i32_i24 v73, v99, s81, v73
	v_lshl_add_u64 v[72:73], v[72:73], 0, s[24:25]
	s_mov_b64 s[6:7], 0
	s_waitcnt vmcnt(1)
	v_pk_mul_f32 v[94:95], v[82:83], v[50:51]
	v_pk_mul_f32 v[98:99], v[84:85], v[48:49]
	v_pk_mul_f32 v[100:101], v[78:79], v[50:51]
	v_pk_mul_f32 v[102:103], v[80:81], v[48:49]
	v_pk_mul_f32 v[104:105], v[90:91], v[50:51]
	v_pk_mul_f32 v[106:107], v[92:93], v[48:49]
	v_pk_mul_f32 v[50:51], v[86:87], v[50:51]
	v_pk_mul_f32 v[48:49], v[88:89], v[48:49]
	s_waitcnt vmcnt(0)
	v_pk_fma_f32 v[78:79], v[78:79], v[76:77], v[94:95] neg_lo:[0,0,1] neg_hi:[0,0,1]
	v_pk_fma_f32 v[80:81], v[80:81], v[74:75], v[98:99] neg_lo:[0,0,1] neg_hi:[0,0,1]
	v_pk_fma_f32 v[82:83], v[82:83], v[76:77], v[100:101]
	v_pk_fma_f32 v[84:85], v[84:85], v[74:75], v[102:103]
	v_pk_fma_f32 v[86:87], v[86:87], v[76:77], v[104:105] neg_lo:[0,0,1] neg_hi:[0,0,1]
	v_pk_fma_f32 v[88:89], v[88:89], v[74:75], v[106:107] neg_lo:[0,0,1] neg_hi:[0,0,1]
	v_pk_fma_f32 v[76:77], v[90:91], v[76:77], v[50:51]
	v_pk_fma_f32 v[74:75], v[92:93], v[74:75], v[48:49]
	v_cvt_pk_bf16_f32 v48, v80, v81
	v_cvt_pk_bf16_f32 v49, v78, v79
	v_cvt_pk_bf16_f32 v50, v84, v85
	v_cvt_pk_bf16_f32 v51, v82, v83
	global_store_dwordx4 v[96:97], v[48:51], off offset:256
	s_nop 1
	v_cvt_pk_bf16_f32 v48, v88, v89
	v_cvt_pk_bf16_f32 v49, v86, v87
	v_cvt_pk_bf16_f32 v50, v74, v75
	v_cvt_pk_bf16_f32 v51, v76, v77

; __device__ __forceinline__ u32x4 pack8bf(const f32x4 a, const f32x4 b) { u32x4 w; w.x = cvt_pk_bf16(a[0], a[1]); w.y = cvt_pk_bf16(a[2], a[3]); w.z = cvt_pk_bf16(b[0], b[1]); w.w = cvt_pk_bf16(b[2], b[3]); return w; }
; __device__ __forceinline__ float rms_scale(const float* ssq, int row, int which) {
;     const f32x4 a = *(const f32x4*)(ssq + (size_t)row * 16 + which * 8), b = *(const f32x4*)(ssq + (size_t)row * 16 + which * 8 + 4);
;     const float s = ((a[0] + a[1]) + (a[2] + a[3])) + ((b[0] + b[1]) + (b[2] + b[3]));
;     return 1.0f / sqrtf(s * (1.0f / 512.0f) + RMS_EPS);
;     __device__ __forceinline__ void operator()(EPI_ARGS) const {
;     ...
;             for (int m = 0; m < 4; ++m) { const int row = row0 + ai * HALF + m * 16; const float rs = rms_scale(ssq, row, 0);
;                 if (u.pn < 8) {
; #pragma unroll
;                     for (int bj = 0; bj < 2; ++bj) { const int h = 2 * u.pn + bj;
;                         *(u32x4*)(Q + ((size_t)h * NTOK + row) * 192 + 32 * wc + 8 * fq) = pack8bf(acc[ai][bj][m][0] * rs, acc[ai][bj][m][1] * rs); }
;                 } else { const int fi = 16 * (wc & 1) + 4 * fq;
;                     const f32x4 c4 = *(const f32x4*)(cs + (size_t)row * 32 + fi), s4 = *(const f32x4*)(sn + (size_t)row * 32 + fi);
; #pragma unroll
;                     for (int bj = 0; bj < 2; ++bj) { const int h = 4 * (u.pn - 8) + 2 * bj + (wc >> 1); const f32x4 v0 = acc[ai][bj][m][0] * rs, v1 = acc[ai][bj][m][1] * rs;
;                         *(u32x4*)(Q + ((size_t)h * NTOK + row) * 192 + 128 + 32 * (wc & 1) + 8 * fq) = pack8bf(v0 * c4 - v1 * s4, v1 * c4 + v0 * s4); } }
;             }
.LBB0_4077:
	v_lshl_add_u64 v[52:53], v[72:73], 0, v[136:137]
	global_store_dwordx4 v[52:53], v[48:51], off
	v_cvt_f32_i32_e32 v45, v45
	v_cvt_f32_i32_e32 v44, v44
	v_add_u32_e32 v48, 0x90, v152
	v_ashrrev_i32_e32 v49, 31, v48
	v_lshlrev_b64 v[50:51], 6, v[48:49]
	v_lshl_add_u64 v[50:51], s[10:11], 0, v[50:51]
	v_mov_b32_e32 v54, v230
	v_mov_b32_e32 v55, v231
	v_mov_b32_e32 v56, v232
	v_mov_b32_e32 v57, v233
	v_mov_b32_e32 v58, v234
	v_mov_b32_e32 v59, v235
	v_mov_b32_e32 v60, v236
	v_mov_b32_e32 v61, v237
	v_cvt_f32_i32_e32 v47, v47
	v_cvt_f32_i32_e32 v46, v46
	v_cvt_f32_i32_e32 v41, v41
	v_cvt_f32_i32_e32 v40, v40
	v_pk_mul_f32 v[52:53], v[44:45], s[26:27] op_sel_hi:[1,0]
	v_pk_mul_f32 v[50:51], v[46:47], s[26:27] op_sel_hi:[1,0]
	v_cvt_f32_i32_e32 v37, v37
	v_pk_mul_f32 v[46:47], v[40:41], s[26:27] op_sel_hi:[1,0]
	v_cvt_f32_i32_e32 v36, v36
	v_cvt_f32_i32_e32 v35, v35
	v_cvt_f32_i32_e32 v34, v34
	v_cvt_f32_i32_e32 v33, v33
	v_cvt_f32_i32_e32 v32, v32
	v_cvt_f32_i32_e32 v43, v43
	v_cvt_f32_i32_e32 v42, v42
	v_cvt_f32_i32_e32 v39, v39
	v_cvt_f32_i32_e32 v38, v38
	v_pk_mul_f32 v[42:43], v[42:43], s[26:27] op_sel_hi:[1,0]
	v_pk_mul_f32 v[38:39], v[38:39], s[26:27] op_sel_hi:[1,0]
	v_add_f32_e32 v40, v54, v55
	v_add_f32_e32 v41, v56, v57
	v_add_f32_e32 v44, v58, v59
	v_add_f32_e32 v45, v60, v61
	v_add_f32_e32 v40, v40, v41
	v_add_f32_e32 v41, v44, v45
	v_add_f32_e32 v40, v40, v41
	v_fmamk_f32 v40, v40, 0x3b000000, v162
	v_rsq_f32_e32 v254, v40
	s_nop 1
	v_pk_mul_f32 v[40:41], v[36:37], s[26:27] op_sel_hi:[1,0]
	v_pk_mul_f32 v[36:37], v[34:35], s[26:27] op_sel_hi:[1,0]
	s_nop 1
	s_nop 1
	s_nop 1
	v_pk_mul_f32 v[44:45], v[32:33], s[26:27] op_sel_hi:[1,0]
	s_and_b64 vcc, exec, s[4:5]
	v_mov_b32_e32 v54, v254
	s_mov_b64 s[6:7], -1
	s_cbranch_vccnz .LBB0_4079
	v_lshlrev_b64 v[56:57], 7, v[48:49]
	v_lshl_add_u64 v[32:33], v[142:143], 0, v[56:57]
	global_load_dwordx4 v[32:35], v[32:33], off
	v_lshl_add_u64 v[56:57], v[140:141], 0, v[56:57]
	global_load_dwordx4 v[58:61], v[56:57], off
	s_or_b32 s6, s40, 2
	s_ashr_i32 s41, s40, 31
	s_ashr_i32 s7, s6, 31
	s_lshl_b64 s[44:45], s[40:41], 14
	s_lshl_b64 s[6:7], s[6:7], 14
	v_mov_b64_e32 v[56:57], s[20:21]
	v_lshl_add_u64 v[78:79], s[44:45], 0, v[48:49]
	v_lshl_add_u64 v[82:83], s[6:7], 0, v[48:49]
	v_pk_mul_f32 v[62:63], v[50:51], v[54:55] op_sel_hi:[1,0]
	v_pk_mul_f32 v[64:65], v[52:53], v[54:55] op_sel_hi:[1,0]
	v_pk_mul_f32 v[66:67], v[42:43], v[54:55] op_sel_hi:[1,0]
	v_pk_mul_f32 v[68:69], v[46:47], v[54:55] op_sel_hi:[1,0]
	v_pk_mul_f32 v[70:71], v[38:39], v[54:55] op_sel_hi:[1,0]
	v_pk_mul_f32 v[72:73], v[40:41], v[54:55] op_sel_hi:[1,0]
	v_pk_mul_f32 v[74:75], v[36:37], v[54:55] op_sel_hi:[1,0]
	v_pk_mul_f32 v[76:77], v[44:45], v[54:55] op_sel_hi:[1,0]
	v_mad_u64_u32 v[80:81], s[44:45], v78, s81, v[146:147]
	v_mad_u64_u32 v[56:57], s[6:7], v82, s81, v[56:57]
	v_mad_i32_i24 v81, v79, s81, v81
	v_mad_i32_i24 v57, v83, s81, v57
	v_lshl_add_u64 v[56:57], v[56:57], 0, s[24:25]
	s_mov_b64 s[6:7], 0
	s_waitcnt vmcnt(1)
	v_pk_mul_f32 v[78:79], v[66:67], v[34:35]
	v_pk_mul_f32 v[82:83], v[68:69], v[32:33]
	v_pk_mul_f32 v[84:85], v[62:63], v[34:35]
	v_pk_mul_f32 v[86:87], v[64:65], v[32:33]
	v_pk_mul_f32 v[88:89], v[74:75], v[34:35]
	v_pk_mul_f32 v[90:91], v[76:77], v[32:33]
	v_pk_mul_f32 v[34:35], v[70:71], v[34:35]
	v_pk_mul_f32 v[32:33], v[72:73], v[32:33]
	s_waitcnt vmcnt(0)
	v_pk_fma_f32 v[62:63], v[62:63], v[60:61], v[78:79] neg_lo:[0,0,1] neg_hi:[0,0,1]
	v_pk_fma_f32 v[64:65], v[64:65], v[58:59], v[82:83] neg_lo:[0,0,1] neg_hi:[0,0,1]
	v_pk_fma_f32 v[66:67], v[66:67], v[60:61], v[84:85]
	v_pk_fma_f32 v[68:69], v[68:69], v[58:59], v[86:87]
	v_pk_fma_f32 v[70:71], v[70:71], v[60:61], v[88:89] neg_lo:[0,0,1] neg_hi:[0,0,1]
	v_pk_fma_f32 v[72:73], v[72:73], v[58:59], v[90:91] neg_lo:[0,0,1] neg_hi:[0,0,1]
	v_pk_fma_f32 v[60:61], v[74:75], v[60:61], v[34:35]
	v_pk_fma_f32 v[58:59], v[76:77], v[58:59], v[32:33]
	v_cvt_pk_bf16_f32 v32, v64, v65
	v_cvt_pk_bf16_f32 v33, v62, v63
	v_cvt_pk_bf16_f32 v34, v68, v69
	v_cvt_pk_bf16_f32 v35, v66, v67
	global_store_dwordx4 v[80:81], v[32:35], off offset:256
	s_nop 1
	v_cvt_pk_bf16_f32 v32, v72, v73
	v_cvt_pk_bf16_f32 v33, v70, v71
	v_cvt_pk_bf16_f32 v34, v58, v59
	v_cvt_pk_bf16_f32 v35, v60, v61

; __device__ __forceinline__ u32x4 pack8bf(const f32x4 a, const f32x4 b) { u32x4 w; w.x = cvt_pk_bf16(a[0], a[1]); w.y = cvt_pk_bf16(a[2], a[3]); w.z = cvt_pk_bf16(b[0], b[1]); w.w = cvt_pk_bf16(b[2], b[3]); return w; }
; __device__ __forceinline__ float rms_scale(const float* ssq, int row, int which) {
;     const f32x4 a = *(const f32x4*)(ssq + (size_t)row * 16 + which * 8), b = *(const f32x4*)(ssq + (size_t)row * 16 + which * 8 + 4);
;     const float s = ((a[0] + a[1]) + (a[2] + a[3])) + ((b[0] + b[1]) + (b[2] + b[3]));
;     return 1.0f / sqrtf(s * (1.0f / 512.0f) + RMS_EPS);
;     __device__ __forceinline__ void operator()(EPI_ARGS) const {
;     ...
;             for (int m = 0; m < 4; ++m) { const int row = row0 + ai * HALF + m * 16; const float rs = rms_scale(ssq, row, 0);
;                 if (u.pn < 8) {
; #pragma unroll
;                     for (int bj = 0; bj < 2; ++bj) { const int h = 2 * u.pn + bj;
;                         *(u32x4*)(Q + ((size_t)h * NTOK + row) * 192 + 32 * wc + 8 * fq) = pack8bf(acc[ai][bj][m][0] * rs, acc[ai][bj][m][1] * rs); }
;                 } else { const int fi = 16 * (wc & 1) + 4 * fq;
;                     const f32x4 c4 = *(const f32x4*)(cs + (size_t)row * 32 + fi), s4 = *(const f32x4*)(sn + (size_t)row * 32 + fi);
; #pragma unroll
;                     for (int bj = 0; bj < 2; ++bj) { const int h = 4 * (u.pn - 8) + 2 * bj + (wc >> 1); const f32x4 v0 = acc[ai][bj][m][0] * rs, v1 = acc[ai][bj][m][1] * rs;
;                         *(u32x4*)(Q + ((size_t)h * NTOK + row) * 192 + 128 + 32 * (wc & 1) + 8 * fq) = pack8bf(v0 * c4 - v1 * s4, v1 * c4 + v0 * s4); } }
;             }
.LBB0_4081:
	v_lshl_add_u64 v[36:37], v[56:57], 0, v[136:137]
	global_store_dwordx4 v[36:37], v[32:35], off
	v_cvt_f32_i32_e32 v29, v29
	v_cvt_f32_i32_e32 v28, v28
	v_add_u32_e32 v32, 0xa0, v152
	v_ashrrev_i32_e32 v33, 31, v32
	v_lshlrev_b64 v[34:35], 6, v[32:33]
	v_lshl_add_u64 v[34:35], s[10:11], 0, v[34:35]
	v_mov_b32_e32 v38, v238
	v_mov_b32_e32 v39, v239
	v_mov_b32_e32 v40, v240
	v_mov_b32_e32 v41, v241
	v_mov_b32_e32 v42, v242
	v_mov_b32_e32 v43, v243
	v_mov_b32_e32 v44, v244
	v_mov_b32_e32 v45, v245
	v_cvt_f32_i32_e32 v31, v31
	v_cvt_f32_i32_e32 v30, v30
	v_cvt_f32_i32_e32 v25, v25
	v_cvt_f32_i32_e32 v24, v24
	v_pk_mul_f32 v[36:37], v[28:29], s[26:27] op_sel_hi:[1,0]
	v_pk_mul_f32 v[34:35], v[30:31], s[26:27] op_sel_hi:[1,0]
	v_cvt_f32_i32_e32 v21, v21
	v_pk_mul_f32 v[30:31], v[24:25], s[26:27] op_sel_hi:[1,0]
	v_cvt_f32_i32_e32 v20, v20
	v_cvt_f32_i32_e32 v19, v19
	v_cvt_f32_i32_e32 v18, v18
	v_cvt_f32_i32_e32 v17, v17
	v_cvt_f32_i32_e32 v16, v16
	v_cvt_f32_i32_e32 v27, v27
	v_cvt_f32_i32_e32 v26, v26
	v_cvt_f32_i32_e32 v23, v23
	v_cvt_f32_i32_e32 v22, v22
	v_pk_mul_f32 v[26:27], v[26:27], s[26:27] op_sel_hi:[1,0]
	v_pk_mul_f32 v[22:23], v[22:23], s[26:27] op_sel_hi:[1,0]
	v_add_f32_e32 v24, v38, v39
	v_add_f32_e32 v25, v40, v41
	v_add_f32_e32 v28, v42, v43
	v_add_f32_e32 v29, v44, v45
	v_add_f32_e32 v24, v24, v25
	v_add_f32_e32 v25, v28, v29
	v_add_f32_e32 v24, v24, v25
	v_fmamk_f32 v24, v24, 0x3b000000, v162
	v_rsq_f32_e32 v254, v24
	s_nop 1
	v_pk_mul_f32 v[24:25], v[20:21], s[26:27] op_sel_hi:[1,0]
	v_pk_mul_f32 v[20:21], v[18:19], s[26:27] op_sel_hi:[1,0]
	s_nop 1
	s_nop 1
	s_nop 1
	v_pk_mul_f32 v[28:29], v[16:17], s[26:27] op_sel_hi:[1,0]
	s_and_b64 vcc, exec, s[4:5]
	v_mov_b32_e32 v38, v254
	s_mov_b64 s[6:7], -1
	s_cbranch_vccnz .LBB0_4083
	v_lshlrev_b64 v[40:41], 7, v[32:33]
	v_lshl_add_u64 v[16:17], v[142:143], 0, v[40:41]
	global_load_dwordx4 v[16:19], v[16:17], off
	v_lshl_add_u64 v[40:41], v[140:141], 0, v[40:41]
	global_load_dwordx4 v[42:45], v[40:41], off
	s_or_b32 s6, s40, 2
	s_ashr_i32 s41, s40, 31
	s_ashr_i32 s7, s6, 31
	s_lshl_b64 s[44:45], s[40:41], 14
	s_lshl_b64 s[6:7], s[6:7], 14
	v_mov_b64_e32 v[40:41], s[20:21]
	v_lshl_add_u64 v[62:63], s[44:45], 0, v[32:33]
	v_lshl_add_u64 v[66:67], s[6:7], 0, v[32:33]
	v_pk_mul_f32 v[46:47], v[34:35], v[38:39] op_sel_hi:[1,0]
	v_pk_mul_f32 v[48:49], v[36:37], v[38:39] op_sel_hi:[1,0]
	v_pk_mul_f32 v[50:51], v[26:27], v[38:39] op_sel_hi:[1,0]
	v_pk_mul_f32 v[52:53], v[30:31], v[38:39] op_sel_hi:[1,0]
	v_pk_mul_f32 v[54:55], v[22:23], v[38:39] op_sel_hi:[1,0]
	v_pk_mul_f32 v[56:57], v[24:25], v[38:39] op_sel_hi:[1,0]
	v_pk_mul_f32 v[58:59], v[20:21], v[38:39] op_sel_hi:[1,0]
	v_pk_mul_f32 v[60:61], v[28:29], v[38:39] op_sel_hi:[1,0]
	v_mad_u64_u32 v[64:65], s[44:45], v62, s81, v[146:147]
	v_mad_u64_u32 v[40:41], s[6:7], v66, s81, v[40:41]
	v_mad_i32_i24 v65, v63, s81, v65
	v_mad_i32_i24 v41, v67, s81, v41
	v_lshl_add_u64 v[40:41], v[40:41], 0, s[24:25]
	s_mov_b64 s[6:7], 0
	s_waitcnt vmcnt(1)
	v_pk_mul_f32 v[62:63], v[50:51], v[18:19]
	v_pk_mul_f32 v[66:67], v[52:53], v[16:17]
	v_pk_mul_f32 v[68:69], v[46:47], v[18:19]
	v_pk_mul_f32 v[70:71], v[48:49], v[16:17]
	v_pk_mul_f32 v[72:73], v[58:59], v[18:19]
	v_pk_mul_f32 v[74:75], v[60:61], v[16:17]
	v_pk_mul_f32 v[18:19], v[54:55], v[18:19]
	v_pk_mul_f32 v[16:17], v[56:57], v[16:17]
	s_waitcnt vmcnt(0)
	v_pk_fma_f32 v[46:47], v[46:47], v[44:45], v[62:63] neg_lo:[0,0,1] neg_hi:[0,0,1]
	v_pk_fma_f32 v[48:49], v[48:49], v[42:43], v[66:67] neg_lo:[0,0,1] neg_hi:[0,0,1]
	v_pk_fma_f32 v[50:51], v[50:51], v[44:45], v[68:69]
	v_pk_fma_f32 v[52:53], v[52:53], v[42:43], v[70:71]
	v_pk_fma_f32 v[54:55], v[54:55], v[44:45], v[72:73] neg_lo:[0,0,1] neg_hi:[0,0,1]
	v_pk_fma_f32 v[56:57], v[56:57], v[42:43], v[74:75] neg_lo:[0,0,1] neg_hi:[0,0,1]
	v_pk_fma_f32 v[44:45], v[58:59], v[44:45], v[18:19]
	v_pk_fma_f32 v[42:43], v[60:61], v[42:43], v[16:17]
	v_cvt_pk_bf16_f32 v16, v48, v49
	v_cvt_pk_bf16_f32 v17, v46, v47
	v_cvt_pk_bf16_f32 v18, v52, v53
	v_cvt_pk_bf16_f32 v19, v50, v51
	global_store_dwordx4 v[64:65], v[16:19], off offset:256
	s_nop 1
	v_cvt_pk_bf16_f32 v16, v56, v57
	v_cvt_pk_bf16_f32 v17, v54, v55
	v_cvt_pk_bf16_f32 v18, v42, v43
	v_cvt_pk_bf16_f32 v19, v44, v45

; __device__ __forceinline__ u32x4 pack8bf(const f32x4 a, const f32x4 b) { u32x4 w; w.x = cvt_pk_bf16(a[0], a[1]); w.y = cvt_pk_bf16(a[2], a[3]); w.z = cvt_pk_bf16(b[0], b[1]); w.w = cvt_pk_bf16(b[2], b[3]); return w; }
; __device__ __forceinline__ float rms_scale(const float* ssq, int row, int which) {
;     const f32x4 a = *(const f32x4*)(ssq + (size_t)row * 16 + which * 8), b = *(const f32x4*)(ssq + (size_t)row * 16 + which * 8 + 4);
;     const float s = ((a[0] + a[1]) + (a[2] + a[3])) + ((b[0] + b[1]) + (b[2] + b[3]));
;     return 1.0f / sqrtf(s * (1.0f / 512.0f) + RMS_EPS);
;     __device__ __forceinline__ void operator()(EPI_ARGS) const {
;     ...
;             for (int m = 0; m < 4; ++m) { const int row = row0 + ai * HALF + m * 16; const float rs = rms_scale(ssq, row, 0);
;                 if (u.pn < 8) {
; #pragma unroll
;                     for (int bj = 0; bj < 2; ++bj) { const int h = 2 * u.pn + bj;
;                         *(u32x4*)(Q + ((size_t)h * NTOK + row) * 192 + 32 * wc + 8 * fq) = pack8bf(acc[ai][bj][m][0] * rs, acc[ai][bj][m][1] * rs); }
;                 } else { const int fi = 16 * (wc & 1) + 4 * fq;
;                     const f32x4 c4 = *(const f32x4*)(cs + (size_t)row * 32 + fi), s4 = *(const f32x4*)(sn + (size_t)row * 32 + fi);
; #pragma unroll
;                     for (int bj = 0; bj < 2; ++bj) { const int h = 4 * (u.pn - 8) + 2 * bj + (wc >> 1); const f32x4 v0 = acc[ai][bj][m][0] * rs, v1 = acc[ai][bj][m][1] * rs;
;                         *(u32x4*)(Q + ((size_t)h * NTOK + row) * 192 + 128 + 32 * (wc & 1) + 8 * fq) = pack8bf(v0 * c4 - v1 * s4, v1 * c4 + v0 * s4); } }
;             }
.LBB0_4085:
	v_lshl_add_u64 v[20:21], v[40:41], 0, v[136:137]
	global_store_dwordx4 v[20:21], v[16:19], off
	v_cvt_f32_i32_e32 v13, v13
	v_cvt_f32_i32_e32 v12, v12
	v_add_u32_e32 v16, 0xb0, v152
	v_ashrrev_i32_e32 v17, 31, v16
	v_lshlrev_b64 v[18:19], 6, v[16:17]
	v_lshl_add_u64 v[18:19], s[10:11], 0, v[18:19]
	v_mov_b32_e32 v22, v246
	v_mov_b32_e32 v23, v247
	v_mov_b32_e32 v24, v248
	v_mov_b32_e32 v25, v249
	v_mov_b32_e32 v26, v250
	v_mov_b32_e32 v27, v251
	v_mov_b32_e32 v28, v252
	v_mov_b32_e32 v29, v253
	v_cvt_f32_i32_e32 v15, v15
	v_cvt_f32_i32_e32 v14, v14
	v_cvt_f32_i32_e32 v9, v9
	v_cvt_f32_i32_e32 v8, v8
	v_pk_mul_f32 v[20:21], v[12:13], s[26:27] op_sel_hi:[1,0]
	v_pk_mul_f32 v[18:19], v[14:15], s[26:27] op_sel_hi:[1,0]
	v_cvt_f32_i32_e32 v5, v5
	v_pk_mul_f32 v[14:15], v[8:9], s[26:27] op_sel_hi:[1,0]
	v_cvt_f32_i32_e32 v4, v4
	v_cvt_f32_i32_e32 v3, v3
	v_cvt_f32_i32_e32 v2, v2
	v_cvt_f32_i32_e32 v1, v1
	v_cvt_f32_i32_e32 v0, v0
	v_cvt_f32_i32_e32 v11, v11
	v_cvt_f32_i32_e32 v10, v10
	v_cvt_f32_i32_e32 v7, v7
	v_cvt_f32_i32_e32 v6, v6
	v_pk_mul_f32 v[10:11], v[10:11], s[26:27] op_sel_hi:[1,0]
	v_pk_mul_f32 v[6:7], v[6:7], s[26:27] op_sel_hi:[1,0]
	v_add_f32_e32 v8, v22, v23
	v_add_f32_e32 v9, v24, v25
	v_add_f32_e32 v12, v26, v27
	v_add_f32_e32 v13, v28, v29
	v_add_f32_e32 v8, v8, v9
	v_add_f32_e32 v9, v12, v13
	v_add_f32_e32 v8, v8, v9
	v_fmamk_f32 v8, v8, 0x3b000000, v162
	v_rsq_f32_e32 v254, v8
	s_nop 1
	v_pk_mul_f32 v[8:9], v[4:5], s[26:27] op_sel_hi:[1,0]
	v_pk_mul_f32 v[4:5], v[2:3], s[26:27] op_sel_hi:[1,0]
	s_nop 1
	s_nop 1
	s_nop 1
	v_pk_mul_f32 v[12:13], v[0:1], s[26:27] op_sel_hi:[1,0]
	s_and_b64 vcc, exec, s[4:5]
	v_mov_b32_e32 v22, v254
	s_mov_b64 s[4:5], -1
	s_cbranch_vccnz .LBB0_4087
	v_lshlrev_b64 v[24:25], 7, v[16:17]
	v_lshl_add_u64 v[0:1], v[142:143], 0, v[24:25]
	global_load_dwordx4 v[0:3], v[0:1], off
	v_lshl_add_u64 v[24:25], v[140:141], 0, v[24:25]
	global_load_dwordx4 v[26:29], v[24:25], off
	s_or_b32 s4, s40, 2
	s_ashr_i32 s41, s40, 31
	s_ashr_i32 s5, s4, 31
	s_lshl_b64 s[6:7], s[40:41], 14
	s_lshl_b64 s[4:5], s[4:5], 14
	v_mov_b64_e32 v[24:25], s[20:21]
	v_lshl_add_u64 v[46:47], s[6:7], 0, v[16:17]
	v_lshl_add_u64 v[50:51], s[4:5], 0, v[16:17]
	v_pk_mul_f32 v[30:31], v[18:19], v[22:23] op_sel_hi:[1,0]
	v_pk_mul_f32 v[32:33], v[20:21], v[22:23] op_sel_hi:[1,0]
	v_pk_mul_f32 v[34:35], v[10:11], v[22:23] op_sel_hi:[1,0]
	v_pk_mul_f32 v[36:37], v[14:15], v[22:23] op_sel_hi:[1,0]
	v_pk_mul_f32 v[38:39], v[6:7], v[22:23] op_sel_hi:[1,0]
	v_pk_mul_f32 v[40:41], v[8:9], v[22:23] op_sel_hi:[1,0]
	v_pk_mul_f32 v[42:43], v[4:5], v[22:23] op_sel_hi:[1,0]
	v_pk_mul_f32 v[44:45], v[12:13], v[22:23] op_sel_hi:[1,0]
	v_mad_u64_u32 v[48:49], s[6:7], v46, s81, v[146:147]
	v_mad_u64_u32 v[24:25], s[4:5], v50, s81, v[24:25]
	v_mad_i32_i24 v49, v47, s81, v49
	v_mad_i32_i24 v25, v51, s81, v25
	v_lshl_add_u64 v[24:25], v[24:25], 0, s[24:25]
	s_mov_b64 s[4:5], 0
	s_waitcnt vmcnt(1)
	v_pk_mul_f32 v[46:47], v[34:35], v[2:3]
	v_pk_mul_f32 v[50:51], v[36:37], v[0:1]
	v_pk_mul_f32 v[52:53], v[30:31], v[2:3]
	v_pk_mul_f32 v[54:55], v[32:33], v[0:1]
	v_pk_mul_f32 v[56:57], v[42:43], v[2:3]
	v_pk_mul_f32 v[58:59], v[44:45], v[0:1]
	v_pk_mul_f32 v[2:3], v[38:39], v[2:3]
	v_pk_mul_f32 v[0:1], v[40:41], v[0:1]
	s_waitcnt vmcnt(0)
	v_pk_fma_f32 v[30:31], v[30:31], v[28:29], v[46:47] neg_lo:[0,0,1] neg_hi:[0,0,1]
	v_pk_fma_f32 v[32:33], v[32:33], v[26:27], v[50:51] neg_lo:[0,0,1] neg_hi:[0,0,1]
	v_pk_fma_f32 v[34:35], v[34:35], v[28:29], v[52:53]
	v_pk_fma_f32 v[36:37], v[36:37], v[26:27], v[54:55]
	v_pk_fma_f32 v[38:39], v[38:39], v[28:29], v[56:57] neg_lo:[0,0,1] neg_hi:[0,0,1]
	v_pk_fma_f32 v[40:41], v[40:41], v[26:27], v[58:59] neg_lo:[0,0,1] neg_hi:[0,0,1]
	v_pk_fma_f32 v[28:29], v[42:43], v[28:29], v[2:3]
	v_pk_fma_f32 v[26:27], v[44:45], v[26:27], v[0:1]
	v_cvt_pk_bf16_f32 v0, v32, v33
	v_cvt_pk_bf16_f32 v1, v30, v31
	v_cvt_pk_bf16_f32 v2, v36, v37
	v_cvt_pk_bf16_f32 v3, v34, v35
	global_store_dwordx4 v[48:49], v[0:3], off offset:256
	s_nop 1
	v_cvt_pk_bf16_f32 v0, v40, v41
	v_cvt_pk_bf16_f32 v1, v38, v39
	v_cvt_pk_bf16_f32 v2, v26, v27
	v_cvt_pk_bf16_f32 v3, v28, v29

; __device__ __forceinline__ void ln_stats(const float* st, int row, float& mu, float& rs) { const f32x2 s = *(const f32x2*)(st + 2 * (size_t)row); mu = s[0] * (1.0f / DM); rs = 1.0f / sqrtf(s[1] * (1.0f / DM) - mu * mu + LN_EPS); }
;     __device__ __forceinline__ void operator()(EPI_ARGS) const {
;     ...
;             for (int m = 0; m < 4; ++m) { const int row = row0 + ai * HALF + m * 16; float mu, rs; ln_stats(st, row, mu, rs);
;                 const f32x4 c4 = *(const f32x4*)(cs + (size_t)row * 32 + fi), s4 = *(const f32x4*)(sn + (size_t)row * 32 + fi);
;                 const f32x4 v0 = (acc[ai][0][m][0] - c0 * mu) * rs + d0, v1 = (acc[ai][0][m][1] - c1 * mu) * rs + d1;
;                 *(u32x2*)((unsigned char*)KPE + (size_t)row * 64 + 32 * (fq & 1) + 8 * (2 * wc + (fq >> 1))) = pack8fp8(v0 * c4 - v1 * s4, v1 * c4 + v0 * s4); }
.LBB0_4117:
	v_lshl_add_u32 v102, s2, 8, v104
	v_ashrrev_i32_e32 v103, 31, v102
	v_lshl_add_u64 v[24:25], v[102:103], 3, s[12:13]
	global_load_dwordx2 v[118:119], v[24:25], off
	global_load_dwordx4 v[36:39], v[94:95], off
	global_load_dwordx4 v[32:35], v[94:95], off offset:16
	global_load_dwordx4 v[28:31], v[96:97], off
	s_nop 0
	global_load_dwordx4 v[24:27], v[96:97], off offset:16
	v_lshlrev_b64 v[114:115], 7, v[102:103]
	v_lshl_add_u64 v[110:111], v[90:91], 0, v[114:115]
	global_load_dwordx4 v[110:113], v[110:111], off
	v_lshl_add_u64 v[114:115], v[88:89], 0, v[114:115]
	global_load_dwordx4 v[114:117], v[114:115], off
	v_lshlrev_b64 v[124:125], 6, v[102:103]
	v_cvt_f32_i32_e32 v73, v73
	v_cvt_f32_i32_e32 v72, v72
	v_cvt_f32_i32_e32 v77, v77
	v_cvt_f32_i32_e32 v76, v76
	v_cvt_f32_i32_e32 v79, v79
	v_cvt_f32_i32_e32 v78, v78
	v_cvt_f32_i32_e32 v75, v75
	v_cvt_f32_i32_e32 v74, v74
	v_mov_b32_e32 v120, 0
	v_mov_b32_e32 v121, 0
	v_or_b32_e32 v122, 16, v102
	v_cvt_f32_i32_e32 v65, v65
	v_cvt_f32_i32_e32 v64, v64
	v_cvt_f32_i32_e32 v69, v69
	v_cvt_f32_i32_e32 v68, v68
	v_cvt_f32_i32_e32 v71, v71
	v_cvt_f32_i32_e32 v70, v70
	v_cvt_f32_i32_e32 v67, v67
	v_cvt_f32_i32_e32 v66, v66
	v_cvt_f32_i32_e32 v57, v57
	v_cvt_f32_i32_e32 v56, v56
	v_cvt_f32_i32_e32 v61, v61
	v_cvt_f32_i32_e32 v60, v60
	v_cvt_f32_i32_e32 v63, v63
	v_cvt_f32_i32_e32 v62, v62
	v_cvt_f32_i32_e32 v59, v59
	v_cvt_f32_i32_e32 v58, v58
	v_cvt_f32_i32_e32 v49, v49
	v_cvt_f32_i32_e32 v48, v48
	v_cvt_f32_i32_e32 v53, v53
	v_cvt_f32_i32_e32 v52, v52
	v_cvt_f32_i32_e32 v55, v55
	v_cvt_f32_i32_e32 v54, v54
	v_cvt_f32_i32_e32 v51, v51
	v_cvt_f32_i32_e32 v50, v50
	v_cvt_f32_i32_e32 v41, v41
	v_cvt_f32_i32_e32 v40, v40
	v_cvt_f32_i32_e32 v45, v45
	v_cvt_f32_i32_e32 v44, v44
	v_cvt_f32_i32_e32 v47, v47
	v_cvt_f32_i32_e32 v46, v46
	v_cvt_f32_i32_e32 v43, v43
	v_cvt_f32_i32_e32 v42, v42
	v_cvt_f32_i32_e32 v17, v17
	v_cvt_f32_i32_e32 v16, v16
	v_cvt_f32_i32_e32 v21, v21
	v_cvt_f32_i32_e32 v20, v20
	v_cvt_f32_i32_e32 v23, v23
	v_cvt_f32_i32_e32 v22, v22
	v_cvt_f32_i32_e32 v19, v19
	v_cvt_f32_i32_e32 v18, v18
	v_cvt_f32_i32_e32 v9, v9
	v_cvt_f32_i32_e32 v8, v8
	v_cvt_f32_i32_e32 v13, v13
	v_cvt_f32_i32_e32 v12, v12
	v_cvt_f32_i32_e32 v15, v15
	v_cvt_f32_i32_e32 v14, v14
	v_cvt_f32_i32_e32 v11, v11
	v_cvt_f32_i32_e32 v10, v10
	v_cvt_f32_i32_e32 v1, v1
	v_cvt_f32_i32_e32 v0, v0
	v_cvt_f32_i32_e32 v5, v5
	v_cvt_f32_i32_e32 v4, v4
	v_cvt_f32_i32_e32 v7, v7
	v_cvt_f32_i32_e32 v6, v6
	v_cvt_f32_i32_e32 v3, v3
	v_cvt_f32_i32_e32 v2, v2
	s_waitcnt vmcnt(0)
	v_pk_mul_f32 v[118:119], v[118:119], s[16:17] op_sel_hi:[1,0]
	s_nop 0
	v_fma_f32 v103, -v118, v118, v119
	v_add_f32_e32 v103, 0x3727c5ac, v103
	v_rsq_f32_e32 v254, v103
	v_pk_mul_f32 v[126:127], v[36:37], v[118:119] op_sel_hi:[1,0]
	v_pk_mul_f32 v[128:129], v[38:39], v[118:119] op_sel_hi:[1,0]
	v_pk_mul_f32 v[130:131], v[34:35], v[118:119] op_sel_hi:[1,0]
	v_pk_mul_f32 v[118:119], v[32:33], v[118:119] op_sel_hi:[1,0]
	v_pk_fma_f32 v[76:77], v[76:77], s[18:19], v[126:127] op_sel_hi:[1,0,1] neg_lo:[0,0,1] neg_hi:[0,0,1]
	v_pk_fma_f32 v[72:73], v[72:73], s[18:19], v[118:119] op_sel_hi:[1,0,1] neg_lo:[0,0,1] neg_hi:[0,0,1]
	v_pk_fma_f32 v[78:79], v[78:79], s[18:19], v[128:129] op_sel_hi:[1,0,1] neg_lo:[0,0,1] neg_hi:[0,0,1]
	v_pk_fma_f32 v[74:75], v[74:75], s[18:19], v[130:131] op_sel_hi:[1,0,1] neg_lo:[0,0,1] neg_hi:[0,0,1]
	s_nop 1
	s_nop 1
	v_mov_b32_e32 v118, v254
	v_pk_fma_f32 v[76:77], v[76:77], v[118:119], v[28:29] op_sel_hi:[1,0,1]
	v_pk_fma_f32 v[72:73], v[72:73], v[118:119], v[24:25] op_sel_hi:[1,0,1]
	v_pk_fma_f32 v[78:79], v[78:79], v[118:119], v[30:31] op_sel_hi:[1,0,1]
	v_pk_fma_f32 v[74:75], v[74:75], v[118:119], v[26:27] op_sel_hi:[1,0,1]
	v_pk_mul_f32 v[118:119], v[110:111], v[72:73]
	v_pk_mul_f32 v[110:111], v[110:111], v[76:77]
	v_pk_fma_f32 v[76:77], v[114:115], v[76:77], v[118:119] neg_lo:[0,0,1] neg_hi:[0,0,1]
	v_pk_fma_f32 v[72:73], v[114:115], v[72:73], v[110:111]
	v_med3_f32 v76, v76, s61, v109
	v_med3_f32 v77, v77, s61, v109
	v_med3_f32 v72, v72, s61, v109
	v_med3_f32 v73, v73, s61, v109
	v_cvt_pk_fp8_f32 v120, v76, v77
	v_cvt_pk_fp8_f32 v121, v72, v73
	v_pk_mul_f32 v[126:127], v[112:113], v[74:75]
	v_pk_mul_f32 v[112:113], v[112:113], v[78:79]
	v_pk_fma_f32 v[78:79], v[116:117], v[78:79], v[126:127] neg_lo:[0,0,1] neg_hi:[0,0,1]
	v_pk_fma_f32 v[74:75], v[116:117], v[74:75], v[112:113]
	v_med3_f32 v78, v78, s61, v109
	v_med3_f32 v79, v79, s61, v109
	v_med3_f32 v72, v74, s61, v109
	v_med3_f32 v73, v75, s61, v109
	v_cvt_pk_fp8_f32 v120, v78, v79 op_sel:[0,0,1]
	v_cvt_pk_fp8_f32 v121, v72, v73 op_sel:[0,0,1]
	v_ashrrev_i32_e32 v123, 31, v122
	v_lshl_add_u64 v[72:73], v[92:93], 0, v[124:125]
	v_lshl_add_u64 v[74:75], v[122:123], 3, s[12:13]
	global_store_dwordx2 v[72:73], v[120:121], off
	global_load_dwordx2 v[110:111], v[74:75], off
	v_lshlrev_b64 v[76:77], 7, v[122:123]
	v_lshl_add_u64 v[72:73], v[90:91], 0, v[76:77]
	global_load_dwordx4 v[72:75], v[72:73], off
	v_lshl_add_u64 v[76:77], v[88:89], 0, v[76:77]
	global_load_dwordx4 v[76:79], v[76:77], off
	v_mov_b32_e32 v112, 0
	v_mov_b32_e32 v113, 0
	v_or_b32_e32 v114, 32, v102
	v_ashrrev_i32_e32 v115, 31, v114
	s_waitcnt vmcnt(2)
; __device__ __forceinline__ void ln_stats(const float* st, int row, float& mu, float& rs) { const f32x2 s = *(const f32x2*)(st + 2 * (size_t)row); mu = s[0] * (1.0f / DM); rs = 1.0f / sqrtf(s[1] * (1.0f / DM) - mu * mu + LN_EPS); }
;     __device__ __forceinline__ void operator()(EPI_ARGS) const {
;     ...
;             for (int m = 0; m < 4; ++m) { const int row = row0 + ai * HALF + m * 16; float mu, rs; ln_stats(st, row, mu, rs);
;                 const f32x4 c4 = *(const f32x4*)(cs + (size_t)row * 32 + fi), s4 = *(const f32x4*)(sn + (size_t)row * 32 + fi);
;                 const f32x4 v0 = (acc[ai][0][m][0] - c0 * mu) * rs + d0, v1 = (acc[ai][0][m][1] - c1 * mu) * rs + d1;
;                 *(u32x2*)((unsigned char*)KPE + (size_t)row * 64 + 32 * (fq & 1) + 8 * (2 * wc + (fq >> 1))) = pack8fp8(v0 * c4 - v1 * s4, v1 * c4 + v0 * s4); }
	v_pk_mul_f32 v[110:111], v[110:111], s[16:17] op_sel_hi:[1,0]
	s_nop 0
	v_fma_f32 v103, -v110, v110, v111
	v_add_f32_e32 v103, 0x3727c5ac, v103
	v_rsq_f32_e32 v254, v103
	v_pk_mul_f32 v[116:117], v[36:37], v[110:111] op_sel_hi:[1,0]
	v_pk_mul_f32 v[118:119], v[38:39], v[110:111] op_sel_hi:[1,0]
	v_pk_mul_f32 v[120:121], v[34:35], v[110:111] op_sel_hi:[1,0]
	v_pk_mul_f32 v[110:111], v[32:33], v[110:111] op_sel_hi:[1,0]
	v_pk_fma_f32 v[68:69], v[68:69], s[18:19], v[116:117] op_sel_hi:[1,0,1] neg_lo:[0,0,1] neg_hi:[0,0,1]
	v_pk_fma_f32 v[64:65], v[64:65], s[18:19], v[110:111] op_sel_hi:[1,0,1] neg_lo:[0,0,1] neg_hi:[0,0,1]
	v_pk_fma_f32 v[70:71], v[70:71], s[18:19], v[118:119] op_sel_hi:[1,0,1] neg_lo:[0,0,1] neg_hi:[0,0,1]
	v_pk_fma_f32 v[66:67], v[66:67], s[18:19], v[120:121] op_sel_hi:[1,0,1] neg_lo:[0,0,1] neg_hi:[0,0,1]
	s_nop 1
	s_nop 1
	v_mov_b32_e32 v110, v254
	v_pk_fma_f32 v[68:69], v[68:69], v[110:111], v[28:29] op_sel_hi:[1,0,1]
	v_pk_fma_f32 v[64:65], v[64:65], v[110:111], v[24:25] op_sel_hi:[1,0,1]
	v_pk_fma_f32 v[70:71], v[70:71], v[110:111], v[30:31] op_sel_hi:[1,0,1]
	v_pk_fma_f32 v[66:67], v[66:67], v[110:111], v[26:27] op_sel_hi:[1,0,1]
	s_waitcnt vmcnt(1)
	v_pk_mul_f32 v[110:111], v[72:73], v[64:65]
	v_pk_mul_f32 v[72:73], v[72:73], v[68:69]
	s_waitcnt vmcnt(0)
	v_pk_fma_f32 v[68:69], v[76:77], v[68:69], v[110:111] neg_lo:[0,0,1] neg_hi:[0,0,1]
	v_pk_fma_f32 v[64:65], v[76:77], v[64:65], v[72:73]
	v_med3_f32 v68, v68, s61, v109
	v_med3_f32 v69, v69, s61, v109
	v_med3_f32 v64, v64, s61, v109
	v_med3_f32 v65, v65, s61, v109
	v_cvt_pk_fp8_f32 v112, v68, v69
	v_cvt_pk_fp8_f32 v113, v64, v65
	v_pk_mul_f32 v[116:117], v[74:75], v[66:67]
	v_pk_mul_f32 v[74:75], v[74:75], v[70:71]
	v_pk_fma_f32 v[70:71], v[78:79], v[70:71], v[116:117] neg_lo:[0,0,1] neg_hi:[0,0,1]
	v_pk_fma_f32 v[66:67], v[78:79], v[66:67], v[74:75]
	v_med3_f32 v70, v70, s61, v109
	v_med3_f32 v71, v71, s61, v109
	v_med3_f32 v64, v66, s61, v109
	v_med3_f32 v65, v67, s61, v109
	v_cvt_pk_fp8_f32 v112, v70, v71 op_sel:[0,0,1]
	v_cvt_pk_fp8_f32 v113, v64, v65 op_sel:[0,0,1]
	v_lshlrev_b64 v[64:65], 6, v[122:123]
	v_lshl_add_u64 v[64:65], v[92:93], 0, v[64:65]
	v_lshl_add_u64 v[66:67], v[114:115], 3, s[12:13]
	global_store_dwordx2 v[64:65], v[112:113], off
	global_load_dwordx2 v[72:73], v[66:67], off
	v_lshlrev_b64 v[68:69], 7, v[114:115]
	v_lshl_add_u64 v[64:65], v[90:91], 0, v[68:69]
	global_load_dwordx4 v[64:67], v[64:65], off
	v_lshl_add_u64 v[68:69], v[88:89], 0, v[68:69]
	global_load_dwordx4 v[68:71], v[68:69], off
	v_mov_b32_e32 v74, 0
	v_mov_b32_e32 v75, 0
	v_or_b32_e32 v76, 48, v102
	v_ashrrev_i32_e32 v77, 31, v76
	s_waitcnt vmcnt(2)
	v_pk_mul_f32 v[72:73], v[72:73], s[16:17] op_sel_hi:[1,0]
	s_nop 0
	v_fma_f32 v103, -v72, v72, v73
	v_add_f32_e32 v103, 0x3727c5ac, v103
	v_rsq_f32_e32 v254, v103
	v_pk_mul_f32 v[78:79], v[36:37], v[72:73] op_sel_hi:[1,0]
	v_pk_mul_f32 v[110:111], v[38:39], v[72:73] op_sel_hi:[1,0]
	v_pk_mul_f32 v[112:113], v[34:35], v[72:73] op_sel_hi:[1,0]
	v_pk_mul_f32 v[72:73], v[32:33], v[72:73] op_sel_hi:[1,0]
	v_pk_fma_f32 v[60:61], v[60:61], s[18:19], v[78:79] op_sel_hi:[1,0,1] neg_lo:[0,0,1] neg_hi:[0,0,1]
	v_pk_fma_f32 v[56:57], v[56:57], s[18:19], v[72:73] op_sel_hi:[1,0,1] neg_lo:[0,0,1] neg_hi:[0,0,1]
	v_pk_fma_f32 v[62:63], v[62:63], s[18:19], v[110:111] op_sel_hi:[1,0,1] neg_lo:[0,0,1] neg_hi:[0,0,1]
	v_pk_fma_f32 v[58:59], v[58:59], s[18:19], v[112:113] op_sel_hi:[1,0,1] neg_lo:[0,0,1] neg_hi:[0,0,1]
	s_nop 1
	s_nop 1
	v_mov_b32_e32 v72, v254
	v_pk_fma_f32 v[60:61], v[60:61], v[72:73], v[28:29] op_sel_hi:[1,0,1]
	v_pk_fma_f32 v[56:57], v[56:57], v[72:73], v[24:25] op_sel_hi:[1,0,1]
	v_pk_fma_f32 v[62:63], v[62:63], v[72:73], v[30:31] op_sel_hi:[1,0,1]
	v_pk_fma_f32 v[58:59], v[58:59], v[72:73], v[26:27] op_sel_hi:[1,0,1]
	s_waitcnt vmcnt(1)
	v_pk_mul_f32 v[72:73], v[64:65], v[56:57]
	v_pk_mul_f32 v[64:65], v[64:65], v[60:61]
	s_waitcnt vmcnt(0)
	v_pk_fma_f32 v[60:61], v[68:69], v[60:61], v[72:73] neg_lo:[0,0,1] neg_hi:[0,0,1]
	v_pk_fma_f32 v[56:57], v[68:69], v[56:57], v[64:65]
	v_med3_f32 v60, v60, s61, v109
	v_med3_f32 v61, v61, s61, v109
	v_med3_f32 v56, v56, s61, v109
	v_med3_f32 v57, v57, s61, v109
	v_cvt_pk_fp8_f32 v74, v60, v61
	v_cvt_pk_fp8_f32 v75, v56, v57
	v_pk_mul_f32 v[78:79], v[66:67], v[58:59]
	v_pk_mul_f32 v[66:67], v[66:67], v[62:63]
	v_pk_fma_f32 v[62:63], v[70:71], v[62:63], v[78:79] neg_lo:[0,0,1] neg_hi:[0,0,1]
	v_pk_fma_f32 v[58:59], v[70:71], v[58:59], v[66:67]
	v_med3_f32 v62, v62, s61, v109
	v_med3_f32 v63, v63, s61, v109
	v_med3_f32 v56, v58, s61, v109
	v_med3_f32 v57, v59, s61, v109
	v_cvt_pk_fp8_f32 v74, v62, v63 op_sel:[0,0,1]
	v_cvt_pk_fp8_f32 v75, v56, v57 op_sel:[0,0,1]
	v_lshlrev_b64 v[56:57], 6, v[114:115]
	v_lshl_add_u64 v[56:57], v[92:93], 0, v[56:57]
	v_lshl_add_u64 v[58:59], v[76:77], 3, s[12:13]
	global_store_dwordx2 v[56:57], v[74:75], off
	global_load_dwordx2 v[64:65], v[58:59], off
	v_lshlrev_b64 v[60:61], 7, v[76:77]
	v_lshl_add_u64 v[56:57], v[90:91], 0, v[60:61]
	global_load_dwordx4 v[56:59], v[56:57], off
	v_lshl_add_u64 v[60:61], v[88:89], 0, v[60:61]
	global_load_dwordx4 v[60:63], v[60:61], off
	v_mov_b32_e32 v66, 0
	v_mov_b32_e32 v67, 0
	v_add_u32_e32 v68, 0x80, v102
	v_ashrrev_i32_e32 v69, 31, v68
	s_waitcnt vmcnt(2)
; __device__ __forceinline__ void ln_stats(const float* st, int row, float& mu, float& rs) { const f32x2 s = *(const f32x2*)(st + 2 * (size_t)row); mu = s[0] * (1.0f / DM); rs = 1.0f / sqrtf(s[1] * (1.0f / DM) - mu * mu + LN_EPS); }
;     __device__ __forceinline__ void operator()(EPI_ARGS) const {
;     ...
;             for (int m = 0; m < 4; ++m) { const int row = row0 + ai * HALF + m * 16; float mu, rs; ln_stats(st, row, mu, rs);
;                 const f32x4 c4 = *(const f32x4*)(cs + (size_t)row * 32 + fi), s4 = *(const f32x4*)(sn + (size_t)row * 32 + fi);
;                 const f32x4 v0 = (acc[ai][0][m][0] - c0 * mu) * rs + d0, v1 = (acc[ai][0][m][1] - c1 * mu) * rs + d1;
;                 *(u32x2*)((unsigned char*)KPE + (size_t)row * 64 + 32 * (fq & 1) + 8 * (2 * wc + (fq >> 1))) = pack8fp8(v0 * c4 - v1 * s4, v1 * c4 + v0 * s4); }
	v_pk_mul_f32 v[64:65], v[64:65], s[16:17] op_sel_hi:[1,0]
	s_nop 0
	v_fma_f32 v78, -v64, v64, v65
	v_add_f32_e32 v78, 0x3727c5ac, v78
	v_rsq_f32_e32 v254, v78
	v_pk_mul_f32 v[70:71], v[36:37], v[64:65] op_sel_hi:[1,0]
	v_pk_mul_f32 v[72:73], v[38:39], v[64:65] op_sel_hi:[1,0]
	v_pk_mul_f32 v[74:75], v[34:35], v[64:65] op_sel_hi:[1,0]
	v_pk_mul_f32 v[64:65], v[32:33], v[64:65] op_sel_hi:[1,0]
	v_pk_fma_f32 v[52:53], v[52:53], s[18:19], v[70:71] op_sel_hi:[1,0,1] neg_lo:[0,0,1] neg_hi:[0,0,1]
	v_pk_fma_f32 v[48:49], v[48:49], s[18:19], v[64:65] op_sel_hi:[1,0,1] neg_lo:[0,0,1] neg_hi:[0,0,1]
	v_pk_fma_f32 v[54:55], v[54:55], s[18:19], v[72:73] op_sel_hi:[1,0,1] neg_lo:[0,0,1] neg_hi:[0,0,1]
	v_pk_fma_f32 v[50:51], v[50:51], s[18:19], v[74:75] op_sel_hi:[1,0,1] neg_lo:[0,0,1] neg_hi:[0,0,1]
	s_nop 1
	s_nop 1
	v_mov_b32_e32 v64, v254
	v_pk_fma_f32 v[52:53], v[52:53], v[64:65], v[28:29] op_sel_hi:[1,0,1]
	v_pk_fma_f32 v[48:49], v[48:49], v[64:65], v[24:25] op_sel_hi:[1,0,1]
	v_pk_fma_f32 v[54:55], v[54:55], v[64:65], v[30:31] op_sel_hi:[1,0,1]
	v_pk_fma_f32 v[50:51], v[50:51], v[64:65], v[26:27] op_sel_hi:[1,0,1]
	s_waitcnt vmcnt(1)
	v_pk_mul_f32 v[64:65], v[56:57], v[48:49]
	v_pk_mul_f32 v[56:57], v[56:57], v[52:53]
	s_waitcnt vmcnt(0)
	v_pk_fma_f32 v[52:53], v[60:61], v[52:53], v[64:65] neg_lo:[0,0,1] neg_hi:[0,0,1]
	v_pk_fma_f32 v[48:49], v[60:61], v[48:49], v[56:57]
	v_med3_f32 v52, v52, s61, v109
	v_med3_f32 v53, v53, s61, v109
	v_med3_f32 v48, v48, s61, v109
	v_med3_f32 v49, v49, s61, v109
	v_cvt_pk_fp8_f32 v66, v52, v53
	v_cvt_pk_fp8_f32 v67, v48, v49
	v_pk_mul_f32 v[70:71], v[58:59], v[50:51]
	v_pk_mul_f32 v[58:59], v[58:59], v[54:55]
	v_pk_fma_f32 v[54:55], v[62:63], v[54:55], v[70:71] neg_lo:[0,0,1] neg_hi:[0,0,1]
	v_pk_fma_f32 v[50:51], v[62:63], v[50:51], v[58:59]
	v_med3_f32 v54, v54, s61, v109
	v_med3_f32 v55, v55, s61, v109
	v_med3_f32 v48, v50, s61, v109
	v_med3_f32 v49, v51, s61, v109
	v_cvt_pk_fp8_f32 v66, v54, v55 op_sel:[0,0,1]
	v_cvt_pk_fp8_f32 v67, v48, v49 op_sel:[0,0,1]
	v_lshlrev_b64 v[48:49], 6, v[76:77]
	v_lshl_add_u64 v[48:49], v[92:93], 0, v[48:49]
	v_lshl_add_u64 v[50:51], v[68:69], 3, s[12:13]
	global_store_dwordx2 v[48:49], v[66:67], off
	global_load_dwordx2 v[56:57], v[50:51], off
	v_lshlrev_b64 v[52:53], 7, v[68:69]
	v_lshl_add_u64 v[48:49], v[90:91], 0, v[52:53]
	global_load_dwordx4 v[48:51], v[48:49], off
	v_lshl_add_u64 v[52:53], v[88:89], 0, v[52:53]
	global_load_dwordx4 v[52:55], v[52:53], off
	v_mov_b32_e32 v58, 0
	v_mov_b32_e32 v59, 0
	v_add_u32_e32 v60, 0x90, v102
	v_ashrrev_i32_e32 v61, 31, v60
	s_waitcnt vmcnt(2)
	v_pk_mul_f32 v[56:57], v[56:57], s[16:17] op_sel_hi:[1,0]
	s_nop 0
	v_fma_f32 v70, -v56, v56, v57
	v_add_f32_e32 v70, 0x3727c5ac, v70
	v_rsq_f32_e32 v254, v70
	v_pk_mul_f32 v[62:63], v[36:37], v[56:57] op_sel_hi:[1,0]
	v_pk_mul_f32 v[64:65], v[38:39], v[56:57] op_sel_hi:[1,0]
	v_pk_mul_f32 v[66:67], v[34:35], v[56:57] op_sel_hi:[1,0]
	v_pk_mul_f32 v[56:57], v[32:33], v[56:57] op_sel_hi:[1,0]
	v_pk_fma_f32 v[44:45], v[44:45], s[18:19], v[62:63] op_sel_hi:[1,0,1] neg_lo:[0,0,1] neg_hi:[0,0,1]
	v_pk_fma_f32 v[40:41], v[40:41], s[18:19], v[56:57] op_sel_hi:[1,0,1] neg_lo:[0,0,1] neg_hi:[0,0,1]
	v_pk_fma_f32 v[46:47], v[46:47], s[18:19], v[64:65] op_sel_hi:[1,0,1] neg_lo:[0,0,1] neg_hi:[0,0,1]
	v_pk_fma_f32 v[42:43], v[42:43], s[18:19], v[66:67] op_sel_hi:[1,0,1] neg_lo:[0,0,1] neg_hi:[0,0,1]
	s_nop 1
	s_nop 1
	v_mov_b32_e32 v56, v254
	v_pk_fma_f32 v[44:45], v[44:45], v[56:57], v[28:29] op_sel_hi:[1,0,1]
	v_pk_fma_f32 v[40:41], v[40:41], v[56:57], v[24:25] op_sel_hi:[1,0,1]
	v_pk_fma_f32 v[46:47], v[46:47], v[56:57], v[30:31] op_sel_hi:[1,0,1]
	v_pk_fma_f32 v[42:43], v[42:43], v[56:57], v[26:27] op_sel_hi:[1,0,1]
	s_waitcnt vmcnt(1)
	v_pk_mul_f32 v[56:57], v[48:49], v[40:41]
	v_pk_mul_f32 v[48:49], v[48:49], v[44:45]
	s_waitcnt vmcnt(0)
	v_pk_fma_f32 v[44:45], v[52:53], v[44:45], v[56:57] neg_lo:[0,0,1] neg_hi:[0,0,1]
	v_pk_fma_f32 v[40:41], v[52:53], v[40:41], v[48:49]
	v_med3_f32 v44, v44, s61, v109
	v_med3_f32 v45, v45, s61, v109
	v_med3_f32 v40, v40, s61, v109
	v_med3_f32 v41, v41, s61, v109
	v_cvt_pk_fp8_f32 v58, v44, v45
	v_cvt_pk_fp8_f32 v59, v40, v41
	v_pk_mul_f32 v[62:63], v[50:51], v[42:43]
	v_pk_mul_f32 v[50:51], v[50:51], v[46:47]
	v_pk_fma_f32 v[46:47], v[54:55], v[46:47], v[62:63] neg_lo:[0,0,1] neg_hi:[0,0,1]
	v_pk_fma_f32 v[42:43], v[54:55], v[42:43], v[50:51]
	v_med3_f32 v46, v46, s61, v109
	v_med3_f32 v47, v47, s61, v109
	v_med3_f32 v40, v42, s61, v109
	v_med3_f32 v41, v43, s61, v109
	v_cvt_pk_fp8_f32 v58, v46, v47 op_sel:[0,0,1]
	v_cvt_pk_fp8_f32 v59, v40, v41 op_sel:[0,0,1]
	v_lshlrev_b64 v[40:41], 6, v[68:69]
	v_lshl_add_u64 v[40:41], v[92:93], 0, v[40:41]
	v_lshl_add_u64 v[42:43], v[60:61], 3, s[12:13]
	global_store_dwordx2 v[40:41], v[58:59], off
	global_load_dwordx2 v[48:49], v[42:43], off
	v_lshlrev_b64 v[44:45], 7, v[60:61]
	v_lshl_add_u64 v[40:41], v[90:91], 0, v[44:45]
	global_load_dwordx4 v[40:43], v[40:41], off
	v_lshl_add_u64 v[44:45], v[88:89], 0, v[44:45]
	global_load_dwordx4 v[44:47], v[44:45], off
	v_mov_b32_e32 v50, 0
	v_mov_b32_e32 v51, 0
	v_add_u32_e32 v52, 0xa0, v102
	v_ashrrev_i32_e32 v53, 31, v52
	s_waitcnt vmcnt(2)
; __device__ __forceinline__ void ln_stats(const float* st, int row, float& mu, float& rs) { const f32x2 s = *(const f32x2*)(st + 2 * (size_t)row); mu = s[0] * (1.0f / DM); rs = 1.0f / sqrtf(s[1] * (1.0f / DM) - mu * mu + LN_EPS); }
;     __device__ __forceinline__ void operator()(EPI_ARGS) const {
;     ...
;             for (int m = 0; m < 4; ++m) { const int row = row0 + ai * HALF + m * 16; float mu, rs; ln_stats(st, row, mu, rs);
;                 const f32x4 c4 = *(const f32x4*)(cs + (size_t)row * 32 + fi), s4 = *(const f32x4*)(sn + (size_t)row * 32 + fi);
;                 const f32x4 v0 = (acc[ai][0][m][0] - c0 * mu) * rs + d0, v1 = (acc[ai][0][m][1] - c1 * mu) * rs + d1;
;                 *(u32x2*)((unsigned char*)KPE + (size_t)row * 64 + 32 * (fq & 1) + 8 * (2 * wc + (fq >> 1))) = pack8fp8(v0 * c4 - v1 * s4, v1 * c4 + v0 * s4); }
	v_pk_mul_f32 v[48:49], v[48:49], s[16:17] op_sel_hi:[1,0]
	s_nop 0
	v_fma_f32 v62, -v48, v48, v49
	v_add_f32_e32 v62, 0x3727c5ac, v62
	v_rsq_f32_e32 v254, v62
	v_pk_mul_f32 v[54:55], v[36:37], v[48:49] op_sel_hi:[1,0]
	v_pk_mul_f32 v[56:57], v[38:39], v[48:49] op_sel_hi:[1,0]
	v_pk_mul_f32 v[58:59], v[34:35], v[48:49] op_sel_hi:[1,0]
	v_pk_mul_f32 v[48:49], v[32:33], v[48:49] op_sel_hi:[1,0]
	v_pk_fma_f32 v[20:21], v[20:21], s[18:19], v[54:55] op_sel_hi:[1,0,1] neg_lo:[0,0,1] neg_hi:[0,0,1]
	v_pk_fma_f32 v[16:17], v[16:17], s[18:19], v[48:49] op_sel_hi:[1,0,1] neg_lo:[0,0,1] neg_hi:[0,0,1]
	v_pk_fma_f32 v[22:23], v[22:23], s[18:19], v[56:57] op_sel_hi:[1,0,1] neg_lo:[0,0,1] neg_hi:[0,0,1]
	v_pk_fma_f32 v[18:19], v[18:19], s[18:19], v[58:59] op_sel_hi:[1,0,1] neg_lo:[0,0,1] neg_hi:[0,0,1]
	s_nop 1
	s_nop 1
	v_mov_b32_e32 v48, v254
	v_pk_fma_f32 v[20:21], v[20:21], v[48:49], v[28:29] op_sel_hi:[1,0,1]
	v_pk_fma_f32 v[16:17], v[16:17], v[48:49], v[24:25] op_sel_hi:[1,0,1]
	v_pk_fma_f32 v[22:23], v[22:23], v[48:49], v[30:31] op_sel_hi:[1,0,1]
	v_pk_fma_f32 v[18:19], v[18:19], v[48:49], v[26:27] op_sel_hi:[1,0,1]
	s_waitcnt vmcnt(1)
	v_pk_mul_f32 v[48:49], v[40:41], v[16:17]
	v_pk_mul_f32 v[40:41], v[40:41], v[20:21]
	s_waitcnt vmcnt(0)
	v_pk_fma_f32 v[20:21], v[44:45], v[20:21], v[48:49] neg_lo:[0,0,1] neg_hi:[0,0,1]
	v_pk_fma_f32 v[16:17], v[44:45], v[16:17], v[40:41]
	v_med3_f32 v20, v20, s61, v109
	v_med3_f32 v21, v21, s61, v109
	v_med3_f32 v16, v16, s61, v109
	v_med3_f32 v17, v17, s61, v109
	v_cvt_pk_fp8_f32 v50, v20, v21
	v_cvt_pk_fp8_f32 v51, v16, v17
	v_pk_mul_f32 v[54:55], v[42:43], v[18:19]
	v_pk_mul_f32 v[42:43], v[42:43], v[22:23]
	v_pk_fma_f32 v[22:23], v[46:47], v[22:23], v[54:55] neg_lo:[0,0,1] neg_hi:[0,0,1]
	v_pk_fma_f32 v[18:19], v[46:47], v[18:19], v[42:43]
	v_med3_f32 v22, v22, s61, v109
	v_med3_f32 v23, v23, s61, v109
	v_med3_f32 v16, v18, s61, v109
	v_med3_f32 v17, v19, s61, v109
	v_cvt_pk_fp8_f32 v50, v22, v23 op_sel:[0,0,1]
	v_cvt_pk_fp8_f32 v51, v16, v17 op_sel:[0,0,1]
	v_lshlrev_b64 v[16:17], 6, v[60:61]
	v_lshl_add_u64 v[16:17], v[92:93], 0, v[16:17]
	v_lshl_add_u64 v[18:19], v[52:53], 3, s[12:13]
	global_store_dwordx2 v[16:17], v[50:51], off
	global_load_dwordx2 v[40:41], v[18:19], off
	v_lshlrev_b64 v[20:21], 7, v[52:53]
	v_lshl_add_u64 v[16:17], v[90:91], 0, v[20:21]
	global_load_dwordx4 v[16:19], v[16:17], off
	v_lshl_add_u64 v[20:21], v[88:89], 0, v[20:21]
	global_load_dwordx4 v[20:23], v[20:21], off
	v_mov_b32_e32 v42, 0
	v_mov_b32_e32 v43, 0
	v_add_u32_e32 v44, 0xb0, v102
	v_ashrrev_i32_e32 v45, 31, v44
	s_waitcnt vmcnt(2)
	v_pk_mul_f32 v[40:41], v[40:41], s[16:17] op_sel_hi:[1,0]
	s_nop 0
	v_fma_f32 v54, -v40, v40, v41
	v_add_f32_e32 v54, 0x3727c5ac, v54
	v_rsq_f32_e32 v254, v54
	v_pk_mul_f32 v[46:47], v[36:37], v[40:41] op_sel_hi:[1,0]
	v_pk_mul_f32 v[48:49], v[38:39], v[40:41] op_sel_hi:[1,0]
	v_pk_mul_f32 v[50:51], v[34:35], v[40:41] op_sel_hi:[1,0]
	v_pk_mul_f32 v[40:41], v[32:33], v[40:41] op_sel_hi:[1,0]
	v_pk_fma_f32 v[12:13], v[12:13], s[18:19], v[46:47] op_sel_hi:[1,0,1] neg_lo:[0,0,1] neg_hi:[0,0,1]
	v_pk_fma_f32 v[8:9], v[8:9], s[18:19], v[40:41] op_sel_hi:[1,0,1] neg_lo:[0,0,1] neg_hi:[0,0,1]
	v_pk_fma_f32 v[14:15], v[14:15], s[18:19], v[48:49] op_sel_hi:[1,0,1] neg_lo:[0,0,1] neg_hi:[0,0,1]
	v_pk_fma_f32 v[10:11], v[10:11], s[18:19], v[50:51] op_sel_hi:[1,0,1] neg_lo:[0,0,1] neg_hi:[0,0,1]
	s_nop 1
	s_nop 1
	v_mov_b32_e32 v40, v254
	v_pk_fma_f32 v[12:13], v[12:13], v[40:41], v[28:29] op_sel_hi:[1,0,1]
	v_pk_fma_f32 v[8:9], v[8:9], v[40:41], v[24:25] op_sel_hi:[1,0,1]
	v_pk_fma_f32 v[14:15], v[14:15], v[40:41], v[30:31] op_sel_hi:[1,0,1]
	v_pk_fma_f32 v[10:11], v[10:11], v[40:41], v[26:27] op_sel_hi:[1,0,1]
	s_waitcnt vmcnt(1)
	v_pk_mul_f32 v[40:41], v[16:17], v[8:9]
	v_pk_mul_f32 v[16:17], v[16:17], v[12:13]
	s_waitcnt vmcnt(0)
; __device__ __forceinline__ void ln_stats(const float* st, int row, float& mu, float& rs) { const f32x2 s = *(const f32x2*)(st + 2 * (size_t)row); mu = s[0] * (1.0f / DM); rs = 1.0f / sqrtf(s[1] * (1.0f / DM) - mu * mu + LN_EPS); }
;     __device__ __forceinline__ void operator()(EPI_ARGS) const {
;     ...
;             for (int m = 0; m < 4; ++m) { const int row = row0 + ai * HALF + m * 16; float mu, rs; ln_stats(st, row, mu, rs);
;                 const f32x4 c4 = *(const f32x4*)(cs + (size_t)row * 32 + fi), s4 = *(const f32x4*)(sn + (size_t)row * 32 + fi);
;                 const f32x4 v0 = (acc[ai][0][m][0] - c0 * mu) * rs + d0, v1 = (acc[ai][0][m][1] - c1 * mu) * rs + d1;
;                 *(u32x2*)((unsigned char*)KPE + (size_t)row * 64 + 32 * (fq & 1) + 8 * (2 * wc + (fq >> 1))) = pack8fp8(v0 * c4 - v1 * s4, v1 * c4 + v0 * s4); }
	v_pk_fma_f32 v[12:13], v[20:21], v[12:13], v[40:41] neg_lo:[0,0,1] neg_hi:[0,0,1]
	v_pk_fma_f32 v[8:9], v[20:21], v[8:9], v[16:17]
	v_med3_f32 v12, v12, s61, v109
	v_med3_f32 v13, v13, s61, v109
	v_med3_f32 v8, v8, s61, v109
	v_med3_f32 v9, v9, s61, v109
	v_cvt_pk_fp8_f32 v42, v12, v13
	v_cvt_pk_fp8_f32 v43, v8, v9
	v_pk_mul_f32 v[46:47], v[18:19], v[10:11]
	v_pk_mul_f32 v[18:19], v[18:19], v[14:15]
	v_pk_fma_f32 v[14:15], v[22:23], v[14:15], v[46:47] neg_lo:[0,0,1] neg_hi:[0,0,1]
	v_pk_fma_f32 v[10:11], v[22:23], v[10:11], v[18:19]
	v_med3_f32 v14, v14, s61, v109
	v_med3_f32 v15, v15, s61, v109
	v_med3_f32 v8, v10, s61, v109
	v_med3_f32 v9, v11, s61, v109
	v_cvt_pk_fp8_f32 v42, v14, v15 op_sel:[0,0,1]
	v_cvt_pk_fp8_f32 v43, v8, v9 op_sel:[0,0,1]
	v_lshlrev_b64 v[8:9], 6, v[52:53]
	v_lshl_add_u64 v[8:9], v[92:93], 0, v[8:9]
	v_lshl_add_u64 v[10:11], v[44:45], 3, s[12:13]
	global_store_dwordx2 v[8:9], v[42:43], off
	global_load_dwordx2 v[16:17], v[10:11], off
	v_lshlrev_b64 v[12:13], 7, v[44:45]
	v_lshl_add_u64 v[8:9], v[90:91], 0, v[12:13]
	global_load_dwordx4 v[8:11], v[8:9], off
	v_lshl_add_u64 v[12:13], v[88:89], 0, v[12:13]
	global_load_dwordx4 v[12:15], v[12:13], off
	v_mov_b32_e32 v18, 0
	v_mov_b32_e32 v19, 0
	s_waitcnt vmcnt(2)
	v_pk_mul_f32 v[16:17], v[16:17], s[16:17] op_sel_hi:[1,0]
	s_nop 0
	v_fma_f32 v40, -v16, v16, v17
	v_pk_mul_f32 v[20:21], v[36:37], v[16:17] op_sel_hi:[1,0]
	v_pk_mul_f32 v[22:23], v[38:39], v[16:17] op_sel_hi:[1,0]
	v_pk_mul_f32 v[34:35], v[34:35], v[16:17] op_sel_hi:[1,0]
	v_pk_mul_f32 v[16:17], v[32:33], v[16:17] op_sel_hi:[1,0]
	v_add_f32_e32 v32, 0x3727c5ac, v40
	v_mul_f32_e32 v33, 0x4f800000, v32
	v_cmp_gt_f32_e32 vcc, s60, v32
	v_pk_fma_f32 v[0:1], v[0:1], s[18:19], v[16:17] op_sel_hi:[1,0,1] neg_lo:[0,0,1] neg_hi:[0,0,1]
	v_pk_fma_f32 v[4:5], v[4:5], s[18:19], v[20:21] op_sel_hi:[1,0,1] neg_lo:[0,0,1] neg_hi:[0,0,1]
	v_cndmask_b32_e32 v32, v32, v33, vcc
	v_sqrt_f32_e32 v33, v32
	v_pk_fma_f32 v[6:7], v[6:7], s[18:19], v[22:23] op_sel_hi:[1,0,1] neg_lo:[0,0,1] neg_hi:[0,0,1]
	v_pk_fma_f32 v[2:3], v[2:3], s[18:19], v[34:35] op_sel_hi:[1,0,1] neg_lo:[0,0,1] neg_hi:[0,0,1]
	v_add_u32_e32 v16, -1, v33
	v_add_u32_e32 v17, 1, v33
	v_fma_f32 v20, -v16, v33, v32
	v_fma_f32 v21, -v17, v33, v32
	v_cmp_ge_f32_e64 s[2:3], 0, v20
	s_nop 1
	v_cndmask_b32_e64 v16, v33, v16, s[2:3]
	v_cmp_lt_f32_e64 s[2:3], 0, v21
	s_nop 1
	v_cndmask_b32_e64 v16, v16, v17, s[2:3]
	v_mul_f32_e32 v17, 0x37800000, v16
	v_cndmask_b32_e32 v16, v16, v17, vcc
	v_cmp_class_f32_e32 vcc, v32, v108
	s_nop 1
	v_cndmask_b32_e32 v16, v16, v32, vcc
	v_div_scale_f32 v17, s[2:3], v16, v16, 1.0
	v_rcp_f32_e32 v20, v17
	v_div_scale_f32 v21, vcc, 1.0, v16, 1.0
	v_fma_f32 v22, -v17, v20, 1.0
	v_fmac_f32_e32 v20, v22, v20
	v_mul_f32_e32 v22, v21, v20
	v_fma_f32 v23, -v17, v22, v21
	v_fmac_f32_e32 v22, v23, v20
	v_fma_f32 v17, -v17, v22, v21
	v_div_fmas_f32 v17, v17, v20, v22
	v_div_fixup_f32 v16, v17, v16, 1.0
	v_pk_fma_f32 v[4:5], v[4:5], v[16:17], v[28:29] op_sel_hi:[1,0,1]
	v_pk_fma_f32 v[0:1], v[0:1], v[16:17], v[24:25] op_sel_hi:[1,0,1]
	v_pk_fma_f32 v[6:7], v[6:7], v[16:17], v[30:31] op_sel_hi:[1,0,1]
	v_pk_fma_f32 v[2:3], v[2:3], v[16:17], v[26:27] op_sel_hi:[1,0,1]
	s_waitcnt vmcnt(1)
	v_pk_mul_f32 v[16:17], v[8:9], v[0:1]
	v_pk_mul_f32 v[8:9], v[8:9], v[4:5]
	s_waitcnt vmcnt(0)
	v_pk_fma_f32 v[4:5], v[12:13], v[4:5], v[16:17] neg_lo:[0,0,1] neg_hi:[0,0,1]
	v_pk_fma_f32 v[0:1], v[12:13], v[0:1], v[8:9]
	v_med3_f32 v4, v4, s61, v109
	v_med3_f32 v5, v5, s61, v109
	v_med3_f32 v0, v0, s61, v109
	v_med3_f32 v1, v1, s61, v109
	v_cvt_pk_fp8_f32 v18, v4, v5
	v_cvt_pk_fp8_f32 v19, v0, v1
	v_pk_mul_f32 v[20:21], v[10:11], v[2:3]
	v_pk_mul_f32 v[10:11], v[10:11], v[6:7]
	v_pk_fma_f32 v[6:7], v[14:15], v[6:7], v[20:21] neg_lo:[0,0,1] neg_hi:[0,0,1]
	v_pk_fma_f32 v[2:3], v[14:15], v[2:3], v[10:11]
	v_med3_f32 v6, v6, s61, v109
	v_med3_f32 v7, v7, s61, v109
	v_med3_f32 v0, v2, s61, v109
	v_med3_f32 v1, v3, s61, v109
	v_cvt_pk_fp8_f32 v18, v6, v7 op_sel:[0,0,1]
	v_cvt_pk_fp8_f32 v19, v0, v1 op_sel:[0,0,1]
	v_lshlrev_b64 v[0:1], 6, v[44:45]
	v_lshl_add_u64 v[0:1], v[92:93], 0, v[0:1]
	global_store_dwordx2 v[0:1], v[18:19], off
	s_andn2_b64 vcc, exec, s[20:21]
	s_mov_b64 s[2:3], -1
	s_cbranch_vccnz .LBB0_4104

; __device__ __forceinline__ float rms_scale(const float* ssq, int row, int which) {
;     const f32x4 a = *(const f32x4*)(ssq + (size_t)row * 16 + which * 8), b = *(const f32x4*)(ssq + (size_t)row * 16 + which * 8 + 4);
;     const float s = ((a[0] + a[1]) + (a[2] + a[3])) + ((b[0] + b[1]) + (b[2] + b[3]));
;     return 1.0f / sqrtf(s * (1.0f / 512.0f) + RMS_EPS);
;     __device__ __forceinline__ void operator()(EPI_ARGS) const {
;         const int row0 = u.pm * BM + wr * 64 + fr; bf16_t* dst = (u.pn < 8) ? KN : V; const int h0 = 2 * (u.pn & 7);
; #pragma unroll
;         for (int ai = 0; ai < 2; ++ai)
; #pragma unroll
;             for (int m = 0; m < 4; ++m) { const int row = row0 + ai * HALF + m * 16; const float rs = rms_scale(ssq, row, 1);
; #pragma unroll
;                 for (int bj = 0; bj < 2; ++bj)
;                     *(u32x2*)((unsigned char*)dst + ((size_t)(h0 + bj) * NTOK + row) * 128 + 64 * (wc >> 1) + 32 * (fq & 1) + 8 * ((2 * wc + (fq >> 1)) & 3)) = pack8fp8(acc[ai][bj][m][0] * rs, acc[ai][bj][m][1] * rs); }
.LBB0_4141:
	v_lshl_add_u32 v144, s4, 8, v146
	v_ashrrev_i32_e32 v145, 31, v144
	v_lshlrev_b64 v[154:155], 6, v[144:145]
	v_lshl_add_u64 v[158:159], s[8:9], 0, v[154:155]
	global_load_dwordx4 v[198:201], v[158:159], off offset:1056
	global_load_dwordx4 v[202:205], v[158:159], off offset:1072
	global_load_dwordx4 v[206:209], v[158:159], off offset:2080
	global_load_dwordx4 v[210:213], v[158:159], off offset:2096
	global_load_dwordx4 v[214:217], v[158:159], off offset:3104
	global_load_dwordx4 v[218:221], v[158:159], off offset:3120
	v_mov_b32_e32 v252, 0x2000
	v_mov_b32_e32 v253, 0
	v_lshl_add_u64 v[252:253], v[158:159], 0, v[252:253]
	global_load_dwordx4 v[222:225], v[252:253], off offset:32
	global_load_dwordx4 v[226:229], v[252:253], off offset:48
	global_load_dwordx4 v[230:233], v[252:253], off offset:1056
	global_load_dwordx4 v[234:237], v[252:253], off offset:1072
	global_load_dwordx4 v[238:241], v[252:253], off offset:2080
	global_load_dwordx4 v[242:245], v[252:253], off offset:2096
	global_load_dwordx4 v[246:249], v[252:253], off offset:3104
	global_load_dwordx4 v[250:253], v[252:253], off offset:3120
	global_load_dwordx4 v[154:157], v[158:159], off offset:32
	s_nop 0
	global_load_dwordx4 v[158:161], v[158:159], off offset:48
	s_cmp_gt_i32 s5, 7
	v_cvt_f32_i32_e32 v113, v113
	v_cvt_f32_i32_e32 v112, v112
	s_cselect_b64 vcc, -1, 0
	s_cmp_lt_i32 s5, 8
	s_cselect_b32 s25, s67, s7
	s_cselect_b32 s4, s66, s6
	s_lshl_b32 s5, s5, 15
	v_cvt_f32_i32_e32 v162, v114
	v_cndmask_b32_e32 v114, v151, v152, vcc
	s_and_b32 s14, s5, 0x38000
	v_pk_mul_f32 v[168:169], v[114:115], v[112:113] op_sel_hi:[0,1]
	v_lshl_add_u64 v[112:113], v[144:145], 0, s[14:15]
	v_lshlrev_b64 v[170:171], 7, v[112:113]
	v_cvt_f32_i32_e32 v127, v127
	v_cvt_f32_i32_e32 v126, v126
	v_cvt_f32_i32_e32 v125, v125
	v_cvt_f32_i32_e32 v124, v124
	v_cvt_f32_i32_e32 v123, v123
	v_cvt_f32_i32_e32 v122, v122
	v_cvt_f32_i32_e32 v121, v121
	v_cvt_f32_i32_e32 v120, v120
	v_cvt_f32_i32_e32 v119, v119
	v_cvt_f32_i32_e32 v118, v118
	v_cvt_f32_i32_e32 v117, v117
	v_cvt_f32_i32_e32 v116, v116
	v_cvt_f32_i32_e32 v163, v115
	v_pk_mul_f32 v[124:125], v[114:115], v[124:125] op_sel_hi:[0,1]
	v_pk_mul_f32 v[126:127], v[114:115], v[126:127] op_sel_hi:[0,1]
	v_pk_mul_f32 v[120:121], v[114:115], v[120:121] op_sel_hi:[0,1]
	v_pk_mul_f32 v[122:123], v[114:115], v[122:123] op_sel_hi:[0,1]
	v_pk_mul_f32 v[116:117], v[114:115], v[116:117] op_sel_hi:[0,1]
	v_pk_mul_f32 v[118:119], v[114:115], v[118:119] op_sel_hi:[0,1]
	v_pk_mul_f32 v[162:163], v[114:115], v[162:163] op_sel_hi:[0,1]
	s_add_u32 s4, s4, s70
	s_mov_b32 s37, s15
	s_addc_u32 s5, s25, 0
	s_or_b32 s36, s14, 0x4000
	v_mov_b32_e32 v166, 0
	v_mov_b32_e32 v167, 0
	v_mov_b32_e32 v164, 0
	v_mov_b32_e32 v165, 0
	v_cvt_f32_i32_e32 v111, v111
	v_cvt_f32_i32_e32 v110, v110
	v_cvt_f32_i32_e32 v109, v109
	v_cvt_f32_i32_e32 v108, v108
	v_cvt_f32_i32_e32 v107, v107
	v_cvt_f32_i32_e32 v106, v106
	v_cvt_f32_i32_e32 v105, v105
	v_cvt_f32_i32_e32 v104, v104
	v_cvt_f32_i32_e32 v103, v103
	v_cvt_f32_i32_e32 v102, v102
	v_cvt_f32_i32_e32 v101, v101
	v_cvt_f32_i32_e32 v100, v100
	v_cvt_f32_i32_e32 v99, v99
	v_cvt_f32_i32_e32 v98, v98
	v_cvt_f32_i32_e32 v97, v97
	v_cvt_f32_i32_e32 v96, v96
	v_cvt_f32_i32_e32 v95, v95
	v_cvt_f32_i32_e32 v94, v94
	v_cvt_f32_i32_e32 v93, v93
	v_cvt_f32_i32_e32 v92, v92
	v_cvt_f32_i32_e32 v91, v91
	v_cvt_f32_i32_e32 v90, v90
	v_cvt_f32_i32_e32 v89, v89
	v_cvt_f32_i32_e32 v88, v88
	v_cvt_f32_i32_e32 v87, v87
	v_cvt_f32_i32_e32 v86, v86
	v_cvt_f32_i32_e32 v85, v85
	v_cvt_f32_i32_e32 v84, v84
	v_cvt_f32_i32_e32 v83, v83
	v_cvt_f32_i32_e32 v82, v82
	v_cvt_f32_i32_e32 v81, v81
	v_cvt_f32_i32_e32 v80, v80
	v_cvt_f32_i32_e32 v77, v77
	v_cvt_f32_i32_e32 v76, v76
	v_cvt_f32_i32_e32 v73, v73
	v_cvt_f32_i32_e32 v72, v72
	s_waitcnt vmcnt(0)
	v_mov_b32_e32 v112, v154
	v_mov_b32_e32 v113, v158
	v_mov_b32_e32 v158, v155
	v_mov_b32_e32 v154, v156
	v_mov_b32_e32 v155, v160
	v_mov_b32_e32 v160, v157
	v_pk_add_f32 v[112:113], v[112:113], v[158:159]
	v_pk_add_f32 v[154:155], v[154:155], v[160:161]
	v_cvt_f32_i32_e32 v69, v69
	v_pk_add_f32 v[112:113], v[112:113], v[154:155]
	v_lshl_add_u64 v[154:155], v[144:145], 0, s[36:37]
	v_add_f32_e32 v112, v112, v113
	v_fmamk_f32 v112, v112, 0x3b000000, v149
	v_rsq_f32_e32 v254, v112
	v_cvt_f32_i32_e32 v68, v68
	v_cvt_f32_i32_e32 v65, v65
	v_lshl_add_u64 v[112:113], s[4:5], 0, v[136:137]
	v_lshl_add_u64 v[112:113], v[112:113], 0, v[138:139]
	v_cvt_f32_i32_e32 v64, v64
	v_cvt_f32_i32_e32 v79, v79
	v_cvt_f32_i32_e32 v78, v78
	v_cvt_f32_i32_e32 v75, v75
	v_cvt_f32_i32_e32 v74, v74
	v_lshl_add_u64 v[156:157], v[112:113], 0, v[170:171]
	v_cvt_f32_i32_e32 v71, v71
	v_cvt_f32_i32_e32 v70, v70
	v_mov_b32_e32 v158, v254
	v_pk_mul_f32 v[126:127], v[126:127], v[158:159] op_sel_hi:[1,0]
	v_pk_mul_f32 v[124:125], v[124:125], v[158:159] op_sel_hi:[1,0]
	v_pk_mul_f32 v[122:123], v[122:123], v[158:159] op_sel_hi:[1,0]
	v_pk_mul_f32 v[120:121], v[120:121], v[158:159] op_sel_hi:[1,0]
	v_pk_mul_f32 v[118:119], v[118:119], v[158:159] op_sel_hi:[1,0]
	v_pk_mul_f32 v[116:117], v[116:117], v[158:159] op_sel_hi:[1,0]
	v_pk_mul_f32 v[160:161], v[162:163], v[158:159] op_sel_hi:[1,0]
	v_pk_mul_f32 v[158:159], v[168:169], v[158:159] op_sel_hi:[1,0]
	v_med3_f32 v115, v124, s74, v153
	v_med3_f32 v124, v125, s74, v153
	v_med3_f32 v125, v126, s74, v153
	v_med3_f32 v126, v127, s74, v153
	v_med3_f32 v116, v116, s74, v153
	v_med3_f32 v117, v117, s74, v153
	v_med3_f32 v127, v158, s74, v153
	v_med3_f32 v145, v159, s74, v153
	v_med3_f32 v120, v120, s74, v153
	v_med3_f32 v121, v121, s74, v153
	v_cvt_pk_fp8_f32 v166, v116, v117
	v_cvt_pk_fp8_f32 v167, v127, v145
; __device__ __forceinline__ float rms_scale(const float* ssq, int row, int which) {
;     const f32x4 a = *(const f32x4*)(ssq + (size_t)row * 16 + which * 8), b = *(const f32x4*)(ssq + (size_t)row * 16 + which * 8 + 4);
;     const float s = ((a[0] + a[1]) + (a[2] + a[3])) + ((b[0] + b[1]) + (b[2] + b[3]));
;     return 1.0f / sqrtf(s * (1.0f / 512.0f) + RMS_EPS);
;     __device__ __forceinline__ void operator()(EPI_ARGS) const {
;         const int row0 = u.pm * BM + wr * 64 + fr; bf16_t* dst = (u.pn < 8) ? KN : V; const int h0 = 2 * (u.pn & 7);
; #pragma unroll
;         for (int ai = 0; ai < 2; ++ai)
; #pragma unroll
;             for (int m = 0; m < 4; ++m) { const int row = row0 + ai * HALF + m * 16; const float rs = rms_scale(ssq, row, 1);
; #pragma unroll
;                 for (int bj = 0; bj < 2; ++bj)
;                     *(u32x2*)((unsigned char*)dst + ((size_t)(h0 + bj) * NTOK + row) * 128 + 64 * (wc >> 1) + 32 * (fq & 1) + 8 * ((2 * wc + (fq >> 1)) & 3)) = pack8fp8(acc[ai][bj][m][0] * rs, acc[ai][bj][m][1] * rs); }
	v_cvt_pk_fp8_f32 v164, v115, v124
	v_cvt_pk_fp8_f32 v165, v120, v121
	v_med3_f32 v118, v118, s74, v153
	v_med3_f32 v119, v119, s74, v153
	v_med3_f32 v158, v160, s74, v153
	v_med3_f32 v115, v161, s74, v153
	v_med3_f32 v122, v122, s74, v153
	v_med3_f32 v123, v123, s74, v153
	v_cvt_pk_fp8_f32 v166, v118, v119 op_sel:[0,0,1]
	v_cvt_pk_fp8_f32 v167, v158, v115 op_sel:[0,0,1]
	v_cvt_pk_fp8_f32 v164, v125, v126 op_sel:[0,0,1]
	v_cvt_pk_fp8_f32 v165, v122, v123 op_sel:[0,0,1]
	v_lshlrev_b64 v[116:117], 7, v[154:155]
	v_or_b32_e32 v124, 16, v144
	v_lshl_add_u64 v[116:117], v[112:113], 0, v[116:117]
	v_ashrrev_i32_e32 v125, 31, v124
	global_store_dwordx2 v[116:117], v[166:167], off
	v_lshlrev_b64 v[116:117], 6, v[124:125]
	global_store_dwordx2 v[156:157], v[164:165], off
	v_lshl_add_u64 v[120:121], s[8:9], 0, v[116:117]
	v_mov_b32_e32 v116, v198
	v_mov_b32_e32 v117, v199
	v_mov_b32_e32 v118, v200
	v_mov_b32_e32 v119, v201
	s_nop 0
	v_mov_b32_e32 v120, v202
	v_mov_b32_e32 v121, v203
	v_mov_b32_e32 v122, v204
	v_mov_b32_e32 v123, v205
	v_pk_mul_f32 v[108:109], v[114:115], v[108:109] op_sel_hi:[0,1]
	v_pk_mul_f32 v[110:111], v[114:115], v[110:111] op_sel_hi:[0,1]
	v_pk_mul_f32 v[104:105], v[114:115], v[104:105] op_sel_hi:[0,1]
	v_pk_mul_f32 v[106:107], v[114:115], v[106:107] op_sel_hi:[0,1]
	v_pk_mul_f32 v[100:101], v[114:115], v[100:101] op_sel_hi:[0,1]
	v_pk_mul_f32 v[102:103], v[114:115], v[102:103] op_sel_hi:[0,1]
	v_pk_mul_f32 v[96:97], v[114:115], v[96:97] op_sel_hi:[0,1]
	v_pk_mul_f32 v[98:99], v[114:115], v[98:99] op_sel_hi:[0,1]
	v_lshl_add_u64 v[160:161], v[124:125], 0, s[14:15]
	v_mov_b32_e32 v126, 0
	v_mov_b32_e32 v127, 0
	v_mov_b32_e32 v154, 0
	v_mov_b32_e32 v155, 0
	v_or_b32_e32 v156, 32, v144
	v_ashrrev_i32_e32 v157, 31, v156
	v_lshlrev_b64 v[158:159], 6, v[156:157]
	v_cvt_f32_i32_e32 v67, v67
	v_cvt_f32_i32_e32 v66, v66
	v_cvt_f32_i32_e32 v61, v61
	v_cvt_f32_i32_e32 v60, v60
	v_cvt_f32_i32_e32 v57, v57
	v_cvt_f32_i32_e32 v56, v56
	v_cvt_f32_i32_e32 v53, v53
	v_cvt_f32_i32_e32 v52, v52
	v_cvt_f32_i32_e32 v49, v49
	v_cvt_f32_i32_e32 v48, v48
	v_cvt_f32_i32_e32 v63, v63
	v_cvt_f32_i32_e32 v62, v62
	v_cvt_f32_i32_e32 v59, v59
	v_cvt_f32_i32_e32 v58, v58
	v_cvt_f32_i32_e32 v55, v55
	v_cvt_f32_i32_e32 v54, v54
	v_cvt_f32_i32_e32 v51, v51
	v_cvt_f32_i32_e32 v50, v50
	v_cvt_f32_i32_e32 v45, v45
	v_cvt_f32_i32_e32 v44, v44
	v_cvt_f32_i32_e32 v41, v41
	v_cvt_f32_i32_e32 v40, v40
	v_cvt_f32_i32_e32 v37, v37
	v_cvt_f32_i32_e32 v36, v36
	v_cvt_f32_i32_e32 v33, v33
	v_cvt_f32_i32_e32 v32, v32
	v_cvt_f32_i32_e32 v47, v47
	v_cvt_f32_i32_e32 v46, v46
	v_cvt_f32_i32_e32 v43, v43
	v_cvt_f32_i32_e32 v42, v42
	v_cvt_f32_i32_e32 v39, v39
	v_cvt_f32_i32_e32 v38, v38
	v_cvt_f32_i32_e32 v35, v35
	v_cvt_f32_i32_e32 v34, v34
	v_cvt_f32_i32_e32 v29, v29
	v_cvt_f32_i32_e32 v28, v28
	v_cvt_f32_i32_e32 v25, v25
	v_cvt_f32_i32_e32 v24, v24
	v_cvt_f32_i32_e32 v21, v21
	v_cvt_f32_i32_e32 v20, v20
	v_cvt_f32_i32_e32 v17, v17
	v_cvt_f32_i32_e32 v16, v16
	v_cvt_f32_i32_e32 v31, v31
	v_cvt_f32_i32_e32 v30, v30
	v_cvt_f32_i32_e32 v27, v27
	v_cvt_f32_i32_e32 v26, v26
	v_cvt_f32_i32_e32 v23, v23
	v_cvt_f32_i32_e32 v22, v22
	v_cvt_f32_i32_e32 v19, v19
	v_cvt_f32_i32_e32 v18, v18
	v_cvt_f32_i32_e32 v13, v13
	v_cvt_f32_i32_e32 v12, v12
	v_cvt_f32_i32_e32 v9, v9
	v_cvt_f32_i32_e32 v8, v8
	v_cvt_f32_i32_e32 v5, v5
	v_cvt_f32_i32_e32 v4, v4
	v_cvt_f32_i32_e32 v1, v1
	v_cvt_f32_i32_e32 v0, v0
	v_cvt_f32_i32_e32 v15, v15
	v_cvt_f32_i32_e32 v14, v14
	v_cvt_f32_i32_e32 v11, v11
	v_cvt_f32_i32_e32 v10, v10
	v_mov_b32_e32 v162, v116
	v_mov_b32_e32 v163, v120
	v_mov_b32_e32 v120, v117
	v_mov_b32_e32 v116, v118
	v_mov_b32_e32 v117, v122
	v_mov_b32_e32 v122, v119
	v_pk_add_f32 v[118:119], v[162:163], v[120:121]
	v_pk_add_f32 v[116:117], v[116:117], v[122:123]
	v_lshl_add_u64 v[120:121], v[124:125], 0, s[36:37]
	v_pk_add_f32 v[116:117], v[118:119], v[116:117]
	v_lshlrev_b64 v[118:119], 7, v[160:161]
	v_add_f32_e32 v115, v116, v117
	v_fmamk_f32 v115, v115, 0x3b000000, v149
	v_rsq_f32_e32 v254, v115
	v_lshlrev_b64 v[120:121], 7, v[120:121]
	v_cvt_f32_i32_e32 v7, v7
	v_lshl_add_u64 v[116:117], s[8:9], 0, v[158:159]
	v_cvt_f32_i32_e32 v6, v6
	v_cvt_f32_i32_e32 v3, v3
	v_cvt_f32_i32_e32 v2, v2
	s_nop 0
	s_nop 1
	s_nop 1
	v_pk_mul_f32 v[92:93], v[114:115], v[92:93] op_sel_hi:[0,1]
	v_mov_b32_e32 v122, v254
	v_pk_mul_f32 v[108:109], v[108:109], v[122:123] op_sel_hi:[1,0]
	v_pk_mul_f32 v[104:105], v[104:105], v[122:123] op_sel_hi:[1,0]
	v_pk_mul_f32 v[100:101], v[100:101], v[122:123] op_sel_hi:[1,0]
	v_pk_mul_f32 v[96:97], v[96:97], v[122:123] op_sel_hi:[1,0]
	v_med3_f32 v108, v108, s74, v153
	v_med3_f32 v109, v109, s74, v153
	v_med3_f32 v104, v104, s74, v153
	v_med3_f32 v105, v105, s74, v153
	v_med3_f32 v100, v100, s74, v153
	v_med3_f32 v101, v101, s74, v153
	v_med3_f32 v96, v96, s74, v153
	v_med3_f32 v97, v97, s74, v153
	v_cvt_pk_fp8_f32 v126, v108, v109
	v_cvt_pk_fp8_f32 v127, v104, v105
	v_cvt_pk_fp8_f32 v154, v100, v101
	v_cvt_pk_fp8_f32 v155, v96, v97
	v_pk_mul_f32 v[110:111], v[110:111], v[122:123] op_sel_hi:[1,0]
	v_pk_mul_f32 v[106:107], v[106:107], v[122:123] op_sel_hi:[1,0]
	v_pk_mul_f32 v[102:103], v[102:103], v[122:123] op_sel_hi:[1,0]
	v_pk_mul_f32 v[98:99], v[98:99], v[122:123] op_sel_hi:[1,0]
	v_med3_f32 v110, v110, s74, v153
	v_med3_f32 v111, v111, s74, v153
	v_med3_f32 v106, v106, s74, v153
	v_med3_f32 v107, v107, s74, v153
	v_med3_f32 v102, v102, s74, v153
	v_med3_f32 v103, v103, s74, v153
	v_med3_f32 v98, v98, s74, v153
	v_med3_f32 v99, v99, s74, v153
	v_cvt_pk_fp8_f32 v126, v110, v111 op_sel:[0,0,1]
	v_cvt_pk_fp8_f32 v127, v106, v107 op_sel:[0,0,1]
; __device__ __forceinline__ float rms_scale(const float* ssq, int row, int which) {
;     const f32x4 a = *(const f32x4*)(ssq + (size_t)row * 16 + which * 8), b = *(const f32x4*)(ssq + (size_t)row * 16 + which * 8 + 4);
;     const float s = ((a[0] + a[1]) + (a[2] + a[3])) + ((b[0] + b[1]) + (b[2] + b[3]));
;     return 1.0f / sqrtf(s * (1.0f / 512.0f) + RMS_EPS);
;     __device__ __forceinline__ void operator()(EPI_ARGS) const {
;         const int row0 = u.pm * BM + wr * 64 + fr; bf16_t* dst = (u.pn < 8) ? KN : V; const int h0 = 2 * (u.pn & 7);
; #pragma unroll
;         for (int ai = 0; ai < 2; ++ai)
; #pragma unroll
;             for (int m = 0; m < 4; ++m) { const int row = row0 + ai * HALF + m * 16; const float rs = rms_scale(ssq, row, 1);
; #pragma unroll
;                 for (int bj = 0; bj < 2; ++bj)
;                     *(u32x2*)((unsigned char*)dst + ((size_t)(h0 + bj) * NTOK + row) * 128 + 64 * (wc >> 1) + 32 * (fq & 1) + 8 * ((2 * wc + (fq >> 1)) & 3)) = pack8fp8(acc[ai][bj][m][0] * rs, acc[ai][bj][m][1] * rs); }
	v_cvt_pk_fp8_f32 v154, v102, v103 op_sel:[0,0,1]
	v_cvt_pk_fp8_f32 v155, v98, v99 op_sel:[0,0,1]
	v_lshl_add_u64 v[96:97], v[112:113], 0, v[118:119]
	v_lshl_add_u64 v[98:99], v[112:113], 0, v[120:121]
	global_store_dwordx2 v[96:97], v[126:127], off
	global_store_dwordx2 v[98:99], v[154:155], off
	v_mov_b32_e32 v96, v206
	v_mov_b32_e32 v97, v207
	v_mov_b32_e32 v98, v208
	v_mov_b32_e32 v99, v209
	s_nop 0
	v_mov_b32_e32 v100, v210
	v_mov_b32_e32 v101, v211
	v_mov_b32_e32 v102, v212
	v_mov_b32_e32 v103, v213
	v_or_b32_e32 v108, 48, v144
	v_ashrrev_i32_e32 v109, 31, v108
	v_lshlrev_b64 v[110:111], 6, v[108:109]
	v_pk_mul_f32 v[94:95], v[114:115], v[94:95] op_sel_hi:[0,1]
	v_pk_mul_f32 v[88:89], v[114:115], v[88:89] op_sel_hi:[0,1]
	v_pk_mul_f32 v[90:91], v[114:115], v[90:91] op_sel_hi:[0,1]
	v_pk_mul_f32 v[84:85], v[114:115], v[84:85] op_sel_hi:[0,1]
	v_pk_mul_f32 v[86:87], v[114:115], v[86:87] op_sel_hi:[0,1]
	v_pk_mul_f32 v[80:81], v[114:115], v[80:81] op_sel_hi:[0,1]
	v_pk_mul_f32 v[82:83], v[114:115], v[82:83] op_sel_hi:[0,1]
	v_lshl_add_u64 v[116:117], v[156:157], 0, s[14:15]
	v_mov_b32_e32 v104, 0
	v_mov_b32_e32 v105, 0
	v_mov_b32_e32 v106, 0
	v_mov_b32_e32 v107, 0
	v_mov_b32_e32 v118, v96
	v_mov_b32_e32 v119, v100
	v_mov_b32_e32 v100, v97
	v_mov_b32_e32 v96, v98
	v_mov_b32_e32 v97, v102
	v_mov_b32_e32 v102, v99
	v_pk_add_f32 v[98:99], v[118:119], v[100:101]
	v_pk_add_f32 v[96:97], v[96:97], v[102:103]
	v_lshl_add_u64 v[100:101], v[156:157], 0, s[36:37]
	v_pk_add_f32 v[96:97], v[98:99], v[96:97]
	v_lshlrev_b64 v[98:99], 7, v[116:117]
	v_add_f32_e32 v96, v96, v97
	v_fmamk_f32 v96, v96, 0x3b000000, v149
	v_rsq_f32_e32 v254, v96
	v_lshlrev_b64 v[100:101], 7, v[100:101]
	s_nop 0
	v_lshl_add_u64 v[96:97], s[8:9], 0, v[110:111]
	s_nop 1
	s_nop 1
	s_nop 1
	v_mov_b32_e32 v102, v254
	v_pk_mul_f32 v[92:93], v[92:93], v[102:103] op_sel_hi:[1,0]
	v_pk_mul_f32 v[88:89], v[88:89], v[102:103] op_sel_hi:[1,0]
	v_pk_mul_f32 v[84:85], v[84:85], v[102:103] op_sel_hi:[1,0]
	v_pk_mul_f32 v[80:81], v[80:81], v[102:103] op_sel_hi:[1,0]
	v_med3_f32 v92, v92, s74, v153
	v_med3_f32 v93, v93, s74, v153
	v_med3_f32 v88, v88, s74, v153
	v_med3_f32 v89, v89, s74, v153
	v_med3_f32 v84, v84, s74, v153
	v_med3_f32 v85, v85, s74, v153
	v_med3_f32 v80, v80, s74, v153
	v_med3_f32 v81, v81, s74, v153
	v_cvt_pk_fp8_f32 v104, v92, v93
	v_cvt_pk_fp8_f32 v105, v88, v89
	v_cvt_pk_fp8_f32 v106, v84, v85
	v_cvt_pk_fp8_f32 v107, v80, v81
	v_pk_mul_f32 v[94:95], v[94:95], v[102:103] op_sel_hi:[1,0]
	v_pk_mul_f32 v[90:91], v[90:91], v[102:103] op_sel_hi:[1,0]
	v_pk_mul_f32 v[86:87], v[86:87], v[102:103] op_sel_hi:[1,0]
	v_pk_mul_f32 v[82:83], v[82:83], v[102:103] op_sel_hi:[1,0]
	v_med3_f32 v94, v94, s74, v153
	v_med3_f32 v95, v95, s74, v153
	v_med3_f32 v90, v90, s74, v153
	v_med3_f32 v91, v91, s74, v153
	v_med3_f32 v86, v86, s74, v153
	v_med3_f32 v87, v87, s74, v153
	v_med3_f32 v82, v82, s74, v153
	v_med3_f32 v83, v83, s74, v153
	v_cvt_pk_fp8_f32 v104, v94, v95 op_sel:[0,0,1]
	v_cvt_pk_fp8_f32 v105, v90, v91 op_sel:[0,0,1]
	v_cvt_pk_fp8_f32 v106, v86, v87 op_sel:[0,0,1]
	v_cvt_pk_fp8_f32 v107, v82, v83 op_sel:[0,0,1]
	v_lshl_add_u64 v[80:81], v[112:113], 0, v[98:99]
	v_lshl_add_u64 v[82:83], v[112:113], 0, v[100:101]
	global_store_dwordx2 v[80:81], v[104:105], off
	global_store_dwordx2 v[82:83], v[106:107], off
	v_mov_b32_e32 v80, v214
	v_mov_b32_e32 v81, v215
	v_mov_b32_e32 v82, v216
	v_mov_b32_e32 v83, v217
	s_nop 0
	v_mov_b32_e32 v84, v218
	v_mov_b32_e32 v85, v219
	v_mov_b32_e32 v86, v220
	v_mov_b32_e32 v87, v221
	v_add_u32_e32 v92, 0x80, v144
	v_ashrrev_i32_e32 v93, 31, v92
	v_lshlrev_b64 v[94:95], 6, v[92:93]
	v_lshl_add_u64 v[96:97], v[108:109], 0, s[14:15]
	v_pk_mul_f32 v[76:77], v[114:115], v[76:77] op_sel_hi:[0,1]
	v_pk_mul_f32 v[72:73], v[114:115], v[72:73] op_sel_hi:[0,1]
	v_pk_mul_f32 v[68:69], v[114:115], v[68:69] op_sel_hi:[0,1]
	v_pk_mul_f32 v[64:65], v[114:115], v[64:65] op_sel_hi:[0,1]
	v_mov_b32_e32 v88, 0
	v_mov_b32_e32 v89, 0
	v_mov_b32_e32 v90, 0
	v_mov_b32_e32 v91, 0
	v_pk_mul_f32 v[78:79], v[114:115], v[78:79] op_sel_hi:[0,1]
	v_pk_mul_f32 v[74:75], v[114:115], v[74:75] op_sel_hi:[0,1]
	v_pk_mul_f32 v[70:71], v[114:115], v[70:71] op_sel_hi:[0,1]
	v_pk_mul_f32 v[66:67], v[114:115], v[66:67] op_sel_hi:[0,1]
	v_pk_mul_f32 v[60:61], v[114:115], v[60:61] op_sel_hi:[0,1]
	v_pk_mul_f32 v[56:57], v[114:115], v[56:57] op_sel_hi:[0,1]
	v_pk_mul_f32 v[52:53], v[114:115], v[52:53] op_sel_hi:[0,1]
	v_pk_mul_f32 v[48:49], v[114:115], v[48:49] op_sel_hi:[0,1]
	v_pk_mul_f32 v[62:63], v[114:115], v[62:63] op_sel_hi:[0,1]
	v_pk_mul_f32 v[58:59], v[114:115], v[58:59] op_sel_hi:[0,1]
	v_pk_mul_f32 v[54:55], v[114:115], v[54:55] op_sel_hi:[0,1]
	v_pk_mul_f32 v[50:51], v[114:115], v[50:51] op_sel_hi:[0,1]
	v_pk_mul_f32 v[44:45], v[114:115], v[44:45] op_sel_hi:[0,1]
	v_pk_mul_f32 v[40:41], v[114:115], v[40:41] op_sel_hi:[0,1]
	v_pk_mul_f32 v[36:37], v[114:115], v[36:37] op_sel_hi:[0,1]
	v_pk_mul_f32 v[32:33], v[114:115], v[32:33] op_sel_hi:[0,1]
	v_pk_mul_f32 v[46:47], v[114:115], v[46:47] op_sel_hi:[0,1]
	v_pk_mul_f32 v[42:43], v[114:115], v[42:43] op_sel_hi:[0,1]
	v_pk_mul_f32 v[38:39], v[114:115], v[38:39] op_sel_hi:[0,1]
	v_pk_mul_f32 v[34:35], v[114:115], v[34:35] op_sel_hi:[0,1]
	v_pk_mul_f32 v[28:29], v[114:115], v[28:29] op_sel_hi:[0,1]
	v_pk_mul_f32 v[24:25], v[114:115], v[24:25] op_sel_hi:[0,1]
	v_pk_mul_f32 v[20:21], v[114:115], v[20:21] op_sel_hi:[0,1]
	v_pk_mul_f32 v[16:17], v[114:115], v[16:17] op_sel_hi:[0,1]
	v_pk_mul_f32 v[30:31], v[114:115], v[30:31] op_sel_hi:[0,1]
	v_pk_mul_f32 v[26:27], v[114:115], v[26:27] op_sel_hi:[0,1]
	v_pk_mul_f32 v[22:23], v[114:115], v[22:23] op_sel_hi:[0,1]
; __device__ __forceinline__ float rms_scale(const float* ssq, int row, int which) {
;     const f32x4 a = *(const f32x4*)(ssq + (size_t)row * 16 + which * 8), b = *(const f32x4*)(ssq + (size_t)row * 16 + which * 8 + 4);
;     const float s = ((a[0] + a[1]) + (a[2] + a[3])) + ((b[0] + b[1]) + (b[2] + b[3]));
;     return 1.0f / sqrtf(s * (1.0f / 512.0f) + RMS_EPS);
;     __device__ __forceinline__ void operator()(EPI_ARGS) const {
;         const int row0 = u.pm * BM + wr * 64 + fr; bf16_t* dst = (u.pn < 8) ? KN : V; const int h0 = 2 * (u.pn & 7);
; #pragma unroll
;         for (int ai = 0; ai < 2; ++ai)
; #pragma unroll
;             for (int m = 0; m < 4; ++m) { const int row = row0 + ai * HALF + m * 16; const float rs = rms_scale(ssq, row, 1);
; #pragma unroll
;                 for (int bj = 0; bj < 2; ++bj)
;                     *(u32x2*)((unsigned char*)dst + ((size_t)(h0 + bj) * NTOK + row) * 128 + 64 * (wc >> 1) + 32 * (fq & 1) + 8 * ((2 * wc + (fq >> 1)) & 3)) = pack8fp8(acc[ai][bj][m][0] * rs, acc[ai][bj][m][1] * rs); }
	v_pk_mul_f32 v[18:19], v[114:115], v[18:19] op_sel_hi:[0,1]
	v_pk_mul_f32 v[12:13], v[114:115], v[12:13] op_sel_hi:[0,1]
	v_pk_mul_f32 v[8:9], v[114:115], v[8:9] op_sel_hi:[0,1]
	v_pk_mul_f32 v[4:5], v[114:115], v[4:5] op_sel_hi:[0,1]
	v_pk_mul_f32 v[0:1], v[114:115], v[0:1] op_sel_hi:[0,1]
	v_pk_mul_f32 v[14:15], v[114:115], v[14:15] op_sel_hi:[0,1]
	v_pk_mul_f32 v[10:11], v[114:115], v[10:11] op_sel_hi:[0,1]
	v_pk_mul_f32 v[6:7], v[114:115], v[6:7] op_sel_hi:[0,1]
	v_pk_mul_f32 v[2:3], v[114:115], v[2:3] op_sel_hi:[0,1]
	v_mov_b32_e32 v98, v80
	v_mov_b32_e32 v99, v84
	v_mov_b32_e32 v84, v81
	v_mov_b32_e32 v80, v82
	v_mov_b32_e32 v81, v86
	v_mov_b32_e32 v86, v83
	v_pk_add_f32 v[82:83], v[98:99], v[84:85]
	v_pk_add_f32 v[80:81], v[80:81], v[86:87]
	v_lshl_add_u64 v[84:85], v[108:109], 0, s[36:37]
	v_pk_add_f32 v[80:81], v[82:83], v[80:81]
	v_lshlrev_b64 v[82:83], 7, v[96:97]
	v_add_f32_e32 v80, v80, v81
	v_fmamk_f32 v80, v80, 0x3b000000, v149
	v_rsq_f32_e32 v254, v80
	v_lshlrev_b64 v[84:85], 7, v[84:85]
	s_nop 0
	v_lshl_add_u64 v[80:81], s[8:9], 0, v[94:95]
	s_nop 1
	s_nop 1
	s_nop 1
	v_mov_b32_e32 v86, v254
	v_pk_mul_f32 v[76:77], v[76:77], v[86:87] op_sel_hi:[1,0]
	v_pk_mul_f32 v[72:73], v[72:73], v[86:87] op_sel_hi:[1,0]
	v_pk_mul_f32 v[68:69], v[68:69], v[86:87] op_sel_hi:[1,0]
	v_pk_mul_f32 v[64:65], v[64:65], v[86:87] op_sel_hi:[1,0]
	v_med3_f32 v76, v76, s74, v153
	v_med3_f32 v77, v77, s74, v153
	v_med3_f32 v72, v72, s74, v153
	v_med3_f32 v73, v73, s74, v153
	v_med3_f32 v68, v68, s74, v153
	v_med3_f32 v69, v69, s74, v153
	v_med3_f32 v64, v64, s74, v153
	v_med3_f32 v65, v65, s74, v153
	v_cvt_pk_fp8_f32 v88, v76, v77
	v_cvt_pk_fp8_f32 v89, v72, v73
	v_cvt_pk_fp8_f32 v90, v68, v69
	v_cvt_pk_fp8_f32 v91, v64, v65
	v_pk_mul_f32 v[78:79], v[78:79], v[86:87] op_sel_hi:[1,0]
	v_pk_mul_f32 v[74:75], v[74:75], v[86:87] op_sel_hi:[1,0]
	v_pk_mul_f32 v[70:71], v[70:71], v[86:87] op_sel_hi:[1,0]
	v_pk_mul_f32 v[66:67], v[66:67], v[86:87] op_sel_hi:[1,0]
	v_med3_f32 v78, v78, s74, v153
	v_med3_f32 v79, v79, s74, v153
	v_med3_f32 v74, v74, s74, v153
	v_med3_f32 v75, v75, s74, v153
	v_med3_f32 v70, v70, s74, v153
	v_med3_f32 v71, v71, s74, v153
	v_med3_f32 v66, v66, s74, v153
	v_med3_f32 v67, v67, s74, v153
	v_cvt_pk_fp8_f32 v88, v78, v79 op_sel:[0,0,1]
	v_cvt_pk_fp8_f32 v89, v74, v75 op_sel:[0,0,1]
	v_cvt_pk_fp8_f32 v90, v70, v71 op_sel:[0,0,1]
	v_cvt_pk_fp8_f32 v91, v66, v67 op_sel:[0,0,1]
	v_lshl_add_u64 v[64:65], v[112:113], 0, v[82:83]
	v_lshl_add_u64 v[66:67], v[112:113], 0, v[84:85]
	global_store_dwordx2 v[64:65], v[88:89], off
	global_store_dwordx2 v[66:67], v[90:91], off
	v_mov_b32_e32 v64, v222
	v_mov_b32_e32 v65, v223
	v_mov_b32_e32 v66, v224
	v_mov_b32_e32 v67, v225
	s_nop 0
	v_mov_b32_e32 v68, v226
	v_mov_b32_e32 v69, v227
	v_mov_b32_e32 v70, v228
	v_mov_b32_e32 v71, v229
	v_add_u32_e32 v76, 0x90, v144
	v_ashrrev_i32_e32 v77, 31, v76
	v_lshlrev_b64 v[78:79], 6, v[76:77]
	v_lshl_add_u64 v[80:81], v[92:93], 0, s[14:15]
	v_mov_b32_e32 v72, 0
	v_mov_b32_e32 v73, 0
	v_mov_b32_e32 v74, 0
	v_mov_b32_e32 v75, 0
	v_mov_b32_e32 v82, v64
	v_mov_b32_e32 v83, v68
	v_mov_b32_e32 v68, v65
	v_mov_b32_e32 v64, v66
	v_mov_b32_e32 v65, v70
	v_mov_b32_e32 v70, v67
	v_pk_add_f32 v[66:67], v[82:83], v[68:69]
	v_pk_add_f32 v[64:65], v[64:65], v[70:71]
	v_lshl_add_u64 v[68:69], v[92:93], 0, s[36:37]
	v_pk_add_f32 v[64:65], v[66:67], v[64:65]
	v_lshlrev_b64 v[66:67], 7, v[80:81]
	v_add_f32_e32 v64, v64, v65
	v_fmamk_f32 v64, v64, 0x3b000000, v149
	v_rsq_f32_e32 v254, v64
	v_lshlrev_b64 v[68:69], 7, v[68:69]
	s_nop 0
	v_lshl_add_u64 v[64:65], s[8:9], 0, v[78:79]
	s_nop 1
	s_nop 1
	s_nop 1
	v_mov_b32_e32 v70, v254
	v_pk_mul_f32 v[60:61], v[60:61], v[70:71] op_sel_hi:[1,0]
	v_pk_mul_f32 v[56:57], v[56:57], v[70:71] op_sel_hi:[1,0]
	v_pk_mul_f32 v[52:53], v[52:53], v[70:71] op_sel_hi:[1,0]
	v_pk_mul_f32 v[48:49], v[48:49], v[70:71] op_sel_hi:[1,0]
	v_med3_f32 v60, v60, s74, v153
	v_med3_f32 v61, v61, s74, v153
	v_med3_f32 v56, v56, s74, v153
	v_med3_f32 v57, v57, s74, v153
	v_med3_f32 v52, v52, s74, v153
	v_med3_f32 v53, v53, s74, v153
	v_med3_f32 v48, v48, s74, v153
	v_med3_f32 v49, v49, s74, v153
	v_cvt_pk_fp8_f32 v72, v60, v61
	v_cvt_pk_fp8_f32 v73, v56, v57
	v_cvt_pk_fp8_f32 v74, v52, v53
	v_cvt_pk_fp8_f32 v75, v48, v49
	v_pk_mul_f32 v[62:63], v[62:63], v[70:71] op_sel_hi:[1,0]
	v_pk_mul_f32 v[58:59], v[58:59], v[70:71] op_sel_hi:[1,0]
	v_pk_mul_f32 v[54:55], v[54:55], v[70:71] op_sel_hi:[1,0]
	v_pk_mul_f32 v[50:51], v[50:51], v[70:71] op_sel_hi:[1,0]
	v_med3_f32 v62, v62, s74, v153
	v_med3_f32 v63, v63, s74, v153
	v_med3_f32 v58, v58, s74, v153
	v_med3_f32 v59, v59, s74, v153
	v_med3_f32 v54, v54, s74, v153
	v_med3_f32 v55, v55, s74, v153
	v_med3_f32 v50, v50, s74, v153
	v_med3_f32 v51, v51, s74, v153
	v_cvt_pk_fp8_f32 v72, v62, v63 op_sel:[0,0,1]
	v_cvt_pk_fp8_f32 v73, v58, v59 op_sel:[0,0,1]
	v_cvt_pk_fp8_f32 v74, v54, v55 op_sel:[0,0,1]
	v_cvt_pk_fp8_f32 v75, v50, v51 op_sel:[0,0,1]
	v_lshl_add_u64 v[48:49], v[112:113], 0, v[66:67]
	v_lshl_add_u64 v[50:51], v[112:113], 0, v[68:69]
	global_store_dwordx2 v[48:49], v[72:73], off
	global_store_dwordx2 v[50:51], v[74:75], off
	v_mov_b32_e32 v48, v230
	v_mov_b32_e32 v49, v231
	v_mov_b32_e32 v50, v232
	v_mov_b32_e32 v51, v233
	s_nop 0
	v_mov_b32_e32 v52, v234
	v_mov_b32_e32 v53, v235
	v_mov_b32_e32 v54, v236
	v_mov_b32_e32 v55, v237
	v_add_u32_e32 v60, 0xa0, v144
	v_ashrrev_i32_e32 v61, 31, v60
	v_lshlrev_b64 v[62:63], 6, v[60:61]
	v_lshl_add_u64 v[64:65], v[76:77], 0, s[14:15]
	v_mov_b32_e32 v56, 0
	v_mov_b32_e32 v57, 0
	v_mov_b32_e32 v58, 0
	v_mov_b32_e32 v59, 0
	v_mov_b32_e32 v66, v48
	v_mov_b32_e32 v67, v52
; __device__ __forceinline__ float rms_scale(const float* ssq, int row, int which) {
;     const f32x4 a = *(const f32x4*)(ssq + (size_t)row * 16 + which * 8), b = *(const f32x4*)(ssq + (size_t)row * 16 + which * 8 + 4);
;     const float s = ((a[0] + a[1]) + (a[2] + a[3])) + ((b[0] + b[1]) + (b[2] + b[3]));
;     return 1.0f / sqrtf(s * (1.0f / 512.0f) + RMS_EPS);
; }
;     __device__ __forceinline__ void operator()(EPI_ARGS) const {
;         const int row0 = u.pm * BM + wr * 64 + fr; bf16_t* dst = (u.pn < 8) ? KN : V; const int h0 = 2 * (u.pn & 7);
; #pragma unroll
;         for (int ai = 0; ai < 2; ++ai)
; #pragma unroll
;             for (int m = 0; m < 4; ++m) { const int row = row0 + ai * HALF + m * 16; const float rs = rms_scale(ssq, row, 1);
; #pragma unroll
;                 for (int bj = 0; bj < 2; ++bj)
;                     *(u32x2*)((unsigned char*)dst + ((size_t)(h0 + bj) * NTOK + row) * 128 + 64 * (wc >> 1) + 32 * (fq & 1) + 8 * ((2 * wc + (fq >> 1)) & 3)) = pack8fp8(acc[ai][bj][m][0] * rs, acc[ai][bj][m][1] * rs); }
;     }
	v_mov_b32_e32 v52, v49
	v_mov_b32_e32 v48, v50
	v_mov_b32_e32 v49, v54
	v_mov_b32_e32 v54, v51
	v_pk_add_f32 v[50:51], v[66:67], v[52:53]
	v_pk_add_f32 v[48:49], v[48:49], v[54:55]
	v_lshl_add_u64 v[52:53], v[76:77], 0, s[36:37]
	v_pk_add_f32 v[48:49], v[50:51], v[48:49]
	v_lshlrev_b64 v[50:51], 7, v[64:65]
	v_add_f32_e32 v48, v48, v49
	v_fmamk_f32 v48, v48, 0x3b000000, v149
	v_rsq_f32_e32 v254, v48
	v_lshlrev_b64 v[52:53], 7, v[52:53]
	s_nop 0
	v_lshl_add_u64 v[48:49], s[8:9], 0, v[62:63]
	s_nop 1
	s_nop 1
	s_nop 1
	v_mov_b32_e32 v54, v254
	v_pk_mul_f32 v[44:45], v[44:45], v[54:55] op_sel_hi:[1,0]
	v_pk_mul_f32 v[40:41], v[40:41], v[54:55] op_sel_hi:[1,0]
	v_pk_mul_f32 v[36:37], v[36:37], v[54:55] op_sel_hi:[1,0]
	v_pk_mul_f32 v[32:33], v[32:33], v[54:55] op_sel_hi:[1,0]
	v_med3_f32 v44, v44, s74, v153
	v_med3_f32 v45, v45, s74, v153
	v_med3_f32 v40, v40, s74, v153
	v_med3_f32 v41, v41, s74, v153
	v_med3_f32 v36, v36, s74, v153
	v_med3_f32 v37, v37, s74, v153
	v_med3_f32 v32, v32, s74, v153
	v_med3_f32 v33, v33, s74, v153
	v_cvt_pk_fp8_f32 v56, v44, v45
	v_cvt_pk_fp8_f32 v57, v40, v41
	v_cvt_pk_fp8_f32 v58, v36, v37
	v_cvt_pk_fp8_f32 v59, v32, v33
	v_pk_mul_f32 v[46:47], v[46:47], v[54:55] op_sel_hi:[1,0]
	v_pk_mul_f32 v[42:43], v[42:43], v[54:55] op_sel_hi:[1,0]
	v_pk_mul_f32 v[38:39], v[38:39], v[54:55] op_sel_hi:[1,0]
	v_pk_mul_f32 v[34:35], v[34:35], v[54:55] op_sel_hi:[1,0]
	v_med3_f32 v46, v46, s74, v153
	v_med3_f32 v47, v47, s74, v153
	v_med3_f32 v42, v42, s74, v153
	v_med3_f32 v43, v43, s74, v153
	v_med3_f32 v38, v38, s74, v153
	v_med3_f32 v39, v39, s74, v153
	v_med3_f32 v34, v34, s74, v153
	v_med3_f32 v35, v35, s74, v153
	v_cvt_pk_fp8_f32 v56, v46, v47 op_sel:[0,0,1]
	v_cvt_pk_fp8_f32 v57, v42, v43 op_sel:[0,0,1]
	v_cvt_pk_fp8_f32 v58, v38, v39 op_sel:[0,0,1]
	v_cvt_pk_fp8_f32 v59, v34, v35 op_sel:[0,0,1]
	v_lshl_add_u64 v[32:33], v[112:113], 0, v[50:51]
	v_lshl_add_u64 v[34:35], v[112:113], 0, v[52:53]
	global_store_dwordx2 v[32:33], v[56:57], off
	global_store_dwordx2 v[34:35], v[58:59], off
	v_mov_b32_e32 v32, v238
	v_mov_b32_e32 v33, v239
	v_mov_b32_e32 v34, v240
	v_mov_b32_e32 v35, v241
	s_nop 0
	v_mov_b32_e32 v36, v242
	v_mov_b32_e32 v37, v243
	v_mov_b32_e32 v38, v244
	v_mov_b32_e32 v39, v245
	v_add_u32_e32 v44, 0xb0, v144
	v_ashrrev_i32_e32 v45, 31, v44
	v_lshlrev_b64 v[46:47], 6, v[44:45]
	v_lshl_add_u64 v[48:49], v[60:61], 0, s[14:15]
	v_mov_b32_e32 v40, 0
	v_mov_b32_e32 v41, 0
	v_mov_b32_e32 v42, 0
	v_mov_b32_e32 v43, 0
	v_mov_b32_e32 v50, v32
	v_mov_b32_e32 v51, v36
	v_mov_b32_e32 v36, v33
	v_mov_b32_e32 v32, v34
	v_mov_b32_e32 v33, v38
	v_mov_b32_e32 v38, v35
	v_pk_add_f32 v[34:35], v[50:51], v[36:37]
	v_pk_add_f32 v[32:33], v[32:33], v[38:39]
	v_lshl_add_u64 v[36:37], v[60:61], 0, s[36:37]
	v_pk_add_f32 v[32:33], v[34:35], v[32:33]
	v_lshlrev_b64 v[34:35], 7, v[48:49]
	v_add_f32_e32 v32, v32, v33
	v_fmamk_f32 v32, v32, 0x3b000000, v149
	v_rsq_f32_e32 v254, v32
	v_lshlrev_b64 v[36:37], 7, v[36:37]
	s_nop 0
	v_lshl_add_u64 v[32:33], s[8:9], 0, v[46:47]
	s_nop 1
	s_nop 1
	s_nop 1
	v_mov_b32_e32 v38, v254
	v_pk_mul_f32 v[28:29], v[28:29], v[38:39] op_sel_hi:[1,0]
	v_pk_mul_f32 v[24:25], v[24:25], v[38:39] op_sel_hi:[1,0]
	v_pk_mul_f32 v[20:21], v[20:21], v[38:39] op_sel_hi:[1,0]
	v_pk_mul_f32 v[16:17], v[16:17], v[38:39] op_sel_hi:[1,0]
	v_med3_f32 v28, v28, s74, v153
	v_med3_f32 v29, v29, s74, v153
	v_med3_f32 v24, v24, s74, v153
	v_med3_f32 v25, v25, s74, v153
	v_med3_f32 v20, v20, s74, v153
	v_med3_f32 v21, v21, s74, v153
	v_med3_f32 v16, v16, s74, v153
	v_med3_f32 v17, v17, s74, v153
	v_cvt_pk_fp8_f32 v40, v28, v29
	v_cvt_pk_fp8_f32 v41, v24, v25
	v_cvt_pk_fp8_f32 v42, v20, v21
	v_cvt_pk_fp8_f32 v43, v16, v17
	v_pk_mul_f32 v[30:31], v[30:31], v[38:39] op_sel_hi:[1,0]
	v_pk_mul_f32 v[26:27], v[26:27], v[38:39] op_sel_hi:[1,0]
	v_pk_mul_f32 v[22:23], v[22:23], v[38:39] op_sel_hi:[1,0]
	v_pk_mul_f32 v[18:19], v[18:19], v[38:39] op_sel_hi:[1,0]
	v_med3_f32 v30, v30, s74, v153
	v_med3_f32 v31, v31, s74, v153
	v_med3_f32 v26, v26, s74, v153
	v_med3_f32 v27, v27, s74, v153
	v_med3_f32 v22, v22, s74, v153
	v_med3_f32 v23, v23, s74, v153
	v_med3_f32 v18, v18, s74, v153
	v_med3_f32 v19, v19, s74, v153
	v_cvt_pk_fp8_f32 v40, v30, v31 op_sel:[0,0,1]
	v_cvt_pk_fp8_f32 v41, v26, v27 op_sel:[0,0,1]
	v_cvt_pk_fp8_f32 v42, v22, v23 op_sel:[0,0,1]
	v_cvt_pk_fp8_f32 v43, v18, v19 op_sel:[0,0,1]
	v_lshl_add_u64 v[16:17], v[112:113], 0, v[34:35]
	v_lshl_add_u64 v[18:19], v[112:113], 0, v[36:37]
	global_store_dwordx2 v[16:17], v[40:41], off
	global_store_dwordx2 v[18:19], v[42:43], off
	v_mov_b32_e32 v16, v246
	v_mov_b32_e32 v17, v247
	v_mov_b32_e32 v18, v248
	v_mov_b32_e32 v19, v249
	s_nop 0
	v_mov_b32_e32 v20, v250
	v_mov_b32_e32 v21, v251
	v_mov_b32_e32 v22, v252
	v_mov_b32_e32 v23, v253
	v_lshl_add_u64 v[28:29], v[44:45], 0, s[14:15]
	v_mov_b32_e32 v24, 0
	v_mov_b32_e32 v25, 0
	v_mov_b32_e32 v26, 0
	v_mov_b32_e32 v27, 0
	v_mov_b32_e32 v30, v16
	v_mov_b32_e32 v31, v20
	v_mov_b32_e32 v20, v17
	v_mov_b32_e32 v16, v18
	v_mov_b32_e32 v17, v22
	v_mov_b32_e32 v22, v19
	v_pk_add_f32 v[18:19], v[30:31], v[20:21]
	v_pk_add_f32 v[16:17], v[16:17], v[22:23]
	s_nop 0
	v_pk_add_f32 v[16:17], v[18:19], v[16:17]
	v_lshl_add_u64 v[18:19], v[44:45], 0, s[36:37]
	v_add_f32_e32 v16, v16, v17
	v_fmamk_f32 v16, v16, 0x3b000000, v149
	v_rsq_f32_e32 v254, v16
	v_lshlrev_b64 v[18:19], 7, v[18:19]
	s_nop 0
	v_lshlrev_b64 v[16:17], 7, v[28:29]
	v_lshl_add_u64 v[16:17], v[112:113], 0, v[16:17]
	s_nop 1
	s_nop 1
	s_nop 1
	v_mov_b32_e32 v20, v254
	v_pk_mul_f32 v[12:13], v[12:13], v[20:21] op_sel_hi:[1,0]
	v_pk_mul_f32 v[8:9], v[8:9], v[20:21] op_sel_hi:[1,0]
	v_pk_mul_f32 v[4:5], v[4:5], v[20:21] op_sel_hi:[1,0]
	v_pk_mul_f32 v[0:1], v[0:1], v[20:21] op_sel_hi:[1,0]
	v_med3_f32 v12, v12, s74, v153
	v_med3_f32 v13, v13, s74, v153
	v_med3_f32 v8, v8, s74, v153
	v_med3_f32 v9, v9, s74, v153
	v_med3_f32 v4, v4, s74, v153
	v_med3_f32 v5, v5, s74, v153
	v_med3_f32 v0, v0, s74, v153
	v_med3_f32 v1, v1, s74, v153
	v_cvt_pk_fp8_f32 v24, v12, v13
	v_cvt_pk_fp8_f32 v25, v8, v9
	v_cvt_pk_fp8_f32 v26, v4, v5
	v_cvt_pk_fp8_f32 v27, v0, v1
	v_pk_mul_f32 v[14:15], v[14:15], v[20:21] op_sel_hi:[1,0]
	v_pk_mul_f32 v[10:11], v[10:11], v[20:21] op_sel_hi:[1,0]
	v_pk_mul_f32 v[6:7], v[6:7], v[20:21] op_sel_hi:[1,0]
	v_pk_mul_f32 v[2:3], v[2:3], v[20:21] op_sel_hi:[1,0]
	v_med3_f32 v14, v14, s74, v153
	v_med3_f32 v15, v15, s74, v153
	v_med3_f32 v10, v10, s74, v153
	v_med3_f32 v11, v11, s74, v153
	v_med3_f32 v6, v6, s74, v153
	v_med3_f32 v7, v7, s74, v153
	v_med3_f32 v2, v2, s74, v153
	v_med3_f32 v3, v3, s74, v153
	v_cvt_pk_fp8_f32 v24, v14, v15 op_sel:[0,0,1]
	v_cvt_pk_fp8_f32 v25, v10, v11 op_sel:[0,0,1]
	v_cvt_pk_fp8_f32 v26, v6, v7 op_sel:[0,0,1]
	v_cvt_pk_fp8_f32 v27, v2, v3 op_sel:[0,0,1]
	s_andn2_b64 vcc, exec, s[2:3]
	s_mov_b64 s[2:3], -1
	v_lshl_add_u64 v[0:1], v[112:113], 0, v[18:19]
	global_store_dwordx2 v[16:17], v[24:25], off
	global_store_dwordx2 v[0:1], v[26:27], off
	s_cbranch_vccnz .LBB0_4130
; #define PG8_BAR __builtin_amdgcn_s_barrier()
;     ...
;         if (!has_next) break;
; #pragma unroll
;         for (int a = 0; a < 2; ++a)
; #pragma unroll
;             for (int b = 0; b < 2; ++b)
; #pragma unroll
;                 for (int m = 0; m < 4; ++m)
; #pragma unroll
;                     for (int n = 0; n < 2; ++n) acc[a][b][m][n] = (f32x4){0.f, 0.f, 0.f, 0.f};
;         cur = nxt; cA = nA; cB = nB; ++ui;
;         if (wr == 1) PG8_BAR;
;     }
	s_andn2_b64 vcc, exec, s[16:17]
	s_cbranch_vccnz .LBB0_4129
	s_barrier
	s_branch .LBB0_4129

;     __device__ __forceinline__ void operator()(EPI_ARGS) const {
;         const int row0 = u.pm * BM + wr * 64 + fr, col0 = u.pn * BM + wc * 32 + 8 * fq;
;         f32x4 gg[2][2], bb[2][2];
;         if constexpr (RESLN) {
; #pragma unroll
;             for (int bj = 0; bj < 2; ++bj)
; #pragma unroll
;                 for (int n = 0; n < 2; ++n) { gg[bj][n] = *(const f32x4*)(lg + col0 + bj * HALF + 4 * n); bb[bj][n] = *(const f32x4*)(lb + col0 + bj * HALF + 4 * n); } }
; #pragma unroll
;         for (int ai = 0; ai < 2; ++ai)
; #pragma unroll
;             for (int m = 0; m < 4; ++m) { const int row = row0 + ai * HALF + m * 16; const size_t off = (size_t)row * DM + col0;
;                 float mu = 0.f, rs = 1.f; if constexpr (RESLN) ln_stats(stin, row, mu, rs);
;                 float ss = 0.f, qq = 0.f;
; #pragma unroll
;                 for (int bj = 0; bj < 2; ++bj) { f32x4 r0 = __builtin_nontemporal_load((const f32x4*)(res + off + bj * HALF)), r1 = __builtin_nontemporal_load((const f32x4*)(res + off + bj * HALF + 4));
;                     if constexpr (RESLN) { r0 = (r0 - mu) * rs * gg[bj][0] + bb[bj][0]; r1 = (r1 - mu) * rs * gg[bj][1] + bb[bj][1]; }
;                     const f32x4 y0 = r0 * DN_ALPHA + acc[ai][bj][m][0] * ascale, y1 = r1 * DN_ALPHA + acc[ai][bj][m][1] * ascale;
;                     if constexpr (COPY != 4) { __builtin_nontemporal_store(y0, (f32x4*)(Y + off + bj * HALF)); __builtin_nontemporal_store(y1, (f32x4*)(Y + off + bj * HALF + 4)); }
;                     if constexpr (STATS) { ss += ((y0[0] + y0[1]) + (y0[2] + y0[3])) + ((y1[0] + y1[1]) + (y1[2] + y1[3]));
;                         qq += ((y0[0] * y0[0] + y0[1] * y0[1]) + (y0[2] * y0[2] + y0[3] * y0[3])) + ((y1[0] * y1[0] + y1[1] * y1[1]) + (y1[2] * y1[2] + y1[3] * y1[3])); }
;                     if constexpr (COPY == 1) *(u32x2*)((unsigned char*)copy + off + bj * HALF) = pack8fp8(y0 * cscale, y1 * cscale);
;                     if constexpr (COPY == 3) *(u32x2*)((unsigned char*)copy + off + bj * HALF) = pack8i8(y0 * cscale, y1 * cscale);
;                     if constexpr (COPY == 2 || COPY == 4) *(u32x4*)((bf16_t*)copy + off + bj * HALF) = pack8bf(y0, y1); }
;                 if constexpr (STATS) { ss += __shfl_xor(ss, 16); ss += __shfl_xor(ss, 32); qq += __shfl_xor(qq, 16); qq += __shfl_xor(qq, 32);
.LBB0_4505:
	v_lshl_add_u32 v178, s4, 8, v184
	v_ashrrev_i32_e32 v179, 31, v178
	v_lshl_add_u64 v[2:3], v[178:179], 3, s[12:13]
	global_load_dwordx2 v[196:197], v[2:3], off
	v_lshl_or_b32 v176, s5, 8, v186
	v_ashrrev_i32_e32 v177, 31, v176
	v_lshlrev_b64 v[0:1], 11, v[178:179]
	v_lshl_add_u64 v[198:199], v[0:1], 0, v[176:177]
	v_lshl_add_u64 v[200:201], v[198:199], 2, s[14:15]
	global_load_dwordx4 v[180:183], v[200:201], off nt
	global_load_dwordx4 v[192:195], v[200:201], off offset:16 nt
	v_lshlrev_b64 v[0:1], 2, v[176:177]
	v_lshl_add_u64 v[4:5], s[8:9], 0, v[0:1]
	v_lshl_add_u64 v[12:13], s[10:11], 0, v[0:1]
	global_load_dwordx4 v[20:23], v[12:13], off
	global_load_dwordx4 v[24:27], v[4:5], off
	global_load_dwordx4 v[16:19], v[4:5], off offset:16
	global_load_dwordx4 v[28:31], v[12:13], off offset:16
	global_load_dwordx4 v[0:3], v[4:5], off offset:528
	global_load_dwordx4 v[8:11], v[4:5], off offset:512
	s_nop 0
	global_load_dwordx4 v[4:7], v[12:13], off offset:528
	s_nop 0
	global_load_dwordx4 v[12:15], v[12:13], off offset:512
	v_lshl_add_u64 v[198:199], v[198:199], 1, s[16:17]
	s_waitcnt vmcnt(0)
	v_pk_mul_f32 v[196:197], v[196:197], s[24:25] op_sel_hi:[1,0]
	s_nop 0
	v_fma_f32 v179, -v196, v196, v197
	v_add_f32_e32 v179, 0x3727c5ac, v179
	v_rsq_f32_e32 v254, v179
	v_sub_f32_e32 v181, v181, v196
	v_sub_f32_e32 v180, v180, v196
	v_sub_f32_e32 v195, v195, v196
	v_sub_f32_e32 v194, v194, v196
	v_sub_f32_e32 v193, v193, v196
	v_sub_f32_e32 v192, v192, v196
	v_sub_f32_e32 v183, v183, v196
	v_sub_f32_e32 v182, v182, v196
	s_nop 0
	s_nop 1
	v_mov_b32_e32 v202, v254
	v_pk_mul_f32 v[180:181], v[180:181], v[202:203] op_sel_hi:[1,0]
	v_pk_mul_f32 v[192:193], v[192:193], v[202:203] op_sel_hi:[1,0]
	v_pk_mul_f32 v[194:195], v[194:195], v[202:203] op_sel_hi:[1,0]
	v_pk_mul_f32 v[182:183], v[182:183], v[202:203] op_sel_hi:[1,0]
	v_pk_fma_f32 v[180:181], v[24:25], v[180:181], v[20:21]
	v_pk_fma_f32 v[194:195], v[18:19], v[194:195], v[30:31]
	v_pk_fma_f32 v[192:193], v[16:17], v[192:193], v[28:29]
	v_pk_fma_f32 v[182:183], v[26:27], v[182:183], v[22:23]
	v_pk_mul_f32 v[180:181], v[180:181], s[26:27] op_sel_hi:[1,0]
	v_pk_mul_f32 v[192:193], v[192:193], s[26:27] op_sel_hi:[1,0]
	v_pk_mul_f32 v[194:195], v[194:195], s[26:27] op_sel_hi:[1,0]
	v_pk_mul_f32 v[182:183], v[182:183], s[26:27] op_sel_hi:[1,0]
	v_pk_fma_f32 v[156:157], v[156:157], s[28:29], v[180:181] op_sel_hi:[1,0,1]
	v_pk_fma_f32 v[180:181], v[154:155], s[28:29], v[194:195] op_sel_hi:[1,0,1]
	v_pk_fma_f32 v[154:155], v[152:153], s[28:29], v[192:193] op_sel_hi:[1,0,1]
	v_pk_fma_f32 v[158:159], v[158:159], s[28:29], v[182:183] op_sel_hi:[1,0,1]
	v_cvt_pk_bf16_f32 v152, v156, v157
	s_nop 0
	v_cvt_pk_bf16_f32 v153, v158, v159
	v_cvt_pk_bf16_f32 v154, v154, v155
	v_cvt_pk_bf16_f32 v155, v180, v181
	global_store_dwordx4 v[198:199], v[152:155], off
	global_load_dwordx4 v[152:155], v[200:201], off offset:512 nt
	s_nop 0
	global_load_dwordx4 v[156:159], v[200:201], off offset:528 nt
	v_or_b32_e32 v180, 16, v178
	v_ashrrev_i32_e32 v181, 31, v180
	v_lshlrev_b64 v[182:183], 11, v[180:181]
	v_lshl_add_u64 v[180:181], v[180:181], 3, s[12:13]
	v_lshl_add_u64 v[182:183], v[182:183], 0, v[176:177]
	s_waitcnt vmcnt(1)
	v_sub_f32_e32 v153, v153, v196
	v_sub_f32_e32 v152, v152, v196
	s_waitcnt vmcnt(0)
	v_sub_f32_e32 v159, v159, v196
	v_sub_f32_e32 v158, v158, v196
	v_sub_f32_e32 v157, v157, v196
	v_sub_f32_e32 v156, v156, v196
	v_sub_f32_e32 v155, v155, v196
	v_sub_f32_e32 v154, v154, v196
	v_pk_mul_f32 v[152:153], v[202:203], v[152:153] op_sel_hi:[0,1]
	v_pk_mul_f32 v[156:157], v[202:203], v[156:157] op_sel_hi:[0,1]
	v_pk_mul_f32 v[158:159], v[202:203], v[158:159] op_sel_hi:[0,1]
	v_pk_mul_f32 v[154:155], v[202:203], v[154:155] op_sel_hi:[0,1]
	v_pk_fma_f32 v[152:153], v[8:9], v[152:153], v[12:13]
	v_pk_fma_f32 v[158:159], v[2:3], v[158:159], v[6:7]
	v_pk_fma_f32 v[156:157], v[0:1], v[156:157], v[4:5]
	v_pk_fma_f32 v[154:155], v[10:11], v[154:155], v[14:15]
	v_pk_mul_f32 v[152:153], v[152:153], s[26:27] op_sel_hi:[1,0]
	v_pk_mul_f32 v[156:157], v[156:157], s[26:27] op_sel_hi:[1,0]
	v_pk_mul_f32 v[158:159], v[158:159], s[26:27] op_sel_hi:[1,0]
	v_pk_mul_f32 v[154:155], v[154:155], s[26:27] op_sel_hi:[1,0]
	v_pk_fma_f32 v[148:149], v[148:149], s[28:29], v[152:153] op_sel_hi:[1,0,1]
	v_pk_fma_f32 v[152:153], v[146:147], s[28:29], v[158:159] op_sel_hi:[1,0,1]
	v_pk_fma_f32 v[146:147], v[144:145], s[28:29], v[156:157] op_sel_hi:[1,0,1]
	v_pk_fma_f32 v[150:151], v[150:151], s[28:29], v[154:155] op_sel_hi:[1,0,1]
	v_cvt_pk_bf16_f32 v144, v148, v149
	v_lshl_add_u64 v[154:155], v[182:183], 2, s[14:15]
	v_cvt_pk_bf16_f32 v145, v150, v151
	v_cvt_pk_bf16_f32 v146, v146, v147
	v_cvt_pk_bf16_f32 v147, v152, v153
	global_store_dwordx4 v[198:199], v[144:147], off offset:256
	global_load_dwordx2 v[152:153], v[180:181], off
	global_load_dwordx4 v[144:147], v[154:155], off nt
	global_load_dwordx4 v[148:151], v[154:155], off offset:16 nt
	v_lshl_add_u64 v[156:157], v[182:183], 1, s[16:17]
	s_waitcnt vmcnt(2)
	v_pk_mul_f32 v[152:153], v[152:153], s[24:25] op_sel_hi:[1,0]
	s_nop 0
	v_fma_f32 v153, -v152, v152, v153
	v_add_f32_e32 v153, 0x3727c5ac, v153
	v_rsq_f32_e32 v254, v153
	s_waitcnt vmcnt(1)
	v_sub_f32_e32 v145, v145, v152
	v_sub_f32_e32 v144, v144, v152
	s_waitcnt vmcnt(0)
;     __device__ __forceinline__ void operator()(EPI_ARGS) const {
;         const int row0 = u.pm * BM + wr * 64 + fr, col0 = u.pn * BM + wc * 32 + 8 * fq;
;         f32x4 gg[2][2], bb[2][2];
;         if constexpr (RESLN) {
; #pragma unroll
;             for (int bj = 0; bj < 2; ++bj)
; #pragma unroll
;                 for (int n = 0; n < 2; ++n) { gg[bj][n] = *(const f32x4*)(lg + col0 + bj * HALF + 4 * n); bb[bj][n] = *(const f32x4*)(lb + col0 + bj * HALF + 4 * n); } }
; #pragma unroll
;         for (int ai = 0; ai < 2; ++ai)
; #pragma unroll
;             for (int m = 0; m < 4; ++m) { const int row = row0 + ai * HALF + m * 16; const size_t off = (size_t)row * DM + col0;
;                 float mu = 0.f, rs = 1.f; if constexpr (RESLN) ln_stats(stin, row, mu, rs);
;                 float ss = 0.f, qq = 0.f;
; #pragma unroll
;                 for (int bj = 0; bj < 2; ++bj) { f32x4 r0 = __builtin_nontemporal_load((const f32x4*)(res + off + bj * HALF)), r1 = __builtin_nontemporal_load((const f32x4*)(res + off + bj * HALF + 4));
;                     if constexpr (RESLN) { r0 = (r0 - mu) * rs * gg[bj][0] + bb[bj][0]; r1 = (r1 - mu) * rs * gg[bj][1] + bb[bj][1]; }
;                     const f32x4 y0 = r0 * DN_ALPHA + acc[ai][bj][m][0] * ascale, y1 = r1 * DN_ALPHA + acc[ai][bj][m][1] * ascale;
;                     if constexpr (COPY != 4) { __builtin_nontemporal_store(y0, (f32x4*)(Y + off + bj * HALF)); __builtin_nontemporal_store(y1, (f32x4*)(Y + off + bj * HALF + 4)); }
;                     if constexpr (STATS) { ss += ((y0[0] + y0[1]) + (y0[2] + y0[3])) + ((y1[0] + y1[1]) + (y1[2] + y1[3]));
;                         qq += ((y0[0] * y0[0] + y0[1] * y0[1]) + (y0[2] * y0[2] + y0[3] * y0[3])) + ((y1[0] * y1[0] + y1[1] * y1[1]) + (y1[2] * y1[2] + y1[3] * y1[3])); }
;                     if constexpr (COPY == 1) *(u32x2*)((unsigned char*)copy + off + bj * HALF) = pack8fp8(y0 * cscale, y1 * cscale);
;                     if constexpr (COPY == 3) *(u32x2*)((unsigned char*)copy + off + bj * HALF) = pack8i8(y0 * cscale, y1 * cscale);
;                     if constexpr (COPY == 2 || COPY == 4) *(u32x4*)((bf16_t*)copy + off + bj * HALF) = pack8bf(y0, y1); }
;                 if constexpr (STATS) { ss += __shfl_xor(ss, 16); ss += __shfl_xor(ss, 32); qq += __shfl_xor(qq, 16); qq += __shfl_xor(qq, 32);
	v_sub_f32_e32 v151, v151, v152
	v_sub_f32_e32 v150, v150, v152
	v_sub_f32_e32 v149, v149, v152
	v_sub_f32_e32 v148, v148, v152
	v_sub_f32_e32 v147, v147, v152
	v_sub_f32_e32 v146, v146, v152
	s_nop 0
	s_nop 1
	v_mov_b32_e32 v158, v254
	v_pk_mul_f32 v[144:145], v[144:145], v[158:159] op_sel_hi:[1,0]
	v_pk_mul_f32 v[148:149], v[148:149], v[158:159] op_sel_hi:[1,0]
	v_pk_mul_f32 v[150:151], v[150:151], v[158:159] op_sel_hi:[1,0]
	v_pk_mul_f32 v[146:147], v[146:147], v[158:159] op_sel_hi:[1,0]
	v_pk_fma_f32 v[144:145], v[24:25], v[144:145], v[20:21]
	v_pk_fma_f32 v[150:151], v[18:19], v[150:151], v[30:31]
	v_pk_fma_f32 v[148:149], v[16:17], v[148:149], v[28:29]
	v_pk_fma_f32 v[146:147], v[26:27], v[146:147], v[22:23]
	v_pk_mul_f32 v[144:145], v[144:145], s[26:27] op_sel_hi:[1,0]
	v_pk_mul_f32 v[148:149], v[148:149], s[26:27] op_sel_hi:[1,0]
	v_pk_mul_f32 v[150:151], v[150:151], s[26:27] op_sel_hi:[1,0]
	v_pk_mul_f32 v[146:147], v[146:147], s[26:27] op_sel_hi:[1,0]
	v_pk_fma_f32 v[140:141], v[140:141], s[28:29], v[144:145] op_sel_hi:[1,0,1]
	v_pk_fma_f32 v[144:145], v[138:139], s[28:29], v[150:151] op_sel_hi:[1,0,1]
	v_pk_fma_f32 v[138:139], v[136:137], s[28:29], v[148:149] op_sel_hi:[1,0,1]
	v_pk_fma_f32 v[142:143], v[142:143], s[28:29], v[146:147] op_sel_hi:[1,0,1]
	v_cvt_pk_bf16_f32 v136, v140, v141
	s_nop 0
	v_cvt_pk_bf16_f32 v137, v142, v143
	v_cvt_pk_bf16_f32 v138, v138, v139
	v_cvt_pk_bf16_f32 v139, v144, v145
	global_store_dwordx4 v[156:157], v[136:139], off
	global_load_dwordx4 v[136:139], v[154:155], off offset:512 nt
	s_nop 0
	global_load_dwordx4 v[140:143], v[154:155], off offset:528 nt
	v_or_b32_e32 v144, 32, v178
	v_ashrrev_i32_e32 v145, 31, v144
	v_lshlrev_b64 v[146:147], 11, v[144:145]
	v_lshl_add_u64 v[144:145], v[144:145], 3, s[12:13]
	v_lshl_add_u64 v[146:147], v[146:147], 0, v[176:177]
	s_waitcnt vmcnt(1)
	v_sub_f32_e32 v137, v137, v152
	v_sub_f32_e32 v136, v136, v152
	s_waitcnt vmcnt(0)
	v_sub_f32_e32 v143, v143, v152
	v_sub_f32_e32 v142, v142, v152
	v_sub_f32_e32 v141, v141, v152
	v_sub_f32_e32 v140, v140, v152
	v_sub_f32_e32 v139, v139, v152
	v_sub_f32_e32 v138, v138, v152
	v_pk_mul_f32 v[136:137], v[158:159], v[136:137] op_sel_hi:[0,1]
	v_pk_mul_f32 v[140:141], v[158:159], v[140:141] op_sel_hi:[0,1]
	v_pk_mul_f32 v[142:143], v[158:159], v[142:143] op_sel_hi:[0,1]
	v_pk_mul_f32 v[138:139], v[158:159], v[138:139] op_sel_hi:[0,1]
	v_pk_fma_f32 v[136:137], v[8:9], v[136:137], v[12:13]
	v_pk_fma_f32 v[142:143], v[2:3], v[142:143], v[6:7]
	v_pk_fma_f32 v[140:141], v[0:1], v[140:141], v[4:5]
	v_pk_fma_f32 v[138:139], v[10:11], v[138:139], v[14:15]
	v_pk_mul_f32 v[136:137], v[136:137], s[26:27] op_sel_hi:[1,0]
	v_pk_mul_f32 v[140:141], v[140:141], s[26:27] op_sel_hi:[1,0]
	v_pk_mul_f32 v[142:143], v[142:143], s[26:27] op_sel_hi:[1,0]
	v_pk_mul_f32 v[138:139], v[138:139], s[26:27] op_sel_hi:[1,0]
	v_pk_fma_f32 v[132:133], v[132:133], s[28:29], v[136:137] op_sel_hi:[1,0,1]
	v_pk_fma_f32 v[136:137], v[130:131], s[28:29], v[142:143] op_sel_hi:[1,0,1]
	v_pk_fma_f32 v[130:131], v[128:129], s[28:29], v[140:141] op_sel_hi:[1,0,1]
	v_pk_fma_f32 v[134:135], v[134:135], s[28:29], v[138:139] op_sel_hi:[1,0,1]
	v_cvt_pk_bf16_f32 v128, v132, v133
	v_lshl_add_u64 v[138:139], v[146:147], 2, s[14:15]
	v_cvt_pk_bf16_f32 v129, v134, v135
	v_cvt_pk_bf16_f32 v130, v130, v131
	v_cvt_pk_bf16_f32 v131, v136, v137
	global_store_dwordx4 v[156:157], v[128:131], off offset:256
	global_load_dwordx2 v[136:137], v[144:145], off
	global_load_dwordx4 v[128:131], v[138:139], off nt
	global_load_dwordx4 v[132:135], v[138:139], off offset:16 nt
	v_lshl_add_u64 v[140:141], v[146:147], 1, s[16:17]
	s_waitcnt vmcnt(2)
	v_pk_mul_f32 v[136:137], v[136:137], s[24:25] op_sel_hi:[1,0]
	s_nop 0
	v_fma_f32 v137, -v136, v136, v137
	v_add_f32_e32 v137, 0x3727c5ac, v137
	v_rsq_f32_e32 v254, v137
	s_waitcnt vmcnt(1)
	v_sub_f32_e32 v129, v129, v136
	v_sub_f32_e32 v128, v128, v136
	s_waitcnt vmcnt(0)
	v_sub_f32_e32 v135, v135, v136
	v_sub_f32_e32 v134, v134, v136
	v_sub_f32_e32 v133, v133, v136
	v_sub_f32_e32 v132, v132, v136
	v_sub_f32_e32 v131, v131, v136
	v_sub_f32_e32 v130, v130, v136
	s_nop 0
	s_nop 1
	v_mov_b32_e32 v142, v254
	v_pk_mul_f32 v[128:129], v[128:129], v[142:143] op_sel_hi:[1,0]
	v_pk_mul_f32 v[132:133], v[132:133], v[142:143] op_sel_hi:[1,0]
	v_pk_mul_f32 v[134:135], v[134:135], v[142:143] op_sel_hi:[1,0]
	v_pk_mul_f32 v[130:131], v[130:131], v[142:143] op_sel_hi:[1,0]
	v_pk_fma_f32 v[128:129], v[24:25], v[128:129], v[20:21]
	v_pk_fma_f32 v[134:135], v[18:19], v[134:135], v[30:31]
	v_pk_fma_f32 v[132:133], v[16:17], v[132:133], v[28:29]
	v_pk_fma_f32 v[130:131], v[26:27], v[130:131], v[22:23]
	v_pk_mul_f32 v[128:129], v[128:129], s[26:27] op_sel_hi:[1,0]
	v_pk_mul_f32 v[132:133], v[132:133], s[26:27] op_sel_hi:[1,0]
	v_pk_mul_f32 v[134:135], v[134:135], s[26:27] op_sel_hi:[1,0]
	v_pk_mul_f32 v[130:131], v[130:131], s[26:27] op_sel_hi:[1,0]
	v_pk_fma_f32 v[124:125], v[124:125], s[28:29], v[128:129] op_sel_hi:[1,0,1]
	v_pk_fma_f32 v[128:129], v[122:123], s[28:29], v[134:135] op_sel_hi:[1,0,1]
	v_pk_fma_f32 v[122:123], v[120:121], s[28:29], v[132:133] op_sel_hi:[1,0,1]
	v_pk_fma_f32 v[126:127], v[126:127], s[28:29], v[130:131] op_sel_hi:[1,0,1]
	v_cvt_pk_bf16_f32 v120, v124, v125
	s_nop 0
	v_cvt_pk_bf16_f32 v121, v126, v127
	v_cvt_pk_bf16_f32 v122, v122, v123
	v_cvt_pk_bf16_f32 v123, v128, v129
	global_store_dwordx4 v[140:141], v[120:123], off
	global_load_dwordx4 v[120:123], v[138:139], off offset:512 nt
	s_nop 0
	global_load_dwordx4 v[124:127], v[138:139], off offset:528 nt
	v_or_b32_e32 v128, 48, v178
	v_ashrrev_i32_e32 v129, 31, v128
	v_lshlrev_b64 v[130:131], 11, v[128:129]
	v_lshl_add_u64 v[128:129], v[128:129], 3, s[12:13]
	v_lshl_add_u64 v[130:131], v[130:131], 0, v[176:177]
	s_waitcnt vmcnt(1)
;     __device__ __forceinline__ void operator()(EPI_ARGS) const {
;         const int row0 = u.pm * BM + wr * 64 + fr, col0 = u.pn * BM + wc * 32 + 8 * fq;
;         f32x4 gg[2][2], bb[2][2];
;         if constexpr (RESLN) {
; #pragma unroll
;             for (int bj = 0; bj < 2; ++bj)
; #pragma unroll
;                 for (int n = 0; n < 2; ++n) { gg[bj][n] = *(const f32x4*)(lg + col0 + bj * HALF + 4 * n); bb[bj][n] = *(const f32x4*)(lb + col0 + bj * HALF + 4 * n); } }
; #pragma unroll
;         for (int ai = 0; ai < 2; ++ai)
; #pragma unroll
;             for (int m = 0; m < 4; ++m) { const int row = row0 + ai * HALF + m * 16; const size_t off = (size_t)row * DM + col0;
;                 float mu = 0.f, rs = 1.f; if constexpr (RESLN) ln_stats(stin, row, mu, rs);
;                 float ss = 0.f, qq = 0.f;
; #pragma unroll
;                 for (int bj = 0; bj < 2; ++bj) { f32x4 r0 = __builtin_nontemporal_load((const f32x4*)(res + off + bj * HALF)), r1 = __builtin_nontemporal_load((const f32x4*)(res + off + bj * HALF + 4));
;                     if constexpr (RESLN) { r0 = (r0 - mu) * rs * gg[bj][0] + bb[bj][0]; r1 = (r1 - mu) * rs * gg[bj][1] + bb[bj][1]; }
;                     const f32x4 y0 = r0 * DN_ALPHA + acc[ai][bj][m][0] * ascale, y1 = r1 * DN_ALPHA + acc[ai][bj][m][1] * ascale;
;                     if constexpr (COPY != 4) { __builtin_nontemporal_store(y0, (f32x4*)(Y + off + bj * HALF)); __builtin_nontemporal_store(y1, (f32x4*)(Y + off + bj * HALF + 4)); }
;                     if constexpr (STATS) { ss += ((y0[0] + y0[1]) + (y0[2] + y0[3])) + ((y1[0] + y1[1]) + (y1[2] + y1[3]));
;                         qq += ((y0[0] * y0[0] + y0[1] * y0[1]) + (y0[2] * y0[2] + y0[3] * y0[3])) + ((y1[0] * y1[0] + y1[1] * y1[1]) + (y1[2] * y1[2] + y1[3] * y1[3])); }
;                     if constexpr (COPY == 1) *(u32x2*)((unsigned char*)copy + off + bj * HALF) = pack8fp8(y0 * cscale, y1 * cscale);
;                     if constexpr (COPY == 3) *(u32x2*)((unsigned char*)copy + off + bj * HALF) = pack8i8(y0 * cscale, y1 * cscale);
;                     if constexpr (COPY == 2 || COPY == 4) *(u32x4*)((bf16_t*)copy + off + bj * HALF) = pack8bf(y0, y1); }
;                 if constexpr (STATS) { ss += __shfl_xor(ss, 16); ss += __shfl_xor(ss, 32); qq += __shfl_xor(qq, 16); qq += __shfl_xor(qq, 32);
	v_sub_f32_e32 v121, v121, v136
	v_sub_f32_e32 v120, v120, v136
	s_waitcnt vmcnt(0)
	v_sub_f32_e32 v127, v127, v136
	v_sub_f32_e32 v126, v126, v136
	v_sub_f32_e32 v125, v125, v136
	v_sub_f32_e32 v124, v124, v136
	v_sub_f32_e32 v123, v123, v136
	v_sub_f32_e32 v122, v122, v136
	v_pk_mul_f32 v[120:121], v[142:143], v[120:121] op_sel_hi:[0,1]
	v_pk_mul_f32 v[124:125], v[142:143], v[124:125] op_sel_hi:[0,1]
	v_pk_mul_f32 v[126:127], v[142:143], v[126:127] op_sel_hi:[0,1]
	v_pk_mul_f32 v[122:123], v[142:143], v[122:123] op_sel_hi:[0,1]
	v_pk_fma_f32 v[120:121], v[8:9], v[120:121], v[12:13]
	v_pk_fma_f32 v[126:127], v[2:3], v[126:127], v[6:7]
	v_pk_fma_f32 v[124:125], v[0:1], v[124:125], v[4:5]
	v_pk_fma_f32 v[122:123], v[10:11], v[122:123], v[14:15]
	v_pk_mul_f32 v[120:121], v[120:121], s[26:27] op_sel_hi:[1,0]
	v_pk_mul_f32 v[124:125], v[124:125], s[26:27] op_sel_hi:[1,0]
	v_pk_mul_f32 v[126:127], v[126:127], s[26:27] op_sel_hi:[1,0]
	v_pk_mul_f32 v[122:123], v[122:123], s[26:27] op_sel_hi:[1,0]
	v_pk_fma_f32 v[116:117], v[116:117], s[28:29], v[120:121] op_sel_hi:[1,0,1]
	v_pk_fma_f32 v[120:121], v[114:115], s[28:29], v[126:127] op_sel_hi:[1,0,1]
	v_pk_fma_f32 v[114:115], v[112:113], s[28:29], v[124:125] op_sel_hi:[1,0,1]
	v_pk_fma_f32 v[118:119], v[118:119], s[28:29], v[122:123] op_sel_hi:[1,0,1]
	v_cvt_pk_bf16_f32 v112, v116, v117
	v_lshl_add_u64 v[122:123], v[130:131], 2, s[14:15]
	v_cvt_pk_bf16_f32 v113, v118, v119
	v_cvt_pk_bf16_f32 v114, v114, v115
	v_cvt_pk_bf16_f32 v115, v120, v121
	global_store_dwordx4 v[140:141], v[112:115], off offset:256
	global_load_dwordx2 v[120:121], v[128:129], off
	global_load_dwordx4 v[112:115], v[122:123], off nt
	global_load_dwordx4 v[116:119], v[122:123], off offset:16 nt
	v_lshl_add_u64 v[124:125], v[130:131], 1, s[16:17]
	s_waitcnt vmcnt(2)
	v_pk_mul_f32 v[120:121], v[120:121], s[24:25] op_sel_hi:[1,0]
	s_nop 0
	v_fma_f32 v121, -v120, v120, v121
	v_add_f32_e32 v121, 0x3727c5ac, v121
	v_rsq_f32_e32 v254, v121
	s_waitcnt vmcnt(1)
	v_sub_f32_e32 v113, v113, v120
	v_sub_f32_e32 v112, v112, v120
	s_waitcnt vmcnt(0)
	v_sub_f32_e32 v119, v119, v120
	v_sub_f32_e32 v118, v118, v120
	v_sub_f32_e32 v117, v117, v120
	v_sub_f32_e32 v116, v116, v120
	v_sub_f32_e32 v115, v115, v120
	v_sub_f32_e32 v114, v114, v120
	s_nop 0
	s_nop 1
	v_mov_b32_e32 v126, v254
	v_pk_mul_f32 v[112:113], v[112:113], v[126:127] op_sel_hi:[1,0]
	v_pk_mul_f32 v[116:117], v[116:117], v[126:127] op_sel_hi:[1,0]
	v_pk_mul_f32 v[118:119], v[118:119], v[126:127] op_sel_hi:[1,0]
	v_pk_mul_f32 v[114:115], v[114:115], v[126:127] op_sel_hi:[1,0]
	v_pk_fma_f32 v[112:113], v[24:25], v[112:113], v[20:21]
	v_pk_fma_f32 v[118:119], v[18:19], v[118:119], v[30:31]
	v_pk_fma_f32 v[116:117], v[16:17], v[116:117], v[28:29]
	v_pk_fma_f32 v[114:115], v[26:27], v[114:115], v[22:23]
	v_pk_mul_f32 v[112:113], v[112:113], s[26:27] op_sel_hi:[1,0]
	v_pk_mul_f32 v[116:117], v[116:117], s[26:27] op_sel_hi:[1,0]
	v_pk_mul_f32 v[118:119], v[118:119], s[26:27] op_sel_hi:[1,0]
	v_pk_mul_f32 v[114:115], v[114:115], s[26:27] op_sel_hi:[1,0]
	v_pk_fma_f32 v[108:109], v[108:109], s[28:29], v[112:113] op_sel_hi:[1,0,1]
	v_pk_fma_f32 v[112:113], v[106:107], s[28:29], v[118:119] op_sel_hi:[1,0,1]
	v_pk_fma_f32 v[106:107], v[104:105], s[28:29], v[116:117] op_sel_hi:[1,0,1]
	v_pk_fma_f32 v[110:111], v[110:111], s[28:29], v[114:115] op_sel_hi:[1,0,1]
	v_cvt_pk_bf16_f32 v104, v108, v109
	s_nop 0
	v_cvt_pk_bf16_f32 v105, v110, v111
	v_cvt_pk_bf16_f32 v106, v106, v107
	v_cvt_pk_bf16_f32 v107, v112, v113
	global_store_dwordx4 v[124:125], v[104:107], off
	global_load_dwordx4 v[104:107], v[122:123], off offset:512 nt
	s_nop 0
	global_load_dwordx4 v[108:111], v[122:123], off offset:528 nt
	v_add_u32_e32 v112, 0x80, v178
	v_ashrrev_i32_e32 v113, 31, v112
	v_lshlrev_b64 v[114:115], 11, v[112:113]
	v_lshl_add_u64 v[112:113], v[112:113], 3, s[12:13]
	v_lshl_add_u64 v[114:115], v[114:115], 0, v[176:177]
	s_waitcnt vmcnt(1)
	v_sub_f32_e32 v105, v105, v120
	v_sub_f32_e32 v104, v104, v120
	s_waitcnt vmcnt(0)
	v_sub_f32_e32 v111, v111, v120
	v_sub_f32_e32 v110, v110, v120
	v_sub_f32_e32 v109, v109, v120
	v_sub_f32_e32 v108, v108, v120
	v_sub_f32_e32 v107, v107, v120
	v_sub_f32_e32 v106, v106, v120
	v_pk_mul_f32 v[104:105], v[126:127], v[104:105] op_sel_hi:[0,1]
	v_pk_mul_f32 v[108:109], v[126:127], v[108:109] op_sel_hi:[0,1]
	v_pk_mul_f32 v[110:111], v[126:127], v[110:111] op_sel_hi:[0,1]
	v_pk_mul_f32 v[106:107], v[126:127], v[106:107] op_sel_hi:[0,1]
	v_pk_fma_f32 v[104:105], v[8:9], v[104:105], v[12:13]
	v_pk_fma_f32 v[110:111], v[2:3], v[110:111], v[6:7]
	v_pk_fma_f32 v[108:109], v[0:1], v[108:109], v[4:5]
	v_pk_fma_f32 v[106:107], v[10:11], v[106:107], v[14:15]
	v_pk_mul_f32 v[104:105], v[104:105], s[26:27] op_sel_hi:[1,0]
	v_pk_mul_f32 v[108:109], v[108:109], s[26:27] op_sel_hi:[1,0]
	v_pk_mul_f32 v[110:111], v[110:111], s[26:27] op_sel_hi:[1,0]
	v_pk_mul_f32 v[106:107], v[106:107], s[26:27] op_sel_hi:[1,0]
	v_pk_fma_f32 v[100:101], v[100:101], s[28:29], v[104:105] op_sel_hi:[1,0,1]
	v_pk_fma_f32 v[104:105], v[98:99], s[28:29], v[110:111] op_sel_hi:[1,0,1]
	v_pk_fma_f32 v[98:99], v[96:97], s[28:29], v[108:109] op_sel_hi:[1,0,1]
	v_pk_fma_f32 v[102:103], v[102:103], s[28:29], v[106:107] op_sel_hi:[1,0,1]
	v_cvt_pk_bf16_f32 v96, v100, v101
	v_lshl_add_u64 v[106:107], v[114:115], 2, s[14:15]
	v_cvt_pk_bf16_f32 v97, v102, v103
	v_cvt_pk_bf16_f32 v98, v98, v99
	v_cvt_pk_bf16_f32 v99, v104, v105
	global_store_dwordx4 v[124:125], v[96:99], off offset:256
	global_load_dwordx2 v[104:105], v[112:113], off
	global_load_dwordx4 v[96:99], v[106:107], off nt
	global_load_dwordx4 v[100:103], v[106:107], off offset:16 nt
	v_lshl_add_u64 v[108:109], v[114:115], 1, s[16:17]
	s_waitcnt vmcnt(2)
;     __device__ __forceinline__ void operator()(EPI_ARGS) const {
;         const int row0 = u.pm * BM + wr * 64 + fr, col0 = u.pn * BM + wc * 32 + 8 * fq;
;         f32x4 gg[2][2], bb[2][2];
;         if constexpr (RESLN) {
; #pragma unroll
;             for (int bj = 0; bj < 2; ++bj)
; #pragma unroll
;                 for (int n = 0; n < 2; ++n) { gg[bj][n] = *(const f32x4*)(lg + col0 + bj * HALF + 4 * n); bb[bj][n] = *(const f32x4*)(lb + col0 + bj * HALF + 4 * n); } }
; #pragma unroll
;         for (int ai = 0; ai < 2; ++ai)
; #pragma unroll
;             for (int m = 0; m < 4; ++m) { const int row = row0 + ai * HALF + m * 16; const size_t off = (size_t)row * DM + col0;
;                 float mu = 0.f, rs = 1.f; if constexpr (RESLN) ln_stats(stin, row, mu, rs);
;                 float ss = 0.f, qq = 0.f;
; #pragma unroll
;                 for (int bj = 0; bj < 2; ++bj) { f32x4 r0 = __builtin_nontemporal_load((const f32x4*)(res + off + bj * HALF)), r1 = __builtin_nontemporal_load((const f32x4*)(res + off + bj * HALF + 4));
;                     if constexpr (RESLN) { r0 = (r0 - mu) * rs * gg[bj][0] + bb[bj][0]; r1 = (r1 - mu) * rs * gg[bj][1] + bb[bj][1]; }
;                     const f32x4 y0 = r0 * DN_ALPHA + acc[ai][bj][m][0] * ascale, y1 = r1 * DN_ALPHA + acc[ai][bj][m][1] * ascale;
;                     if constexpr (COPY != 4) { __builtin_nontemporal_store(y0, (f32x4*)(Y + off + bj * HALF)); __builtin_nontemporal_store(y1, (f32x4*)(Y + off + bj * HALF + 4)); }
;                     if constexpr (STATS) { ss += ((y0[0] + y0[1]) + (y0[2] + y0[3])) + ((y1[0] + y1[1]) + (y1[2] + y1[3]));
;                         qq += ((y0[0] * y0[0] + y0[1] * y0[1]) + (y0[2] * y0[2] + y0[3] * y0[3])) + ((y1[0] * y1[0] + y1[1] * y1[1]) + (y1[2] * y1[2] + y1[3] * y1[3])); }
;                     if constexpr (COPY == 1) *(u32x2*)((unsigned char*)copy + off + bj * HALF) = pack8fp8(y0 * cscale, y1 * cscale);
;                     if constexpr (COPY == 3) *(u32x2*)((unsigned char*)copy + off + bj * HALF) = pack8i8(y0 * cscale, y1 * cscale);
;                     if constexpr (COPY == 2 || COPY == 4) *(u32x4*)((bf16_t*)copy + off + bj * HALF) = pack8bf(y0, y1); }
;                 if constexpr (STATS) { ss += __shfl_xor(ss, 16); ss += __shfl_xor(ss, 32); qq += __shfl_xor(qq, 16); qq += __shfl_xor(qq, 32);
	v_pk_mul_f32 v[104:105], v[104:105], s[24:25] op_sel_hi:[1,0]
	s_nop 0
	v_fma_f32 v105, -v104, v104, v105
	v_add_f32_e32 v105, 0x3727c5ac, v105
	v_rsq_f32_e32 v254, v105
	s_waitcnt vmcnt(1)
	v_sub_f32_e32 v97, v97, v104
	v_sub_f32_e32 v96, v96, v104
	s_waitcnt vmcnt(0)
	v_sub_f32_e32 v103, v103, v104
	v_sub_f32_e32 v102, v102, v104
	v_sub_f32_e32 v101, v101, v104
	v_sub_f32_e32 v100, v100, v104
	v_sub_f32_e32 v99, v99, v104
	v_sub_f32_e32 v98, v98, v104
	s_nop 0
	s_nop 1
	v_mov_b32_e32 v110, v254
	v_pk_mul_f32 v[96:97], v[96:97], v[110:111] op_sel_hi:[1,0]
	v_pk_mul_f32 v[100:101], v[100:101], v[110:111] op_sel_hi:[1,0]
	v_pk_mul_f32 v[102:103], v[102:103], v[110:111] op_sel_hi:[1,0]
	v_pk_mul_f32 v[98:99], v[98:99], v[110:111] op_sel_hi:[1,0]
	v_pk_fma_f32 v[96:97], v[24:25], v[96:97], v[20:21]
	v_pk_fma_f32 v[102:103], v[18:19], v[102:103], v[30:31]
	v_pk_fma_f32 v[100:101], v[16:17], v[100:101], v[28:29]
	v_pk_fma_f32 v[98:99], v[26:27], v[98:99], v[22:23]
	v_pk_mul_f32 v[96:97], v[96:97], s[26:27] op_sel_hi:[1,0]
	v_pk_mul_f32 v[100:101], v[100:101], s[26:27] op_sel_hi:[1,0]
	v_pk_mul_f32 v[102:103], v[102:103], s[26:27] op_sel_hi:[1,0]
	v_pk_mul_f32 v[98:99], v[98:99], s[26:27] op_sel_hi:[1,0]
	v_pk_fma_f32 v[92:93], v[92:93], s[28:29], v[96:97] op_sel_hi:[1,0,1]
	v_pk_fma_f32 v[96:97], v[90:91], s[28:29], v[102:103] op_sel_hi:[1,0,1]
	v_pk_fma_f32 v[90:91], v[88:89], s[28:29], v[100:101] op_sel_hi:[1,0,1]
	v_pk_fma_f32 v[94:95], v[94:95], s[28:29], v[98:99] op_sel_hi:[1,0,1]
	v_cvt_pk_bf16_f32 v88, v92, v93
	s_nop 0
	v_cvt_pk_bf16_f32 v89, v94, v95
	v_cvt_pk_bf16_f32 v90, v90, v91
	v_cvt_pk_bf16_f32 v91, v96, v97
	global_store_dwordx4 v[108:109], v[88:91], off
	global_load_dwordx4 v[88:91], v[106:107], off offset:512 nt
	s_nop 0
	global_load_dwordx4 v[92:95], v[106:107], off offset:528 nt
	v_add_u32_e32 v96, 0x90, v178
	v_ashrrev_i32_e32 v97, 31, v96
	v_lshlrev_b64 v[98:99], 11, v[96:97]
	v_lshl_add_u64 v[96:97], v[96:97], 3, s[12:13]
	v_lshl_add_u64 v[98:99], v[98:99], 0, v[176:177]
	s_waitcnt vmcnt(1)
	v_sub_f32_e32 v89, v89, v104
	v_sub_f32_e32 v88, v88, v104
	s_waitcnt vmcnt(0)
	v_sub_f32_e32 v95, v95, v104
	v_sub_f32_e32 v94, v94, v104
	v_sub_f32_e32 v93, v93, v104
	v_sub_f32_e32 v92, v92, v104
	v_sub_f32_e32 v91, v91, v104
	v_sub_f32_e32 v90, v90, v104
	v_pk_mul_f32 v[88:89], v[110:111], v[88:89] op_sel_hi:[0,1]
	v_pk_mul_f32 v[92:93], v[110:111], v[92:93] op_sel_hi:[0,1]
	v_pk_mul_f32 v[94:95], v[110:111], v[94:95] op_sel_hi:[0,1]
	v_pk_mul_f32 v[90:91], v[110:111], v[90:91] op_sel_hi:[0,1]
	v_pk_fma_f32 v[88:89], v[8:9], v[88:89], v[12:13]
	v_pk_fma_f32 v[94:95], v[2:3], v[94:95], v[6:7]
	v_pk_fma_f32 v[92:93], v[0:1], v[92:93], v[4:5]
	v_pk_fma_f32 v[90:91], v[10:11], v[90:91], v[14:15]
	v_pk_mul_f32 v[88:89], v[88:89], s[26:27] op_sel_hi:[1,0]
	v_pk_mul_f32 v[92:93], v[92:93], s[26:27] op_sel_hi:[1,0]
	v_pk_mul_f32 v[94:95], v[94:95], s[26:27] op_sel_hi:[1,0]
	v_pk_mul_f32 v[90:91], v[90:91], s[26:27] op_sel_hi:[1,0]
	v_pk_fma_f32 v[84:85], v[84:85], s[28:29], v[88:89] op_sel_hi:[1,0,1]
	v_pk_fma_f32 v[88:89], v[82:83], s[28:29], v[94:95] op_sel_hi:[1,0,1]
	v_pk_fma_f32 v[82:83], v[80:81], s[28:29], v[92:93] op_sel_hi:[1,0,1]
	v_pk_fma_f32 v[86:87], v[86:87], s[28:29], v[90:91] op_sel_hi:[1,0,1]
	v_cvt_pk_bf16_f32 v80, v84, v85
	v_lshl_add_u64 v[90:91], v[98:99], 2, s[14:15]
	v_cvt_pk_bf16_f32 v81, v86, v87
	v_cvt_pk_bf16_f32 v82, v82, v83
	v_cvt_pk_bf16_f32 v83, v88, v89
	global_store_dwordx4 v[108:109], v[80:83], off offset:256
	global_load_dwordx2 v[88:89], v[96:97], off
	global_load_dwordx4 v[80:83], v[90:91], off nt
	global_load_dwordx4 v[84:87], v[90:91], off offset:16 nt
	v_lshl_add_u64 v[92:93], v[98:99], 1, s[16:17]
	s_waitcnt vmcnt(2)
	v_pk_mul_f32 v[88:89], v[88:89], s[24:25] op_sel_hi:[1,0]
	s_nop 0
	v_fma_f32 v89, -v88, v88, v89
	v_add_f32_e32 v89, 0x3727c5ac, v89
	v_rsq_f32_e32 v254, v89
	s_waitcnt vmcnt(1)
	v_sub_f32_e32 v81, v81, v88
	v_sub_f32_e32 v80, v80, v88
	s_waitcnt vmcnt(0)
	v_sub_f32_e32 v87, v87, v88
	v_sub_f32_e32 v86, v86, v88
	v_sub_f32_e32 v85, v85, v88
	v_sub_f32_e32 v84, v84, v88
	v_sub_f32_e32 v83, v83, v88
	v_sub_f32_e32 v82, v82, v88
	s_nop 0
	s_nop 1
	v_mov_b32_e32 v94, v254
	v_pk_mul_f32 v[80:81], v[80:81], v[94:95] op_sel_hi:[1,0]
	v_pk_mul_f32 v[84:85], v[84:85], v[94:95] op_sel_hi:[1,0]
	v_pk_mul_f32 v[86:87], v[86:87], v[94:95] op_sel_hi:[1,0]
	v_pk_mul_f32 v[82:83], v[82:83], v[94:95] op_sel_hi:[1,0]
	v_pk_fma_f32 v[80:81], v[24:25], v[80:81], v[20:21]
	v_pk_fma_f32 v[86:87], v[18:19], v[86:87], v[30:31]
	v_pk_fma_f32 v[84:85], v[16:17], v[84:85], v[28:29]
	v_pk_fma_f32 v[82:83], v[26:27], v[82:83], v[22:23]
	v_pk_mul_f32 v[80:81], v[80:81], s[26:27] op_sel_hi:[1,0]
	v_pk_mul_f32 v[84:85], v[84:85], s[26:27] op_sel_hi:[1,0]
	v_pk_mul_f32 v[86:87], v[86:87], s[26:27] op_sel_hi:[1,0]
	v_pk_mul_f32 v[82:83], v[82:83], s[26:27] op_sel_hi:[1,0]
	v_pk_fma_f32 v[76:77], v[76:77], s[28:29], v[80:81] op_sel_hi:[1,0,1]
	v_pk_fma_f32 v[80:81], v[74:75], s[28:29], v[86:87] op_sel_hi:[1,0,1]
	v_pk_fma_f32 v[74:75], v[72:73], s[28:29], v[84:85] op_sel_hi:[1,0,1]
	v_pk_fma_f32 v[78:79], v[78:79], s[28:29], v[82:83] op_sel_hi:[1,0,1]
	v_cvt_pk_bf16_f32 v72, v76, v77
	s_nop 0
	v_cvt_pk_bf16_f32 v73, v78, v79
	v_cvt_pk_bf16_f32 v74, v74, v75
	v_cvt_pk_bf16_f32 v75, v80, v81
	global_store_dwordx4 v[92:93], v[72:75], off
	global_load_dwordx4 v[72:75], v[90:91], off offset:512 nt
	s_nop 0
	global_load_dwordx4 v[76:79], v[90:91], off offset:528 nt
	v_add_u32_e32 v80, 0xa0, v178
	v_ashrrev_i32_e32 v81, 31, v80
	v_lshlrev_b64 v[82:83], 11, v[80:81]
	v_lshl_add_u64 v[80:81], v[80:81], 3, s[12:13]
	v_lshl_add_u64 v[82:83], v[82:83], 0, v[176:177]
	s_waitcnt vmcnt(1)
;     __device__ __forceinline__ void operator()(EPI_ARGS) const {
;         const int row0 = u.pm * BM + wr * 64 + fr, col0 = u.pn * BM + wc * 32 + 8 * fq;
;         f32x4 gg[2][2], bb[2][2];
;         if constexpr (RESLN) {
; #pragma unroll
;             for (int bj = 0; bj < 2; ++bj)
; #pragma unroll
;                 for (int n = 0; n < 2; ++n) { gg[bj][n] = *(const f32x4*)(lg + col0 + bj * HALF + 4 * n); bb[bj][n] = *(const f32x4*)(lb + col0 + bj * HALF + 4 * n); } }
; #pragma unroll
;         for (int ai = 0; ai < 2; ++ai)
; #pragma unroll
;             for (int m = 0; m < 4; ++m) { const int row = row0 + ai * HALF + m * 16; const size_t off = (size_t)row * DM + col0;
;                 float mu = 0.f, rs = 1.f; if constexpr (RESLN) ln_stats(stin, row, mu, rs);
;                 float ss = 0.f, qq = 0.f;
; #pragma unroll
;                 for (int bj = 0; bj < 2; ++bj) { f32x4 r0 = __builtin_nontemporal_load((const f32x4*)(res + off + bj * HALF)), r1 = __builtin_nontemporal_load((const f32x4*)(res + off + bj * HALF + 4));
;                     if constexpr (RESLN) { r0 = (r0 - mu) * rs * gg[bj][0] + bb[bj][0]; r1 = (r1 - mu) * rs * gg[bj][1] + bb[bj][1]; }
;                     const f32x4 y0 = r0 * DN_ALPHA + acc[ai][bj][m][0] * ascale, y1 = r1 * DN_ALPHA + acc[ai][bj][m][1] * ascale;
;                     if constexpr (COPY != 4) { __builtin_nontemporal_store(y0, (f32x4*)(Y + off + bj * HALF)); __builtin_nontemporal_store(y1, (f32x4*)(Y + off + bj * HALF + 4)); }
;                     if constexpr (STATS) { ss += ((y0[0] + y0[1]) + (y0[2] + y0[3])) + ((y1[0] + y1[1]) + (y1[2] + y1[3]));
;                         qq += ((y0[0] * y0[0] + y0[1] * y0[1]) + (y0[2] * y0[2] + y0[3] * y0[3])) + ((y1[0] * y1[0] + y1[1] * y1[1]) + (y1[2] * y1[2] + y1[3] * y1[3])); }
;                     if constexpr (COPY == 1) *(u32x2*)((unsigned char*)copy + off + bj * HALF) = pack8fp8(y0 * cscale, y1 * cscale);
;                     if constexpr (COPY == 3) *(u32x2*)((unsigned char*)copy + off + bj * HALF) = pack8i8(y0 * cscale, y1 * cscale);
;                     if constexpr (COPY == 2 || COPY == 4) *(u32x4*)((bf16_t*)copy + off + bj * HALF) = pack8bf(y0, y1); }
;                 if constexpr (STATS) { ss += __shfl_xor(ss, 16); ss += __shfl_xor(ss, 32); qq += __shfl_xor(qq, 16); qq += __shfl_xor(qq, 32);
	v_sub_f32_e32 v73, v73, v88
	v_sub_f32_e32 v72, v72, v88
	s_waitcnt vmcnt(0)
	v_sub_f32_e32 v79, v79, v88
	v_sub_f32_e32 v78, v78, v88
	v_sub_f32_e32 v77, v77, v88
	v_sub_f32_e32 v76, v76, v88
	v_sub_f32_e32 v75, v75, v88
	v_sub_f32_e32 v74, v74, v88
	v_pk_mul_f32 v[72:73], v[94:95], v[72:73] op_sel_hi:[0,1]
	v_pk_mul_f32 v[76:77], v[94:95], v[76:77] op_sel_hi:[0,1]
	v_pk_mul_f32 v[78:79], v[94:95], v[78:79] op_sel_hi:[0,1]
	v_pk_mul_f32 v[74:75], v[94:95], v[74:75] op_sel_hi:[0,1]
	v_pk_fma_f32 v[72:73], v[8:9], v[72:73], v[12:13]
	v_pk_fma_f32 v[78:79], v[2:3], v[78:79], v[6:7]
	v_pk_fma_f32 v[76:77], v[0:1], v[76:77], v[4:5]
	v_pk_fma_f32 v[74:75], v[10:11], v[74:75], v[14:15]
	v_pk_mul_f32 v[72:73], v[72:73], s[26:27] op_sel_hi:[1,0]
	v_pk_mul_f32 v[76:77], v[76:77], s[26:27] op_sel_hi:[1,0]
	v_pk_mul_f32 v[78:79], v[78:79], s[26:27] op_sel_hi:[1,0]
	v_pk_mul_f32 v[74:75], v[74:75], s[26:27] op_sel_hi:[1,0]
	v_pk_fma_f32 v[68:69], v[68:69], s[28:29], v[72:73] op_sel_hi:[1,0,1]
	v_pk_fma_f32 v[72:73], v[66:67], s[28:29], v[78:79] op_sel_hi:[1,0,1]
	v_pk_fma_f32 v[66:67], v[64:65], s[28:29], v[76:77] op_sel_hi:[1,0,1]
	v_pk_fma_f32 v[70:71], v[70:71], s[28:29], v[74:75] op_sel_hi:[1,0,1]
	v_cvt_pk_bf16_f32 v64, v68, v69
	v_lshl_add_u64 v[74:75], v[82:83], 2, s[14:15]
	v_cvt_pk_bf16_f32 v65, v70, v71
	v_cvt_pk_bf16_f32 v66, v66, v67
	v_cvt_pk_bf16_f32 v67, v72, v73
	global_store_dwordx4 v[92:93], v[64:67], off offset:256
	global_load_dwordx2 v[72:73], v[80:81], off
	global_load_dwordx4 v[64:67], v[74:75], off nt
	global_load_dwordx4 v[68:71], v[74:75], off offset:16 nt
	v_lshl_add_u64 v[76:77], v[82:83], 1, s[16:17]
	s_waitcnt vmcnt(2)
	v_pk_mul_f32 v[72:73], v[72:73], s[24:25] op_sel_hi:[1,0]
	s_nop 0
	v_fma_f32 v73, -v72, v72, v73
	v_add_f32_e32 v73, 0x3727c5ac, v73
	v_rsq_f32_e32 v254, v73
	s_waitcnt vmcnt(1)
	v_sub_f32_e32 v65, v65, v72
	v_sub_f32_e32 v64, v64, v72
	s_waitcnt vmcnt(0)
	v_sub_f32_e32 v71, v71, v72
	v_sub_f32_e32 v70, v70, v72
	v_sub_f32_e32 v69, v69, v72
	v_sub_f32_e32 v68, v68, v72
	v_sub_f32_e32 v67, v67, v72
	v_sub_f32_e32 v66, v66, v72
	s_nop 0
	s_nop 1
	v_mov_b32_e32 v78, v254
	v_pk_mul_f32 v[64:65], v[64:65], v[78:79] op_sel_hi:[1,0]
	v_pk_mul_f32 v[68:69], v[68:69], v[78:79] op_sel_hi:[1,0]
	v_pk_mul_f32 v[70:71], v[70:71], v[78:79] op_sel_hi:[1,0]
	v_pk_mul_f32 v[66:67], v[66:67], v[78:79] op_sel_hi:[1,0]
	v_pk_fma_f32 v[64:65], v[24:25], v[64:65], v[20:21]
	v_pk_fma_f32 v[70:71], v[18:19], v[70:71], v[30:31]
	v_pk_fma_f32 v[68:69], v[16:17], v[68:69], v[28:29]
	v_pk_fma_f32 v[66:67], v[26:27], v[66:67], v[22:23]
	v_pk_mul_f32 v[64:65], v[64:65], s[26:27] op_sel_hi:[1,0]
	v_pk_mul_f32 v[68:69], v[68:69], s[26:27] op_sel_hi:[1,0]
	v_pk_mul_f32 v[70:71], v[70:71], s[26:27] op_sel_hi:[1,0]
	v_pk_mul_f32 v[66:67], v[66:67], s[26:27] op_sel_hi:[1,0]
	v_pk_fma_f32 v[60:61], v[60:61], s[28:29], v[64:65] op_sel_hi:[1,0,1]
	v_pk_fma_f32 v[64:65], v[58:59], s[28:29], v[70:71] op_sel_hi:[1,0,1]
	v_pk_fma_f32 v[58:59], v[56:57], s[28:29], v[68:69] op_sel_hi:[1,0,1]
	v_pk_fma_f32 v[62:63], v[62:63], s[28:29], v[66:67] op_sel_hi:[1,0,1]
	v_cvt_pk_bf16_f32 v56, v60, v61
	s_nop 0
	v_cvt_pk_bf16_f32 v57, v62, v63
	v_cvt_pk_bf16_f32 v58, v58, v59
	v_cvt_pk_bf16_f32 v59, v64, v65
	global_store_dwordx4 v[76:77], v[56:59], off
	global_load_dwordx4 v[56:59], v[74:75], off offset:512 nt
	s_nop 0
	global_load_dwordx4 v[60:63], v[74:75], off offset:528 nt
	v_add_u32_e32 v64, 0xb0, v178
	v_ashrrev_i32_e32 v65, 31, v64
	v_lshlrev_b64 v[66:67], 11, v[64:65]
	v_lshl_add_u64 v[64:65], v[64:65], 3, s[12:13]
	v_lshl_add_u64 v[66:67], v[66:67], 0, v[176:177]
	s_waitcnt vmcnt(1)
	v_sub_f32_e32 v57, v57, v72
	v_sub_f32_e32 v56, v56, v72
	s_waitcnt vmcnt(0)
;     __device__ __forceinline__ void operator()(EPI_ARGS) const {
;         const int row0 = u.pm * BM + wr * 64 + fr, col0 = u.pn * BM + wc * 32 + 8 * fq;
;         f32x4 gg[2][2], bb[2][2];
;         if constexpr (RESLN) {
; #pragma unroll
;             for (int bj = 0; bj < 2; ++bj)
; #pragma unroll
;                 for (int n = 0; n < 2; ++n) { gg[bj][n] = *(const f32x4*)(lg + col0 + bj * HALF + 4 * n); bb[bj][n] = *(const f32x4*)(lb + col0 + bj * HALF + 4 * n); } }
; #pragma unroll
;         for (int ai = 0; ai < 2; ++ai)
; #pragma unroll
;             for (int m = 0; m < 4; ++m) { const int row = row0 + ai * HALF + m * 16; const size_t off = (size_t)row * DM + col0;
;                 float mu = 0.f, rs = 1.f; if constexpr (RESLN) ln_stats(stin, row, mu, rs);
;                 float ss = 0.f, qq = 0.f;
; #pragma unroll
;                 for (int bj = 0; bj < 2; ++bj) { f32x4 r0 = __builtin_nontemporal_load((const f32x4*)(res + off + bj * HALF)), r1 = __builtin_nontemporal_load((const f32x4*)(res + off + bj * HALF + 4));
;                     if constexpr (RESLN) { r0 = (r0 - mu) * rs * gg[bj][0] + bb[bj][0]; r1 = (r1 - mu) * rs * gg[bj][1] + bb[bj][1]; }
;                     const f32x4 y0 = r0 * DN_ALPHA + acc[ai][bj][m][0] * ascale, y1 = r1 * DN_ALPHA + acc[ai][bj][m][1] * ascale;
;                     if constexpr (COPY != 4) { __builtin_nontemporal_store(y0, (f32x4*)(Y + off + bj * HALF)); __builtin_nontemporal_store(y1, (f32x4*)(Y + off + bj * HALF + 4)); }
;                     if constexpr (STATS) { ss += ((y0[0] + y0[1]) + (y0[2] + y0[3])) + ((y1[0] + y1[1]) + (y1[2] + y1[3]));
;                         qq += ((y0[0] * y0[0] + y0[1] * y0[1]) + (y0[2] * y0[2] + y0[3] * y0[3])) + ((y1[0] * y1[0] + y1[1] * y1[1]) + (y1[2] * y1[2] + y1[3] * y1[3])); }
;                     if constexpr (COPY == 1) *(u32x2*)((unsigned char*)copy + off + bj * HALF) = pack8fp8(y0 * cscale, y1 * cscale);
;                     if constexpr (COPY == 3) *(u32x2*)((unsigned char*)copy + off + bj * HALF) = pack8i8(y0 * cscale, y1 * cscale);
;                     if constexpr (COPY == 2 || COPY == 4) *(u32x4*)((bf16_t*)copy + off + bj * HALF) = pack8bf(y0, y1); }
;                 if constexpr (STATS) { ss += __shfl_xor(ss, 16); ss += __shfl_xor(ss, 32); qq += __shfl_xor(qq, 16); qq += __shfl_xor(qq, 32);
	v_sub_f32_e32 v63, v63, v72
	v_sub_f32_e32 v62, v62, v72
	v_sub_f32_e32 v61, v61, v72
	v_sub_f32_e32 v60, v60, v72
	v_sub_f32_e32 v59, v59, v72
	v_sub_f32_e32 v58, v58, v72
	v_pk_mul_f32 v[56:57], v[78:79], v[56:57] op_sel_hi:[0,1]
	v_pk_mul_f32 v[60:61], v[78:79], v[60:61] op_sel_hi:[0,1]
	v_pk_mul_f32 v[62:63], v[78:79], v[62:63] op_sel_hi:[0,1]
	v_pk_mul_f32 v[58:59], v[78:79], v[58:59] op_sel_hi:[0,1]
	v_pk_fma_f32 v[56:57], v[8:9], v[56:57], v[12:13]
	v_pk_fma_f32 v[62:63], v[2:3], v[62:63], v[6:7]
	v_pk_fma_f32 v[60:61], v[0:1], v[60:61], v[4:5]
	v_pk_fma_f32 v[58:59], v[10:11], v[58:59], v[14:15]
	v_pk_mul_f32 v[56:57], v[56:57], s[26:27] op_sel_hi:[1,0]
	v_pk_mul_f32 v[60:61], v[60:61], s[26:27] op_sel_hi:[1,0]
	v_pk_mul_f32 v[62:63], v[62:63], s[26:27] op_sel_hi:[1,0]
	v_pk_mul_f32 v[58:59], v[58:59], s[26:27] op_sel_hi:[1,0]
	v_pk_fma_f32 v[52:53], v[52:53], s[28:29], v[56:57] op_sel_hi:[1,0,1]
	v_pk_fma_f32 v[56:57], v[50:51], s[28:29], v[62:63] op_sel_hi:[1,0,1]
	v_pk_fma_f32 v[50:51], v[48:49], s[28:29], v[60:61] op_sel_hi:[1,0,1]
	v_pk_fma_f32 v[54:55], v[54:55], s[28:29], v[58:59] op_sel_hi:[1,0,1]
	v_cvt_pk_bf16_f32 v48, v52, v53
	v_lshl_add_u64 v[58:59], v[66:67], 2, s[14:15]
	v_cvt_pk_bf16_f32 v49, v54, v55
	v_cvt_pk_bf16_f32 v50, v50, v51
	v_cvt_pk_bf16_f32 v51, v56, v57
	global_store_dwordx4 v[76:77], v[48:51], off offset:256
	global_load_dwordx2 v[56:57], v[64:65], off
	global_load_dwordx4 v[48:51], v[58:59], off nt
	global_load_dwordx4 v[52:55], v[58:59], off offset:16 nt
	v_lshl_add_u64 v[60:61], v[66:67], 1, s[16:17]
	s_waitcnt vmcnt(2)
	v_pk_mul_f32 v[56:57], v[56:57], s[24:25] op_sel_hi:[1,0]
	s_nop 0
	v_fma_f32 v57, -v56, v56, v57
	v_add_f32_e32 v57, 0x3727c5ac, v57
	v_rsq_f32_e32 v254, v57
	s_waitcnt vmcnt(0)
	v_sub_f32_e32 v55, v55, v56
	v_sub_f32_e32 v54, v54, v56
	v_sub_f32_e32 v53, v53, v56
	v_sub_f32_e32 v52, v52, v56
	v_sub_f32_e32 v51, v51, v56
	v_sub_f32_e32 v50, v50, v56
	v_sub_f32_e32 v49, v49, v56
	v_sub_f32_e32 v48, v48, v56
	s_nop 0
	s_nop 1
	v_mov_b32_e32 v62, v254
	v_pk_mul_f32 v[52:53], v[52:53], v[62:63] op_sel_hi:[1,0]
	v_pk_mul_f32 v[54:55], v[54:55], v[62:63] op_sel_hi:[1,0]
	v_pk_mul_f32 v[48:49], v[48:49], v[62:63] op_sel_hi:[1,0]
	v_pk_mul_f32 v[50:51], v[50:51], v[62:63] op_sel_hi:[1,0]
	v_pk_fma_f32 v[18:19], v[18:19], v[54:55], v[30:31]
	v_pk_fma_f32 v[16:17], v[16:17], v[52:53], v[28:29]
	v_pk_fma_f32 v[22:23], v[26:27], v[50:51], v[22:23]
	v_pk_fma_f32 v[20:21], v[24:25], v[48:49], v[20:21]
	v_pk_mul_f32 v[16:17], v[16:17], s[26:27] op_sel_hi:[1,0]
	v_pk_mul_f32 v[18:19], v[18:19], s[26:27] op_sel_hi:[1,0]
	v_pk_mul_f32 v[20:21], v[20:21], s[26:27] op_sel_hi:[1,0]
	v_pk_mul_f32 v[22:23], v[22:23], s[26:27] op_sel_hi:[1,0]
	v_pk_fma_f32 v[24:25], v[42:43], s[28:29], v[18:19] op_sel_hi:[1,0,1]
	v_pk_fma_f32 v[18:19], v[40:41], s[28:29], v[16:17] op_sel_hi:[1,0,1]
	v_pk_fma_f32 v[22:23], v[46:47], s[28:29], v[22:23] op_sel_hi:[1,0,1]
	v_pk_fma_f32 v[20:21], v[44:45], s[28:29], v[20:21] op_sel_hi:[1,0,1]
	s_andn2_b64 vcc, exec, s[2:3]
	v_cvt_pk_bf16_f32 v16, v20, v21
	v_cvt_pk_bf16_f32 v17, v22, v23
	v_cvt_pk_bf16_f32 v18, v18, v19
	v_cvt_pk_bf16_f32 v19, v24, v25
	global_store_dwordx4 v[60:61], v[16:19], off
	global_load_dwordx4 v[16:19], v[58:59], off offset:512 nt
	s_nop 0
	global_load_dwordx4 v[20:23], v[58:59], off offset:528 nt
	s_mov_b64 s[2:3], -1
	s_waitcnt vmcnt(1)
	v_sub_f32_e32 v19, v19, v56
	s_waitcnt vmcnt(0)
	v_sub_f32_e32 v23, v23, v56
	v_sub_f32_e32 v22, v22, v56
	v_sub_f32_e32 v21, v21, v56
	v_sub_f32_e32 v20, v20, v56
	v_sub_f32_e32 v18, v18, v56
	v_sub_f32_e32 v17, v17, v56
	v_sub_f32_e32 v16, v16, v56
	v_pk_mul_f32 v[20:21], v[62:63], v[20:21] op_sel_hi:[0,1]
	v_pk_mul_f32 v[22:23], v[62:63], v[22:23] op_sel_hi:[0,1]
	v_pk_mul_f32 v[16:17], v[62:63], v[16:17] op_sel_hi:[0,1]
	v_pk_mul_f32 v[18:19], v[62:63], v[18:19] op_sel_hi:[0,1]
	v_pk_fma_f32 v[2:3], v[2:3], v[22:23], v[6:7]
	v_pk_fma_f32 v[0:1], v[0:1], v[20:21], v[4:5]
	v_pk_fma_f32 v[10:11], v[10:11], v[18:19], v[14:15]
	v_pk_fma_f32 v[8:9], v[8:9], v[16:17], v[12:13]
	v_pk_mul_f32 v[0:1], v[0:1], s[26:27] op_sel_hi:[1,0]
	v_pk_mul_f32 v[2:3], v[2:3], s[26:27] op_sel_hi:[1,0]
	v_pk_mul_f32 v[4:5], v[8:9], s[26:27] op_sel_hi:[1,0]
	v_pk_mul_f32 v[6:7], v[10:11], s[26:27] op_sel_hi:[1,0]
	v_pk_fma_f32 v[8:9], v[34:35], s[28:29], v[2:3] op_sel_hi:[1,0,1]
	v_pk_fma_f32 v[2:3], v[32:33], s[28:29], v[0:1] op_sel_hi:[1,0,1]
	v_pk_fma_f32 v[6:7], v[38:39], s[28:29], v[6:7] op_sel_hi:[1,0,1]
	v_pk_fma_f32 v[4:5], v[36:37], s[28:29], v[4:5] op_sel_hi:[1,0,1]
	s_nop 0
	v_cvt_pk_bf16_f32 v0, v4, v5
	v_cvt_pk_bf16_f32 v1, v6, v7
	v_cvt_pk_bf16_f32 v2, v2, v3
	v_cvt_pk_bf16_f32 v3, v8, v9
	global_store_dwordx4 v[60:61], v[0:3], off offset:256
	s_cbranch_vccnz .LBB0_4494
	s_andn2_b64 vcc, exec, s[6:7]
	s_cbranch_vccnz .LBB0_4493
	s_barrier
	s_branch .LBB0_4493
